# static s_setprio 1 for the younger half (wr==1) around each GEMM K loop with all per-phase flips deleted, on top of v51
# baseline (speedup 1.0000x reference)
; #define PG8_STAGE(bufoff, gbase, voff) do { _Pragma("unroll") for (int _i = 0; _i < 2; ++_i) \
;         __builtin_amdgcn_global_load_lds((const unsigned*)((const char*)(gbase) + (voff)[_i]), (LAS unsigned*)(lds + (bufoff) + ldsw + _i * 8192), 16, 0, 0); } while (0)
; #define PG8_LDA(dst, b, h) do { _Pragma("unroll") for (int m = 0; m < 4; ++m) _Pragma("unroll") for (int k = 0; k < 2; ++k) dst[m][k] = *(const LAS bf16x8*)(lds + PG8_SA(b, h) + aoff + m * 2048 + k * 1024); } while (0)
; #define PG8_LDB(dst, b, h) do { _Pragma("unroll") for (int n = 0; n < 2; ++n) _Pragma("unroll") for (int k = 0; k < 2; ++k) dst[n][k] = *(const LAS bf16x8*)(lds + PG8_SB(b, h) + boff + n * 2048 + k * 1024); } while (0)
; #define PG8_SCHED __builtin_amdgcn_sched_barrier(0)
; template <class Epi>
; DI void gemm_phase(int wv, LAS unsigned char* lds, LAS unsigned char* scr, const Sched& S, const Epi& E) {
;     ...
; #pragma unroll
;     for (int a = 0; a < 2; ++a)
; #pragma unroll
;         for (int b = 0; b < 2; ++b)
; #pragma unroll
;             for (int m = 0; m < 4; ++m)
; #pragma unroll
;                 for (int n = 0; n < 2; ++n) acc[a][b][m][n] = (f32x4){0.f, 0.f, 0.f, 0.f};
;     ...
;         const bool has_next = S.next(ui + 1, nxt);
;         const char* nA = has_next ? S.baseA(nxt) : cA; const char* nB = has_next ? S.baseB(nxt) : cB;
;         for (int t = 0; t < nt; t += 2) {
;             const bool last = (t == nt - 2);
;             const char* a1 = cA + (size_t)(t + 1) * kstep;
;             const char* a2 = last ? nA : cA + (size_t)(t + 2) * kstep; const char* b2 = last ? nB : cB + (size_t)(t + 2) * kstep;
;             const char* a3 = a2 + kstep; const char* b3 = b2 + kstep;
;             PG8_LDB(B0, 0, 0); PG8_LDB(B1, 0, 1); PG8_SCHED; PG8_LDA(At, 0, 0); PG8_STAGE(PG8_SA(1, 1), a1 + hstepA, voffA);
.LBB0_42:
	s_ashr_i32 s15, s14, 31
	s_lshl_b64 s[16:17], s[14:15], 19
	s_add_u32 s16, s33, s16
	s_addc_u32 s17, s34, s17
	s_and_b64 s[18:19], s[10:11], exec
	s_cselect_b32 s7, s17, s21
	s_cselect_b32 s9, s16, s20
	s_ashr_i32 s13, s12, 31
	s_lshl_b64 s[18:19], s[12:13], 19
	s_add_u32 s18, s35, s18
	s_addc_u32 s19, s36, s19
	s_and_b64 s[24:25], s[10:11], exec
	s_cselect_b32 s13, s19, s23
	s_cselect_b32 s15, s18, s22
	s_add_u32 s49, s22, 0x100
	s_addc_u32 s52, s23, 0
	s_add_u32 s20, s20, 0x40080
	v_mov_b32_e32 v0, 0
	v_mov_b32_e32 v220, 0x358637bd
	s_addc_u32 s21, s21, 0
	s_mov_b32 s53, -2
	v_mov_b32_e32 v1, v0
	v_mov_b32_e32 v2, v0
	v_mov_b32_e32 v3, v0
	v_mov_b32_e32 v4, v0
	v_mov_b32_e32 v5, v0
	v_mov_b32_e32 v6, v0
	v_mov_b32_e32 v7, v0
	v_mov_b32_e32 v8, v0
	v_mov_b32_e32 v9, v0
	v_mov_b32_e32 v10, v0
	v_mov_b32_e32 v11, v0
	v_mov_b32_e32 v12, v0
	v_mov_b32_e32 v13, v0
	v_mov_b32_e32 v14, v0
	v_mov_b32_e32 v15, v0
	v_mov_b32_e32 v24, v0
	v_mov_b32_e32 v25, v0
	v_mov_b32_e32 v26, v0
	v_mov_b32_e32 v27, v0
	v_mov_b32_e32 v28, v0
	v_mov_b32_e32 v29, v0
	v_mov_b32_e32 v30, v0
	v_mov_b32_e32 v31, v0
	v_mov_b32_e32 v40, v0
	v_mov_b32_e32 v41, v0
	v_mov_b32_e32 v42, v0
	v_mov_b32_e32 v43, v0
	s_waitcnt vmcnt(0)
	v_mov_b32_e32 v44, v0
	v_mov_b32_e32 v45, v0
	v_mov_b32_e32 v46, v0
	v_mov_b32_e32 v47, v0
	v_mov_b32_e32 v16, v0
	v_mov_b32_e32 v17, v0
	v_mov_b32_e32 v18, v0
	v_mov_b32_e32 v19, v0
	v_mov_b32_e32 v20, v0
	v_mov_b32_e32 v21, v0
	v_mov_b32_e32 v22, v0
	v_mov_b32_e32 v23, v0
	v_mov_b32_e32 v32, v0
	v_mov_b32_e32 v33, v0
	v_mov_b32_e32 v34, v0
	v_mov_b32_e32 v35, v0
	v_mov_b32_e32 v36, v0
	v_mov_b32_e32 v37, v0
	v_mov_b32_e32 v38, v0
	v_mov_b32_e32 v39, v0
	v_mov_b32_e32 v48, v0
	v_mov_b32_e32 v49, v0
	v_mov_b32_e32 v50, v0
	v_mov_b32_e32 v51, v0
	v_mov_b32_e32 v52, v0
	v_mov_b32_e32 v53, v0
	v_mov_b32_e32 v54, v0
	v_mov_b32_e32 v55, v0
	v_mov_b32_e32 v56, v0
	v_mov_b32_e32 v57, v0
	v_mov_b32_e32 v58, v0
	v_mov_b32_e32 v59, v0
	v_mov_b32_e32 v60, v0
	v_mov_b32_e32 v61, v0
	v_mov_b32_e32 v62, v0
	v_mov_b32_e32 v63, v0
	v_mov_b32_e32 v64, v0
	v_mov_b32_e32 v65, v0
	v_mov_b32_e32 v66, v0
	v_mov_b32_e32 v67, v0
	v_mov_b32_e32 v68, v0
	v_mov_b32_e32 v69, v0
	v_mov_b32_e32 v70, v0
	v_mov_b32_e32 v71, v0
	v_mov_b32_e32 v72, v0
	v_mov_b32_e32 v73, v0
	v_mov_b32_e32 v74, v0
	v_mov_b32_e32 v75, v0
	v_mov_b32_e32 v76, v0
	v_mov_b32_e32 v77, v0
	v_mov_b32_e32 v78, v0
	v_mov_b32_e32 v79, v0
	v_mov_b32_e32 v88, v0
	v_mov_b32_e32 v89, v0
	v_mov_b32_e32 v90, v0
	v_mov_b32_e32 v91, v0
	v_mov_b32_e32 v92, v0
	v_mov_b32_e32 v93, v0
	v_mov_b32_e32 v94, v0
	v_mov_b32_e32 v95, v0
	v_mov_b32_e32 v104, v0
	v_mov_b32_e32 v105, v0
	v_mov_b32_e32 v106, v0
	v_mov_b32_e32 v107, v0
	v_mov_b32_e32 v108, v0
	v_mov_b32_e32 v109, v0
	v_mov_b32_e32 v110, v0
	v_mov_b32_e32 v111, v0
	v_mov_b32_e32 v80, v0
	v_mov_b32_e32 v81, v0
	v_mov_b32_e32 v82, v0
	v_mov_b32_e32 v83, v0
	v_mov_b32_e32 v84, v0
	v_mov_b32_e32 v85, v0
	v_mov_b32_e32 v86, v0
	v_mov_b32_e32 v87, v0
	v_mov_b32_e32 v96, v0
	v_mov_b32_e32 v97, v0
	v_mov_b32_e32 v98, v0
	v_mov_b32_e32 v99, v0
	v_mov_b32_e32 v100, v0
	v_mov_b32_e32 v101, v0
	v_mov_b32_e32 v102, v0
	v_mov_b32_e32 v103, v0
	v_mov_b32_e32 v112, v0
	v_mov_b32_e32 v113, v0
	v_mov_b32_e32 v114, v0
	v_mov_b32_e32 v115, v0
	v_mov_b32_e32 v116, v0
	v_mov_b32_e32 v117, v0
	v_mov_b32_e32 v118, v0
	v_mov_b32_e32 v119, v0
	v_mov_b32_e32 v120, v0
	v_mov_b32_e32 v121, v0
	v_mov_b32_e32 v122, v0
	v_mov_b32_e32 v123, v0
	v_mov_b32_e32 v124, v0
	v_mov_b32_e32 v125, v0
	v_mov_b32_e32 v126, v0
	v_mov_b32_e32 v127, v0
	s_cmp_lg_u64 s[4:5], 0
	s_cbranch_scc1 .Lgp_1
	s_setprio 1
.Lgp_1:
.LBB0_43:
	s_add_u32 s22, s20, 0xfffc0080
	s_addc_u32 s23, s21, -1
	s_add_i32 s56, 0, 0x10000
	s_cmp_eq_u32 s53, 12
	s_cselect_b32 s25, s7, s23
	s_cselect_b32 s24, s9, s22
	s_cselect_b32 s23, s13, s52
	s_cselect_b32 s22, s15, s49
	s_add_i32 s58, 0, 0x14000
	v_add_u32_e32 v156, s56, v142
	v_add_u32_e32 v172, s58, v142
	ds_read_b128 v[144:147], v156
	ds_read_b128 v[148:151], v156 offset:1024
	ds_read_b128 v[152:155], v156 offset:2048
	ds_read_b128 v[156:159], v156 offset:3072
	ds_read_b128 v[160:163], v172
	ds_read_b128 v[164:167], v172 offset:1024
	ds_read_b128 v[168:171], v172 offset:2048
	ds_read_b128 v[172:175], v172 offset:3072
	v_lshl_add_u64 v[210:211], s[20:21], 0, v[140:141]
	s_add_i32 m0, s38, 0xc000
	ds_read_b128 v[176:179], v143
	ds_read_b128 v[180:183], v143 offset:1024
	ds_read_b128 v[184:187], v143 offset:2048
	ds_read_b128 v[188:191], v143 offset:3072
	ds_read_b128 v[194:197], v143 offset:4096
	ds_read_b128 v[198:201], v143 offset:5120
	ds_read_b128 v[202:205], v143 offset:6144
	ds_read_b128 v[206:209], v143 offset:7168
	global_load_lds_dwordx4 v[210:211], off
	v_lshl_add_u64 v[210:211], s[20:21], 0, v[138:139]
	s_add_i32 m0, s38, 0xe000
	s_nop 0
	global_load_lds_dwordx4 v[210:211], off
	s_waitcnt vmcnt(8)
	s_waitcnt lgkmcnt(0)
	s_barrier
; #define PG8_STAGE(bufoff, gbase, voff) do { _Pragma("unroll") for (int _i = 0; _i < 2; ++_i) \
;         __builtin_amdgcn_global_load_lds((const unsigned*)((const char*)(gbase) + (voff)[_i]), (LAS unsigned*)(lds + (bufoff) + ldsw + _i * 8192), 16, 0, 0); } while (0)
; #define PG8_LDA(dst, b, h) do { _Pragma("unroll") for (int m = 0; m < 4; ++m) _Pragma("unroll") for (int k = 0; k < 2; ++k) dst[m][k] = *(const LAS bf16x8*)(lds + PG8_SA(b, h) + aoff + m * 2048 + k * 1024); } while (0)
; #define PG8_MMA(ai, bj, At, Bt) do { __builtin_amdgcn_s_setprio(1); _Pragma("unroll") for (int m = 0; m < 4; ++m) _Pragma("unroll") for (int n = 0; n < 2; ++n) _Pragma("unroll") for (int k = 0; k < 2; ++k) \
;         acc[ai][bj][m][n] = __builtin_amdgcn_mfma_f32_16x16x32_bf16(Bt[n][k], At[m][k], acc[ai][bj][m][n], 0, 0, 0); __builtin_amdgcn_s_setprio(0); } while (0)
; #define PG8_WAIT_V(n) asm volatile("s_waitcnt vmcnt(" #n ")" ::: "memory")
; #define PG8_WAIT_L(n) asm volatile("s_waitcnt lgkmcnt(" #n ")" ::: "memory")
; #define PG8_BAR __builtin_amdgcn_s_barrier()
; #define PG8_SCHED __builtin_amdgcn_sched_barrier(0)
; template <class Epi>
; DI void gemm_phase(int wv, LAS unsigned char* lds, LAS unsigned char* scr, const Sched& S, const Epi& E) {
;     ...
;             PG8_WAIT_V(8); PG8_WAIT_L(0); PG8_BAR; PG8_MMA(0, 0, At, B0); PG8_MMA(0, 1, At, B1); PG8_BAR; PG8_SCHED;
;             PG8_LDA(At, 0, 1); PG8_STAGE(PG8_SB(0, 0), b2, voffB); PG8_STAGE(PG8_SB(0, 1), b2 + hstepB, voffB); PG8_STAGE(PG8_SA(0, 0), a2, voffA);
;             PG8_WAIT_V(8); PG8_WAIT_L(0); PG8_BAR; PG8_MMA(1, 0, At, B0); PG8_MMA(1, 1, At, B1); PG8_BAR; PG8_SCHED;
	s_waitcnt lgkmcnt(0)
	v_mfma_f32_16x16x32_bf16 v[124:127], v[144:147], v[176:179], v[124:127]
	v_mfma_f32_16x16x32_bf16 v[120:123], v[152:155], v[176:179], v[120:123]
	v_mfma_f32_16x16x32_bf16 v[116:119], v[144:147], v[184:187], v[116:119]
	v_mfma_f32_16x16x32_bf16 v[112:115], v[152:155], v[184:187], v[112:115]
	v_mfma_f32_16x16x32_bf16 v[100:103], v[144:147], v[194:197], v[100:103]
	v_mfma_f32_16x16x32_bf16 v[96:99], v[152:155], v[194:197], v[96:99]
	v_mfma_f32_16x16x32_bf16 v[84:87], v[144:147], v[202:205], v[84:87]
	v_mfma_f32_16x16x32_bf16 v[80:83], v[152:155], v[202:205], v[80:83]
	v_mfma_f32_16x16x32_bf16 v[124:127], v[148:151], v[180:183], v[124:127]
	v_mfma_f32_16x16x32_bf16 v[120:123], v[156:159], v[180:183], v[120:123]
	v_mfma_f32_16x16x32_bf16 v[116:119], v[148:151], v[188:191], v[116:119]
	v_mfma_f32_16x16x32_bf16 v[112:115], v[156:159], v[188:191], v[112:115]
	v_mfma_f32_16x16x32_bf16 v[100:103], v[148:151], v[198:201], v[100:103]
	v_mfma_f32_16x16x32_bf16 v[96:99], v[156:159], v[198:201], v[96:99]
	v_mfma_f32_16x16x32_bf16 v[84:87], v[148:151], v[206:209], v[84:87]
	v_mfma_f32_16x16x32_bf16 v[80:83], v[156:159], v[206:209], v[80:83]
	v_mfma_f32_16x16x32_bf16 v[108:111], v[160:163], v[176:179], v[108:111]
	v_mfma_f32_16x16x32_bf16 v[104:107], v[168:171], v[176:179], v[104:107]
	v_mfma_f32_16x16x32_bf16 v[92:95], v[160:163], v[184:187], v[92:95]
	v_mfma_f32_16x16x32_bf16 v[88:91], v[168:171], v[184:187], v[88:91]
	v_mfma_f32_16x16x32_bf16 v[76:79], v[160:163], v[194:197], v[76:79]
	v_mfma_f32_16x16x32_bf16 v[72:75], v[168:171], v[194:197], v[72:75]
	v_mfma_f32_16x16x32_bf16 v[68:71], v[160:163], v[202:205], v[68:71]
	v_mfma_f32_16x16x32_bf16 v[64:67], v[168:171], v[202:205], v[64:67]
	v_mfma_f32_16x16x32_bf16 v[108:111], v[164:167], v[180:183], v[108:111]
	v_mfma_f32_16x16x32_bf16 v[104:107], v[172:175], v[180:183], v[104:107]
	v_mfma_f32_16x16x32_bf16 v[92:95], v[164:167], v[188:191], v[92:95]
	v_mfma_f32_16x16x32_bf16 v[88:91], v[172:175], v[188:191], v[88:91]
	v_mfma_f32_16x16x32_bf16 v[76:79], v[164:167], v[198:201], v[76:79]
	v_mfma_f32_16x16x32_bf16 v[72:75], v[172:175], v[198:201], v[72:75]
	v_mfma_f32_16x16x32_bf16 v[68:71], v[164:167], v[206:209], v[68:71]
	v_mfma_f32_16x16x32_bf16 v[64:67], v[172:175], v[206:209], v[64:67]
	s_barrier
	s_add_i32 s56, s56, s37
	v_lshl_add_u64 v[210:211], s[22:23], 0, v[130:131]
	s_mov_b32 m0, s56
	ds_read_b128 v[176:179], v143 offset:16384
	ds_read_b128 v[180:183], v143 offset:17408
	ds_read_b128 v[184:187], v143 offset:18432
	ds_read_b128 v[188:191], v143 offset:19456
	ds_read_b128 v[194:197], v143 offset:20480
	ds_read_b128 v[198:201], v143 offset:21504
	ds_read_b128 v[202:205], v143 offset:22528
	ds_read_b128 v[206:209], v143 offset:23552
	global_load_lds_dwordx4 v[210:211], off
	s_add_i32 m0, s56, 0x2000
	s_add_u32 s56, s22, 0x40000
	v_lshl_add_u64 v[212:213], s[22:23], 0, v[134:135]
	s_addc_u32 s57, s23, 0
	s_add_i32 s58, s58, s37
	global_load_lds_dwordx4 v[212:213], off
	v_lshl_add_u64 v[214:215], s[56:57], 0, v[130:131]
	s_mov_b32 m0, s58
	v_lshl_add_u64 v[216:217], s[24:25], 0, v[132:133]
	global_load_lds_dwordx4 v[214:215], off
	v_lshl_add_u64 v[214:215], s[56:57], 0, v[134:135]
	s_add_i32 m0, s58, 0x2000
	s_nop 0
	global_load_lds_dwordx4 v[214:215], off
	v_lshl_add_u64 v[214:215], s[24:25], 0, v[128:129]
	s_mov_b32 m0, s38
	s_nop 0
	global_load_lds_dwordx4 v[214:215], off
	s_mov_b32 m0, s39
	s_nop 0
	global_load_lds_dwordx4 v[216:217], off
	s_waitcnt vmcnt(8)
	s_waitcnt lgkmcnt(0)
	s_barrier
	s_waitcnt lgkmcnt(0)
	v_mfma_f32_16x16x32_bf16 v[60:63], v[144:147], v[176:179], v[60:63]
	v_mfma_f32_16x16x32_bf16 v[56:59], v[152:155], v[176:179], v[56:59]
	v_mfma_f32_16x16x32_bf16 v[52:55], v[144:147], v[184:187], v[52:55]
	v_mfma_f32_16x16x32_bf16 v[48:51], v[152:155], v[184:187], v[48:51]
	v_mfma_f32_16x16x32_bf16 v[36:39], v[144:147], v[194:197], v[36:39]
	v_mfma_f32_16x16x32_bf16 v[32:35], v[152:155], v[194:197], v[32:35]
	v_mfma_f32_16x16x32_bf16 v[20:23], v[144:147], v[202:205], v[20:23]
	v_mfma_f32_16x16x32_bf16 v[16:19], v[152:155], v[202:205], v[16:19]
	v_mfma_f32_16x16x32_bf16 v[60:63], v[148:151], v[180:183], v[60:63]
	v_mfma_f32_16x16x32_bf16 v[56:59], v[156:159], v[180:183], v[56:59]
	v_mfma_f32_16x16x32_bf16 v[52:55], v[148:151], v[188:191], v[52:55]
	v_mfma_f32_16x16x32_bf16 v[48:51], v[156:159], v[188:191], v[48:51]
	v_mfma_f32_16x16x32_bf16 v[36:39], v[148:151], v[198:201], v[36:39]
	v_mfma_f32_16x16x32_bf16 v[32:35], v[156:159], v[198:201], v[32:35]
	v_mfma_f32_16x16x32_bf16 v[20:23], v[148:151], v[206:209], v[20:23]
	v_mfma_f32_16x16x32_bf16 v[16:19], v[156:159], v[206:209], v[16:19]
	v_mfma_f32_16x16x32_bf16 v[44:47], v[160:163], v[176:179], v[44:47]
	v_mfma_f32_16x16x32_bf16 v[40:43], v[168:171], v[176:179], v[40:43]
	v_mfma_f32_16x16x32_bf16 v[28:31], v[160:163], v[184:187], v[28:31]
	v_mfma_f32_16x16x32_bf16 v[24:27], v[168:171], v[184:187], v[24:27]
	v_mfma_f32_16x16x32_bf16 v[12:15], v[160:163], v[194:197], v[12:15]
	v_mfma_f32_16x16x32_bf16 v[8:11], v[168:171], v[194:197], v[8:11]
	v_mfma_f32_16x16x32_bf16 v[4:7], v[160:163], v[202:205], v[4:7]
	v_mfma_f32_16x16x32_bf16 v[0:3], v[168:171], v[202:205], v[0:3]
	v_mfma_f32_16x16x32_bf16 v[44:47], v[164:167], v[180:183], v[44:47]
	v_mfma_f32_16x16x32_bf16 v[40:43], v[172:175], v[180:183], v[40:43]
	v_mfma_f32_16x16x32_bf16 v[28:31], v[164:167], v[188:191], v[28:31]
	v_mfma_f32_16x16x32_bf16 v[24:27], v[172:175], v[188:191], v[24:27]
	v_mfma_f32_16x16x32_bf16 v[12:15], v[164:167], v[198:201], v[12:15]
	v_mfma_f32_16x16x32_bf16 v[8:11], v[172:175], v[198:201], v[8:11]
	v_mfma_f32_16x16x32_bf16 v[4:7], v[164:167], v[206:209], v[4:7]
	v_mfma_f32_16x16x32_bf16 v[0:3], v[172:175], v[206:209], v[0:3]
	s_barrier
; #define PG8_STAGE(bufoff, gbase, voff) do { _Pragma("unroll") for (int _i = 0; _i < 2; ++_i) \
;         __builtin_amdgcn_global_load_lds((const unsigned*)((const char*)(gbase) + (voff)[_i]), (LAS unsigned*)(lds + (bufoff) + ldsw + _i * 8192), 16, 0, 0); } while (0)
; #define PG8_LDA(dst, b, h) do { _Pragma("unroll") for (int m = 0; m < 4; ++m) _Pragma("unroll") for (int k = 0; k < 2; ++k) dst[m][k] = *(const LAS bf16x8*)(lds + PG8_SA(b, h) + aoff + m * 2048 + k * 1024); } while (0)
; #define PG8_LDB(dst, b, h) do { _Pragma("unroll") for (int n = 0; n < 2; ++n) _Pragma("unroll") for (int k = 0; k < 2; ++k) dst[n][k] = *(const LAS bf16x8*)(lds + PG8_SB(b, h) + boff + n * 2048 + k * 1024); } while (0)
; #define PG8_MMA(ai, bj, At, Bt) do { __builtin_amdgcn_s_setprio(1); _Pragma("unroll") for (int m = 0; m < 4; ++m) _Pragma("unroll") for (int n = 0; n < 2; ++n) _Pragma("unroll") for (int k = 0; k < 2; ++k) \
;         acc[ai][bj][m][n] = __builtin_amdgcn_mfma_f32_16x16x32_bf16(Bt[n][k], At[m][k], acc[ai][bj][m][n], 0, 0, 0); __builtin_amdgcn_s_setprio(0); } while (0)
; #define PG8_WAIT_V(n) asm volatile("s_waitcnt vmcnt(" #n ")" ::: "memory")
; #define PG8_WAIT_L(n) asm volatile("s_waitcnt lgkmcnt(" #n ")" ::: "memory")
; #define PG8_BAR __builtin_amdgcn_s_barrier()
; #define PG8_SCHED __builtin_amdgcn_sched_barrier(0)
; template <class Epi>
; DI void gemm_phase(int wv, LAS unsigned char* lds, LAS unsigned char* scr, const Sched& S, const Epi& E) {
;     ...
;             PG8_LDB(B0, 1, 0); PG8_LDB(B1, 1, 1); PG8_SCHED; PG8_LDA(At, 1, 0); PG8_STAGE(PG8_SA(0, 1), a2 + hstepA, voffA);
;             PG8_WAIT_V(8); PG8_WAIT_L(0); PG8_BAR; PG8_MMA(0, 0, At, B0); PG8_MMA(0, 1, At, B1); PG8_BAR; PG8_SCHED;
	s_add_i32 s56, 0, 0x18000
	s_add_i32 s57, 0, 0x1c000
	v_add_u32_e32 v156, s56, v142
	v_add_u32_e32 v172, s57, v142
	ds_read_b128 v[144:147], v156
	ds_read_b128 v[148:151], v156 offset:1024
	ds_read_b128 v[152:155], v156 offset:2048
	ds_read_b128 v[156:159], v156 offset:3072
	ds_read_b128 v[160:163], v172
	ds_read_b128 v[164:167], v172 offset:1024
	ds_read_b128 v[168:171], v172 offset:2048
	ds_read_b128 v[172:175], v172 offset:3072
	s_add_u32 s24, s24, 0x40000
	s_addc_u32 s25, s25, 0
	s_mov_b32 m0, s42
	v_lshl_add_u64 v[218:219], s[24:25], 0, v[128:129]
	ds_read_b128 v[176:179], v143 offset:32768
	ds_read_b128 v[180:183], v143 offset:33792
	ds_read_b128 v[184:187], v143 offset:34816
	ds_read_b128 v[188:191], v143 offset:35840
	ds_read_b128 v[194:197], v143 offset:36864
	ds_read_b128 v[198:201], v143 offset:37888
	ds_read_b128 v[202:205], v143 offset:38912
	ds_read_b128 v[206:209], v143 offset:39936
	global_load_lds_dwordx4 v[218:219], off
	v_lshl_add_u64 v[218:219], s[24:25], 0, v[132:133]
	s_mov_b32 m0, s43
	s_nop 0
	global_load_lds_dwordx4 v[218:219], off
	s_waitcnt vmcnt(8)
	s_waitcnt lgkmcnt(0)
	s_barrier
	s_waitcnt lgkmcnt(0)
	v_mfma_f32_16x16x32_bf16 v[124:127], v[144:147], v[176:179], v[124:127]
	v_mfma_f32_16x16x32_bf16 v[120:123], v[152:155], v[176:179], v[120:123]
	v_mfma_f32_16x16x32_bf16 v[116:119], v[144:147], v[184:187], v[116:119]
	v_mfma_f32_16x16x32_bf16 v[112:115], v[152:155], v[184:187], v[112:115]
	v_mfma_f32_16x16x32_bf16 v[100:103], v[144:147], v[194:197], v[100:103]
	v_mfma_f32_16x16x32_bf16 v[96:99], v[152:155], v[194:197], v[96:99]
	v_mfma_f32_16x16x32_bf16 v[84:87], v[144:147], v[202:205], v[84:87]
	v_mfma_f32_16x16x32_bf16 v[80:83], v[152:155], v[202:205], v[80:83]
	v_mfma_f32_16x16x32_bf16 v[124:127], v[148:151], v[180:183], v[124:127]
	v_mfma_f32_16x16x32_bf16 v[120:123], v[156:159], v[180:183], v[120:123]
	v_mfma_f32_16x16x32_bf16 v[116:119], v[148:151], v[188:191], v[116:119]
	v_mfma_f32_16x16x32_bf16 v[112:115], v[156:159], v[188:191], v[112:115]
	v_mfma_f32_16x16x32_bf16 v[100:103], v[148:151], v[198:201], v[100:103]
	v_mfma_f32_16x16x32_bf16 v[96:99], v[156:159], v[198:201], v[96:99]
	v_mfma_f32_16x16x32_bf16 v[84:87], v[148:151], v[206:209], v[84:87]
	v_mfma_f32_16x16x32_bf16 v[80:83], v[156:159], v[206:209], v[80:83]
	v_mfma_f32_16x16x32_bf16 v[108:111], v[160:163], v[176:179], v[108:111]
	v_mfma_f32_16x16x32_bf16 v[104:107], v[168:171], v[176:179], v[104:107]
	v_mfma_f32_16x16x32_bf16 v[92:95], v[160:163], v[184:187], v[92:95]
	v_mfma_f32_16x16x32_bf16 v[88:91], v[168:171], v[184:187], v[88:91]
	v_mfma_f32_16x16x32_bf16 v[76:79], v[160:163], v[194:197], v[76:79]
	v_mfma_f32_16x16x32_bf16 v[72:75], v[168:171], v[194:197], v[72:75]
	v_mfma_f32_16x16x32_bf16 v[68:71], v[160:163], v[202:205], v[68:71]
	v_mfma_f32_16x16x32_bf16 v[64:67], v[168:171], v[202:205], v[64:67]
	v_mfma_f32_16x16x32_bf16 v[108:111], v[164:167], v[180:183], v[108:111]
	v_mfma_f32_16x16x32_bf16 v[104:107], v[172:175], v[180:183], v[104:107]
	v_mfma_f32_16x16x32_bf16 v[92:95], v[164:167], v[188:191], v[92:95]
	v_mfma_f32_16x16x32_bf16 v[88:91], v[172:175], v[188:191], v[88:91]
	v_mfma_f32_16x16x32_bf16 v[76:79], v[164:167], v[198:201], v[76:79]
	v_mfma_f32_16x16x32_bf16 v[72:75], v[172:175], v[198:201], v[72:75]
	v_mfma_f32_16x16x32_bf16 v[68:71], v[164:167], v[206:209], v[68:71]
	v_mfma_f32_16x16x32_bf16 v[64:67], v[172:175], v[206:209], v[64:67]
	s_barrier
; #define PG8_STAGE(bufoff, gbase, voff) do { _Pragma("unroll") for (int _i = 0; _i < 2; ++_i) \
;         __builtin_amdgcn_global_load_lds((const unsigned*)((const char*)(gbase) + (voff)[_i]), (LAS unsigned*)(lds + (bufoff) + ldsw + _i * 8192), 16, 0, 0); } while (0)
; #define PG8_LDA(dst, b, h) do { _Pragma("unroll") for (int m = 0; m < 4; ++m) _Pragma("unroll") for (int k = 0; k < 2; ++k) dst[m][k] = *(const LAS bf16x8*)(lds + PG8_SA(b, h) + aoff + m * 2048 + k * 1024); } while (0)
; #define PG8_MMA(ai, bj, At, Bt) do { __builtin_amdgcn_s_setprio(1); _Pragma("unroll") for (int m = 0; m < 4; ++m) _Pragma("unroll") for (int n = 0; n < 2; ++n) _Pragma("unroll") for (int k = 0; k < 2; ++k) \
;         acc[ai][bj][m][n] = __builtin_amdgcn_mfma_f32_16x16x32_bf16(Bt[n][k], At[m][k], acc[ai][bj][m][n], 0, 0, 0); __builtin_amdgcn_s_setprio(0); } while (0)
; #define PG8_WAIT_V(n) asm volatile("s_waitcnt vmcnt(" #n ")" ::: "memory")
; #define PG8_WAIT_L(n) asm volatile("s_waitcnt lgkmcnt(" #n ")" ::: "memory")
; #define PG8_BAR __builtin_amdgcn_s_barrier()
; #define PG8_SCHED __builtin_amdgcn_sched_barrier(0)
; template <class Epi>
; DI void gemm_phase(int wv, LAS unsigned char* lds, LAS unsigned char* scr, const Sched& S, const Epi& E) {
;     ...
;             PG8_LDA(At, 1, 1); PG8_STAGE(PG8_SB(1, 0), b3, voffB); PG8_STAGE(PG8_SB(1, 1), b3 + hstepB, voffB); PG8_STAGE(PG8_SA(1, 0), a3, voffA);
;             PG8_WAIT_V(8); PG8_WAIT_L(0); PG8_BAR; PG8_MMA(1, 0, At, B0); PG8_MMA(1, 1, At, B1); PG8_BAR; PG8_SCHED;
;         }
;         if (wr == 0) PG8_BAR;
	s_add_i32 s24, s56, s37
	v_lshl_add_u64 v[210:211], v[210:211], 0, s[2:3]
	s_mov_b32 m0, s24
	ds_read_b128 v[176:179], v143 offset:49152
	ds_read_b128 v[180:183], v143 offset:50176
	ds_read_b128 v[184:187], v143 offset:51200
	ds_read_b128 v[188:191], v143 offset:52224
	ds_read_b128 v[194:197], v143 offset:53248
	ds_read_b128 v[198:201], v143 offset:54272
	ds_read_b128 v[202:205], v143 offset:55296
	ds_read_b128 v[206:209], v143 offset:56320
	global_load_lds_dwordx4 v[210:211], off
	s_add_i32 m0, s24, 0x2000
	s_add_u32 s22, s22, 0x40080
	v_lshl_add_u64 v[210:211], v[212:213], 0, s[2:3]
	s_addc_u32 s23, s23, 0
	s_add_i32 s24, s57, s37
	global_load_lds_dwordx4 v[210:211], off
	v_lshl_add_u64 v[210:211], s[22:23], 0, v[130:131]
	s_mov_b32 m0, s24
	s_nop 0
	global_load_lds_dwordx4 v[210:211], off
	v_lshl_add_u64 v[210:211], s[22:23], 0, v[134:135]
	s_add_i32 m0, s24, 0x2000
	s_nop 0
	global_load_lds_dwordx4 v[210:211], off
	v_lshl_add_u64 v[210:211], v[214:215], 0, s[2:3]
	s_mov_b32 m0, s46
	s_nop 0
	global_load_lds_dwordx4 v[210:211], off
	v_lshl_add_u64 v[210:211], v[216:217], 0, s[2:3]
	s_mov_b32 m0, s47
	s_nop 0
	global_load_lds_dwordx4 v[210:211], off
	s_waitcnt vmcnt(8)
	s_waitcnt lgkmcnt(0)
	s_barrier
	s_waitcnt lgkmcnt(0)
	v_mfma_f32_16x16x32_bf16 v[60:63], v[144:147], v[176:179], v[60:63]
	v_mfma_f32_16x16x32_bf16 v[56:59], v[152:155], v[176:179], v[56:59]
	v_mfma_f32_16x16x32_bf16 v[52:55], v[144:147], v[184:187], v[52:55]
	v_mfma_f32_16x16x32_bf16 v[48:51], v[152:155], v[184:187], v[48:51]
	v_mfma_f32_16x16x32_bf16 v[36:39], v[144:147], v[194:197], v[36:39]
	v_mfma_f32_16x16x32_bf16 v[32:35], v[152:155], v[194:197], v[32:35]
	v_mfma_f32_16x16x32_bf16 v[20:23], v[144:147], v[202:205], v[20:23]
	v_mfma_f32_16x16x32_bf16 v[16:19], v[152:155], v[202:205], v[16:19]
	v_mfma_f32_16x16x32_bf16 v[60:63], v[148:151], v[180:183], v[60:63]
	v_mfma_f32_16x16x32_bf16 v[56:59], v[156:159], v[180:183], v[56:59]
	v_mfma_f32_16x16x32_bf16 v[52:55], v[148:151], v[188:191], v[52:55]
	v_mfma_f32_16x16x32_bf16 v[48:51], v[156:159], v[188:191], v[48:51]
	v_mfma_f32_16x16x32_bf16 v[36:39], v[148:151], v[198:201], v[36:39]
	v_mfma_f32_16x16x32_bf16 v[32:35], v[156:159], v[198:201], v[32:35]
	v_mfma_f32_16x16x32_bf16 v[20:23], v[148:151], v[206:209], v[20:23]
	v_mfma_f32_16x16x32_bf16 v[16:19], v[156:159], v[206:209], v[16:19]
	v_mfma_f32_16x16x32_bf16 v[44:47], v[160:163], v[176:179], v[44:47]
	v_mfma_f32_16x16x32_bf16 v[40:43], v[168:171], v[176:179], v[40:43]
	v_mfma_f32_16x16x32_bf16 v[28:31], v[160:163], v[184:187], v[28:31]
	v_mfma_f32_16x16x32_bf16 v[24:27], v[168:171], v[184:187], v[24:27]
	v_mfma_f32_16x16x32_bf16 v[12:15], v[160:163], v[194:197], v[12:15]
	v_mfma_f32_16x16x32_bf16 v[8:11], v[168:171], v[194:197], v[8:11]
	v_mfma_f32_16x16x32_bf16 v[4:7], v[160:163], v[202:205], v[4:7]
	v_mfma_f32_16x16x32_bf16 v[0:3], v[168:171], v[202:205], v[0:3]
	v_mfma_f32_16x16x32_bf16 v[44:47], v[164:167], v[180:183], v[44:47]
	v_mfma_f32_16x16x32_bf16 v[40:43], v[172:175], v[180:183], v[40:43]
	v_mfma_f32_16x16x32_bf16 v[28:31], v[164:167], v[188:191], v[28:31]
	v_mfma_f32_16x16x32_bf16 v[24:27], v[172:175], v[188:191], v[24:27]
	v_mfma_f32_16x16x32_bf16 v[12:15], v[164:167], v[198:201], v[12:15]
	v_mfma_f32_16x16x32_bf16 v[8:11], v[172:175], v[198:201], v[8:11]
	v_mfma_f32_16x16x32_bf16 v[4:7], v[164:167], v[206:209], v[4:7]
	v_mfma_f32_16x16x32_bf16 v[0:3], v[172:175], v[206:209], v[0:3]
	s_barrier
	s_add_i32 s53, s53, 2
	s_add_u32 s49, s49, 0x100
	s_addc_u32 s52, s52, 0
	s_add_u32 s20, s20, 0x100
	s_addc_u32 s21, s21, 0
	s_cmp_gt_u32 s53, 13
	s_cbranch_scc0 .LBB0_43
	s_setprio 0
	s_and_b64 vcc, exec, s[4:5]
	s_cbranch_vccz .LBB0_46
	s_barrier

; #define PG8_STAGE(bufoff, gbase, voff) do { _Pragma("unroll") for (int _i = 0; _i < 2; ++_i) \
;         __builtin_amdgcn_global_load_lds((const unsigned*)((const char*)(gbase) + (voff)[_i]), (LAS unsigned*)(lds + (bufoff) + ldsw + _i * 8192), 16, 0, 0); } while (0)
; #define PG8_LDA(dst, b, h) do { _Pragma("unroll") for (int m = 0; m < 4; ++m) _Pragma("unroll") for (int k = 0; k < 2; ++k) dst[m][k] = *(const LAS bf16x8*)(lds + PG8_SA(b, h) + aoff + m * 2048 + k * 1024); } while (0)
; #define PG8_LDB(dst, b, h) do { _Pragma("unroll") for (int n = 0; n < 2; ++n) _Pragma("unroll") for (int k = 0; k < 2; ++k) dst[n][k] = *(const LAS bf16x8*)(lds + PG8_SB(b, h) + boff + n * 2048 + k * 1024); } while (0)
; #define PG8_SCHED __builtin_amdgcn_sched_barrier(0)
; template <class Epi>
; DI void gemm_phase(int wv, LAS unsigned char* lds, LAS unsigned char* scr, const Sched& S, const Epi& E) {
;     ...
;         const bool has_next = S.next(ui + 1, nxt);
;         const char* nA = has_next ? S.baseA(nxt) : cA; const char* nB = has_next ? S.baseB(nxt) : cB;
;         for (int t = 0; t < nt; t += 2) {
;             const bool last = (t == nt - 2);
;             const char* a1 = cA + (size_t)(t + 1) * kstep;
;             const char* a2 = last ? nA : cA + (size_t)(t + 2) * kstep; const char* b2 = last ? nB : cB + (size_t)(t + 2) * kstep;
;             const char* a3 = a2 + kstep; const char* b3 = b2 + kstep;
;             PG8_LDB(B0, 0, 0); PG8_LDB(B1, 0, 1); PG8_SCHED; PG8_LDA(At, 0, 0); PG8_STAGE(PG8_SA(1, 1), a1 + hstepA, voffA);
;     ...
; #pragma unroll
;         for (int a = 0; a < 2; ++a)
; #pragma unroll
;             for (int b = 0; b < 2; ++b)
; #pragma unroll
;                 for (int m = 0; m < 4; ++m)
; #pragma unroll
;                     for (int n = 0; n < 2; ++n) acc[a][b][m][n] = (f32x4){0.f, 0.f, 0.f, 0.f};
;         cur = nxt; cA = nA; cB = nB; ++ui;
.LBB0_88:
	s_ashr_i32 s15, s14, 31
	s_lshl_b64 s[16:17], s[14:15], 19
	s_add_u32 s16, s52, s16
	s_addc_u32 s17, s53, s17
	s_and_b64 s[18:19], s[4:5], exec
	s_cselect_b32 s15, s17, s23
	s_cselect_b32 s33, s16, s22
	s_ashr_i32 s13, s12, 31
	s_lshl_b64 s[18:19], s[12:13], 19
	s_add_u32 s18, s31, s18
	s_addc_u32 s19, s34, s19
	s_and_b64 s[26:27], s[4:5], exec
	s_cselect_b32 s13, s19, s25
	s_cselect_b32 s47, s18, s24
	s_add_u32 s48, s24, 0x100
	s_addc_u32 s49, s25, 0
	s_add_u32 s22, s22, 0x40080
	v_mov_b32_e32 v0, 0
	v_mov_b32_e32 v226, 0x358637bd
	s_addc_u32 s23, s23, 0
	s_mov_b32 s57, -2
	v_mov_b32_e32 v1, v0
	v_mov_b32_e32 v2, v0
	v_mov_b32_e32 v3, v0
	v_mov_b32_e32 v4, v0
	v_mov_b32_e32 v5, v0
	v_mov_b32_e32 v6, v0
	v_mov_b32_e32 v7, v0
	v_mov_b32_e32 v16, v0
	v_mov_b32_e32 v17, v0
	v_mov_b32_e32 v18, v0
	v_mov_b32_e32 v19, v0
	v_mov_b32_e32 v20, v0
	v_mov_b32_e32 v21, v0
	v_mov_b32_e32 v22, v0
	v_mov_b32_e32 v23, v0
	s_waitcnt vmcnt(0)
	v_mov_b32_e32 v32, v0
	v_mov_b32_e32 v33, v0
	v_mov_b32_e32 v34, v0
	v_mov_b32_e32 v35, v0
	v_mov_b32_e32 v36, v0
	v_mov_b32_e32 v37, v0
	v_mov_b32_e32 v38, v0
	v_mov_b32_e32 v39, v0
	v_mov_b32_e32 v48, v0
	v_mov_b32_e32 v49, v0
	v_mov_b32_e32 v50, v0
	v_mov_b32_e32 v51, v0
	v_mov_b32_e32 v52, v0
	v_mov_b32_e32 v53, v0
	v_mov_b32_e32 v54, v0
	v_mov_b32_e32 v55, v0
	v_mov_b32_e32 v8, v0
	v_mov_b32_e32 v9, v0
	v_mov_b32_e32 v10, v0
	v_mov_b32_e32 v11, v0
	v_mov_b32_e32 v12, v0
	v_mov_b32_e32 v13, v0
	v_mov_b32_e32 v14, v0
	v_mov_b32_e32 v15, v0
	v_mov_b32_e32 v24, v0
	v_mov_b32_e32 v25, v0
	v_mov_b32_e32 v26, v0
	v_mov_b32_e32 v27, v0
	v_mov_b32_e32 v28, v0
	v_mov_b32_e32 v29, v0
	v_mov_b32_e32 v30, v0
	v_mov_b32_e32 v31, v0
	v_mov_b32_e32 v40, v0
	v_mov_b32_e32 v41, v0
	v_mov_b32_e32 v42, v0
	v_mov_b32_e32 v43, v0
	v_mov_b32_e32 v44, v0
	v_mov_b32_e32 v45, v0
	v_mov_b32_e32 v46, v0
	v_mov_b32_e32 v47, v0
	v_mov_b32_e32 v56, v0
	v_mov_b32_e32 v57, v0
	v_mov_b32_e32 v58, v0
	v_mov_b32_e32 v59, v0
	v_mov_b32_e32 v60, v0
	v_mov_b32_e32 v61, v0
	v_mov_b32_e32 v62, v0
	v_mov_b32_e32 v63, v0
	v_mov_b32_e32 v64, v0
	v_mov_b32_e32 v65, v0
	v_mov_b32_e32 v66, v0
	v_mov_b32_e32 v67, v0
	v_mov_b32_e32 v68, v0
	v_mov_b32_e32 v69, v0
	v_mov_b32_e32 v70, v0
	v_mov_b32_e32 v71, v0
	v_mov_b32_e32 v80, v0
	v_mov_b32_e32 v81, v0
	v_mov_b32_e32 v82, v0
	v_mov_b32_e32 v83, v0
	v_mov_b32_e32 v84, v0
	v_mov_b32_e32 v85, v0
	v_mov_b32_e32 v86, v0
	v_mov_b32_e32 v87, v0
	v_mov_b32_e32 v96, v0
	v_mov_b32_e32 v97, v0
	v_mov_b32_e32 v98, v0
	v_mov_b32_e32 v99, v0
	v_mov_b32_e32 v100, v0
	v_mov_b32_e32 v101, v0
	v_mov_b32_e32 v102, v0
	v_mov_b32_e32 v103, v0
	v_mov_b32_e32 v112, v0
	v_mov_b32_e32 v113, v0
	v_mov_b32_e32 v114, v0
	v_mov_b32_e32 v115, v0
	v_mov_b32_e32 v116, v0
	v_mov_b32_e32 v117, v0
	v_mov_b32_e32 v118, v0
	v_mov_b32_e32 v119, v0
	v_mov_b32_e32 v72, v0
	v_mov_b32_e32 v73, v0
	v_mov_b32_e32 v74, v0
	v_mov_b32_e32 v75, v0
	v_mov_b32_e32 v76, v0
	v_mov_b32_e32 v77, v0
	v_mov_b32_e32 v78, v0
	v_mov_b32_e32 v79, v0
	v_mov_b32_e32 v88, v0
	v_mov_b32_e32 v89, v0
	v_mov_b32_e32 v90, v0
	v_mov_b32_e32 v91, v0
	v_mov_b32_e32 v92, v0
	v_mov_b32_e32 v93, v0
	v_mov_b32_e32 v94, v0
	v_mov_b32_e32 v95, v0
	v_mov_b32_e32 v104, v0
	v_mov_b32_e32 v105, v0
	v_mov_b32_e32 v106, v0
	v_mov_b32_e32 v107, v0
	v_mov_b32_e32 v108, v0
	v_mov_b32_e32 v109, v0
	v_mov_b32_e32 v110, v0
	v_mov_b32_e32 v111, v0
	v_mov_b32_e32 v120, v0
	v_mov_b32_e32 v121, v0
	v_mov_b32_e32 v122, v0
	v_mov_b32_e32 v123, v0
	v_mov_b32_e32 v124, v0
	v_mov_b32_e32 v125, v0
	v_mov_b32_e32 v126, v0
	v_mov_b32_e32 v127, v0
	s_cmp_lg_u64 s[10:11], 0
	s_cbranch_scc1 .Lgp_3
	s_setprio 1
.Lgp_3:
.LBB0_89:
	s_add_u32 s24, s22, 0xfffc0080
	s_addc_u32 s25, s23, -1
	s_add_i32 s58, 0, 0x10000
	s_cmp_eq_u32 s57, 12
	s_cselect_b32 s27, s15, s25
	s_cselect_b32 s26, s33, s24
	v_add_u32_e32 v145, s58, v150
	s_cselect_b32 s25, s13, s49
	s_cselect_b32 s24, s47, s48
	s_add_i32 s62, 0, 0x14000
	ds_read_b128 v[152:155], v145
	ds_read_b128 v[156:159], v145 offset:1024
	ds_read_b128 v[160:163], v145 offset:2048
	ds_read_b128 v[164:167], v145 offset:3072
	v_add_u32_e32 v145, s62, v150
	ds_read_b128 v[168:171], v145
	ds_read_b128 v[172:175], v145 offset:1024
	ds_read_b128 v[176:179], v145 offset:2048
	ds_read_b128 v[180:183], v145 offset:3072
	v_lshl_add_u64 v[148:149], s[22:23], 0, v[142:143]
	s_add_i32 m0, s36, 0xc000
	ds_read_b128 v[184:187], v151
	ds_read_b128 v[188:191], v151 offset:1024
	ds_read_b128 v[194:197], v151 offset:2048
	ds_read_b128 v[198:201], v151 offset:3072
	ds_read_b128 v[202:205], v151 offset:4096
	ds_read_b128 v[206:209], v151 offset:5120
	ds_read_b128 v[210:213], v151 offset:6144
	ds_read_b128 v[214:217], v151 offset:7168
	global_load_lds_dwordx4 v[148:149], off
	v_lshl_add_u64 v[148:149], s[22:23], 0, v[140:141]
	s_add_i32 m0, s36, 0xe000
	s_nop 0
	global_load_lds_dwordx4 v[148:149], off
	s_waitcnt vmcnt(8)
	s_waitcnt lgkmcnt(0)
	s_barrier
; #define PG8_STAGE(bufoff, gbase, voff) do { _Pragma("unroll") for (int _i = 0; _i < 2; ++_i) \
;         __builtin_amdgcn_global_load_lds((const unsigned*)((const char*)(gbase) + (voff)[_i]), (LAS unsigned*)(lds + (bufoff) + ldsw + _i * 8192), 16, 0, 0); } while (0)
; #define PG8_LDA(dst, b, h) do { _Pragma("unroll") for (int m = 0; m < 4; ++m) _Pragma("unroll") for (int k = 0; k < 2; ++k) dst[m][k] = *(const LAS bf16x8*)(lds + PG8_SA(b, h) + aoff + m * 2048 + k * 1024); } while (0)
; #define PG8_MMA(ai, bj, At, Bt) do { __builtin_amdgcn_s_setprio(1); _Pragma("unroll") for (int m = 0; m < 4; ++m) _Pragma("unroll") for (int n = 0; n < 2; ++n) _Pragma("unroll") for (int k = 0; k < 2; ++k) \
;         acc[ai][bj][m][n] = __builtin_amdgcn_mfma_f32_16x16x32_bf16(Bt[n][k], At[m][k], acc[ai][bj][m][n], 0, 0, 0); __builtin_amdgcn_s_setprio(0); } while (0)
; #define PG8_WAIT_V(n) asm volatile("s_waitcnt vmcnt(" #n ")" ::: "memory")
; #define PG8_WAIT_L(n) asm volatile("s_waitcnt lgkmcnt(" #n ")" ::: "memory")
; #define PG8_BAR __builtin_amdgcn_s_barrier()
; #define PG8_SCHED __builtin_amdgcn_sched_barrier(0)
; template <class Epi>
; DI void gemm_phase(int wv, LAS unsigned char* lds, LAS unsigned char* scr, const Sched& S, const Epi& E) {
;     ...
;             PG8_WAIT_V(8); PG8_WAIT_L(0); PG8_BAR; PG8_MMA(0, 0, At, B0); PG8_MMA(0, 1, At, B1); PG8_BAR; PG8_SCHED;
;             PG8_LDA(At, 0, 1); PG8_STAGE(PG8_SB(0, 0), b2, voffB); PG8_STAGE(PG8_SB(0, 1), b2 + hstepB, voffB); PG8_STAGE(PG8_SA(0, 0), a2, voffA);
;             PG8_WAIT_V(8); PG8_WAIT_L(0); PG8_BAR; PG8_MMA(1, 0, At, B0); PG8_MMA(1, 1, At, B1); PG8_BAR; PG8_SCHED;
	s_waitcnt lgkmcnt(0)
	v_mfma_f32_16x16x32_bf16 v[124:127], v[152:155], v[184:187], v[124:127]
	v_mfma_f32_16x16x32_bf16 v[120:123], v[160:163], v[184:187], v[120:123]
	v_mfma_f32_16x16x32_bf16 v[108:111], v[152:155], v[194:197], v[108:111]
	v_mfma_f32_16x16x32_bf16 v[104:107], v[160:163], v[194:197], v[104:107]
	v_mfma_f32_16x16x32_bf16 v[92:95], v[152:155], v[202:205], v[92:95]
	v_mfma_f32_16x16x32_bf16 v[88:91], v[160:163], v[202:205], v[88:91]
	v_mfma_f32_16x16x32_bf16 v[76:79], v[152:155], v[210:213], v[76:79]
	v_mfma_f32_16x16x32_bf16 v[72:75], v[160:163], v[210:213], v[72:75]
	v_mfma_f32_16x16x32_bf16 v[124:127], v[156:159], v[188:191], v[124:127]
	v_mfma_f32_16x16x32_bf16 v[120:123], v[164:167], v[188:191], v[120:123]
	v_mfma_f32_16x16x32_bf16 v[108:111], v[156:159], v[198:201], v[108:111]
	v_mfma_f32_16x16x32_bf16 v[104:107], v[164:167], v[198:201], v[104:107]
	v_mfma_f32_16x16x32_bf16 v[92:95], v[156:159], v[206:209], v[92:95]
	v_mfma_f32_16x16x32_bf16 v[88:91], v[164:167], v[206:209], v[88:91]
	v_mfma_f32_16x16x32_bf16 v[76:79], v[156:159], v[214:217], v[76:79]
	v_mfma_f32_16x16x32_bf16 v[72:75], v[164:167], v[214:217], v[72:75]
	v_mfma_f32_16x16x32_bf16 v[116:119], v[168:171], v[184:187], v[116:119]
	v_mfma_f32_16x16x32_bf16 v[112:115], v[176:179], v[184:187], v[112:115]
	v_mfma_f32_16x16x32_bf16 v[100:103], v[168:171], v[194:197], v[100:103]
	v_mfma_f32_16x16x32_bf16 v[96:99], v[176:179], v[194:197], v[96:99]
	v_mfma_f32_16x16x32_bf16 v[84:87], v[168:171], v[202:205], v[84:87]
	v_mfma_f32_16x16x32_bf16 v[80:83], v[176:179], v[202:205], v[80:83]
	v_mfma_f32_16x16x32_bf16 v[68:71], v[168:171], v[210:213], v[68:71]
	v_mfma_f32_16x16x32_bf16 v[64:67], v[176:179], v[210:213], v[64:67]
	v_mfma_f32_16x16x32_bf16 v[116:119], v[172:175], v[188:191], v[116:119]
	v_mfma_f32_16x16x32_bf16 v[112:115], v[180:183], v[188:191], v[112:115]
	v_mfma_f32_16x16x32_bf16 v[100:103], v[172:175], v[198:201], v[100:103]
	v_mfma_f32_16x16x32_bf16 v[96:99], v[180:183], v[198:201], v[96:99]
	v_mfma_f32_16x16x32_bf16 v[84:87], v[172:175], v[206:209], v[84:87]
	v_mfma_f32_16x16x32_bf16 v[80:83], v[180:183], v[206:209], v[80:83]
	v_mfma_f32_16x16x32_bf16 v[68:71], v[172:175], v[214:217], v[68:71]
	v_mfma_f32_16x16x32_bf16 v[64:67], v[180:183], v[214:217], v[64:67]
	s_barrier
	s_add_i32 s58, s58, s35
	v_lshl_add_u64 v[148:149], s[24:25], 0, v[130:131]
	s_mov_b32 m0, s58
	ds_read_b128 v[184:187], v151 offset:16384
	ds_read_b128 v[188:191], v151 offset:17408
	ds_read_b128 v[194:197], v151 offset:18432
	ds_read_b128 v[198:201], v151 offset:19456
	ds_read_b128 v[202:205], v151 offset:20480
	ds_read_b128 v[206:209], v151 offset:21504
	ds_read_b128 v[210:213], v151 offset:22528
	ds_read_b128 v[214:217], v151 offset:23552
	global_load_lds_dwordx4 v[148:149], off
	s_add_i32 m0, s58, 0x2000
	s_add_u32 s60, s24, 0x40000
	v_lshl_add_u64 v[218:219], s[24:25], 0, v[134:135]
	s_addc_u32 s61, s25, 0
	s_add_i32 s58, s62, s35
	global_load_lds_dwordx4 v[218:219], off
	v_lshl_add_u64 v[220:221], s[60:61], 0, v[130:131]
	s_mov_b32 m0, s58
	v_lshl_add_u64 v[222:223], s[26:27], 0, v[132:133]
	global_load_lds_dwordx4 v[220:221], off
	v_lshl_add_u64 v[220:221], s[60:61], 0, v[134:135]
	s_add_i32 m0, s58, 0x2000
	s_nop 0
	global_load_lds_dwordx4 v[220:221], off
	v_lshl_add_u64 v[220:221], s[26:27], 0, v[128:129]
	s_mov_b32 m0, s36
	s_nop 0
	global_load_lds_dwordx4 v[220:221], off
	s_mov_b32 m0, s37
	s_nop 0
	global_load_lds_dwordx4 v[222:223], off
	s_waitcnt vmcnt(8)
	s_waitcnt lgkmcnt(0)
	s_barrier
	s_waitcnt lgkmcnt(0)
	v_mfma_f32_16x16x32_bf16 v[60:63], v[152:155], v[184:187], v[60:63]
	v_mfma_f32_16x16x32_bf16 v[56:59], v[160:163], v[184:187], v[56:59]
	v_mfma_f32_16x16x32_bf16 v[44:47], v[152:155], v[194:197], v[44:47]
	v_mfma_f32_16x16x32_bf16 v[40:43], v[160:163], v[194:197], v[40:43]
	v_mfma_f32_16x16x32_bf16 v[28:31], v[152:155], v[202:205], v[28:31]
	v_mfma_f32_16x16x32_bf16 v[24:27], v[160:163], v[202:205], v[24:27]
	v_mfma_f32_16x16x32_bf16 v[12:15], v[152:155], v[210:213], v[12:15]
	v_mfma_f32_16x16x32_bf16 v[8:11], v[160:163], v[210:213], v[8:11]
	v_mfma_f32_16x16x32_bf16 v[60:63], v[156:159], v[188:191], v[60:63]
	v_mfma_f32_16x16x32_bf16 v[56:59], v[164:167], v[188:191], v[56:59]
	v_mfma_f32_16x16x32_bf16 v[44:47], v[156:159], v[198:201], v[44:47]
	v_mfma_f32_16x16x32_bf16 v[40:43], v[164:167], v[198:201], v[40:43]
	v_mfma_f32_16x16x32_bf16 v[28:31], v[156:159], v[206:209], v[28:31]
	v_mfma_f32_16x16x32_bf16 v[24:27], v[164:167], v[206:209], v[24:27]
	v_mfma_f32_16x16x32_bf16 v[12:15], v[156:159], v[214:217], v[12:15]
	v_mfma_f32_16x16x32_bf16 v[8:11], v[164:167], v[214:217], v[8:11]
	v_mfma_f32_16x16x32_bf16 v[52:55], v[168:171], v[184:187], v[52:55]
	v_mfma_f32_16x16x32_bf16 v[48:51], v[176:179], v[184:187], v[48:51]
	v_mfma_f32_16x16x32_bf16 v[36:39], v[168:171], v[194:197], v[36:39]
	v_mfma_f32_16x16x32_bf16 v[32:35], v[176:179], v[194:197], v[32:35]
	v_mfma_f32_16x16x32_bf16 v[20:23], v[168:171], v[202:205], v[20:23]
	v_mfma_f32_16x16x32_bf16 v[16:19], v[176:179], v[202:205], v[16:19]
	v_mfma_f32_16x16x32_bf16 v[4:7], v[168:171], v[210:213], v[4:7]
	v_mfma_f32_16x16x32_bf16 v[0:3], v[176:179], v[210:213], v[0:3]
	v_mfma_f32_16x16x32_bf16 v[52:55], v[172:175], v[188:191], v[52:55]
	v_mfma_f32_16x16x32_bf16 v[48:51], v[180:183], v[188:191], v[48:51]
	v_mfma_f32_16x16x32_bf16 v[36:39], v[172:175], v[198:201], v[36:39]
	v_mfma_f32_16x16x32_bf16 v[32:35], v[180:183], v[198:201], v[32:35]
	v_mfma_f32_16x16x32_bf16 v[20:23], v[172:175], v[206:209], v[20:23]
	v_mfma_f32_16x16x32_bf16 v[16:19], v[180:183], v[206:209], v[16:19]
	v_mfma_f32_16x16x32_bf16 v[4:7], v[172:175], v[214:217], v[4:7]
	v_mfma_f32_16x16x32_bf16 v[0:3], v[180:183], v[214:217], v[0:3]
	s_barrier
; #define PG8_STAGE(bufoff, gbase, voff) do { _Pragma("unroll") for (int _i = 0; _i < 2; ++_i) \
;         __builtin_amdgcn_global_load_lds((const unsigned*)((const char*)(gbase) + (voff)[_i]), (LAS unsigned*)(lds + (bufoff) + ldsw + _i * 8192), 16, 0, 0); } while (0)
; #define PG8_LDA(dst, b, h) do { _Pragma("unroll") for (int m = 0; m < 4; ++m) _Pragma("unroll") for (int k = 0; k < 2; ++k) dst[m][k] = *(const LAS bf16x8*)(lds + PG8_SA(b, h) + aoff + m * 2048 + k * 1024); } while (0)
; #define PG8_LDB(dst, b, h) do { _Pragma("unroll") for (int n = 0; n < 2; ++n) _Pragma("unroll") for (int k = 0; k < 2; ++k) dst[n][k] = *(const LAS bf16x8*)(lds + PG8_SB(b, h) + boff + n * 2048 + k * 1024); } while (0)
; #define PG8_MMA(ai, bj, At, Bt) do { __builtin_amdgcn_s_setprio(1); _Pragma("unroll") for (int m = 0; m < 4; ++m) _Pragma("unroll") for (int n = 0; n < 2; ++n) _Pragma("unroll") for (int k = 0; k < 2; ++k) \
;         acc[ai][bj][m][n] = __builtin_amdgcn_mfma_f32_16x16x32_bf16(Bt[n][k], At[m][k], acc[ai][bj][m][n], 0, 0, 0); __builtin_amdgcn_s_setprio(0); } while (0)
; #define PG8_WAIT_V(n) asm volatile("s_waitcnt vmcnt(" #n ")" ::: "memory")
; #define PG8_WAIT_L(n) asm volatile("s_waitcnt lgkmcnt(" #n ")" ::: "memory")
; #define PG8_BAR __builtin_amdgcn_s_barrier()
; #define PG8_SCHED __builtin_amdgcn_sched_barrier(0)
; template <class Epi>
; DI void gemm_phase(int wv, LAS unsigned char* lds, LAS unsigned char* scr, const Sched& S, const Epi& E) {
;     ...
;             PG8_LDB(B0, 1, 0); PG8_LDB(B1, 1, 1); PG8_SCHED; PG8_LDA(At, 1, 0); PG8_STAGE(PG8_SA(0, 1), a2 + hstepA, voffA);
;             PG8_WAIT_V(8); PG8_WAIT_L(0); PG8_BAR; PG8_MMA(0, 0, At, B0); PG8_MMA(0, 1, At, B1); PG8_BAR; PG8_SCHED;
	s_add_i32 s58, 0, 0x18000
	v_add_u32_e32 v145, s58, v150
	s_add_i32 s60, 0, 0x1c000
	ds_read_b128 v[152:155], v145
	ds_read_b128 v[156:159], v145 offset:1024
	ds_read_b128 v[160:163], v145 offset:2048
	ds_read_b128 v[164:167], v145 offset:3072
	v_add_u32_e32 v145, s60, v150
	ds_read_b128 v[168:171], v145
	ds_read_b128 v[172:175], v145 offset:1024
	ds_read_b128 v[176:179], v145 offset:2048
	ds_read_b128 v[180:183], v145 offset:3072
	s_add_u32 s26, s26, 0x40000
	s_addc_u32 s27, s27, 0
	s_mov_b32 m0, s38
	v_lshl_add_u64 v[224:225], s[26:27], 0, v[128:129]
	ds_read_b128 v[184:187], v151 offset:32768
	ds_read_b128 v[188:191], v151 offset:33792
	ds_read_b128 v[194:197], v151 offset:34816
	ds_read_b128 v[198:201], v151 offset:35840
	ds_read_b128 v[202:205], v151 offset:36864
	ds_read_b128 v[206:209], v151 offset:37888
	ds_read_b128 v[210:213], v151 offset:38912
	ds_read_b128 v[214:217], v151 offset:39936
	global_load_lds_dwordx4 v[224:225], off
	v_lshl_add_u64 v[224:225], s[26:27], 0, v[132:133]
	s_mov_b32 m0, s39
	s_nop 0
	global_load_lds_dwordx4 v[224:225], off
	s_waitcnt vmcnt(8)
	s_waitcnt lgkmcnt(0)
	s_barrier
	s_waitcnt lgkmcnt(0)
	v_mfma_f32_16x16x32_bf16 v[124:127], v[152:155], v[184:187], v[124:127]
	v_mfma_f32_16x16x32_bf16 v[120:123], v[160:163], v[184:187], v[120:123]
	v_mfma_f32_16x16x32_bf16 v[108:111], v[152:155], v[194:197], v[108:111]
	v_mfma_f32_16x16x32_bf16 v[104:107], v[160:163], v[194:197], v[104:107]
	v_mfma_f32_16x16x32_bf16 v[92:95], v[152:155], v[202:205], v[92:95]
	v_mfma_f32_16x16x32_bf16 v[88:91], v[160:163], v[202:205], v[88:91]
	v_mfma_f32_16x16x32_bf16 v[76:79], v[152:155], v[210:213], v[76:79]
	v_mfma_f32_16x16x32_bf16 v[72:75], v[160:163], v[210:213], v[72:75]
	v_mfma_f32_16x16x32_bf16 v[124:127], v[156:159], v[188:191], v[124:127]
	v_mfma_f32_16x16x32_bf16 v[120:123], v[164:167], v[188:191], v[120:123]
	v_mfma_f32_16x16x32_bf16 v[108:111], v[156:159], v[198:201], v[108:111]
	v_mfma_f32_16x16x32_bf16 v[104:107], v[164:167], v[198:201], v[104:107]
	v_mfma_f32_16x16x32_bf16 v[92:95], v[156:159], v[206:209], v[92:95]
	v_mfma_f32_16x16x32_bf16 v[88:91], v[164:167], v[206:209], v[88:91]
	v_mfma_f32_16x16x32_bf16 v[76:79], v[156:159], v[214:217], v[76:79]
	v_mfma_f32_16x16x32_bf16 v[72:75], v[164:167], v[214:217], v[72:75]
	v_mfma_f32_16x16x32_bf16 v[116:119], v[168:171], v[184:187], v[116:119]
	v_mfma_f32_16x16x32_bf16 v[112:115], v[176:179], v[184:187], v[112:115]
	v_mfma_f32_16x16x32_bf16 v[100:103], v[168:171], v[194:197], v[100:103]
	v_mfma_f32_16x16x32_bf16 v[96:99], v[176:179], v[194:197], v[96:99]
	v_mfma_f32_16x16x32_bf16 v[84:87], v[168:171], v[202:205], v[84:87]
	v_mfma_f32_16x16x32_bf16 v[80:83], v[176:179], v[202:205], v[80:83]
	v_mfma_f32_16x16x32_bf16 v[68:71], v[168:171], v[210:213], v[68:71]
	v_mfma_f32_16x16x32_bf16 v[64:67], v[176:179], v[210:213], v[64:67]
	v_mfma_f32_16x16x32_bf16 v[116:119], v[172:175], v[188:191], v[116:119]
	v_mfma_f32_16x16x32_bf16 v[112:115], v[180:183], v[188:191], v[112:115]
	v_mfma_f32_16x16x32_bf16 v[100:103], v[172:175], v[198:201], v[100:103]
	v_mfma_f32_16x16x32_bf16 v[96:99], v[180:183], v[198:201], v[96:99]
	v_mfma_f32_16x16x32_bf16 v[84:87], v[172:175], v[206:209], v[84:87]
	v_mfma_f32_16x16x32_bf16 v[80:83], v[180:183], v[206:209], v[80:83]
	v_mfma_f32_16x16x32_bf16 v[68:71], v[172:175], v[214:217], v[68:71]
	v_mfma_f32_16x16x32_bf16 v[64:67], v[180:183], v[214:217], v[64:67]
	s_barrier
; #define PG8_STAGE(bufoff, gbase, voff) do { _Pragma("unroll") for (int _i = 0; _i < 2; ++_i) \
;         __builtin_amdgcn_global_load_lds((const unsigned*)((const char*)(gbase) + (voff)[_i]), (LAS unsigned*)(lds + (bufoff) + ldsw + _i * 8192), 16, 0, 0); } while (0)
; #define PG8_LDA(dst, b, h) do { _Pragma("unroll") for (int m = 0; m < 4; ++m) _Pragma("unroll") for (int k = 0; k < 2; ++k) dst[m][k] = *(const LAS bf16x8*)(lds + PG8_SA(b, h) + aoff + m * 2048 + k * 1024); } while (0)
; #define PG8_MMA(ai, bj, At, Bt) do { __builtin_amdgcn_s_setprio(1); _Pragma("unroll") for (int m = 0; m < 4; ++m) _Pragma("unroll") for (int n = 0; n < 2; ++n) _Pragma("unroll") for (int k = 0; k < 2; ++k) \
;         acc[ai][bj][m][n] = __builtin_amdgcn_mfma_f32_16x16x32_bf16(Bt[n][k], At[m][k], acc[ai][bj][m][n], 0, 0, 0); __builtin_amdgcn_s_setprio(0); } while (0)
; #define PG8_WAIT_V(n) asm volatile("s_waitcnt vmcnt(" #n ")" ::: "memory")
; #define PG8_WAIT_L(n) asm volatile("s_waitcnt lgkmcnt(" #n ")" ::: "memory")
; #define PG8_BAR __builtin_amdgcn_s_barrier()
; #define PG8_SCHED __builtin_amdgcn_sched_barrier(0)
; template <class Epi>
; DI void gemm_phase(int wv, LAS unsigned char* lds, LAS unsigned char* scr, const Sched& S, const Epi& E) {
;     ...
;             PG8_LDA(At, 1, 1); PG8_STAGE(PG8_SB(1, 0), b3, voffB); PG8_STAGE(PG8_SB(1, 1), b3 + hstepB, voffB); PG8_STAGE(PG8_SA(1, 0), a3, voffA);
;             PG8_WAIT_V(8); PG8_WAIT_L(0); PG8_BAR; PG8_MMA(1, 0, At, B0); PG8_MMA(1, 1, At, B1); PG8_BAR; PG8_SCHED;
;         }
	s_add_i32 s26, s58, s35
	v_lshl_add_u64 v[148:149], v[148:149], 0, s[2:3]
	s_mov_b32 m0, s26
	ds_read_b128 v[184:187], v151 offset:49152
	ds_read_b128 v[188:191], v151 offset:50176
	ds_read_b128 v[194:197], v151 offset:51200
	ds_read_b128 v[198:201], v151 offset:52224
	ds_read_b128 v[202:205], v151 offset:53248
	ds_read_b128 v[206:209], v151 offset:54272
	ds_read_b128 v[210:213], v151 offset:55296
	ds_read_b128 v[214:217], v151 offset:56320
	global_load_lds_dwordx4 v[148:149], off
	s_add_i32 m0, s26, 0x2000
	s_add_u32 s24, s24, 0x40080
	v_lshl_add_u64 v[148:149], v[218:219], 0, s[2:3]
	s_addc_u32 s25, s25, 0
	s_add_i32 s26, s60, s35
	global_load_lds_dwordx4 v[148:149], off
	v_lshl_add_u64 v[148:149], s[24:25], 0, v[130:131]
	s_mov_b32 m0, s26
	s_nop 0
	global_load_lds_dwordx4 v[148:149], off
	v_lshl_add_u64 v[148:149], s[24:25], 0, v[134:135]
	s_add_i32 m0, s26, 0x2000
	s_nop 0
	global_load_lds_dwordx4 v[148:149], off
	v_lshl_add_u64 v[148:149], v[220:221], 0, s[2:3]
	s_mov_b32 m0, s42
	s_nop 0
	global_load_lds_dwordx4 v[148:149], off
	v_lshl_add_u64 v[148:149], v[222:223], 0, s[2:3]
	s_mov_b32 m0, s43
	s_nop 0
	global_load_lds_dwordx4 v[148:149], off
	s_waitcnt vmcnt(8)
	s_waitcnt lgkmcnt(0)
	s_barrier
	s_waitcnt lgkmcnt(0)
	v_mfma_f32_16x16x32_bf16 v[60:63], v[152:155], v[184:187], v[60:63]
	v_mfma_f32_16x16x32_bf16 v[56:59], v[160:163], v[184:187], v[56:59]
	v_mfma_f32_16x16x32_bf16 v[44:47], v[152:155], v[194:197], v[44:47]
	v_mfma_f32_16x16x32_bf16 v[40:43], v[160:163], v[194:197], v[40:43]
	v_mfma_f32_16x16x32_bf16 v[28:31], v[152:155], v[202:205], v[28:31]
	v_mfma_f32_16x16x32_bf16 v[24:27], v[160:163], v[202:205], v[24:27]
	v_mfma_f32_16x16x32_bf16 v[12:15], v[152:155], v[210:213], v[12:15]
	v_mfma_f32_16x16x32_bf16 v[8:11], v[160:163], v[210:213], v[8:11]
	v_mfma_f32_16x16x32_bf16 v[60:63], v[156:159], v[188:191], v[60:63]
	v_mfma_f32_16x16x32_bf16 v[56:59], v[164:167], v[188:191], v[56:59]
	v_mfma_f32_16x16x32_bf16 v[44:47], v[156:159], v[198:201], v[44:47]
	v_mfma_f32_16x16x32_bf16 v[40:43], v[164:167], v[198:201], v[40:43]
	v_mfma_f32_16x16x32_bf16 v[28:31], v[156:159], v[206:209], v[28:31]
	v_mfma_f32_16x16x32_bf16 v[24:27], v[164:167], v[206:209], v[24:27]
	v_mfma_f32_16x16x32_bf16 v[12:15], v[156:159], v[214:217], v[12:15]
	v_mfma_f32_16x16x32_bf16 v[8:11], v[164:167], v[214:217], v[8:11]
	v_mfma_f32_16x16x32_bf16 v[52:55], v[168:171], v[184:187], v[52:55]
	v_mfma_f32_16x16x32_bf16 v[48:51], v[176:179], v[184:187], v[48:51]
	v_mfma_f32_16x16x32_bf16 v[36:39], v[168:171], v[194:197], v[36:39]
	v_mfma_f32_16x16x32_bf16 v[32:35], v[176:179], v[194:197], v[32:35]
	v_mfma_f32_16x16x32_bf16 v[20:23], v[168:171], v[202:205], v[20:23]
	v_mfma_f32_16x16x32_bf16 v[16:19], v[176:179], v[202:205], v[16:19]
	v_mfma_f32_16x16x32_bf16 v[4:7], v[168:171], v[210:213], v[4:7]
	v_mfma_f32_16x16x32_bf16 v[0:3], v[176:179], v[210:213], v[0:3]
	v_mfma_f32_16x16x32_bf16 v[52:55], v[172:175], v[188:191], v[52:55]
	v_mfma_f32_16x16x32_bf16 v[48:51], v[180:183], v[188:191], v[48:51]
	v_mfma_f32_16x16x32_bf16 v[36:39], v[172:175], v[198:201], v[36:39]
	v_mfma_f32_16x16x32_bf16 v[32:35], v[180:183], v[198:201], v[32:35]
	v_mfma_f32_16x16x32_bf16 v[20:23], v[172:175], v[206:209], v[20:23]
	v_mfma_f32_16x16x32_bf16 v[16:19], v[180:183], v[206:209], v[16:19]
	v_mfma_f32_16x16x32_bf16 v[4:7], v[172:175], v[214:217], v[4:7]
	v_mfma_f32_16x16x32_bf16 v[0:3], v[180:183], v[214:217], v[0:3]
	s_barrier
	s_add_i32 s57, s57, 2
	s_add_u32 s48, s48, 0x100
	s_addc_u32 s49, s49, 0
	s_add_u32 s22, s22, 0x100
	s_addc_u32 s23, s23, 0
	s_cmp_gt_u32 s57, 13
	s_cbranch_scc0 .LBB0_89
	s_setprio 0
	s_and_b64 vcc, exec, s[10:11]
	s_cbranch_vccz .LBB0_92
	s_barrier

; #define PG8_STAGE(bufoff, gbase, voff) do { _Pragma("unroll") for (int _i = 0; _i < 2; ++_i) \
;         __builtin_amdgcn_global_load_lds((const unsigned*)((const char*)(gbase) + (voff)[_i]), (LAS unsigned*)(lds + (bufoff) + ldsw + _i * 8192), 16, 0, 0); } while (0)
; #define PG8_LDA(dst, b, h) do { _Pragma("unroll") for (int m = 0; m < 4; ++m) _Pragma("unroll") for (int k = 0; k < 2; ++k) dst[m][k] = *(const LAS bf16x8*)(lds + PG8_SA(b, h) + aoff + m * 2048 + k * 1024); } while (0)
; #define PG8_LDB(dst, b, h) do { _Pragma("unroll") for (int n = 0; n < 2; ++n) _Pragma("unroll") for (int k = 0; k < 2; ++k) dst[n][k] = *(const LAS bf16x8*)(lds + PG8_SB(b, h) + boff + n * 2048 + k * 1024); } while (0)
; #define PG8_SCHED __builtin_amdgcn_sched_barrier(0)
; template <class Epi>
; DI void gemm_phase(int wv, LAS unsigned char* lds, LAS unsigned char* scr, const Sched& S, const Epi& E) {
;     ...
;         const bool has_next = S.next(ui + 1, nxt);
;         const char* nA = has_next ? S.baseA(nxt) : cA; const char* nB = has_next ? S.baseB(nxt) : cB;
;         for (int t = 0; t < nt; t += 2) {
;             const bool last = (t == nt - 2);
;             const char* a1 = cA + (size_t)(t + 1) * kstep;
;             const char* a2 = last ? nA : cA + (size_t)(t + 2) * kstep; const char* b2 = last ? nB : cB + (size_t)(t + 2) * kstep;
;             const char* a3 = a2 + kstep; const char* b3 = b2 + kstep;
;             PG8_LDB(B0, 0, 0); PG8_LDB(B1, 0, 1); PG8_SCHED; PG8_LDA(At, 0, 0); PG8_STAGE(PG8_SA(1, 1), a1 + hstepA, voffA);
;     ...
; #pragma unroll
;         for (int a = 0; a < 2; ++a)
; #pragma unroll
;             for (int b = 0; b < 2; ++b)
; #pragma unroll
;                 for (int m = 0; m < 4; ++m)
; #pragma unroll
;                     for (int n = 0; n < 2; ++n) acc[a][b][m][n] = (f32x4){0.f, 0.f, 0.f, 0.f};
;         cur = nxt; cA = nA; cB = nB; ++ui;
.LBB0_112:
	s_ashr_i32 s37, s36, 31
	s_lshl_b64 s[38:39], s[36:37], 19
	s_add_u32 s38, s9, s38
	s_addc_u32 s39, s33, s39
	s_and_b64 s[42:43], s[4:5], exec
	s_cselect_b32 s29, s39, s45
	s_cselect_b32 s31, s38, s44
	s_ashr_i32 s35, s34, 31
	s_lshl_b64 s[42:43], s[34:35], 19
	s_add_u32 s42, s52, s42
	s_addc_u32 s43, s53, s43
	s_and_b64 s[48:49], s[4:5], exec
	s_cselect_b32 s35, s43, s47
	s_cselect_b32 s37, s42, s46
	s_add_u32 s72, s46, 0x100
	s_addc_u32 s73, s47, 0
	s_add_u32 s44, s44, 0x40080
	v_mov_b32_e32 v0, 0
	v_mov_b32_e32 v220, 0x358637bd
	s_addc_u32 s45, s45, 0
	s_mov_b32 s74, -2
	v_mov_b32_e32 v1, v0
	v_mov_b32_e32 v2, v0
	v_mov_b32_e32 v3, v0
	v_mov_b32_e32 v4, v0
	v_mov_b32_e32 v5, v0
	v_mov_b32_e32 v6, v0
	v_mov_b32_e32 v7, v0
	v_mov_b32_e32 v8, v0
	v_mov_b32_e32 v9, v0
	v_mov_b32_e32 v10, v0
	v_mov_b32_e32 v11, v0
	v_mov_b32_e32 v12, v0
	v_mov_b32_e32 v13, v0
	v_mov_b32_e32 v14, v0
	v_mov_b32_e32 v15, v0
	v_mov_b32_e32 v24, v0
	v_mov_b32_e32 v25, v0
	v_mov_b32_e32 v26, v0
	v_mov_b32_e32 v27, v0
	v_mov_b32_e32 v28, v0
	v_mov_b32_e32 v29, v0
	v_mov_b32_e32 v30, v0
	v_mov_b32_e32 v31, v0
	v_mov_b32_e32 v40, v0
	v_mov_b32_e32 v41, v0
	v_mov_b32_e32 v42, v0
	v_mov_b32_e32 v43, v0
	s_waitcnt vmcnt(0)
	v_mov_b32_e32 v44, v0
	v_mov_b32_e32 v45, v0
	v_mov_b32_e32 v46, v0
	v_mov_b32_e32 v47, v0
	v_mov_b32_e32 v16, v0
	v_mov_b32_e32 v17, v0
	v_mov_b32_e32 v18, v0
	v_mov_b32_e32 v19, v0
	v_mov_b32_e32 v20, v0
	v_mov_b32_e32 v21, v0
	v_mov_b32_e32 v22, v0
	v_mov_b32_e32 v23, v0
	v_mov_b32_e32 v32, v0
	v_mov_b32_e32 v33, v0
	v_mov_b32_e32 v34, v0
	v_mov_b32_e32 v35, v0
	v_mov_b32_e32 v36, v0
	v_mov_b32_e32 v37, v0
	v_mov_b32_e32 v38, v0
	v_mov_b32_e32 v39, v0
	v_mov_b32_e32 v48, v0
	v_mov_b32_e32 v49, v0
	v_mov_b32_e32 v50, v0
	v_mov_b32_e32 v51, v0
	v_mov_b32_e32 v52, v0
	v_mov_b32_e32 v53, v0
	v_mov_b32_e32 v54, v0
	v_mov_b32_e32 v55, v0
	v_mov_b32_e32 v56, v0
	v_mov_b32_e32 v57, v0
	v_mov_b32_e32 v58, v0
	v_mov_b32_e32 v59, v0
	v_mov_b32_e32 v60, v0
	v_mov_b32_e32 v61, v0
	v_mov_b32_e32 v62, v0
	v_mov_b32_e32 v63, v0
	v_mov_b32_e32 v64, v0
	v_mov_b32_e32 v65, v0
	v_mov_b32_e32 v66, v0
	v_mov_b32_e32 v67, v0
	v_mov_b32_e32 v68, v0
	v_mov_b32_e32 v69, v0
	v_mov_b32_e32 v70, v0
	v_mov_b32_e32 v71, v0
	v_mov_b32_e32 v72, v0
	v_mov_b32_e32 v73, v0
	v_mov_b32_e32 v74, v0
	v_mov_b32_e32 v75, v0
	v_mov_b32_e32 v76, v0
	v_mov_b32_e32 v77, v0
	v_mov_b32_e32 v78, v0
	v_mov_b32_e32 v79, v0
	v_mov_b32_e32 v88, v0
	v_mov_b32_e32 v89, v0
	v_mov_b32_e32 v90, v0
	v_mov_b32_e32 v91, v0
	v_mov_b32_e32 v92, v0
	v_mov_b32_e32 v93, v0
	v_mov_b32_e32 v94, v0
	v_mov_b32_e32 v95, v0
	v_mov_b32_e32 v104, v0
	v_mov_b32_e32 v105, v0
	v_mov_b32_e32 v106, v0
	v_mov_b32_e32 v107, v0
	v_mov_b32_e32 v108, v0
	v_mov_b32_e32 v109, v0
	v_mov_b32_e32 v110, v0
	v_mov_b32_e32 v111, v0
	v_mov_b32_e32 v80, v0
	v_mov_b32_e32 v81, v0
	v_mov_b32_e32 v82, v0
	v_mov_b32_e32 v83, v0
	v_mov_b32_e32 v84, v0
	v_mov_b32_e32 v85, v0
	v_mov_b32_e32 v86, v0
	v_mov_b32_e32 v87, v0
	v_mov_b32_e32 v96, v0
	v_mov_b32_e32 v97, v0
	v_mov_b32_e32 v98, v0
	v_mov_b32_e32 v99, v0
	v_mov_b32_e32 v100, v0
	v_mov_b32_e32 v101, v0
	v_mov_b32_e32 v102, v0
	v_mov_b32_e32 v103, v0
	v_mov_b32_e32 v112, v0
	v_mov_b32_e32 v113, v0
	v_mov_b32_e32 v114, v0
	v_mov_b32_e32 v115, v0
	v_mov_b32_e32 v116, v0
	v_mov_b32_e32 v117, v0
	v_mov_b32_e32 v118, v0
	v_mov_b32_e32 v119, v0
	v_mov_b32_e32 v120, v0
	v_mov_b32_e32 v121, v0
	v_mov_b32_e32 v122, v0
	v_mov_b32_e32 v123, v0
	v_mov_b32_e32 v124, v0
	v_mov_b32_e32 v125, v0
	v_mov_b32_e32 v126, v0
	v_mov_b32_e32 v127, v0
	s_cmp_lg_u64 s[14:15], 0
	s_cbranch_scc1 .Lgp_4
	s_setprio 1
.Lgp_4:
.LBB0_113:
	s_add_u32 s46, s44, 0xfffc0080
	s_addc_u32 s47, s45, -1
	s_add_i32 s75, 0, 0x10000
	s_cmp_eq_u32 s74, 12
	s_cselect_b32 s49, s29, s47
	s_cselect_b32 s48, s31, s46
	s_cselect_b32 s47, s35, s73
	s_cselect_b32 s46, s37, s72
	s_add_i32 s78, 0, 0x14000
	v_add_u32_e32 v156, s75, v142
	v_add_u32_e32 v172, s78, v142
	ds_read_b128 v[144:147], v156
	ds_read_b128 v[148:151], v156 offset:1024
	ds_read_b128 v[152:155], v156 offset:2048
	ds_read_b128 v[156:159], v156 offset:3072
	ds_read_b128 v[160:163], v172
	ds_read_b128 v[164:167], v172 offset:1024
	ds_read_b128 v[168:171], v172 offset:2048
	ds_read_b128 v[172:175], v172 offset:3072
	v_lshl_add_u64 v[210:211], s[44:45], 0, v[140:141]
	s_add_i32 m0, s62, 0xc000
	ds_read_b128 v[176:179], v143
	ds_read_b128 v[180:183], v143 offset:1024
	ds_read_b128 v[184:187], v143 offset:2048
	ds_read_b128 v[188:191], v143 offset:3072
	ds_read_b128 v[194:197], v143 offset:4096
	ds_read_b128 v[198:201], v143 offset:5120
	ds_read_b128 v[202:205], v143 offset:6144
	ds_read_b128 v[206:209], v143 offset:7168
	global_load_lds_dwordx4 v[210:211], off
	v_lshl_add_u64 v[210:211], s[44:45], 0, v[138:139]
	s_add_i32 m0, s62, 0xe000
	s_nop 0
	global_load_lds_dwordx4 v[210:211], off
	s_waitcnt vmcnt(8)
	s_waitcnt lgkmcnt(0)
	s_barrier
; #define PG8_STAGE(bufoff, gbase, voff) do { _Pragma("unroll") for (int _i = 0; _i < 2; ++_i) \
;         __builtin_amdgcn_global_load_lds((const unsigned*)((const char*)(gbase) + (voff)[_i]), (LAS unsigned*)(lds + (bufoff) + ldsw + _i * 8192), 16, 0, 0); } while (0)
; #define PG8_LDA(dst, b, h) do { _Pragma("unroll") for (int m = 0; m < 4; ++m) _Pragma("unroll") for (int k = 0; k < 2; ++k) dst[m][k] = *(const LAS bf16x8*)(lds + PG8_SA(b, h) + aoff + m * 2048 + k * 1024); } while (0)
; #define PG8_MMA(ai, bj, At, Bt) do { __builtin_amdgcn_s_setprio(1); _Pragma("unroll") for (int m = 0; m < 4; ++m) _Pragma("unroll") for (int n = 0; n < 2; ++n) _Pragma("unroll") for (int k = 0; k < 2; ++k) \
;         acc[ai][bj][m][n] = __builtin_amdgcn_mfma_f32_16x16x32_bf16(Bt[n][k], At[m][k], acc[ai][bj][m][n], 0, 0, 0); __builtin_amdgcn_s_setprio(0); } while (0)
; #define PG8_WAIT_V(n) asm volatile("s_waitcnt vmcnt(" #n ")" ::: "memory")
; #define PG8_WAIT_L(n) asm volatile("s_waitcnt lgkmcnt(" #n ")" ::: "memory")
; #define PG8_BAR __builtin_amdgcn_s_barrier()
; #define PG8_SCHED __builtin_amdgcn_sched_barrier(0)
; template <class Epi>
; DI void gemm_phase(int wv, LAS unsigned char* lds, LAS unsigned char* scr, const Sched& S, const Epi& E) {
;     ...
;             PG8_WAIT_V(8); PG8_WAIT_L(0); PG8_BAR; PG8_MMA(0, 0, At, B0); PG8_MMA(0, 1, At, B1); PG8_BAR; PG8_SCHED;
;             PG8_LDA(At, 0, 1); PG8_STAGE(PG8_SB(0, 0), b2, voffB); PG8_STAGE(PG8_SB(0, 1), b2 + hstepB, voffB); PG8_STAGE(PG8_SA(0, 0), a2, voffA);
;             PG8_WAIT_V(8); PG8_WAIT_L(0); PG8_BAR; PG8_MMA(1, 0, At, B0); PG8_MMA(1, 1, At, B1); PG8_BAR; PG8_SCHED;
	s_waitcnt lgkmcnt(0)
	v_mfma_f32_16x16x32_bf16 v[124:127], v[144:147], v[176:179], v[124:127]
	v_mfma_f32_16x16x32_bf16 v[120:123], v[152:155], v[176:179], v[120:123]
	v_mfma_f32_16x16x32_bf16 v[116:119], v[144:147], v[184:187], v[116:119]
	v_mfma_f32_16x16x32_bf16 v[112:115], v[152:155], v[184:187], v[112:115]
	v_mfma_f32_16x16x32_bf16 v[100:103], v[144:147], v[194:197], v[100:103]
	v_mfma_f32_16x16x32_bf16 v[96:99], v[152:155], v[194:197], v[96:99]
	v_mfma_f32_16x16x32_bf16 v[84:87], v[144:147], v[202:205], v[84:87]
	v_mfma_f32_16x16x32_bf16 v[80:83], v[152:155], v[202:205], v[80:83]
	v_mfma_f32_16x16x32_bf16 v[124:127], v[148:151], v[180:183], v[124:127]
	v_mfma_f32_16x16x32_bf16 v[120:123], v[156:159], v[180:183], v[120:123]
	v_mfma_f32_16x16x32_bf16 v[116:119], v[148:151], v[188:191], v[116:119]
	v_mfma_f32_16x16x32_bf16 v[112:115], v[156:159], v[188:191], v[112:115]
	v_mfma_f32_16x16x32_bf16 v[100:103], v[148:151], v[198:201], v[100:103]
	v_mfma_f32_16x16x32_bf16 v[96:99], v[156:159], v[198:201], v[96:99]
	v_mfma_f32_16x16x32_bf16 v[84:87], v[148:151], v[206:209], v[84:87]
	v_mfma_f32_16x16x32_bf16 v[80:83], v[156:159], v[206:209], v[80:83]
	v_mfma_f32_16x16x32_bf16 v[108:111], v[160:163], v[176:179], v[108:111]
	v_mfma_f32_16x16x32_bf16 v[104:107], v[168:171], v[176:179], v[104:107]
	v_mfma_f32_16x16x32_bf16 v[92:95], v[160:163], v[184:187], v[92:95]
	v_mfma_f32_16x16x32_bf16 v[88:91], v[168:171], v[184:187], v[88:91]
	v_mfma_f32_16x16x32_bf16 v[76:79], v[160:163], v[194:197], v[76:79]
	v_mfma_f32_16x16x32_bf16 v[72:75], v[168:171], v[194:197], v[72:75]
	v_mfma_f32_16x16x32_bf16 v[68:71], v[160:163], v[202:205], v[68:71]
	v_mfma_f32_16x16x32_bf16 v[64:67], v[168:171], v[202:205], v[64:67]
	v_mfma_f32_16x16x32_bf16 v[108:111], v[164:167], v[180:183], v[108:111]
	v_mfma_f32_16x16x32_bf16 v[104:107], v[172:175], v[180:183], v[104:107]
	v_mfma_f32_16x16x32_bf16 v[92:95], v[164:167], v[188:191], v[92:95]
	v_mfma_f32_16x16x32_bf16 v[88:91], v[172:175], v[188:191], v[88:91]
	v_mfma_f32_16x16x32_bf16 v[76:79], v[164:167], v[198:201], v[76:79]
	v_mfma_f32_16x16x32_bf16 v[72:75], v[172:175], v[198:201], v[72:75]
	v_mfma_f32_16x16x32_bf16 v[68:71], v[164:167], v[206:209], v[68:71]
	v_mfma_f32_16x16x32_bf16 v[64:67], v[172:175], v[206:209], v[64:67]
	s_barrier
	s_add_i32 s75, s75, s60
	v_lshl_add_u64 v[210:211], s[46:47], 0, v[130:131]
	s_mov_b32 m0, s75
	ds_read_b128 v[176:179], v143 offset:16384
	ds_read_b128 v[180:183], v143 offset:17408
	ds_read_b128 v[184:187], v143 offset:18432
	ds_read_b128 v[188:191], v143 offset:19456
	ds_read_b128 v[194:197], v143 offset:20480
	ds_read_b128 v[198:201], v143 offset:21504
	ds_read_b128 v[202:205], v143 offset:22528
	ds_read_b128 v[206:209], v143 offset:23552
	global_load_lds_dwordx4 v[210:211], off
	s_add_i32 m0, s75, 0x2000
	s_add_u32 s76, s46, 0x40000
	v_lshl_add_u64 v[212:213], s[46:47], 0, v[134:135]
	s_addc_u32 s77, s47, 0
	s_add_i32 s75, s78, s60
	global_load_lds_dwordx4 v[212:213], off
	v_lshl_add_u64 v[214:215], s[76:77], 0, v[130:131]
	s_mov_b32 m0, s75
	v_lshl_add_u64 v[216:217], s[48:49], 0, v[132:133]
	global_load_lds_dwordx4 v[214:215], off
	v_lshl_add_u64 v[214:215], s[76:77], 0, v[134:135]
	s_add_i32 m0, s75, 0x2000
	s_nop 0
	global_load_lds_dwordx4 v[214:215], off
	v_lshl_add_u64 v[214:215], s[48:49], 0, v[128:129]
	s_mov_b32 m0, s62
	s_nop 0
	global_load_lds_dwordx4 v[214:215], off
	s_mov_b32 m0, s63
	s_nop 0
	global_load_lds_dwordx4 v[216:217], off
	s_waitcnt vmcnt(8)
	s_waitcnt lgkmcnt(0)
	s_barrier
	s_waitcnt lgkmcnt(0)
	v_mfma_f32_16x16x32_bf16 v[60:63], v[144:147], v[176:179], v[60:63]
	v_mfma_f32_16x16x32_bf16 v[56:59], v[152:155], v[176:179], v[56:59]
	v_mfma_f32_16x16x32_bf16 v[52:55], v[144:147], v[184:187], v[52:55]
	v_mfma_f32_16x16x32_bf16 v[48:51], v[152:155], v[184:187], v[48:51]
	v_mfma_f32_16x16x32_bf16 v[36:39], v[144:147], v[194:197], v[36:39]
	v_mfma_f32_16x16x32_bf16 v[32:35], v[152:155], v[194:197], v[32:35]
	v_mfma_f32_16x16x32_bf16 v[20:23], v[144:147], v[202:205], v[20:23]
	v_mfma_f32_16x16x32_bf16 v[16:19], v[152:155], v[202:205], v[16:19]
	v_mfma_f32_16x16x32_bf16 v[60:63], v[148:151], v[180:183], v[60:63]
	v_mfma_f32_16x16x32_bf16 v[56:59], v[156:159], v[180:183], v[56:59]
	v_mfma_f32_16x16x32_bf16 v[52:55], v[148:151], v[188:191], v[52:55]
	v_mfma_f32_16x16x32_bf16 v[48:51], v[156:159], v[188:191], v[48:51]
	v_mfma_f32_16x16x32_bf16 v[36:39], v[148:151], v[198:201], v[36:39]
	v_mfma_f32_16x16x32_bf16 v[32:35], v[156:159], v[198:201], v[32:35]
	v_mfma_f32_16x16x32_bf16 v[20:23], v[148:151], v[206:209], v[20:23]
	v_mfma_f32_16x16x32_bf16 v[16:19], v[156:159], v[206:209], v[16:19]
	v_mfma_f32_16x16x32_bf16 v[44:47], v[160:163], v[176:179], v[44:47]
	v_mfma_f32_16x16x32_bf16 v[40:43], v[168:171], v[176:179], v[40:43]
	v_mfma_f32_16x16x32_bf16 v[28:31], v[160:163], v[184:187], v[28:31]
	v_mfma_f32_16x16x32_bf16 v[24:27], v[168:171], v[184:187], v[24:27]
	v_mfma_f32_16x16x32_bf16 v[12:15], v[160:163], v[194:197], v[12:15]
	v_mfma_f32_16x16x32_bf16 v[8:11], v[168:171], v[194:197], v[8:11]
	v_mfma_f32_16x16x32_bf16 v[4:7], v[160:163], v[202:205], v[4:7]
	v_mfma_f32_16x16x32_bf16 v[0:3], v[168:171], v[202:205], v[0:3]
	v_mfma_f32_16x16x32_bf16 v[44:47], v[164:167], v[180:183], v[44:47]
	v_mfma_f32_16x16x32_bf16 v[40:43], v[172:175], v[180:183], v[40:43]
	v_mfma_f32_16x16x32_bf16 v[28:31], v[164:167], v[188:191], v[28:31]
	v_mfma_f32_16x16x32_bf16 v[24:27], v[172:175], v[188:191], v[24:27]
	v_mfma_f32_16x16x32_bf16 v[12:15], v[164:167], v[198:201], v[12:15]
	v_mfma_f32_16x16x32_bf16 v[8:11], v[172:175], v[198:201], v[8:11]
	v_mfma_f32_16x16x32_bf16 v[4:7], v[164:167], v[206:209], v[4:7]
	v_mfma_f32_16x16x32_bf16 v[0:3], v[172:175], v[206:209], v[0:3]
	s_barrier
; #define PG8_STAGE(bufoff, gbase, voff) do { _Pragma("unroll") for (int _i = 0; _i < 2; ++_i) \
;         __builtin_amdgcn_global_load_lds((const unsigned*)((const char*)(gbase) + (voff)[_i]), (LAS unsigned*)(lds + (bufoff) + ldsw + _i * 8192), 16, 0, 0); } while (0)
; #define PG8_LDA(dst, b, h) do { _Pragma("unroll") for (int m = 0; m < 4; ++m) _Pragma("unroll") for (int k = 0; k < 2; ++k) dst[m][k] = *(const LAS bf16x8*)(lds + PG8_SA(b, h) + aoff + m * 2048 + k * 1024); } while (0)
; #define PG8_LDB(dst, b, h) do { _Pragma("unroll") for (int n = 0; n < 2; ++n) _Pragma("unroll") for (int k = 0; k < 2; ++k) dst[n][k] = *(const LAS bf16x8*)(lds + PG8_SB(b, h) + boff + n * 2048 + k * 1024); } while (0)
; #define PG8_MMA(ai, bj, At, Bt) do { __builtin_amdgcn_s_setprio(1); _Pragma("unroll") for (int m = 0; m < 4; ++m) _Pragma("unroll") for (int n = 0; n < 2; ++n) _Pragma("unroll") for (int k = 0; k < 2; ++k) \
;         acc[ai][bj][m][n] = __builtin_amdgcn_mfma_f32_16x16x32_bf16(Bt[n][k], At[m][k], acc[ai][bj][m][n], 0, 0, 0); __builtin_amdgcn_s_setprio(0); } while (0)
; #define PG8_WAIT_V(n) asm volatile("s_waitcnt vmcnt(" #n ")" ::: "memory")
; #define PG8_WAIT_L(n) asm volatile("s_waitcnt lgkmcnt(" #n ")" ::: "memory")
; #define PG8_BAR __builtin_amdgcn_s_barrier()
; #define PG8_SCHED __builtin_amdgcn_sched_barrier(0)
; template <class Epi>
; DI void gemm_phase(int wv, LAS unsigned char* lds, LAS unsigned char* scr, const Sched& S, const Epi& E) {
;     ...
;             PG8_LDB(B0, 1, 0); PG8_LDB(B1, 1, 1); PG8_SCHED; PG8_LDA(At, 1, 0); PG8_STAGE(PG8_SA(0, 1), a2 + hstepA, voffA);
;             PG8_WAIT_V(8); PG8_WAIT_L(0); PG8_BAR; PG8_MMA(0, 0, At, B0); PG8_MMA(0, 1, At, B1); PG8_BAR; PG8_SCHED;
	s_add_i32 s75, 0, 0x18000
	s_add_i32 s76, 0, 0x1c000
	v_add_u32_e32 v156, s75, v142
	v_add_u32_e32 v172, s76, v142
	ds_read_b128 v[144:147], v156
	ds_read_b128 v[148:151], v156 offset:1024
	ds_read_b128 v[152:155], v156 offset:2048
	ds_read_b128 v[156:159], v156 offset:3072
	ds_read_b128 v[160:163], v172
	ds_read_b128 v[164:167], v172 offset:1024
	ds_read_b128 v[168:171], v172 offset:2048
	ds_read_b128 v[172:175], v172 offset:3072
	s_add_u32 s48, s48, 0x40000
	s_addc_u32 s49, s49, 0
	s_mov_b32 m0, s64
	v_lshl_add_u64 v[218:219], s[48:49], 0, v[128:129]
	ds_read_b128 v[176:179], v143 offset:32768
	ds_read_b128 v[180:183], v143 offset:33792
	ds_read_b128 v[184:187], v143 offset:34816
	ds_read_b128 v[188:191], v143 offset:35840
	ds_read_b128 v[194:197], v143 offset:36864
	ds_read_b128 v[198:201], v143 offset:37888
	ds_read_b128 v[202:205], v143 offset:38912
	ds_read_b128 v[206:209], v143 offset:39936
	global_load_lds_dwordx4 v[218:219], off
	v_lshl_add_u64 v[218:219], s[48:49], 0, v[132:133]
	s_mov_b32 m0, s65
	s_nop 0
	global_load_lds_dwordx4 v[218:219], off
	s_waitcnt vmcnt(8)
	s_waitcnt lgkmcnt(0)
	s_barrier
	s_waitcnt lgkmcnt(0)
	v_mfma_f32_16x16x32_bf16 v[124:127], v[144:147], v[176:179], v[124:127]
	v_mfma_f32_16x16x32_bf16 v[120:123], v[152:155], v[176:179], v[120:123]
	v_mfma_f32_16x16x32_bf16 v[116:119], v[144:147], v[184:187], v[116:119]
	v_mfma_f32_16x16x32_bf16 v[112:115], v[152:155], v[184:187], v[112:115]
	v_mfma_f32_16x16x32_bf16 v[100:103], v[144:147], v[194:197], v[100:103]
	v_mfma_f32_16x16x32_bf16 v[96:99], v[152:155], v[194:197], v[96:99]
	v_mfma_f32_16x16x32_bf16 v[84:87], v[144:147], v[202:205], v[84:87]
	v_mfma_f32_16x16x32_bf16 v[80:83], v[152:155], v[202:205], v[80:83]
	v_mfma_f32_16x16x32_bf16 v[124:127], v[148:151], v[180:183], v[124:127]
	v_mfma_f32_16x16x32_bf16 v[120:123], v[156:159], v[180:183], v[120:123]
	v_mfma_f32_16x16x32_bf16 v[116:119], v[148:151], v[188:191], v[116:119]
	v_mfma_f32_16x16x32_bf16 v[112:115], v[156:159], v[188:191], v[112:115]
	v_mfma_f32_16x16x32_bf16 v[100:103], v[148:151], v[198:201], v[100:103]
	v_mfma_f32_16x16x32_bf16 v[96:99], v[156:159], v[198:201], v[96:99]
	v_mfma_f32_16x16x32_bf16 v[84:87], v[148:151], v[206:209], v[84:87]
	v_mfma_f32_16x16x32_bf16 v[80:83], v[156:159], v[206:209], v[80:83]
	v_mfma_f32_16x16x32_bf16 v[108:111], v[160:163], v[176:179], v[108:111]
	v_mfma_f32_16x16x32_bf16 v[104:107], v[168:171], v[176:179], v[104:107]
	v_mfma_f32_16x16x32_bf16 v[92:95], v[160:163], v[184:187], v[92:95]
	v_mfma_f32_16x16x32_bf16 v[88:91], v[168:171], v[184:187], v[88:91]
	v_mfma_f32_16x16x32_bf16 v[76:79], v[160:163], v[194:197], v[76:79]
	v_mfma_f32_16x16x32_bf16 v[72:75], v[168:171], v[194:197], v[72:75]
	v_mfma_f32_16x16x32_bf16 v[68:71], v[160:163], v[202:205], v[68:71]
	v_mfma_f32_16x16x32_bf16 v[64:67], v[168:171], v[202:205], v[64:67]
	v_mfma_f32_16x16x32_bf16 v[108:111], v[164:167], v[180:183], v[108:111]
	v_mfma_f32_16x16x32_bf16 v[104:107], v[172:175], v[180:183], v[104:107]
	v_mfma_f32_16x16x32_bf16 v[92:95], v[164:167], v[188:191], v[92:95]
	v_mfma_f32_16x16x32_bf16 v[88:91], v[172:175], v[188:191], v[88:91]
	v_mfma_f32_16x16x32_bf16 v[76:79], v[164:167], v[198:201], v[76:79]
	v_mfma_f32_16x16x32_bf16 v[72:75], v[172:175], v[198:201], v[72:75]
	v_mfma_f32_16x16x32_bf16 v[68:71], v[164:167], v[206:209], v[68:71]
	v_mfma_f32_16x16x32_bf16 v[64:67], v[172:175], v[206:209], v[64:67]
	s_barrier
; #define PG8_STAGE(bufoff, gbase, voff) do { _Pragma("unroll") for (int _i = 0; _i < 2; ++_i) \
;         __builtin_amdgcn_global_load_lds((const unsigned*)((const char*)(gbase) + (voff)[_i]), (LAS unsigned*)(lds + (bufoff) + ldsw + _i * 8192), 16, 0, 0); } while (0)
; #define PG8_LDA(dst, b, h) do { _Pragma("unroll") for (int m = 0; m < 4; ++m) _Pragma("unroll") for (int k = 0; k < 2; ++k) dst[m][k] = *(const LAS bf16x8*)(lds + PG8_SA(b, h) + aoff + m * 2048 + k * 1024); } while (0)
; #define PG8_MMA(ai, bj, At, Bt) do { __builtin_amdgcn_s_setprio(1); _Pragma("unroll") for (int m = 0; m < 4; ++m) _Pragma("unroll") for (int n = 0; n < 2; ++n) _Pragma("unroll") for (int k = 0; k < 2; ++k) \
;         acc[ai][bj][m][n] = __builtin_amdgcn_mfma_f32_16x16x32_bf16(Bt[n][k], At[m][k], acc[ai][bj][m][n], 0, 0, 0); __builtin_amdgcn_s_setprio(0); } while (0)
; #define PG8_WAIT_V(n) asm volatile("s_waitcnt vmcnt(" #n ")" ::: "memory")
; #define PG8_WAIT_L(n) asm volatile("s_waitcnt lgkmcnt(" #n ")" ::: "memory")
; #define PG8_BAR __builtin_amdgcn_s_barrier()
; #define PG8_SCHED __builtin_amdgcn_sched_barrier(0)
; template <class Epi>
; DI void gemm_phase(int wv, LAS unsigned char* lds, LAS unsigned char* scr, const Sched& S, const Epi& E) {
;     ...
;             PG8_LDA(At, 1, 1); PG8_STAGE(PG8_SB(1, 0), b3, voffB); PG8_STAGE(PG8_SB(1, 1), b3 + hstepB, voffB); PG8_STAGE(PG8_SA(1, 0), a3, voffA);
;             PG8_WAIT_V(8); PG8_WAIT_L(0); PG8_BAR; PG8_MMA(1, 0, At, B0); PG8_MMA(1, 1, At, B1); PG8_BAR; PG8_SCHED;
;         }
	s_add_i32 s48, s75, s60
	v_lshl_add_u64 v[210:211], v[210:211], 0, s[2:3]
	s_mov_b32 m0, s48
	ds_read_b128 v[176:179], v143 offset:49152
	ds_read_b128 v[180:183], v143 offset:50176
	ds_read_b128 v[184:187], v143 offset:51200
	ds_read_b128 v[188:191], v143 offset:52224
	ds_read_b128 v[194:197], v143 offset:53248
	ds_read_b128 v[198:201], v143 offset:54272
	ds_read_b128 v[202:205], v143 offset:55296
	ds_read_b128 v[206:209], v143 offset:56320
	global_load_lds_dwordx4 v[210:211], off
	s_add_i32 m0, s48, 0x2000
	s_add_u32 s46, s46, 0x40080
	v_lshl_add_u64 v[210:211], v[212:213], 0, s[2:3]
	s_addc_u32 s47, s47, 0
	s_add_i32 s48, s76, s60
	global_load_lds_dwordx4 v[210:211], off
	v_lshl_add_u64 v[210:211], s[46:47], 0, v[130:131]
	s_mov_b32 m0, s48
	s_nop 0
	global_load_lds_dwordx4 v[210:211], off
	v_lshl_add_u64 v[210:211], s[46:47], 0, v[134:135]
	s_add_i32 m0, s48, 0x2000
	s_nop 0
	global_load_lds_dwordx4 v[210:211], off
	v_lshl_add_u64 v[210:211], v[214:215], 0, s[2:3]
	s_mov_b32 m0, s66
	s_nop 0
	global_load_lds_dwordx4 v[210:211], off
	v_lshl_add_u64 v[210:211], v[216:217], 0, s[2:3]
	s_mov_b32 m0, s67
	s_nop 0
	global_load_lds_dwordx4 v[210:211], off
	s_waitcnt vmcnt(8)
	s_waitcnt lgkmcnt(0)
	s_barrier
	s_waitcnt lgkmcnt(0)
	v_mfma_f32_16x16x32_bf16 v[60:63], v[144:147], v[176:179], v[60:63]
	v_mfma_f32_16x16x32_bf16 v[56:59], v[152:155], v[176:179], v[56:59]
	v_mfma_f32_16x16x32_bf16 v[52:55], v[144:147], v[184:187], v[52:55]
	v_mfma_f32_16x16x32_bf16 v[48:51], v[152:155], v[184:187], v[48:51]
	v_mfma_f32_16x16x32_bf16 v[36:39], v[144:147], v[194:197], v[36:39]
	v_mfma_f32_16x16x32_bf16 v[32:35], v[152:155], v[194:197], v[32:35]
	v_mfma_f32_16x16x32_bf16 v[20:23], v[144:147], v[202:205], v[20:23]
	v_mfma_f32_16x16x32_bf16 v[16:19], v[152:155], v[202:205], v[16:19]
	v_mfma_f32_16x16x32_bf16 v[60:63], v[148:151], v[180:183], v[60:63]
	v_mfma_f32_16x16x32_bf16 v[56:59], v[156:159], v[180:183], v[56:59]
	v_mfma_f32_16x16x32_bf16 v[52:55], v[148:151], v[188:191], v[52:55]
	v_mfma_f32_16x16x32_bf16 v[48:51], v[156:159], v[188:191], v[48:51]
	v_mfma_f32_16x16x32_bf16 v[36:39], v[148:151], v[198:201], v[36:39]
	v_mfma_f32_16x16x32_bf16 v[32:35], v[156:159], v[198:201], v[32:35]
	v_mfma_f32_16x16x32_bf16 v[20:23], v[148:151], v[206:209], v[20:23]
	v_mfma_f32_16x16x32_bf16 v[16:19], v[156:159], v[206:209], v[16:19]
	v_mfma_f32_16x16x32_bf16 v[44:47], v[160:163], v[176:179], v[44:47]
	v_mfma_f32_16x16x32_bf16 v[40:43], v[168:171], v[176:179], v[40:43]
	v_mfma_f32_16x16x32_bf16 v[28:31], v[160:163], v[184:187], v[28:31]
	v_mfma_f32_16x16x32_bf16 v[24:27], v[168:171], v[184:187], v[24:27]
	v_mfma_f32_16x16x32_bf16 v[12:15], v[160:163], v[194:197], v[12:15]
	v_mfma_f32_16x16x32_bf16 v[8:11], v[168:171], v[194:197], v[8:11]
	v_mfma_f32_16x16x32_bf16 v[4:7], v[160:163], v[202:205], v[4:7]
	v_mfma_f32_16x16x32_bf16 v[0:3], v[168:171], v[202:205], v[0:3]
	v_mfma_f32_16x16x32_bf16 v[44:47], v[164:167], v[180:183], v[44:47]
	v_mfma_f32_16x16x32_bf16 v[40:43], v[172:175], v[180:183], v[40:43]
	v_mfma_f32_16x16x32_bf16 v[28:31], v[164:167], v[188:191], v[28:31]
	v_mfma_f32_16x16x32_bf16 v[24:27], v[172:175], v[188:191], v[24:27]
	v_mfma_f32_16x16x32_bf16 v[12:15], v[164:167], v[198:201], v[12:15]
	v_mfma_f32_16x16x32_bf16 v[8:11], v[172:175], v[198:201], v[8:11]
	v_mfma_f32_16x16x32_bf16 v[4:7], v[164:167], v[206:209], v[4:7]
	v_mfma_f32_16x16x32_bf16 v[0:3], v[172:175], v[206:209], v[0:3]
	s_barrier
	s_add_i32 s74, s74, 2
	s_add_u32 s72, s72, 0x100
	s_addc_u32 s73, s73, 0
	s_add_u32 s44, s44, 0x100
	s_addc_u32 s45, s45, 0
	s_cmp_gt_u32 s74, 13
	s_cbranch_scc0 .LBB0_113
	s_setprio 0
	s_and_b64 vcc, exec, s[14:15]
	s_movk_i32 s74, 0x4000
	s_mov_b64 s[72:73], s[92:93]
	s_cbranch_vccz .LBB0_116
	s_barrier

; #define PG8_STAGE(bufoff, gbase, voff) do { _Pragma("unroll") for (int _i = 0; _i < 2; ++_i) \
;         __builtin_amdgcn_global_load_lds((const unsigned*)((const char*)(gbase) + (voff)[_i]), (LAS unsigned*)(lds + (bufoff) + ldsw + _i * 8192), 16, 0, 0); } while (0)
; #define PG8_LDA(dst, b, h) do { _Pragma("unroll") for (int m = 0; m < 4; ++m) _Pragma("unroll") for (int k = 0; k < 2; ++k) dst[m][k] = *(const LAS bf16x8*)(lds + PG8_SA(b, h) + aoff + m * 2048 + k * 1024); } while (0)
; #define PG8_LDB(dst, b, h) do { _Pragma("unroll") for (int n = 0; n < 2; ++n) _Pragma("unroll") for (int k = 0; k < 2; ++k) dst[n][k] = *(const LAS bf16x8*)(lds + PG8_SB(b, h) + boff + n * 2048 + k * 1024); } while (0)
; #define PG8_SCHED __builtin_amdgcn_sched_barrier(0)
; template <class Epi>
; DI void gemm_phase(int wv, LAS unsigned char* lds, LAS unsigned char* scr, const Sched& S, const Epi& E) {
;     ...
;         const bool has_next = S.next(ui + 1, nxt);
;         const char* nA = has_next ? S.baseA(nxt) : cA; const char* nB = has_next ? S.baseB(nxt) : cB;
;         for (int t = 0; t < nt; t += 2) {
;             const bool last = (t == nt - 2);
;             const char* a1 = cA + (size_t)(t + 1) * kstep;
;             const char* a2 = last ? nA : cA + (size_t)(t + 2) * kstep; const char* b2 = last ? nB : cB + (size_t)(t + 2) * kstep;
;             const char* a3 = a2 + kstep; const char* b3 = b2 + kstep;
;             PG8_LDB(B0, 0, 0); PG8_LDB(B1, 0, 1); PG8_SCHED; PG8_LDA(At, 0, 0); PG8_STAGE(PG8_SA(1, 1), a1 + hstepA, voffA);
;     ...
; #pragma unroll
;         for (int a = 0; a < 2; ++a)
; #pragma unroll
;             for (int b = 0; b < 2; ++b)
; #pragma unroll
;                 for (int m = 0; m < 4; ++m)
; #pragma unroll
;                     for (int n = 0; n < 2; ++n) acc[a][b][m][n] = (f32x4){0.f, 0.f, 0.f, 0.f};
;         cur = nxt; cA = nA; cB = nB; ++ui;
.LBB0_136:
	s_ashr_i32 s25, s24, 31
	s_lshl_b64 s[26:27], s[24:25], 19
	s_add_u32 s26, s9, s26
	s_addc_u32 s27, s33, s27
	s_and_b64 s[28:29], s[4:5], exec
	s_cselect_b32 s25, s27, s31
	s_cselect_b32 s60, s26, s30
	s_ashr_i32 s23, s22, 31
	s_lshl_b64 s[28:29], s[22:23], 19
	s_add_u32 s28, s52, s28
	s_addc_u32 s29, s53, s29
	s_and_b64 s[36:37], s[4:5], exec
	s_cselect_b32 s23, s29, s35
	s_cselect_b32 s61, s28, s34
	s_add_u32 s62, s34, 0x100
	s_addc_u32 s63, s35, 0
	s_add_u32 s30, s30, 0x40080
	v_mov_b32_e32 v0, 0
	v_mov_b32_e32 v220, 0x358637bd
	s_addc_u32 s31, s31, 0
	s_mov_b32 s64, -2
	v_mov_b32_e32 v1, v0
	v_mov_b32_e32 v2, v0
	v_mov_b32_e32 v3, v0
	v_mov_b32_e32 v4, v0
	v_mov_b32_e32 v5, v0
	v_mov_b32_e32 v6, v0
	v_mov_b32_e32 v7, v0
	v_mov_b32_e32 v8, v0
	v_mov_b32_e32 v9, v0
	v_mov_b32_e32 v10, v0
	v_mov_b32_e32 v11, v0
	v_mov_b32_e32 v12, v0
	v_mov_b32_e32 v13, v0
	v_mov_b32_e32 v14, v0
	v_mov_b32_e32 v15, v0
	v_mov_b32_e32 v24, v0
	v_mov_b32_e32 v25, v0
	v_mov_b32_e32 v26, v0
	v_mov_b32_e32 v27, v0
	v_mov_b32_e32 v28, v0
	v_mov_b32_e32 v29, v0
	v_mov_b32_e32 v30, v0
	v_mov_b32_e32 v31, v0
	v_mov_b32_e32 v40, v0
	v_mov_b32_e32 v41, v0
	v_mov_b32_e32 v42, v0
	v_mov_b32_e32 v43, v0
	s_waitcnt vmcnt(0)
	v_mov_b32_e32 v44, v0
	v_mov_b32_e32 v45, v0
	v_mov_b32_e32 v46, v0
	v_mov_b32_e32 v47, v0
	v_mov_b32_e32 v16, v0
	v_mov_b32_e32 v17, v0
	v_mov_b32_e32 v18, v0
	v_mov_b32_e32 v19, v0
	v_mov_b32_e32 v20, v0
	v_mov_b32_e32 v21, v0
	v_mov_b32_e32 v22, v0
	v_mov_b32_e32 v23, v0
	v_mov_b32_e32 v32, v0
	v_mov_b32_e32 v33, v0
	v_mov_b32_e32 v34, v0
	v_mov_b32_e32 v35, v0
	v_mov_b32_e32 v36, v0
	v_mov_b32_e32 v37, v0
	v_mov_b32_e32 v38, v0
	v_mov_b32_e32 v39, v0
	v_mov_b32_e32 v48, v0
	v_mov_b32_e32 v49, v0
	v_mov_b32_e32 v50, v0
	v_mov_b32_e32 v51, v0
	v_mov_b32_e32 v52, v0
	v_mov_b32_e32 v53, v0
	v_mov_b32_e32 v54, v0
	v_mov_b32_e32 v55, v0
	v_mov_b32_e32 v56, v0
	v_mov_b32_e32 v57, v0
	v_mov_b32_e32 v58, v0
	v_mov_b32_e32 v59, v0
	v_mov_b32_e32 v60, v0
	v_mov_b32_e32 v61, v0
	v_mov_b32_e32 v62, v0
	v_mov_b32_e32 v63, v0
	v_mov_b32_e32 v64, v0
	v_mov_b32_e32 v65, v0
	v_mov_b32_e32 v66, v0
	v_mov_b32_e32 v67, v0
	v_mov_b32_e32 v68, v0
	v_mov_b32_e32 v69, v0
	v_mov_b32_e32 v70, v0
	v_mov_b32_e32 v71, v0
	v_mov_b32_e32 v72, v0
	v_mov_b32_e32 v73, v0
	v_mov_b32_e32 v74, v0
	v_mov_b32_e32 v75, v0
	v_mov_b32_e32 v76, v0
	v_mov_b32_e32 v77, v0
	v_mov_b32_e32 v78, v0
	v_mov_b32_e32 v79, v0
	v_mov_b32_e32 v88, v0
	v_mov_b32_e32 v89, v0
	v_mov_b32_e32 v90, v0
	v_mov_b32_e32 v91, v0
	v_mov_b32_e32 v92, v0
	v_mov_b32_e32 v93, v0
	v_mov_b32_e32 v94, v0
	v_mov_b32_e32 v95, v0
	v_mov_b32_e32 v104, v0
	v_mov_b32_e32 v105, v0
	v_mov_b32_e32 v106, v0
	v_mov_b32_e32 v107, v0
	v_mov_b32_e32 v108, v0
	v_mov_b32_e32 v109, v0
	v_mov_b32_e32 v110, v0
	v_mov_b32_e32 v111, v0
	v_mov_b32_e32 v80, v0
	v_mov_b32_e32 v81, v0
	v_mov_b32_e32 v82, v0
	v_mov_b32_e32 v83, v0
	v_mov_b32_e32 v84, v0
	v_mov_b32_e32 v85, v0
	v_mov_b32_e32 v86, v0
	v_mov_b32_e32 v87, v0
	v_mov_b32_e32 v96, v0
	v_mov_b32_e32 v97, v0
	v_mov_b32_e32 v98, v0
	v_mov_b32_e32 v99, v0
	v_mov_b32_e32 v100, v0
	v_mov_b32_e32 v101, v0
	v_mov_b32_e32 v102, v0
	v_mov_b32_e32 v103, v0
	v_mov_b32_e32 v112, v0
	v_mov_b32_e32 v113, v0
	v_mov_b32_e32 v114, v0
	v_mov_b32_e32 v115, v0
	v_mov_b32_e32 v116, v0
	v_mov_b32_e32 v117, v0
	v_mov_b32_e32 v118, v0
	v_mov_b32_e32 v119, v0
	v_mov_b32_e32 v120, v0
	v_mov_b32_e32 v121, v0
	v_mov_b32_e32 v122, v0
	v_mov_b32_e32 v123, v0
	v_mov_b32_e32 v124, v0
	v_mov_b32_e32 v125, v0
	v_mov_b32_e32 v126, v0
	v_mov_b32_e32 v127, v0
	s_cmp_lg_u64 s[18:19], 0
	s_cbranch_scc1 .Lgp_5
	s_setprio 1
.Lgp_5:
.LBB0_137:
	s_add_u32 s34, s30, 0xfffc0080
	s_addc_u32 s35, s31, -1
	s_add_i32 s65, 0, 0x10000
	s_cmp_eq_u32 s64, 12
	s_cselect_b32 s37, s25, s35
	s_cselect_b32 s36, s60, s34
	v_add_u32_e32 v143, s65, v140
	s_cselect_b32 s35, s23, s63
	s_cselect_b32 s34, s61, s62
	s_add_i32 s68, 0, 0x14000
	ds_read_b128 v[144:147], v143
	ds_read_b128 v[148:151], v143 offset:1024
	ds_read_b128 v[152:155], v143 offset:2048
	ds_read_b128 v[156:159], v143 offset:3072
	v_add_u32_e32 v143, s68, v140
	ds_read_b128 v[160:163], v143
	ds_read_b128 v[164:167], v143 offset:1024
	ds_read_b128 v[168:171], v143 offset:2048
	ds_read_b128 v[172:175], v143 offset:3072
	v_lshl_add_u64 v[210:211], s[30:31], 0, v[138:139]
	s_add_i32 m0, s17, 0xc000
	ds_read_b128 v[176:179], v142
	ds_read_b128 v[180:183], v142 offset:1024
	ds_read_b128 v[184:187], v142 offset:2048
	ds_read_b128 v[188:191], v142 offset:3072
	ds_read_b128 v[194:197], v142 offset:4096
	ds_read_b128 v[198:201], v142 offset:5120
	ds_read_b128 v[202:205], v142 offset:6144
	ds_read_b128 v[206:209], v142 offset:7168
	global_load_lds_dwordx4 v[210:211], off
	v_lshl_add_u64 v[210:211], s[30:31], 0, v[136:137]
	s_add_i32 m0, s17, 0xe000
	s_nop 0
	global_load_lds_dwordx4 v[210:211], off
	s_waitcnt vmcnt(8)
	s_waitcnt lgkmcnt(0)
	s_barrier
; #define PG8_STAGE(bufoff, gbase, voff) do { _Pragma("unroll") for (int _i = 0; _i < 2; ++_i) \
;         __builtin_amdgcn_global_load_lds((const unsigned*)((const char*)(gbase) + (voff)[_i]), (LAS unsigned*)(lds + (bufoff) + ldsw + _i * 8192), 16, 0, 0); } while (0)
; #define PG8_LDA(dst, b, h) do { _Pragma("unroll") for (int m = 0; m < 4; ++m) _Pragma("unroll") for (int k = 0; k < 2; ++k) dst[m][k] = *(const LAS bf16x8*)(lds + PG8_SA(b, h) + aoff + m * 2048 + k * 1024); } while (0)
; #define PG8_MMA(ai, bj, At, Bt) do { __builtin_amdgcn_s_setprio(1); _Pragma("unroll") for (int m = 0; m < 4; ++m) _Pragma("unroll") for (int n = 0; n < 2; ++n) _Pragma("unroll") for (int k = 0; k < 2; ++k) \
;         acc[ai][bj][m][n] = __builtin_amdgcn_mfma_f32_16x16x32_bf16(Bt[n][k], At[m][k], acc[ai][bj][m][n], 0, 0, 0); __builtin_amdgcn_s_setprio(0); } while (0)
; #define PG8_WAIT_V(n) asm volatile("s_waitcnt vmcnt(" #n ")" ::: "memory")
; #define PG8_WAIT_L(n) asm volatile("s_waitcnt lgkmcnt(" #n ")" ::: "memory")
; #define PG8_BAR __builtin_amdgcn_s_barrier()
; #define PG8_SCHED __builtin_amdgcn_sched_barrier(0)
; template <class Epi>
; DI void gemm_phase(int wv, LAS unsigned char* lds, LAS unsigned char* scr, const Sched& S, const Epi& E) {
;     ...
;             PG8_WAIT_V(8); PG8_WAIT_L(0); PG8_BAR; PG8_MMA(0, 0, At, B0); PG8_MMA(0, 1, At, B1); PG8_BAR; PG8_SCHED;
;             PG8_LDA(At, 0, 1); PG8_STAGE(PG8_SB(0, 0), b2, voffB); PG8_STAGE(PG8_SB(0, 1), b2 + hstepB, voffB); PG8_STAGE(PG8_SA(0, 0), a2, voffA);
;             PG8_WAIT_V(8); PG8_WAIT_L(0); PG8_BAR; PG8_MMA(1, 0, At, B0); PG8_MMA(1, 1, At, B1); PG8_BAR; PG8_SCHED;
	s_waitcnt lgkmcnt(0)
	v_mfma_f32_16x16x32_bf16 v[124:127], v[144:147], v[176:179], v[124:127]
	v_mfma_f32_16x16x32_bf16 v[120:123], v[152:155], v[176:179], v[120:123]
	v_mfma_f32_16x16x32_bf16 v[116:119], v[144:147], v[184:187], v[116:119]
	v_mfma_f32_16x16x32_bf16 v[112:115], v[152:155], v[184:187], v[112:115]
	v_mfma_f32_16x16x32_bf16 v[100:103], v[144:147], v[194:197], v[100:103]
	v_mfma_f32_16x16x32_bf16 v[96:99], v[152:155], v[194:197], v[96:99]
	v_mfma_f32_16x16x32_bf16 v[84:87], v[144:147], v[202:205], v[84:87]
	v_mfma_f32_16x16x32_bf16 v[80:83], v[152:155], v[202:205], v[80:83]
	v_mfma_f32_16x16x32_bf16 v[124:127], v[148:151], v[180:183], v[124:127]
	v_mfma_f32_16x16x32_bf16 v[120:123], v[156:159], v[180:183], v[120:123]
	v_mfma_f32_16x16x32_bf16 v[116:119], v[148:151], v[188:191], v[116:119]
	v_mfma_f32_16x16x32_bf16 v[112:115], v[156:159], v[188:191], v[112:115]
	v_mfma_f32_16x16x32_bf16 v[100:103], v[148:151], v[198:201], v[100:103]
	v_mfma_f32_16x16x32_bf16 v[96:99], v[156:159], v[198:201], v[96:99]
	v_mfma_f32_16x16x32_bf16 v[84:87], v[148:151], v[206:209], v[84:87]
	v_mfma_f32_16x16x32_bf16 v[80:83], v[156:159], v[206:209], v[80:83]
	v_mfma_f32_16x16x32_bf16 v[108:111], v[160:163], v[176:179], v[108:111]
	v_mfma_f32_16x16x32_bf16 v[104:107], v[168:171], v[176:179], v[104:107]
	v_mfma_f32_16x16x32_bf16 v[92:95], v[160:163], v[184:187], v[92:95]
	v_mfma_f32_16x16x32_bf16 v[88:91], v[168:171], v[184:187], v[88:91]
	v_mfma_f32_16x16x32_bf16 v[76:79], v[160:163], v[194:197], v[76:79]
	v_mfma_f32_16x16x32_bf16 v[72:75], v[168:171], v[194:197], v[72:75]
	v_mfma_f32_16x16x32_bf16 v[68:71], v[160:163], v[202:205], v[68:71]
	v_mfma_f32_16x16x32_bf16 v[64:67], v[168:171], v[202:205], v[64:67]
	v_mfma_f32_16x16x32_bf16 v[108:111], v[164:167], v[180:183], v[108:111]
	v_mfma_f32_16x16x32_bf16 v[104:107], v[172:175], v[180:183], v[104:107]
	v_mfma_f32_16x16x32_bf16 v[92:95], v[164:167], v[188:191], v[92:95]
	v_mfma_f32_16x16x32_bf16 v[88:91], v[172:175], v[188:191], v[88:91]
	v_mfma_f32_16x16x32_bf16 v[76:79], v[164:167], v[198:201], v[76:79]
	v_mfma_f32_16x16x32_bf16 v[72:75], v[172:175], v[198:201], v[72:75]
	v_mfma_f32_16x16x32_bf16 v[68:71], v[164:167], v[206:209], v[68:71]
	v_mfma_f32_16x16x32_bf16 v[64:67], v[172:175], v[206:209], v[64:67]
	s_barrier
	s_add_i32 s65, s65, s39
	v_lshl_add_u64 v[210:211], s[34:35], 0, v[192:193]
	s_mov_b32 m0, s65
	ds_read_b128 v[176:179], v142 offset:16384
	ds_read_b128 v[180:183], v142 offset:17408
	ds_read_b128 v[184:187], v142 offset:18432
	ds_read_b128 v[188:191], v142 offset:19456
	ds_read_b128 v[194:197], v142 offset:20480
	ds_read_b128 v[198:201], v142 offset:21504
	ds_read_b128 v[202:205], v142 offset:22528
	ds_read_b128 v[206:209], v142 offset:23552
	global_load_lds_dwordx4 v[210:211], off
	s_add_i32 m0, s65, 0x2000
	s_add_u32 s66, s34, 0x40000
	v_lshl_add_u64 v[212:213], s[34:35], 0, v[132:133]
	s_addc_u32 s67, s35, 0
	s_add_i32 s65, s68, s39
	global_load_lds_dwordx4 v[212:213], off
	v_lshl_add_u64 v[214:215], s[66:67], 0, v[192:193]
	s_mov_b32 m0, s65
	v_lshl_add_u64 v[216:217], s[36:37], 0, v[130:131]
	global_load_lds_dwordx4 v[214:215], off
	v_lshl_add_u64 v[214:215], s[66:67], 0, v[132:133]
	s_add_i32 m0, s65, 0x2000
	s_nop 0
	global_load_lds_dwordx4 v[214:215], off
	v_lshl_add_u64 v[214:215], s[36:37], 0, v[128:129]
	s_mov_b32 m0, s17
	s_nop 0
	global_load_lds_dwordx4 v[214:215], off
	s_mov_b32 m0, s21
	s_nop 0
	global_load_lds_dwordx4 v[216:217], off
	s_waitcnt vmcnt(8)
	s_waitcnt lgkmcnt(0)
	s_barrier
	s_waitcnt lgkmcnt(0)
	v_mfma_f32_16x16x32_bf16 v[60:63], v[144:147], v[176:179], v[60:63]
	v_mfma_f32_16x16x32_bf16 v[56:59], v[152:155], v[176:179], v[56:59]
	v_mfma_f32_16x16x32_bf16 v[52:55], v[144:147], v[184:187], v[52:55]
	v_mfma_f32_16x16x32_bf16 v[48:51], v[152:155], v[184:187], v[48:51]
	v_mfma_f32_16x16x32_bf16 v[36:39], v[144:147], v[194:197], v[36:39]
	v_mfma_f32_16x16x32_bf16 v[32:35], v[152:155], v[194:197], v[32:35]
	v_mfma_f32_16x16x32_bf16 v[20:23], v[144:147], v[202:205], v[20:23]
	v_mfma_f32_16x16x32_bf16 v[16:19], v[152:155], v[202:205], v[16:19]
	v_mfma_f32_16x16x32_bf16 v[60:63], v[148:151], v[180:183], v[60:63]
	v_mfma_f32_16x16x32_bf16 v[56:59], v[156:159], v[180:183], v[56:59]
	v_mfma_f32_16x16x32_bf16 v[52:55], v[148:151], v[188:191], v[52:55]
	v_mfma_f32_16x16x32_bf16 v[48:51], v[156:159], v[188:191], v[48:51]
	v_mfma_f32_16x16x32_bf16 v[36:39], v[148:151], v[198:201], v[36:39]
	v_mfma_f32_16x16x32_bf16 v[32:35], v[156:159], v[198:201], v[32:35]
	v_mfma_f32_16x16x32_bf16 v[20:23], v[148:151], v[206:209], v[20:23]
	v_mfma_f32_16x16x32_bf16 v[16:19], v[156:159], v[206:209], v[16:19]
	v_mfma_f32_16x16x32_bf16 v[44:47], v[160:163], v[176:179], v[44:47]
	v_mfma_f32_16x16x32_bf16 v[40:43], v[168:171], v[176:179], v[40:43]
	v_mfma_f32_16x16x32_bf16 v[28:31], v[160:163], v[184:187], v[28:31]
	v_mfma_f32_16x16x32_bf16 v[24:27], v[168:171], v[184:187], v[24:27]
	v_mfma_f32_16x16x32_bf16 v[12:15], v[160:163], v[194:197], v[12:15]
	v_mfma_f32_16x16x32_bf16 v[8:11], v[168:171], v[194:197], v[8:11]
	v_mfma_f32_16x16x32_bf16 v[4:7], v[160:163], v[202:205], v[4:7]
	v_mfma_f32_16x16x32_bf16 v[0:3], v[168:171], v[202:205], v[0:3]
	v_mfma_f32_16x16x32_bf16 v[44:47], v[164:167], v[180:183], v[44:47]
	v_mfma_f32_16x16x32_bf16 v[40:43], v[172:175], v[180:183], v[40:43]
	v_mfma_f32_16x16x32_bf16 v[28:31], v[164:167], v[188:191], v[28:31]
	v_mfma_f32_16x16x32_bf16 v[24:27], v[172:175], v[188:191], v[24:27]
	v_mfma_f32_16x16x32_bf16 v[12:15], v[164:167], v[198:201], v[12:15]
	v_mfma_f32_16x16x32_bf16 v[8:11], v[172:175], v[198:201], v[8:11]
	v_mfma_f32_16x16x32_bf16 v[4:7], v[164:167], v[206:209], v[4:7]
	v_mfma_f32_16x16x32_bf16 v[0:3], v[172:175], v[206:209], v[0:3]
	s_barrier
; #define PG8_STAGE(bufoff, gbase, voff) do { _Pragma("unroll") for (int _i = 0; _i < 2; ++_i) \
;         __builtin_amdgcn_global_load_lds((const unsigned*)((const char*)(gbase) + (voff)[_i]), (LAS unsigned*)(lds + (bufoff) + ldsw + _i * 8192), 16, 0, 0); } while (0)
; #define PG8_LDA(dst, b, h) do { _Pragma("unroll") for (int m = 0; m < 4; ++m) _Pragma("unroll") for (int k = 0; k < 2; ++k) dst[m][k] = *(const LAS bf16x8*)(lds + PG8_SA(b, h) + aoff + m * 2048 + k * 1024); } while (0)
; #define PG8_LDB(dst, b, h) do { _Pragma("unroll") for (int n = 0; n < 2; ++n) _Pragma("unroll") for (int k = 0; k < 2; ++k) dst[n][k] = *(const LAS bf16x8*)(lds + PG8_SB(b, h) + boff + n * 2048 + k * 1024); } while (0)
; #define PG8_MMA(ai, bj, At, Bt) do { __builtin_amdgcn_s_setprio(1); _Pragma("unroll") for (int m = 0; m < 4; ++m) _Pragma("unroll") for (int n = 0; n < 2; ++n) _Pragma("unroll") for (int k = 0; k < 2; ++k) \
;         acc[ai][bj][m][n] = __builtin_amdgcn_mfma_f32_16x16x32_bf16(Bt[n][k], At[m][k], acc[ai][bj][m][n], 0, 0, 0); __builtin_amdgcn_s_setprio(0); } while (0)
; #define PG8_WAIT_V(n) asm volatile("s_waitcnt vmcnt(" #n ")" ::: "memory")
; #define PG8_WAIT_L(n) asm volatile("s_waitcnt lgkmcnt(" #n ")" ::: "memory")
; #define PG8_BAR __builtin_amdgcn_s_barrier()
; #define PG8_SCHED __builtin_amdgcn_sched_barrier(0)
; template <class Epi>
; DI void gemm_phase(int wv, LAS unsigned char* lds, LAS unsigned char* scr, const Sched& S, const Epi& E) {
;     ...
;             PG8_LDB(B0, 1, 0); PG8_LDB(B1, 1, 1); PG8_SCHED; PG8_LDA(At, 1, 0); PG8_STAGE(PG8_SA(0, 1), a2 + hstepA, voffA);
;             PG8_WAIT_V(8); PG8_WAIT_L(0); PG8_BAR; PG8_MMA(0, 0, At, B0); PG8_MMA(0, 1, At, B1); PG8_BAR; PG8_SCHED;
	s_add_i32 s65, 0, 0x18000
	v_add_u32_e32 v143, s65, v140
	s_add_i32 s66, 0, 0x1c000
	ds_read_b128 v[144:147], v143
	ds_read_b128 v[148:151], v143 offset:1024
	ds_read_b128 v[152:155], v143 offset:2048
	ds_read_b128 v[156:159], v143 offset:3072
	v_add_u32_e32 v143, s66, v140
	ds_read_b128 v[160:163], v143
	ds_read_b128 v[164:167], v143 offset:1024
	ds_read_b128 v[168:171], v143 offset:2048
	ds_read_b128 v[172:175], v143 offset:3072
	s_add_u32 s36, s36, 0x40000
	s_addc_u32 s37, s37, 0
	s_mov_b32 m0, s42
	v_lshl_add_u64 v[218:219], s[36:37], 0, v[128:129]
	ds_read_b128 v[176:179], v142 offset:32768
	ds_read_b128 v[180:183], v142 offset:33792
	ds_read_b128 v[184:187], v142 offset:34816
	ds_read_b128 v[188:191], v142 offset:35840
	ds_read_b128 v[194:197], v142 offset:36864
	ds_read_b128 v[198:201], v142 offset:37888
	ds_read_b128 v[202:205], v142 offset:38912
	ds_read_b128 v[206:209], v142 offset:39936
	global_load_lds_dwordx4 v[218:219], off
	v_lshl_add_u64 v[218:219], s[36:37], 0, v[130:131]
	s_mov_b32 m0, s43
	s_nop 0
	global_load_lds_dwordx4 v[218:219], off
	s_waitcnt vmcnt(8)
	s_waitcnt lgkmcnt(0)
	s_barrier
	s_waitcnt lgkmcnt(0)
	v_mfma_f32_16x16x32_bf16 v[124:127], v[144:147], v[176:179], v[124:127]
	v_mfma_f32_16x16x32_bf16 v[120:123], v[152:155], v[176:179], v[120:123]
	v_mfma_f32_16x16x32_bf16 v[116:119], v[144:147], v[184:187], v[116:119]
	v_mfma_f32_16x16x32_bf16 v[112:115], v[152:155], v[184:187], v[112:115]
	v_mfma_f32_16x16x32_bf16 v[100:103], v[144:147], v[194:197], v[100:103]
	v_mfma_f32_16x16x32_bf16 v[96:99], v[152:155], v[194:197], v[96:99]
	v_mfma_f32_16x16x32_bf16 v[84:87], v[144:147], v[202:205], v[84:87]
	v_mfma_f32_16x16x32_bf16 v[80:83], v[152:155], v[202:205], v[80:83]
	v_mfma_f32_16x16x32_bf16 v[124:127], v[148:151], v[180:183], v[124:127]
	v_mfma_f32_16x16x32_bf16 v[120:123], v[156:159], v[180:183], v[120:123]
	v_mfma_f32_16x16x32_bf16 v[116:119], v[148:151], v[188:191], v[116:119]
	v_mfma_f32_16x16x32_bf16 v[112:115], v[156:159], v[188:191], v[112:115]
	v_mfma_f32_16x16x32_bf16 v[100:103], v[148:151], v[198:201], v[100:103]
	v_mfma_f32_16x16x32_bf16 v[96:99], v[156:159], v[198:201], v[96:99]
	v_mfma_f32_16x16x32_bf16 v[84:87], v[148:151], v[206:209], v[84:87]
	v_mfma_f32_16x16x32_bf16 v[80:83], v[156:159], v[206:209], v[80:83]
	v_mfma_f32_16x16x32_bf16 v[108:111], v[160:163], v[176:179], v[108:111]
	v_mfma_f32_16x16x32_bf16 v[104:107], v[168:171], v[176:179], v[104:107]
	v_mfma_f32_16x16x32_bf16 v[92:95], v[160:163], v[184:187], v[92:95]
	v_mfma_f32_16x16x32_bf16 v[88:91], v[168:171], v[184:187], v[88:91]
	v_mfma_f32_16x16x32_bf16 v[76:79], v[160:163], v[194:197], v[76:79]
	v_mfma_f32_16x16x32_bf16 v[72:75], v[168:171], v[194:197], v[72:75]
	v_mfma_f32_16x16x32_bf16 v[68:71], v[160:163], v[202:205], v[68:71]
	v_mfma_f32_16x16x32_bf16 v[64:67], v[168:171], v[202:205], v[64:67]
	v_mfma_f32_16x16x32_bf16 v[108:111], v[164:167], v[180:183], v[108:111]
	v_mfma_f32_16x16x32_bf16 v[104:107], v[172:175], v[180:183], v[104:107]
	v_mfma_f32_16x16x32_bf16 v[92:95], v[164:167], v[188:191], v[92:95]
	v_mfma_f32_16x16x32_bf16 v[88:91], v[172:175], v[188:191], v[88:91]
	v_mfma_f32_16x16x32_bf16 v[76:79], v[164:167], v[198:201], v[76:79]
	v_mfma_f32_16x16x32_bf16 v[72:75], v[172:175], v[198:201], v[72:75]
	v_mfma_f32_16x16x32_bf16 v[68:71], v[164:167], v[206:209], v[68:71]
	v_mfma_f32_16x16x32_bf16 v[64:67], v[172:175], v[206:209], v[64:67]
	s_barrier
; #define PG8_STAGE(bufoff, gbase, voff) do { _Pragma("unroll") for (int _i = 0; _i < 2; ++_i) \
;         __builtin_amdgcn_global_load_lds((const unsigned*)((const char*)(gbase) + (voff)[_i]), (LAS unsigned*)(lds + (bufoff) + ldsw + _i * 8192), 16, 0, 0); } while (0)
; #define PG8_LDA(dst, b, h) do { _Pragma("unroll") for (int m = 0; m < 4; ++m) _Pragma("unroll") for (int k = 0; k < 2; ++k) dst[m][k] = *(const LAS bf16x8*)(lds + PG8_SA(b, h) + aoff + m * 2048 + k * 1024); } while (0)
; #define PG8_MMA(ai, bj, At, Bt) do { __builtin_amdgcn_s_setprio(1); _Pragma("unroll") for (int m = 0; m < 4; ++m) _Pragma("unroll") for (int n = 0; n < 2; ++n) _Pragma("unroll") for (int k = 0; k < 2; ++k) \
;         acc[ai][bj][m][n] = __builtin_amdgcn_mfma_f32_16x16x32_bf16(Bt[n][k], At[m][k], acc[ai][bj][m][n], 0, 0, 0); __builtin_amdgcn_s_setprio(0); } while (0)
; #define PG8_WAIT_V(n) asm volatile("s_waitcnt vmcnt(" #n ")" ::: "memory")
; #define PG8_WAIT_L(n) asm volatile("s_waitcnt lgkmcnt(" #n ")" ::: "memory")
; #define PG8_BAR __builtin_amdgcn_s_barrier()
; #define PG8_SCHED __builtin_amdgcn_sched_barrier(0)
; template <class Epi>
; DI void gemm_phase(int wv, LAS unsigned char* lds, LAS unsigned char* scr, const Sched& S, const Epi& E) {
;     ...
;             PG8_LDA(At, 1, 1); PG8_STAGE(PG8_SB(1, 0), b3, voffB); PG8_STAGE(PG8_SB(1, 1), b3 + hstepB, voffB); PG8_STAGE(PG8_SA(1, 0), a3, voffA);
;             PG8_WAIT_V(8); PG8_WAIT_L(0); PG8_BAR; PG8_MMA(1, 0, At, B0); PG8_MMA(1, 1, At, B1); PG8_BAR; PG8_SCHED;
;         }
	s_add_i32 s36, s65, s39
	v_lshl_add_u64 v[210:211], v[210:211], 0, s[2:3]
	s_mov_b32 m0, s36
	ds_read_b128 v[176:179], v142 offset:49152
	ds_read_b128 v[180:183], v142 offset:50176
	ds_read_b128 v[184:187], v142 offset:51200
	ds_read_b128 v[188:191], v142 offset:52224
	ds_read_b128 v[194:197], v142 offset:53248
	ds_read_b128 v[198:201], v142 offset:54272
	ds_read_b128 v[202:205], v142 offset:55296
	ds_read_b128 v[206:209], v142 offset:56320
	global_load_lds_dwordx4 v[210:211], off
	s_add_i32 m0, s36, 0x2000
	s_add_u32 s34, s34, 0x40080
	v_lshl_add_u64 v[210:211], v[212:213], 0, s[2:3]
	s_addc_u32 s35, s35, 0
	s_add_i32 s36, s66, s39
	global_load_lds_dwordx4 v[210:211], off
	v_lshl_add_u64 v[210:211], s[34:35], 0, v[192:193]
	s_mov_b32 m0, s36
	s_nop 0
	global_load_lds_dwordx4 v[210:211], off
	v_lshl_add_u64 v[210:211], s[34:35], 0, v[132:133]
	s_add_i32 m0, s36, 0x2000
	s_nop 0
	global_load_lds_dwordx4 v[210:211], off
	v_lshl_add_u64 v[210:211], v[214:215], 0, s[2:3]
	s_mov_b32 m0, s44
	s_nop 0
	global_load_lds_dwordx4 v[210:211], off
	v_lshl_add_u64 v[210:211], v[216:217], 0, s[2:3]
	s_mov_b32 m0, s45
	s_nop 0
	global_load_lds_dwordx4 v[210:211], off
	s_waitcnt vmcnt(8)
	s_waitcnt lgkmcnt(0)
	s_barrier
	s_waitcnt lgkmcnt(0)
	v_mfma_f32_16x16x32_bf16 v[60:63], v[144:147], v[176:179], v[60:63]
	v_mfma_f32_16x16x32_bf16 v[56:59], v[152:155], v[176:179], v[56:59]
	v_mfma_f32_16x16x32_bf16 v[52:55], v[144:147], v[184:187], v[52:55]
	v_mfma_f32_16x16x32_bf16 v[48:51], v[152:155], v[184:187], v[48:51]
	v_mfma_f32_16x16x32_bf16 v[36:39], v[144:147], v[194:197], v[36:39]
	v_mfma_f32_16x16x32_bf16 v[32:35], v[152:155], v[194:197], v[32:35]
	v_mfma_f32_16x16x32_bf16 v[20:23], v[144:147], v[202:205], v[20:23]
	v_mfma_f32_16x16x32_bf16 v[16:19], v[152:155], v[202:205], v[16:19]
	v_mfma_f32_16x16x32_bf16 v[60:63], v[148:151], v[180:183], v[60:63]
	v_mfma_f32_16x16x32_bf16 v[56:59], v[156:159], v[180:183], v[56:59]
	v_mfma_f32_16x16x32_bf16 v[52:55], v[148:151], v[188:191], v[52:55]
	v_mfma_f32_16x16x32_bf16 v[48:51], v[156:159], v[188:191], v[48:51]
	v_mfma_f32_16x16x32_bf16 v[36:39], v[148:151], v[198:201], v[36:39]
	v_mfma_f32_16x16x32_bf16 v[32:35], v[156:159], v[198:201], v[32:35]
	v_mfma_f32_16x16x32_bf16 v[20:23], v[148:151], v[206:209], v[20:23]
	v_mfma_f32_16x16x32_bf16 v[16:19], v[156:159], v[206:209], v[16:19]
	v_mfma_f32_16x16x32_bf16 v[44:47], v[160:163], v[176:179], v[44:47]
	v_mfma_f32_16x16x32_bf16 v[40:43], v[168:171], v[176:179], v[40:43]
	v_mfma_f32_16x16x32_bf16 v[28:31], v[160:163], v[184:187], v[28:31]
	v_mfma_f32_16x16x32_bf16 v[24:27], v[168:171], v[184:187], v[24:27]
	v_mfma_f32_16x16x32_bf16 v[12:15], v[160:163], v[194:197], v[12:15]
	v_mfma_f32_16x16x32_bf16 v[8:11], v[168:171], v[194:197], v[8:11]
	v_mfma_f32_16x16x32_bf16 v[4:7], v[160:163], v[202:205], v[4:7]
	v_mfma_f32_16x16x32_bf16 v[0:3], v[168:171], v[202:205], v[0:3]
	v_mfma_f32_16x16x32_bf16 v[44:47], v[164:167], v[180:183], v[44:47]
	v_mfma_f32_16x16x32_bf16 v[40:43], v[172:175], v[180:183], v[40:43]
	v_mfma_f32_16x16x32_bf16 v[28:31], v[164:167], v[188:191], v[28:31]
	v_mfma_f32_16x16x32_bf16 v[24:27], v[172:175], v[188:191], v[24:27]
	v_mfma_f32_16x16x32_bf16 v[12:15], v[164:167], v[198:201], v[12:15]
	v_mfma_f32_16x16x32_bf16 v[8:11], v[172:175], v[198:201], v[8:11]
	v_mfma_f32_16x16x32_bf16 v[4:7], v[164:167], v[206:209], v[4:7]
	v_mfma_f32_16x16x32_bf16 v[0:3], v[172:175], v[206:209], v[0:3]
	s_barrier
	s_add_i32 s64, s64, 2
	s_add_u32 s62, s62, 0x100
	s_addc_u32 s63, s63, 0
	s_add_u32 s30, s30, 0x100
	s_addc_u32 s31, s31, 0
	s_cmp_gt_u32 s64, 13
	s_cbranch_scc0 .LBB0_137
	s_setprio 0
	s_and_b64 vcc, exec, s[18:19]
	s_cbranch_vccz .LBB0_140
	s_barrier

; #define PG8_STAGE(bufoff, gbase, voff) do { _Pragma("unroll") for (int _i = 0; _i < 2; ++_i) \
;         __builtin_amdgcn_global_load_lds((const unsigned*)((const char*)(gbase) + (voff)[_i]), (LAS unsigned*)(lds + (bufoff) + ldsw + _i * 8192), 16, 0, 0); } while (0)
; #define PG8_LDA(dst, b, h) do { _Pragma("unroll") for (int m = 0; m < 4; ++m) _Pragma("unroll") for (int k = 0; k < 2; ++k) dst[m][k] = *(const LAS bf16x8*)(lds + PG8_SA(b, h) + aoff + m * 2048 + k * 1024); } while (0)
; #define PG8_LDB(dst, b, h) do { _Pragma("unroll") for (int n = 0; n < 2; ++n) _Pragma("unroll") for (int k = 0; k < 2; ++k) dst[n][k] = *(const LAS bf16x8*)(lds + PG8_SB(b, h) + boff + n * 2048 + k * 1024); } while (0)
; #define PG8_SCHED __builtin_amdgcn_sched_barrier(0)
; template <class Epi>
; DI void gemm_phase(int wv, LAS unsigned char* lds, LAS unsigned char* scr, const Sched& S, const Epi& E) {
;     ...
;         const bool has_next = S.next(ui + 1, nxt);
;         const char* nA = has_next ? S.baseA(nxt) : cA; const char* nB = has_next ? S.baseB(nxt) : cB;
;         for (int t = 0; t < nt; t += 2) {
;             const bool last = (t == nt - 2);
;             const char* a1 = cA + (size_t)(t + 1) * kstep;
;             const char* a2 = last ? nA : cA + (size_t)(t + 2) * kstep; const char* b2 = last ? nB : cB + (size_t)(t + 2) * kstep;
;             const char* a3 = a2 + kstep; const char* b3 = b2 + kstep;
;             PG8_LDB(B0, 0, 0); PG8_LDB(B1, 0, 1); PG8_SCHED; PG8_LDA(At, 0, 0); PG8_STAGE(PG8_SA(1, 1), a1 + hstepA, voffA);
;     ...
; #pragma unroll
;         for (int a = 0; a < 2; ++a)
; #pragma unroll
;             for (int b = 0; b < 2; ++b)
; #pragma unroll
;                 for (int m = 0; m < 4; ++m)
; #pragma unroll
;                     for (int n = 0; n < 2; ++n) acc[a][b][m][n] = (f32x4){0.f, 0.f, 0.f, 0.f};
;         cur = nxt; cA = nA; cB = nB; ++ui;
.LBB0_162:
	s_ashr_i32 s21, s20, 31
	s_lshl_b64 s[24:25], s[20:21], 19
	s_add_u32 s24, s9, s24
	s_addc_u32 s25, s30, s25
	s_and_b64 s[6:7], s[6:7], exec
	s_cselect_b32 s21, s25, s27
	s_cselect_b32 s40, s24, s26
	s_add_u32 s55, s28, 0x100
	s_addc_u32 s60, s29, 0
	s_add_u32 s6, s26, 0x40080
	v_mov_b32_e32 v0, 0
	s_addc_u32 s7, s27, 0
	s_mov_b32 s61, -2
	v_mov_b32_e32 v1, v0
	v_mov_b32_e32 v2, v0
	v_mov_b32_e32 v3, v0
	v_mov_b32_e32 v4, v0
	v_mov_b32_e32 v5, v0
	v_mov_b32_e32 v6, v0
	v_mov_b32_e32 v7, v0
	v_mov_b32_e32 v8, v0
	v_mov_b32_e32 v9, v0
	v_mov_b32_e32 v10, v0
	v_mov_b32_e32 v11, v0
	v_mov_b32_e32 v12, v0
	v_mov_b32_e32 v13, v0
	v_mov_b32_e32 v14, v0
	v_mov_b32_e32 v15, v0
	v_mov_b32_e32 v24, v0
	v_mov_b32_e32 v25, v0
	v_mov_b32_e32 v26, v0
	v_mov_b32_e32 v27, v0
	v_mov_b32_e32 v28, v0
	v_mov_b32_e32 v29, v0
	v_mov_b32_e32 v30, v0
	v_mov_b32_e32 v31, v0
	v_mov_b32_e32 v40, v0
	v_mov_b32_e32 v41, v0
	v_mov_b32_e32 v42, v0
	v_mov_b32_e32 v43, v0
	s_waitcnt vmcnt(0)
	v_mov_b32_e32 v44, v0
	v_mov_b32_e32 v45, v0
	v_mov_b32_e32 v46, v0
	v_mov_b32_e32 v47, v0
	v_mov_b32_e32 v16, v0
	v_mov_b32_e32 v17, v0
	v_mov_b32_e32 v18, v0
	v_mov_b32_e32 v19, v0
	v_mov_b32_e32 v20, v0
	v_mov_b32_e32 v21, v0
	v_mov_b32_e32 v22, v0
	v_mov_b32_e32 v23, v0
	v_mov_b32_e32 v32, v0
	v_mov_b32_e32 v33, v0
	v_mov_b32_e32 v34, v0
	v_mov_b32_e32 v35, v0
	v_mov_b32_e32 v36, v0
	v_mov_b32_e32 v37, v0
	v_mov_b32_e32 v38, v0
	v_mov_b32_e32 v39, v0
	v_mov_b32_e32 v48, v0
	v_mov_b32_e32 v49, v0
	v_mov_b32_e32 v50, v0
	v_mov_b32_e32 v51, v0
	v_mov_b32_e32 v52, v0
	v_mov_b32_e32 v53, v0
	v_mov_b32_e32 v54, v0
	v_mov_b32_e32 v55, v0
	v_mov_b32_e32 v56, v0
	v_mov_b32_e32 v57, v0
	v_mov_b32_e32 v58, v0
	v_mov_b32_e32 v59, v0
	v_mov_b32_e32 v60, v0
	v_mov_b32_e32 v61, v0
	v_mov_b32_e32 v62, v0
	v_mov_b32_e32 v63, v0
	v_mov_b32_e32 v64, v0
	v_mov_b32_e32 v65, v0
	v_mov_b32_e32 v66, v0
	v_mov_b32_e32 v67, v0
	v_mov_b32_e32 v68, v0
	v_mov_b32_e32 v69, v0
	v_mov_b32_e32 v70, v0
	v_mov_b32_e32 v71, v0
	v_mov_b32_e32 v72, v0
	v_mov_b32_e32 v73, v0
	v_mov_b32_e32 v74, v0
	v_mov_b32_e32 v75, v0
	v_mov_b32_e32 v76, v0
	v_mov_b32_e32 v77, v0
	v_mov_b32_e32 v78, v0
	v_mov_b32_e32 v79, v0
	v_mov_b32_e32 v88, v0
	v_mov_b32_e32 v89, v0
	v_mov_b32_e32 v90, v0
	v_mov_b32_e32 v91, v0
	v_mov_b32_e32 v92, v0
	v_mov_b32_e32 v93, v0
	v_mov_b32_e32 v94, v0
	v_mov_b32_e32 v95, v0
	v_mov_b32_e32 v104, v0
	v_mov_b32_e32 v105, v0
	v_mov_b32_e32 v106, v0
	v_mov_b32_e32 v107, v0
	v_mov_b32_e32 v108, v0
	v_mov_b32_e32 v109, v0
	v_mov_b32_e32 v110, v0
	v_mov_b32_e32 v111, v0
	v_mov_b32_e32 v80, v0
	v_mov_b32_e32 v81, v0
	v_mov_b32_e32 v82, v0
	v_mov_b32_e32 v83, v0
	v_mov_b32_e32 v84, v0
	v_mov_b32_e32 v85, v0
	v_mov_b32_e32 v86, v0
	v_mov_b32_e32 v87, v0
	v_mov_b32_e32 v96, v0
	v_mov_b32_e32 v97, v0
	v_mov_b32_e32 v98, v0
	v_mov_b32_e32 v99, v0
	v_mov_b32_e32 v100, v0
	v_mov_b32_e32 v101, v0
	v_mov_b32_e32 v102, v0
	v_mov_b32_e32 v103, v0
	v_mov_b32_e32 v112, v0
	v_mov_b32_e32 v113, v0
	v_mov_b32_e32 v114, v0
	v_mov_b32_e32 v115, v0
	v_mov_b32_e32 v116, v0
	v_mov_b32_e32 v117, v0
	v_mov_b32_e32 v118, v0
	v_mov_b32_e32 v119, v0
	v_mov_b32_e32 v120, v0
	v_mov_b32_e32 v121, v0
	v_mov_b32_e32 v122, v0
	v_mov_b32_e32 v123, v0
	v_mov_b32_e32 v124, v0
	v_mov_b32_e32 v125, v0
	v_mov_b32_e32 v126, v0
	v_mov_b32_e32 v127, v0
	s_cmp_lg_u64 s[18:19], 0
	s_cbranch_scc1 .Lgp_6
	s_setprio 1
.Lgp_6:
.LBB0_163:
	s_add_u32 s26, s6, 0xfffc0080
	s_addc_u32 s27, s7, -1
	s_add_i32 s62, 0, 0x10000
	s_cmp_eq_u32 s61, 12
	s_cselect_b32 s29, s21, s27
	s_cselect_b32 s28, s40, s26
	v_add_u32_e32 v143, s62, v140
	s_cselect_b32 s27, s23, s60
	s_cselect_b32 s26, s22, s55
	s_add_i32 s64, 0, 0x14000
	ds_read_b128 v[144:147], v143
	ds_read_b128 v[148:151], v143 offset:1024
	ds_read_b128 v[152:155], v143 offset:2048
	ds_read_b128 v[156:159], v143 offset:3072
	v_add_u32_e32 v143, s64, v140
	ds_read_b128 v[160:163], v143
	ds_read_b128 v[164:167], v143 offset:1024
	ds_read_b128 v[168:171], v143 offset:2048
	ds_read_b128 v[172:175], v143 offset:3072
	v_lshl_add_u64 v[210:211], s[6:7], 0, v[138:139]
	s_add_i32 m0, s37, 0xc000
	ds_read_b128 v[176:179], v142
	ds_read_b128 v[180:183], v142 offset:1024
	ds_read_b128 v[184:187], v142 offset:2048
	ds_read_b128 v[188:191], v142 offset:3072
	ds_read_b128 v[194:197], v142 offset:4096
	ds_read_b128 v[198:201], v142 offset:5120
	ds_read_b128 v[202:205], v142 offset:6144
	ds_read_b128 v[206:209], v142 offset:7168
	global_load_lds_dwordx4 v[210:211], off
	v_lshl_add_u64 v[210:211], s[6:7], 0, v[136:137]
	s_add_i32 m0, s37, 0xe000
	s_nop 0
	global_load_lds_dwordx4 v[210:211], off
	s_waitcnt vmcnt(8)
	s_waitcnt lgkmcnt(0)
	s_barrier
; #define PG8_STAGE(bufoff, gbase, voff) do { _Pragma("unroll") for (int _i = 0; _i < 2; ++_i) \
;         __builtin_amdgcn_global_load_lds((const unsigned*)((const char*)(gbase) + (voff)[_i]), (LAS unsigned*)(lds + (bufoff) + ldsw + _i * 8192), 16, 0, 0); } while (0)
; #define PG8_LDA(dst, b, h) do { _Pragma("unroll") for (int m = 0; m < 4; ++m) _Pragma("unroll") for (int k = 0; k < 2; ++k) dst[m][k] = *(const LAS bf16x8*)(lds + PG8_SA(b, h) + aoff + m * 2048 + k * 1024); } while (0)
; #define PG8_MMA(ai, bj, At, Bt) do { __builtin_amdgcn_s_setprio(1); _Pragma("unroll") for (int m = 0; m < 4; ++m) _Pragma("unroll") for (int n = 0; n < 2; ++n) _Pragma("unroll") for (int k = 0; k < 2; ++k) \
;         acc[ai][bj][m][n] = __builtin_amdgcn_mfma_f32_16x16x32_bf16(Bt[n][k], At[m][k], acc[ai][bj][m][n], 0, 0, 0); __builtin_amdgcn_s_setprio(0); } while (0)
; #define PG8_WAIT_V(n) asm volatile("s_waitcnt vmcnt(" #n ")" ::: "memory")
; #define PG8_WAIT_L(n) asm volatile("s_waitcnt lgkmcnt(" #n ")" ::: "memory")
; #define PG8_BAR __builtin_amdgcn_s_barrier()
; #define PG8_SCHED __builtin_amdgcn_sched_barrier(0)
; template <class Epi>
; DI void gemm_phase(int wv, LAS unsigned char* lds, LAS unsigned char* scr, const Sched& S, const Epi& E) {
;     ...
;             PG8_WAIT_V(8); PG8_WAIT_L(0); PG8_BAR; PG8_MMA(0, 0, At, B0); PG8_MMA(0, 1, At, B1); PG8_BAR; PG8_SCHED;
;             PG8_LDA(At, 0, 1); PG8_STAGE(PG8_SB(0, 0), b2, voffB); PG8_STAGE(PG8_SB(0, 1), b2 + hstepB, voffB); PG8_STAGE(PG8_SA(0, 0), a2, voffA);
;             PG8_WAIT_V(8); PG8_WAIT_L(0); PG8_BAR; PG8_MMA(1, 0, At, B0); PG8_MMA(1, 1, At, B1); PG8_BAR; PG8_SCHED;
	s_waitcnt lgkmcnt(0)
	v_mfma_f32_16x16x32_bf16 v[124:127], v[144:147], v[176:179], v[124:127]
	v_mfma_f32_16x16x32_bf16 v[120:123], v[152:155], v[176:179], v[120:123]
	v_mfma_f32_16x16x32_bf16 v[116:119], v[144:147], v[184:187], v[116:119]
	v_mfma_f32_16x16x32_bf16 v[112:115], v[152:155], v[184:187], v[112:115]
	v_mfma_f32_16x16x32_bf16 v[100:103], v[144:147], v[194:197], v[100:103]
	v_mfma_f32_16x16x32_bf16 v[96:99], v[152:155], v[194:197], v[96:99]
	v_mfma_f32_16x16x32_bf16 v[84:87], v[144:147], v[202:205], v[84:87]
	v_mfma_f32_16x16x32_bf16 v[80:83], v[152:155], v[202:205], v[80:83]
	v_mfma_f32_16x16x32_bf16 v[124:127], v[148:151], v[180:183], v[124:127]
	v_mfma_f32_16x16x32_bf16 v[120:123], v[156:159], v[180:183], v[120:123]
	v_mfma_f32_16x16x32_bf16 v[116:119], v[148:151], v[188:191], v[116:119]
	v_mfma_f32_16x16x32_bf16 v[112:115], v[156:159], v[188:191], v[112:115]
	v_mfma_f32_16x16x32_bf16 v[100:103], v[148:151], v[198:201], v[100:103]
	v_mfma_f32_16x16x32_bf16 v[96:99], v[156:159], v[198:201], v[96:99]
	v_mfma_f32_16x16x32_bf16 v[84:87], v[148:151], v[206:209], v[84:87]
	v_mfma_f32_16x16x32_bf16 v[80:83], v[156:159], v[206:209], v[80:83]
	v_mfma_f32_16x16x32_bf16 v[108:111], v[160:163], v[176:179], v[108:111]
	v_mfma_f32_16x16x32_bf16 v[104:107], v[168:171], v[176:179], v[104:107]
	v_mfma_f32_16x16x32_bf16 v[92:95], v[160:163], v[184:187], v[92:95]
	v_mfma_f32_16x16x32_bf16 v[88:91], v[168:171], v[184:187], v[88:91]
	v_mfma_f32_16x16x32_bf16 v[76:79], v[160:163], v[194:197], v[76:79]
	v_mfma_f32_16x16x32_bf16 v[72:75], v[168:171], v[194:197], v[72:75]
	v_mfma_f32_16x16x32_bf16 v[68:71], v[160:163], v[202:205], v[68:71]
	v_mfma_f32_16x16x32_bf16 v[64:67], v[168:171], v[202:205], v[64:67]
	v_mfma_f32_16x16x32_bf16 v[108:111], v[164:167], v[180:183], v[108:111]
	v_mfma_f32_16x16x32_bf16 v[104:107], v[172:175], v[180:183], v[104:107]
	v_mfma_f32_16x16x32_bf16 v[92:95], v[164:167], v[188:191], v[92:95]
	v_mfma_f32_16x16x32_bf16 v[88:91], v[172:175], v[188:191], v[88:91]
	v_mfma_f32_16x16x32_bf16 v[76:79], v[164:167], v[198:201], v[76:79]
	v_mfma_f32_16x16x32_bf16 v[72:75], v[172:175], v[198:201], v[72:75]
	v_mfma_f32_16x16x32_bf16 v[68:71], v[164:167], v[206:209], v[68:71]
	v_mfma_f32_16x16x32_bf16 v[64:67], v[172:175], v[206:209], v[64:67]
	s_barrier
	s_add_i32 s62, s62, s33
	v_lshl_add_u64 v[210:211], s[26:27], 0, v[192:193]
	s_mov_b32 m0, s62
	ds_read_b128 v[176:179], v142 offset:16384
	ds_read_b128 v[180:183], v142 offset:17408
	ds_read_b128 v[184:187], v142 offset:18432
	ds_read_b128 v[188:191], v142 offset:19456
	ds_read_b128 v[194:197], v142 offset:20480
	ds_read_b128 v[198:201], v142 offset:21504
	ds_read_b128 v[202:205], v142 offset:22528
	ds_read_b128 v[206:209], v142 offset:23552
	global_load_lds_dwordx4 v[210:211], off
	s_add_i32 m0, s62, 0x2000
	s_add_u32 s62, s26, 0x100000
	v_lshl_add_u64 v[212:213], s[26:27], 0, v[132:133]
	s_addc_u32 s63, s27, 0
	s_add_i32 s64, s64, s33
	global_load_lds_dwordx4 v[212:213], off
	v_lshl_add_u64 v[214:215], s[62:63], 0, v[192:193]
	s_mov_b32 m0, s64
	v_lshl_add_u64 v[216:217], s[28:29], 0, v[130:131]
	global_load_lds_dwordx4 v[214:215], off
	v_lshl_add_u64 v[214:215], s[62:63], 0, v[132:133]
	s_add_i32 m0, s64, 0x2000
	s_nop 0
	global_load_lds_dwordx4 v[214:215], off
	v_lshl_add_u64 v[214:215], s[28:29], 0, v[128:129]
	s_mov_b32 m0, s37
	s_nop 0
	global_load_lds_dwordx4 v[214:215], off
	s_mov_b32 m0, s38
	s_nop 0
	global_load_lds_dwordx4 v[216:217], off
	s_waitcnt vmcnt(8)
	s_waitcnt lgkmcnt(0)
	s_barrier
	s_waitcnt lgkmcnt(0)
	v_mfma_f32_16x16x32_bf16 v[60:63], v[144:147], v[176:179], v[60:63]
	v_mfma_f32_16x16x32_bf16 v[56:59], v[152:155], v[176:179], v[56:59]
	v_mfma_f32_16x16x32_bf16 v[52:55], v[144:147], v[184:187], v[52:55]
	v_mfma_f32_16x16x32_bf16 v[48:51], v[152:155], v[184:187], v[48:51]
	v_mfma_f32_16x16x32_bf16 v[36:39], v[144:147], v[194:197], v[36:39]
	v_mfma_f32_16x16x32_bf16 v[32:35], v[152:155], v[194:197], v[32:35]
	v_mfma_f32_16x16x32_bf16 v[20:23], v[144:147], v[202:205], v[20:23]
	v_mfma_f32_16x16x32_bf16 v[16:19], v[152:155], v[202:205], v[16:19]
	v_mfma_f32_16x16x32_bf16 v[60:63], v[148:151], v[180:183], v[60:63]
	v_mfma_f32_16x16x32_bf16 v[56:59], v[156:159], v[180:183], v[56:59]
	v_mfma_f32_16x16x32_bf16 v[52:55], v[148:151], v[188:191], v[52:55]
	v_mfma_f32_16x16x32_bf16 v[48:51], v[156:159], v[188:191], v[48:51]
	v_mfma_f32_16x16x32_bf16 v[36:39], v[148:151], v[198:201], v[36:39]
	v_mfma_f32_16x16x32_bf16 v[32:35], v[156:159], v[198:201], v[32:35]
	v_mfma_f32_16x16x32_bf16 v[20:23], v[148:151], v[206:209], v[20:23]
	v_mfma_f32_16x16x32_bf16 v[16:19], v[156:159], v[206:209], v[16:19]
	v_mfma_f32_16x16x32_bf16 v[44:47], v[160:163], v[176:179], v[44:47]
	v_mfma_f32_16x16x32_bf16 v[40:43], v[168:171], v[176:179], v[40:43]
	v_mfma_f32_16x16x32_bf16 v[28:31], v[160:163], v[184:187], v[28:31]
	v_mfma_f32_16x16x32_bf16 v[24:27], v[168:171], v[184:187], v[24:27]
	v_mfma_f32_16x16x32_bf16 v[12:15], v[160:163], v[194:197], v[12:15]
	v_mfma_f32_16x16x32_bf16 v[8:11], v[168:171], v[194:197], v[8:11]
	v_mfma_f32_16x16x32_bf16 v[4:7], v[160:163], v[202:205], v[4:7]
	v_mfma_f32_16x16x32_bf16 v[0:3], v[168:171], v[202:205], v[0:3]
	v_mfma_f32_16x16x32_bf16 v[44:47], v[164:167], v[180:183], v[44:47]
	v_mfma_f32_16x16x32_bf16 v[40:43], v[172:175], v[180:183], v[40:43]
	v_mfma_f32_16x16x32_bf16 v[28:31], v[164:167], v[188:191], v[28:31]
	v_mfma_f32_16x16x32_bf16 v[24:27], v[172:175], v[188:191], v[24:27]
	v_mfma_f32_16x16x32_bf16 v[12:15], v[164:167], v[198:201], v[12:15]
	v_mfma_f32_16x16x32_bf16 v[8:11], v[172:175], v[198:201], v[8:11]
	v_mfma_f32_16x16x32_bf16 v[4:7], v[164:167], v[206:209], v[4:7]
	v_mfma_f32_16x16x32_bf16 v[0:3], v[172:175], v[206:209], v[0:3]
	s_barrier
; #define PG8_STAGE(bufoff, gbase, voff) do { _Pragma("unroll") for (int _i = 0; _i < 2; ++_i) \
;         __builtin_amdgcn_global_load_lds((const unsigned*)((const char*)(gbase) + (voff)[_i]), (LAS unsigned*)(lds + (bufoff) + ldsw + _i * 8192), 16, 0, 0); } while (0)
; #define PG8_LDA(dst, b, h) do { _Pragma("unroll") for (int m = 0; m < 4; ++m) _Pragma("unroll") for (int k = 0; k < 2; ++k) dst[m][k] = *(const LAS bf16x8*)(lds + PG8_SA(b, h) + aoff + m * 2048 + k * 1024); } while (0)
; #define PG8_LDB(dst, b, h) do { _Pragma("unroll") for (int n = 0; n < 2; ++n) _Pragma("unroll") for (int k = 0; k < 2; ++k) dst[n][k] = *(const LAS bf16x8*)(lds + PG8_SB(b, h) + boff + n * 2048 + k * 1024); } while (0)
; #define PG8_MMA(ai, bj, At, Bt) do { __builtin_amdgcn_s_setprio(1); _Pragma("unroll") for (int m = 0; m < 4; ++m) _Pragma("unroll") for (int n = 0; n < 2; ++n) _Pragma("unroll") for (int k = 0; k < 2; ++k) \
;         acc[ai][bj][m][n] = __builtin_amdgcn_mfma_f32_16x16x32_bf16(Bt[n][k], At[m][k], acc[ai][bj][m][n], 0, 0, 0); __builtin_amdgcn_s_setprio(0); } while (0)
; #define PG8_WAIT_V(n) asm volatile("s_waitcnt vmcnt(" #n ")" ::: "memory")
; #define PG8_WAIT_L(n) asm volatile("s_waitcnt lgkmcnt(" #n ")" ::: "memory")
; #define PG8_BAR __builtin_amdgcn_s_barrier()
; #define PG8_SCHED __builtin_amdgcn_sched_barrier(0)
; template <class Epi>
; DI void gemm_phase(int wv, LAS unsigned char* lds, LAS unsigned char* scr, const Sched& S, const Epi& E) {
;     ...
;             PG8_LDB(B0, 1, 0); PG8_LDB(B1, 1, 1); PG8_SCHED; PG8_LDA(At, 1, 0); PG8_STAGE(PG8_SA(0, 1), a2 + hstepA, voffA);
;             PG8_WAIT_V(8); PG8_WAIT_L(0); PG8_BAR; PG8_MMA(0, 0, At, B0); PG8_MMA(0, 1, At, B1); PG8_BAR; PG8_SCHED;
	s_add_i32 s62, 0, 0x18000
	v_add_u32_e32 v143, s62, v140
	s_add_i32 s63, 0, 0x1c000
	ds_read_b128 v[144:147], v143
	ds_read_b128 v[148:151], v143 offset:1024
	ds_read_b128 v[152:155], v143 offset:2048
	ds_read_b128 v[156:159], v143 offset:3072
	v_add_u32_e32 v143, s63, v140
	ds_read_b128 v[160:163], v143
	ds_read_b128 v[164:167], v143 offset:1024
	ds_read_b128 v[168:171], v143 offset:2048
	ds_read_b128 v[172:175], v143 offset:3072
	s_add_u32 s28, s28, 0x40000
	s_addc_u32 s29, s29, 0
	s_mov_b32 m0, s39
	v_lshl_add_u64 v[218:219], s[28:29], 0, v[128:129]
	ds_read_b128 v[176:179], v142 offset:32768
	ds_read_b128 v[180:183], v142 offset:33792
	ds_read_b128 v[184:187], v142 offset:34816
	ds_read_b128 v[188:191], v142 offset:35840
	ds_read_b128 v[194:197], v142 offset:36864
	ds_read_b128 v[198:201], v142 offset:37888
	ds_read_b128 v[202:205], v142 offset:38912
	ds_read_b128 v[206:209], v142 offset:39936
	global_load_lds_dwordx4 v[218:219], off
	v_lshl_add_u64 v[218:219], s[28:29], 0, v[130:131]
	s_mov_b32 m0, s42
	s_nop 0
	global_load_lds_dwordx4 v[218:219], off
	s_waitcnt vmcnt(8)
	s_waitcnt lgkmcnt(0)
	s_barrier
	s_waitcnt lgkmcnt(0)
	v_mfma_f32_16x16x32_bf16 v[124:127], v[144:147], v[176:179], v[124:127]
	v_mfma_f32_16x16x32_bf16 v[120:123], v[152:155], v[176:179], v[120:123]
	v_mfma_f32_16x16x32_bf16 v[116:119], v[144:147], v[184:187], v[116:119]
	v_mfma_f32_16x16x32_bf16 v[112:115], v[152:155], v[184:187], v[112:115]
	v_mfma_f32_16x16x32_bf16 v[100:103], v[144:147], v[194:197], v[100:103]
	v_mfma_f32_16x16x32_bf16 v[96:99], v[152:155], v[194:197], v[96:99]
	v_mfma_f32_16x16x32_bf16 v[84:87], v[144:147], v[202:205], v[84:87]
	v_mfma_f32_16x16x32_bf16 v[80:83], v[152:155], v[202:205], v[80:83]
	v_mfma_f32_16x16x32_bf16 v[124:127], v[148:151], v[180:183], v[124:127]
	v_mfma_f32_16x16x32_bf16 v[120:123], v[156:159], v[180:183], v[120:123]
	v_mfma_f32_16x16x32_bf16 v[116:119], v[148:151], v[188:191], v[116:119]
	v_mfma_f32_16x16x32_bf16 v[112:115], v[156:159], v[188:191], v[112:115]
	v_mfma_f32_16x16x32_bf16 v[100:103], v[148:151], v[198:201], v[100:103]
	v_mfma_f32_16x16x32_bf16 v[96:99], v[156:159], v[198:201], v[96:99]
	v_mfma_f32_16x16x32_bf16 v[84:87], v[148:151], v[206:209], v[84:87]
	v_mfma_f32_16x16x32_bf16 v[80:83], v[156:159], v[206:209], v[80:83]
	v_mfma_f32_16x16x32_bf16 v[108:111], v[160:163], v[176:179], v[108:111]
	v_mfma_f32_16x16x32_bf16 v[104:107], v[168:171], v[176:179], v[104:107]
	v_mfma_f32_16x16x32_bf16 v[92:95], v[160:163], v[184:187], v[92:95]
	v_mfma_f32_16x16x32_bf16 v[88:91], v[168:171], v[184:187], v[88:91]
	v_mfma_f32_16x16x32_bf16 v[76:79], v[160:163], v[194:197], v[76:79]
	v_mfma_f32_16x16x32_bf16 v[72:75], v[168:171], v[194:197], v[72:75]
	v_mfma_f32_16x16x32_bf16 v[68:71], v[160:163], v[202:205], v[68:71]
	v_mfma_f32_16x16x32_bf16 v[64:67], v[168:171], v[202:205], v[64:67]
	v_mfma_f32_16x16x32_bf16 v[108:111], v[164:167], v[180:183], v[108:111]
	v_mfma_f32_16x16x32_bf16 v[104:107], v[172:175], v[180:183], v[104:107]
	v_mfma_f32_16x16x32_bf16 v[92:95], v[164:167], v[188:191], v[92:95]
	v_mfma_f32_16x16x32_bf16 v[88:91], v[172:175], v[188:191], v[88:91]
	v_mfma_f32_16x16x32_bf16 v[76:79], v[164:167], v[198:201], v[76:79]
	v_mfma_f32_16x16x32_bf16 v[72:75], v[172:175], v[198:201], v[72:75]
	v_mfma_f32_16x16x32_bf16 v[68:71], v[164:167], v[206:209], v[68:71]
	v_mfma_f32_16x16x32_bf16 v[64:67], v[172:175], v[206:209], v[64:67]
	s_barrier
; #define PG8_STAGE(bufoff, gbase, voff) do { _Pragma("unroll") for (int _i = 0; _i < 2; ++_i) \
;         __builtin_amdgcn_global_load_lds((const unsigned*)((const char*)(gbase) + (voff)[_i]), (LAS unsigned*)(lds + (bufoff) + ldsw + _i * 8192), 16, 0, 0); } while (0)
; #define PG8_LDA(dst, b, h) do { _Pragma("unroll") for (int m = 0; m < 4; ++m) _Pragma("unroll") for (int k = 0; k < 2; ++k) dst[m][k] = *(const LAS bf16x8*)(lds + PG8_SA(b, h) + aoff + m * 2048 + k * 1024); } while (0)
; #define PG8_MMA(ai, bj, At, Bt) do { __builtin_amdgcn_s_setprio(1); _Pragma("unroll") for (int m = 0; m < 4; ++m) _Pragma("unroll") for (int n = 0; n < 2; ++n) _Pragma("unroll") for (int k = 0; k < 2; ++k) \
;         acc[ai][bj][m][n] = __builtin_amdgcn_mfma_f32_16x16x32_bf16(Bt[n][k], At[m][k], acc[ai][bj][m][n], 0, 0, 0); __builtin_amdgcn_s_setprio(0); } while (0)
; #define PG8_WAIT_V(n) asm volatile("s_waitcnt vmcnt(" #n ")" ::: "memory")
; #define PG8_WAIT_L(n) asm volatile("s_waitcnt lgkmcnt(" #n ")" ::: "memory")
; #define PG8_BAR __builtin_amdgcn_s_barrier()
; #define PG8_SCHED __builtin_amdgcn_sched_barrier(0)
; template <class Epi>
; DI void gemm_phase(int wv, LAS unsigned char* lds, LAS unsigned char* scr, const Sched& S, const Epi& E) {
;     ...
;             PG8_LDA(At, 1, 1); PG8_STAGE(PG8_SB(1, 0), b3, voffB); PG8_STAGE(PG8_SB(1, 1), b3 + hstepB, voffB); PG8_STAGE(PG8_SA(1, 0), a3, voffA);
;             PG8_WAIT_V(8); PG8_WAIT_L(0); PG8_BAR; PG8_MMA(1, 0, At, B0); PG8_MMA(1, 1, At, B1); PG8_BAR; PG8_SCHED;
;         }
	s_add_i32 s28, s62, s33
	v_lshl_add_u64 v[210:211], v[210:211], 0, s[2:3]
	s_mov_b32 m0, s28
	ds_read_b128 v[176:179], v142 offset:49152
	ds_read_b128 v[180:183], v142 offset:50176
	ds_read_b128 v[184:187], v142 offset:51200
	ds_read_b128 v[188:191], v142 offset:52224
	ds_read_b128 v[194:197], v142 offset:53248
	ds_read_b128 v[198:201], v142 offset:54272
	ds_read_b128 v[202:205], v142 offset:55296
	ds_read_b128 v[206:209], v142 offset:56320
	global_load_lds_dwordx4 v[210:211], off
	s_add_i32 m0, s28, 0x2000
	s_add_u32 s26, s26, 0x100080
	v_lshl_add_u64 v[210:211], v[212:213], 0, s[2:3]
	s_addc_u32 s27, s27, 0
	s_add_i32 s28, s63, s33
	global_load_lds_dwordx4 v[210:211], off
	v_lshl_add_u64 v[210:211], s[26:27], 0, v[192:193]
	s_mov_b32 m0, s28
	s_nop 0
	global_load_lds_dwordx4 v[210:211], off
	v_lshl_add_u64 v[210:211], s[26:27], 0, v[132:133]
	s_add_i32 m0, s28, 0x2000
	s_nop 0
	global_load_lds_dwordx4 v[210:211], off
	v_lshl_add_u64 v[210:211], v[214:215], 0, s[2:3]
	s_mov_b32 m0, s43
	s_nop 0
	global_load_lds_dwordx4 v[210:211], off
	v_lshl_add_u64 v[210:211], v[216:217], 0, s[2:3]
	s_mov_b32 m0, s44
	s_nop 0
	global_load_lds_dwordx4 v[210:211], off
	s_waitcnt vmcnt(8)
	s_waitcnt lgkmcnt(0)
	s_barrier
	s_waitcnt lgkmcnt(0)
	v_mfma_f32_16x16x32_bf16 v[60:63], v[144:147], v[176:179], v[60:63]
	v_mfma_f32_16x16x32_bf16 v[56:59], v[152:155], v[176:179], v[56:59]
	v_mfma_f32_16x16x32_bf16 v[52:55], v[144:147], v[184:187], v[52:55]
	v_mfma_f32_16x16x32_bf16 v[48:51], v[152:155], v[184:187], v[48:51]
	v_mfma_f32_16x16x32_bf16 v[36:39], v[144:147], v[194:197], v[36:39]
	v_mfma_f32_16x16x32_bf16 v[32:35], v[152:155], v[194:197], v[32:35]
	v_mfma_f32_16x16x32_bf16 v[20:23], v[144:147], v[202:205], v[20:23]
	v_mfma_f32_16x16x32_bf16 v[16:19], v[152:155], v[202:205], v[16:19]
	v_mfma_f32_16x16x32_bf16 v[60:63], v[148:151], v[180:183], v[60:63]
	v_mfma_f32_16x16x32_bf16 v[56:59], v[156:159], v[180:183], v[56:59]
	v_mfma_f32_16x16x32_bf16 v[52:55], v[148:151], v[188:191], v[52:55]
	v_mfma_f32_16x16x32_bf16 v[48:51], v[156:159], v[188:191], v[48:51]
	v_mfma_f32_16x16x32_bf16 v[36:39], v[148:151], v[198:201], v[36:39]
	v_mfma_f32_16x16x32_bf16 v[32:35], v[156:159], v[198:201], v[32:35]
	v_mfma_f32_16x16x32_bf16 v[20:23], v[148:151], v[206:209], v[20:23]
	v_mfma_f32_16x16x32_bf16 v[16:19], v[156:159], v[206:209], v[16:19]
	v_mfma_f32_16x16x32_bf16 v[44:47], v[160:163], v[176:179], v[44:47]
	v_mfma_f32_16x16x32_bf16 v[40:43], v[168:171], v[176:179], v[40:43]
	v_mfma_f32_16x16x32_bf16 v[28:31], v[160:163], v[184:187], v[28:31]
	v_mfma_f32_16x16x32_bf16 v[24:27], v[168:171], v[184:187], v[24:27]
	v_mfma_f32_16x16x32_bf16 v[12:15], v[160:163], v[194:197], v[12:15]
	v_mfma_f32_16x16x32_bf16 v[8:11], v[168:171], v[194:197], v[8:11]
	v_mfma_f32_16x16x32_bf16 v[4:7], v[160:163], v[202:205], v[4:7]
	v_mfma_f32_16x16x32_bf16 v[0:3], v[168:171], v[202:205], v[0:3]
	v_mfma_f32_16x16x32_bf16 v[44:47], v[164:167], v[180:183], v[44:47]
	v_mfma_f32_16x16x32_bf16 v[40:43], v[172:175], v[180:183], v[40:43]
	v_mfma_f32_16x16x32_bf16 v[28:31], v[164:167], v[188:191], v[28:31]
	v_mfma_f32_16x16x32_bf16 v[24:27], v[172:175], v[188:191], v[24:27]
	v_mfma_f32_16x16x32_bf16 v[12:15], v[164:167], v[198:201], v[12:15]
	v_mfma_f32_16x16x32_bf16 v[8:11], v[172:175], v[198:201], v[8:11]
	v_mfma_f32_16x16x32_bf16 v[4:7], v[164:167], v[206:209], v[4:7]
	v_mfma_f32_16x16x32_bf16 v[0:3], v[172:175], v[206:209], v[0:3]
	s_barrier
	s_add_i32 s61, s61, 2
	s_add_u32 s55, s55, 0x100
	s_addc_u32 s60, s60, 0
	s_add_u32 s6, s6, 0x100
	s_addc_u32 s7, s7, 0
	s_cmp_gt_u32 s61, 13
	s_cbranch_scc0 .LBB0_163
	s_setprio 0
	s_and_b64 vcc, exec, s[18:19]
	s_cbranch_vccz .LBB0_166
	s_barrier

; #define PG8_STAGE(bufoff, gbase, voff) do { _Pragma("unroll") for (int _i = 0; _i < 2; ++_i) \
;         __builtin_amdgcn_global_load_lds((const unsigned*)((const char*)(gbase) + (voff)[_i]), (LAS unsigned*)(lds + (bufoff) + ldsw + _i * 8192), 16, 0, 0); } while (0)
; #define PG8_LDA(dst, b, h) do { _Pragma("unroll") for (int m = 0; m < 4; ++m) _Pragma("unroll") for (int k = 0; k < 2; ++k) dst[m][k] = *(const LAS bf16x8*)(lds + PG8_SA(b, h) + aoff + m * 2048 + k * 1024); } while (0)
; #define PG8_LDB(dst, b, h) do { _Pragma("unroll") for (int n = 0; n < 2; ++n) _Pragma("unroll") for (int k = 0; k < 2; ++k) dst[n][k] = *(const LAS bf16x8*)(lds + PG8_SB(b, h) + boff + n * 2048 + k * 1024); } while (0)
; #define PG8_SCHED __builtin_amdgcn_sched_barrier(0)
; template <class Epi>
; DI void gemm_phase(int wv, LAS unsigned char* lds, LAS unsigned char* scr, const Sched& S, const Epi& E) {
;     ...
;         const bool has_next = S.next(ui + 1, nxt);
;         const char* nA = has_next ? S.baseA(nxt) : cA; const char* nB = has_next ? S.baseB(nxt) : cB;
;         for (int t = 0; t < nt; t += 2) {
;             const bool last = (t == nt - 2);
;             const char* a1 = cA + (size_t)(t + 1) * kstep;
;             const char* a2 = last ? nA : cA + (size_t)(t + 2) * kstep; const char* b2 = last ? nB : cB + (size_t)(t + 2) * kstep;
;             const char* a3 = a2 + kstep; const char* b3 = b2 + kstep;
;             PG8_LDB(B0, 0, 0); PG8_LDB(B1, 0, 1); PG8_SCHED; PG8_LDA(At, 0, 0); PG8_STAGE(PG8_SA(1, 1), a1 + hstepA, voffA);
;     ...
; #pragma unroll
;         for (int a = 0; a < 2; ++a)
; #pragma unroll
;             for (int b = 0; b < 2; ++b)
; #pragma unroll
;                 for (int m = 0; m < 4; ++m)
; #pragma unroll
;                     for (int n = 0; n < 2; ++n) acc[a][b][m][n] = (f32x4){0.f, 0.f, 0.f, 0.f};
;         cur = nxt; cA = nA; cB = nB; ++ui;
.LBB0_188:
	s_ashr_i32 s21, s20, 31
	s_lshl_b64 s[24:25], s[20:21], 19
	s_add_u32 s24, s9, s24
	s_addc_u32 s25, s30, s25
	s_and_b64 s[6:7], s[6:7], exec
	s_cselect_b32 s21, s25, s27
	s_cselect_b32 s40, s24, s26
	s_add_u32 s51, s28, 0x100
	s_addc_u32 s54, s29, 0
	s_add_u32 s6, s26, 0x40080
	v_mov_b32_e32 v0, 0
	s_addc_u32 s7, s27, 0
	s_mov_b32 s55, -2
	v_mov_b32_e32 v1, v0
	v_mov_b32_e32 v2, v0
	v_mov_b32_e32 v3, v0
	v_mov_b32_e32 v4, v0
	v_mov_b32_e32 v5, v0
	v_mov_b32_e32 v6, v0
	v_mov_b32_e32 v7, v0
	v_mov_b32_e32 v8, v0
	v_mov_b32_e32 v9, v0
	v_mov_b32_e32 v10, v0
	v_mov_b32_e32 v11, v0
	v_mov_b32_e32 v12, v0
	v_mov_b32_e32 v13, v0
	v_mov_b32_e32 v14, v0
	v_mov_b32_e32 v15, v0
	v_mov_b32_e32 v24, v0
	v_mov_b32_e32 v25, v0
	v_mov_b32_e32 v26, v0
	v_mov_b32_e32 v27, v0
	v_mov_b32_e32 v28, v0
	v_mov_b32_e32 v29, v0
	v_mov_b32_e32 v30, v0
	v_mov_b32_e32 v31, v0
	v_mov_b32_e32 v40, v0
	v_mov_b32_e32 v41, v0
	v_mov_b32_e32 v42, v0
	v_mov_b32_e32 v43, v0
	s_waitcnt vmcnt(0)
	v_mov_b32_e32 v44, v0
	v_mov_b32_e32 v45, v0
	v_mov_b32_e32 v46, v0
	v_mov_b32_e32 v47, v0
	v_mov_b32_e32 v16, v0
	v_mov_b32_e32 v17, v0
	v_mov_b32_e32 v18, v0
	v_mov_b32_e32 v19, v0
	v_mov_b32_e32 v20, v0
	v_mov_b32_e32 v21, v0
	v_mov_b32_e32 v22, v0
	v_mov_b32_e32 v23, v0
	v_mov_b32_e32 v32, v0
	v_mov_b32_e32 v33, v0
	v_mov_b32_e32 v34, v0
	v_mov_b32_e32 v35, v0
	v_mov_b32_e32 v36, v0
	v_mov_b32_e32 v37, v0
	v_mov_b32_e32 v38, v0
	v_mov_b32_e32 v39, v0
	v_mov_b32_e32 v48, v0
	v_mov_b32_e32 v49, v0
	v_mov_b32_e32 v50, v0
	v_mov_b32_e32 v51, v0
	v_mov_b32_e32 v52, v0
	v_mov_b32_e32 v53, v0
	v_mov_b32_e32 v54, v0
	v_mov_b32_e32 v55, v0
	v_mov_b32_e32 v56, v0
	v_mov_b32_e32 v57, v0
	v_mov_b32_e32 v58, v0
	v_mov_b32_e32 v59, v0
	v_mov_b32_e32 v60, v0
	v_mov_b32_e32 v61, v0
	v_mov_b32_e32 v62, v0
	v_mov_b32_e32 v63, v0
	v_mov_b32_e32 v64, v0
	v_mov_b32_e32 v65, v0
	v_mov_b32_e32 v66, v0
	v_mov_b32_e32 v67, v0
	v_mov_b32_e32 v68, v0
	v_mov_b32_e32 v69, v0
	v_mov_b32_e32 v70, v0
	v_mov_b32_e32 v71, v0
	v_mov_b32_e32 v72, v0
	v_mov_b32_e32 v73, v0
	v_mov_b32_e32 v74, v0
	v_mov_b32_e32 v75, v0
	v_mov_b32_e32 v76, v0
	v_mov_b32_e32 v77, v0
	v_mov_b32_e32 v78, v0
	v_mov_b32_e32 v79, v0
	v_mov_b32_e32 v88, v0
	v_mov_b32_e32 v89, v0
	v_mov_b32_e32 v90, v0
	v_mov_b32_e32 v91, v0
	v_mov_b32_e32 v92, v0
	v_mov_b32_e32 v93, v0
	v_mov_b32_e32 v94, v0
	v_mov_b32_e32 v95, v0
	v_mov_b32_e32 v104, v0
	v_mov_b32_e32 v105, v0
	v_mov_b32_e32 v106, v0
	v_mov_b32_e32 v107, v0
	v_mov_b32_e32 v108, v0
	v_mov_b32_e32 v109, v0
	v_mov_b32_e32 v110, v0
	v_mov_b32_e32 v111, v0
	v_mov_b32_e32 v80, v0
	v_mov_b32_e32 v81, v0
	v_mov_b32_e32 v82, v0
	v_mov_b32_e32 v83, v0
	v_mov_b32_e32 v84, v0
	v_mov_b32_e32 v85, v0
	v_mov_b32_e32 v86, v0
	v_mov_b32_e32 v87, v0
	v_mov_b32_e32 v96, v0
	v_mov_b32_e32 v97, v0
	v_mov_b32_e32 v98, v0
	v_mov_b32_e32 v99, v0
	v_mov_b32_e32 v100, v0
	v_mov_b32_e32 v101, v0
	v_mov_b32_e32 v102, v0
	v_mov_b32_e32 v103, v0
	v_mov_b32_e32 v112, v0
	v_mov_b32_e32 v113, v0
	v_mov_b32_e32 v114, v0
	v_mov_b32_e32 v115, v0
	v_mov_b32_e32 v116, v0
	v_mov_b32_e32 v117, v0
	v_mov_b32_e32 v118, v0
	v_mov_b32_e32 v119, v0
	v_mov_b32_e32 v120, v0
	v_mov_b32_e32 v121, v0
	v_mov_b32_e32 v122, v0
	v_mov_b32_e32 v123, v0
	v_mov_b32_e32 v124, v0
	v_mov_b32_e32 v125, v0
	v_mov_b32_e32 v126, v0
	v_mov_b32_e32 v127, v0
	s_cmp_lg_u64 s[18:19], 0
	s_cbranch_scc1 .Lgp_7
	s_setprio 1
.Lgp_7:
.LBB0_189:
	s_add_u32 s26, s6, 0xfffc0080
	s_addc_u32 s27, s7, -1
	s_add_i32 s59, 0, 0x10000
	s_cmp_eq_u32 s55, 12
	s_cselect_b32 s29, s21, s27
	s_cselect_b32 s28, s40, s26
	v_add_u32_e32 v143, s59, v140
	s_cselect_b32 s27, s23, s54
	s_cselect_b32 s26, s22, s51
	s_add_i32 s62, 0, 0x14000
	ds_read_b128 v[144:147], v143
	ds_read_b128 v[148:151], v143 offset:1024
	ds_read_b128 v[152:155], v143 offset:2048
	ds_read_b128 v[156:159], v143 offset:3072
	v_add_u32_e32 v143, s62, v140
	ds_read_b128 v[160:163], v143
	ds_read_b128 v[164:167], v143 offset:1024
	ds_read_b128 v[168:171], v143 offset:2048
	ds_read_b128 v[172:175], v143 offset:3072
	v_lshl_add_u64 v[210:211], s[6:7], 0, v[138:139]
	s_add_i32 m0, s37, 0xc000
	ds_read_b128 v[176:179], v142
	ds_read_b128 v[180:183], v142 offset:1024
	ds_read_b128 v[184:187], v142 offset:2048
	ds_read_b128 v[188:191], v142 offset:3072
	ds_read_b128 v[194:197], v142 offset:4096
	ds_read_b128 v[198:201], v142 offset:5120
	ds_read_b128 v[202:205], v142 offset:6144
	ds_read_b128 v[206:209], v142 offset:7168
	global_load_lds_dwordx4 v[210:211], off
	v_lshl_add_u64 v[210:211], s[6:7], 0, v[136:137]
	s_add_i32 m0, s37, 0xe000
	s_nop 0
	global_load_lds_dwordx4 v[210:211], off
	s_waitcnt vmcnt(8)
	s_waitcnt lgkmcnt(0)
	s_barrier
; #define PG8_STAGE(bufoff, gbase, voff) do { _Pragma("unroll") for (int _i = 0; _i < 2; ++_i) \
;         __builtin_amdgcn_global_load_lds((const unsigned*)((const char*)(gbase) + (voff)[_i]), (LAS unsigned*)(lds + (bufoff) + ldsw + _i * 8192), 16, 0, 0); } while (0)
; #define PG8_LDA(dst, b, h) do { _Pragma("unroll") for (int m = 0; m < 4; ++m) _Pragma("unroll") for (int k = 0; k < 2; ++k) dst[m][k] = *(const LAS bf16x8*)(lds + PG8_SA(b, h) + aoff + m * 2048 + k * 1024); } while (0)
; #define PG8_MMA(ai, bj, At, Bt) do { __builtin_amdgcn_s_setprio(1); _Pragma("unroll") for (int m = 0; m < 4; ++m) _Pragma("unroll") for (int n = 0; n < 2; ++n) _Pragma("unroll") for (int k = 0; k < 2; ++k) \
;         acc[ai][bj][m][n] = __builtin_amdgcn_mfma_f32_16x16x32_bf16(Bt[n][k], At[m][k], acc[ai][bj][m][n], 0, 0, 0); __builtin_amdgcn_s_setprio(0); } while (0)
; #define PG8_WAIT_V(n) asm volatile("s_waitcnt vmcnt(" #n ")" ::: "memory")
; #define PG8_WAIT_L(n) asm volatile("s_waitcnt lgkmcnt(" #n ")" ::: "memory")
; #define PG8_BAR __builtin_amdgcn_s_barrier()
; #define PG8_SCHED __builtin_amdgcn_sched_barrier(0)
; template <class Epi>
; DI void gemm_phase(int wv, LAS unsigned char* lds, LAS unsigned char* scr, const Sched& S, const Epi& E) {
;     ...
;             PG8_WAIT_V(8); PG8_WAIT_L(0); PG8_BAR; PG8_MMA(0, 0, At, B0); PG8_MMA(0, 1, At, B1); PG8_BAR; PG8_SCHED;
;             PG8_LDA(At, 0, 1); PG8_STAGE(PG8_SB(0, 0), b2, voffB); PG8_STAGE(PG8_SB(0, 1), b2 + hstepB, voffB); PG8_STAGE(PG8_SA(0, 0), a2, voffA);
;             PG8_WAIT_V(8); PG8_WAIT_L(0); PG8_BAR; PG8_MMA(1, 0, At, B0); PG8_MMA(1, 1, At, B1); PG8_BAR; PG8_SCHED;
	s_waitcnt lgkmcnt(0)
	v_mfma_f32_16x16x32_bf16 v[124:127], v[144:147], v[176:179], v[124:127]
	v_mfma_f32_16x16x32_bf16 v[120:123], v[152:155], v[176:179], v[120:123]
	v_mfma_f32_16x16x32_bf16 v[116:119], v[144:147], v[184:187], v[116:119]
	v_mfma_f32_16x16x32_bf16 v[112:115], v[152:155], v[184:187], v[112:115]
	v_mfma_f32_16x16x32_bf16 v[100:103], v[144:147], v[194:197], v[100:103]
	v_mfma_f32_16x16x32_bf16 v[96:99], v[152:155], v[194:197], v[96:99]
	v_mfma_f32_16x16x32_bf16 v[84:87], v[144:147], v[202:205], v[84:87]
	v_mfma_f32_16x16x32_bf16 v[80:83], v[152:155], v[202:205], v[80:83]
	v_mfma_f32_16x16x32_bf16 v[124:127], v[148:151], v[180:183], v[124:127]
	v_mfma_f32_16x16x32_bf16 v[120:123], v[156:159], v[180:183], v[120:123]
	v_mfma_f32_16x16x32_bf16 v[116:119], v[148:151], v[188:191], v[116:119]
	v_mfma_f32_16x16x32_bf16 v[112:115], v[156:159], v[188:191], v[112:115]
	v_mfma_f32_16x16x32_bf16 v[100:103], v[148:151], v[198:201], v[100:103]
	v_mfma_f32_16x16x32_bf16 v[96:99], v[156:159], v[198:201], v[96:99]
	v_mfma_f32_16x16x32_bf16 v[84:87], v[148:151], v[206:209], v[84:87]
	v_mfma_f32_16x16x32_bf16 v[80:83], v[156:159], v[206:209], v[80:83]
	v_mfma_f32_16x16x32_bf16 v[108:111], v[160:163], v[176:179], v[108:111]
	v_mfma_f32_16x16x32_bf16 v[104:107], v[168:171], v[176:179], v[104:107]
	v_mfma_f32_16x16x32_bf16 v[92:95], v[160:163], v[184:187], v[92:95]
	v_mfma_f32_16x16x32_bf16 v[88:91], v[168:171], v[184:187], v[88:91]
	v_mfma_f32_16x16x32_bf16 v[76:79], v[160:163], v[194:197], v[76:79]
	v_mfma_f32_16x16x32_bf16 v[72:75], v[168:171], v[194:197], v[72:75]
	v_mfma_f32_16x16x32_bf16 v[68:71], v[160:163], v[202:205], v[68:71]
	v_mfma_f32_16x16x32_bf16 v[64:67], v[168:171], v[202:205], v[64:67]
	v_mfma_f32_16x16x32_bf16 v[108:111], v[164:167], v[180:183], v[108:111]
	v_mfma_f32_16x16x32_bf16 v[104:107], v[172:175], v[180:183], v[104:107]
	v_mfma_f32_16x16x32_bf16 v[92:95], v[164:167], v[188:191], v[92:95]
	v_mfma_f32_16x16x32_bf16 v[88:91], v[172:175], v[188:191], v[88:91]
	v_mfma_f32_16x16x32_bf16 v[76:79], v[164:167], v[198:201], v[76:79]
	v_mfma_f32_16x16x32_bf16 v[72:75], v[172:175], v[198:201], v[72:75]
	v_mfma_f32_16x16x32_bf16 v[68:71], v[164:167], v[206:209], v[68:71]
	v_mfma_f32_16x16x32_bf16 v[64:67], v[172:175], v[206:209], v[64:67]
	s_barrier
	s_add_i32 s59, s59, s33
	v_lshl_add_u64 v[210:211], s[26:27], 0, v[192:193]
	s_mov_b32 m0, s59
	ds_read_b128 v[176:179], v142 offset:16384
	ds_read_b128 v[180:183], v142 offset:17408
	ds_read_b128 v[184:187], v142 offset:18432
	ds_read_b128 v[188:191], v142 offset:19456
	ds_read_b128 v[194:197], v142 offset:20480
	ds_read_b128 v[198:201], v142 offset:21504
	ds_read_b128 v[202:205], v142 offset:22528
	ds_read_b128 v[206:209], v142 offset:23552
	global_load_lds_dwordx4 v[210:211], off
	s_add_i32 m0, s59, 0x2000
	s_add_u32 s60, s26, 0x400000
	v_lshl_add_u64 v[212:213], s[26:27], 0, v[132:133]
	s_addc_u32 s61, s27, 0
	s_add_i32 s59, s62, s33
	global_load_lds_dwordx4 v[212:213], off
	v_lshl_add_u64 v[214:215], s[60:61], 0, v[192:193]
	s_mov_b32 m0, s59
	v_lshl_add_u64 v[216:217], s[28:29], 0, v[130:131]
	global_load_lds_dwordx4 v[214:215], off
	v_lshl_add_u64 v[214:215], s[60:61], 0, v[132:133]
	s_add_i32 m0, s59, 0x2000
	s_nop 0
	global_load_lds_dwordx4 v[214:215], off
	v_lshl_add_u64 v[214:215], s[28:29], 0, v[128:129]
	s_mov_b32 m0, s37
	s_nop 0
	global_load_lds_dwordx4 v[214:215], off
	s_mov_b32 m0, s38
	s_nop 0
	global_load_lds_dwordx4 v[216:217], off
	s_waitcnt vmcnt(8)
	s_waitcnt lgkmcnt(0)
	s_barrier
	s_waitcnt lgkmcnt(0)
	v_mfma_f32_16x16x32_bf16 v[60:63], v[144:147], v[176:179], v[60:63]
	v_mfma_f32_16x16x32_bf16 v[56:59], v[152:155], v[176:179], v[56:59]
	v_mfma_f32_16x16x32_bf16 v[52:55], v[144:147], v[184:187], v[52:55]
	v_mfma_f32_16x16x32_bf16 v[48:51], v[152:155], v[184:187], v[48:51]
	v_mfma_f32_16x16x32_bf16 v[36:39], v[144:147], v[194:197], v[36:39]
	v_mfma_f32_16x16x32_bf16 v[32:35], v[152:155], v[194:197], v[32:35]
	v_mfma_f32_16x16x32_bf16 v[20:23], v[144:147], v[202:205], v[20:23]
	v_mfma_f32_16x16x32_bf16 v[16:19], v[152:155], v[202:205], v[16:19]
	v_mfma_f32_16x16x32_bf16 v[60:63], v[148:151], v[180:183], v[60:63]
	v_mfma_f32_16x16x32_bf16 v[56:59], v[156:159], v[180:183], v[56:59]
	v_mfma_f32_16x16x32_bf16 v[52:55], v[148:151], v[188:191], v[52:55]
	v_mfma_f32_16x16x32_bf16 v[48:51], v[156:159], v[188:191], v[48:51]
	v_mfma_f32_16x16x32_bf16 v[36:39], v[148:151], v[198:201], v[36:39]
	v_mfma_f32_16x16x32_bf16 v[32:35], v[156:159], v[198:201], v[32:35]
	v_mfma_f32_16x16x32_bf16 v[20:23], v[148:151], v[206:209], v[20:23]
	v_mfma_f32_16x16x32_bf16 v[16:19], v[156:159], v[206:209], v[16:19]
	v_mfma_f32_16x16x32_bf16 v[44:47], v[160:163], v[176:179], v[44:47]
	v_mfma_f32_16x16x32_bf16 v[40:43], v[168:171], v[176:179], v[40:43]
	v_mfma_f32_16x16x32_bf16 v[28:31], v[160:163], v[184:187], v[28:31]
	v_mfma_f32_16x16x32_bf16 v[24:27], v[168:171], v[184:187], v[24:27]
	v_mfma_f32_16x16x32_bf16 v[12:15], v[160:163], v[194:197], v[12:15]
	v_mfma_f32_16x16x32_bf16 v[8:11], v[168:171], v[194:197], v[8:11]
	v_mfma_f32_16x16x32_bf16 v[4:7], v[160:163], v[202:205], v[4:7]
	v_mfma_f32_16x16x32_bf16 v[0:3], v[168:171], v[202:205], v[0:3]
	v_mfma_f32_16x16x32_bf16 v[44:47], v[164:167], v[180:183], v[44:47]
	v_mfma_f32_16x16x32_bf16 v[40:43], v[172:175], v[180:183], v[40:43]
	v_mfma_f32_16x16x32_bf16 v[28:31], v[164:167], v[188:191], v[28:31]
	v_mfma_f32_16x16x32_bf16 v[24:27], v[172:175], v[188:191], v[24:27]
	v_mfma_f32_16x16x32_bf16 v[12:15], v[164:167], v[198:201], v[12:15]
	v_mfma_f32_16x16x32_bf16 v[8:11], v[172:175], v[198:201], v[8:11]
	v_mfma_f32_16x16x32_bf16 v[4:7], v[164:167], v[206:209], v[4:7]
	v_mfma_f32_16x16x32_bf16 v[0:3], v[172:175], v[206:209], v[0:3]
	s_barrier
; #define PG8_STAGE(bufoff, gbase, voff) do { _Pragma("unroll") for (int _i = 0; _i < 2; ++_i) \
;         __builtin_amdgcn_global_load_lds((const unsigned*)((const char*)(gbase) + (voff)[_i]), (LAS unsigned*)(lds + (bufoff) + ldsw + _i * 8192), 16, 0, 0); } while (0)
; #define PG8_LDA(dst, b, h) do { _Pragma("unroll") for (int m = 0; m < 4; ++m) _Pragma("unroll") for (int k = 0; k < 2; ++k) dst[m][k] = *(const LAS bf16x8*)(lds + PG8_SA(b, h) + aoff + m * 2048 + k * 1024); } while (0)
; #define PG8_LDB(dst, b, h) do { _Pragma("unroll") for (int n = 0; n < 2; ++n) _Pragma("unroll") for (int k = 0; k < 2; ++k) dst[n][k] = *(const LAS bf16x8*)(lds + PG8_SB(b, h) + boff + n * 2048 + k * 1024); } while (0)
; #define PG8_MMA(ai, bj, At, Bt) do { __builtin_amdgcn_s_setprio(1); _Pragma("unroll") for (int m = 0; m < 4; ++m) _Pragma("unroll") for (int n = 0; n < 2; ++n) _Pragma("unroll") for (int k = 0; k < 2; ++k) \
;         acc[ai][bj][m][n] = __builtin_amdgcn_mfma_f32_16x16x32_bf16(Bt[n][k], At[m][k], acc[ai][bj][m][n], 0, 0, 0); __builtin_amdgcn_s_setprio(0); } while (0)
; #define PG8_WAIT_V(n) asm volatile("s_waitcnt vmcnt(" #n ")" ::: "memory")
; #define PG8_WAIT_L(n) asm volatile("s_waitcnt lgkmcnt(" #n ")" ::: "memory")
; #define PG8_BAR __builtin_amdgcn_s_barrier()
; #define PG8_SCHED __builtin_amdgcn_sched_barrier(0)
; template <class Epi>
; DI void gemm_phase(int wv, LAS unsigned char* lds, LAS unsigned char* scr, const Sched& S, const Epi& E) {
;     ...
;             PG8_LDB(B0, 1, 0); PG8_LDB(B1, 1, 1); PG8_SCHED; PG8_LDA(At, 1, 0); PG8_STAGE(PG8_SA(0, 1), a2 + hstepA, voffA);
;             PG8_WAIT_V(8); PG8_WAIT_L(0); PG8_BAR; PG8_MMA(0, 0, At, B0); PG8_MMA(0, 1, At, B1); PG8_BAR; PG8_SCHED;
	s_add_i32 s59, 0, 0x18000
	v_add_u32_e32 v143, s59, v140
	s_add_i32 s60, 0, 0x1c000
	ds_read_b128 v[144:147], v143
	ds_read_b128 v[148:151], v143 offset:1024
	ds_read_b128 v[152:155], v143 offset:2048
	ds_read_b128 v[156:159], v143 offset:3072
	v_add_u32_e32 v143, s60, v140
	ds_read_b128 v[160:163], v143
	ds_read_b128 v[164:167], v143 offset:1024
	ds_read_b128 v[168:171], v143 offset:2048
	ds_read_b128 v[172:175], v143 offset:3072
	s_add_u32 s28, s28, 0x40000
	s_addc_u32 s29, s29, 0
	s_mov_b32 m0, s39
	v_lshl_add_u64 v[218:219], s[28:29], 0, v[128:129]
	ds_read_b128 v[176:179], v142 offset:32768
	ds_read_b128 v[180:183], v142 offset:33792
	ds_read_b128 v[184:187], v142 offset:34816
	ds_read_b128 v[188:191], v142 offset:35840
	ds_read_b128 v[194:197], v142 offset:36864
	ds_read_b128 v[198:201], v142 offset:37888
	ds_read_b128 v[202:205], v142 offset:38912
	ds_read_b128 v[206:209], v142 offset:39936
	global_load_lds_dwordx4 v[218:219], off
	v_lshl_add_u64 v[218:219], s[28:29], 0, v[130:131]
	s_mov_b32 m0, s42
	s_nop 0
	global_load_lds_dwordx4 v[218:219], off
	s_waitcnt vmcnt(8)
	s_waitcnt lgkmcnt(0)
	s_barrier
	s_waitcnt lgkmcnt(0)
	v_mfma_f32_16x16x32_bf16 v[124:127], v[144:147], v[176:179], v[124:127]
	v_mfma_f32_16x16x32_bf16 v[120:123], v[152:155], v[176:179], v[120:123]
	v_mfma_f32_16x16x32_bf16 v[116:119], v[144:147], v[184:187], v[116:119]
	v_mfma_f32_16x16x32_bf16 v[112:115], v[152:155], v[184:187], v[112:115]
	v_mfma_f32_16x16x32_bf16 v[100:103], v[144:147], v[194:197], v[100:103]
	v_mfma_f32_16x16x32_bf16 v[96:99], v[152:155], v[194:197], v[96:99]
	v_mfma_f32_16x16x32_bf16 v[84:87], v[144:147], v[202:205], v[84:87]
	v_mfma_f32_16x16x32_bf16 v[80:83], v[152:155], v[202:205], v[80:83]
	v_mfma_f32_16x16x32_bf16 v[124:127], v[148:151], v[180:183], v[124:127]
	v_mfma_f32_16x16x32_bf16 v[120:123], v[156:159], v[180:183], v[120:123]
	v_mfma_f32_16x16x32_bf16 v[116:119], v[148:151], v[188:191], v[116:119]
	v_mfma_f32_16x16x32_bf16 v[112:115], v[156:159], v[188:191], v[112:115]
	v_mfma_f32_16x16x32_bf16 v[100:103], v[148:151], v[198:201], v[100:103]
	v_mfma_f32_16x16x32_bf16 v[96:99], v[156:159], v[198:201], v[96:99]
	v_mfma_f32_16x16x32_bf16 v[84:87], v[148:151], v[206:209], v[84:87]
	v_mfma_f32_16x16x32_bf16 v[80:83], v[156:159], v[206:209], v[80:83]
	v_mfma_f32_16x16x32_bf16 v[108:111], v[160:163], v[176:179], v[108:111]
	v_mfma_f32_16x16x32_bf16 v[104:107], v[168:171], v[176:179], v[104:107]
	v_mfma_f32_16x16x32_bf16 v[92:95], v[160:163], v[184:187], v[92:95]
	v_mfma_f32_16x16x32_bf16 v[88:91], v[168:171], v[184:187], v[88:91]
	v_mfma_f32_16x16x32_bf16 v[76:79], v[160:163], v[194:197], v[76:79]
	v_mfma_f32_16x16x32_bf16 v[72:75], v[168:171], v[194:197], v[72:75]
	v_mfma_f32_16x16x32_bf16 v[68:71], v[160:163], v[202:205], v[68:71]
	v_mfma_f32_16x16x32_bf16 v[64:67], v[168:171], v[202:205], v[64:67]
	v_mfma_f32_16x16x32_bf16 v[108:111], v[164:167], v[180:183], v[108:111]
	v_mfma_f32_16x16x32_bf16 v[104:107], v[172:175], v[180:183], v[104:107]
	v_mfma_f32_16x16x32_bf16 v[92:95], v[164:167], v[188:191], v[92:95]
	v_mfma_f32_16x16x32_bf16 v[88:91], v[172:175], v[188:191], v[88:91]
	v_mfma_f32_16x16x32_bf16 v[76:79], v[164:167], v[198:201], v[76:79]
	v_mfma_f32_16x16x32_bf16 v[72:75], v[172:175], v[198:201], v[72:75]
	v_mfma_f32_16x16x32_bf16 v[68:71], v[164:167], v[206:209], v[68:71]
	v_mfma_f32_16x16x32_bf16 v[64:67], v[172:175], v[206:209], v[64:67]
	s_barrier
; #define PG8_STAGE(bufoff, gbase, voff) do { _Pragma("unroll") for (int _i = 0; _i < 2; ++_i) \
;         __builtin_amdgcn_global_load_lds((const unsigned*)((const char*)(gbase) + (voff)[_i]), (LAS unsigned*)(lds + (bufoff) + ldsw + _i * 8192), 16, 0, 0); } while (0)
; #define PG8_LDA(dst, b, h) do { _Pragma("unroll") for (int m = 0; m < 4; ++m) _Pragma("unroll") for (int k = 0; k < 2; ++k) dst[m][k] = *(const LAS bf16x8*)(lds + PG8_SA(b, h) + aoff + m * 2048 + k * 1024); } while (0)
; #define PG8_MMA(ai, bj, At, Bt) do { __builtin_amdgcn_s_setprio(1); _Pragma("unroll") for (int m = 0; m < 4; ++m) _Pragma("unroll") for (int n = 0; n < 2; ++n) _Pragma("unroll") for (int k = 0; k < 2; ++k) \
;         acc[ai][bj][m][n] = __builtin_amdgcn_mfma_f32_16x16x32_bf16(Bt[n][k], At[m][k], acc[ai][bj][m][n], 0, 0, 0); __builtin_amdgcn_s_setprio(0); } while (0)
; #define PG8_WAIT_V(n) asm volatile("s_waitcnt vmcnt(" #n ")" ::: "memory")
; #define PG8_WAIT_L(n) asm volatile("s_waitcnt lgkmcnt(" #n ")" ::: "memory")
; #define PG8_BAR __builtin_amdgcn_s_barrier()
; #define PG8_SCHED __builtin_amdgcn_sched_barrier(0)
; template <class Epi>
; DI void gemm_phase(int wv, LAS unsigned char* lds, LAS unsigned char* scr, const Sched& S, const Epi& E) {
;     ...
;             PG8_LDA(At, 1, 1); PG8_STAGE(PG8_SB(1, 0), b3, voffB); PG8_STAGE(PG8_SB(1, 1), b3 + hstepB, voffB); PG8_STAGE(PG8_SA(1, 0), a3, voffA);
;             PG8_WAIT_V(8); PG8_WAIT_L(0); PG8_BAR; PG8_MMA(1, 0, At, B0); PG8_MMA(1, 1, At, B1); PG8_BAR; PG8_SCHED;
;         }
	s_add_i32 s28, s59, s33
	v_lshl_add_u64 v[210:211], v[210:211], 0, s[2:3]
	s_mov_b32 m0, s28
	ds_read_b128 v[176:179], v142 offset:49152
	ds_read_b128 v[180:183], v142 offset:50176
	ds_read_b128 v[184:187], v142 offset:51200
	ds_read_b128 v[188:191], v142 offset:52224
	ds_read_b128 v[194:197], v142 offset:53248
	ds_read_b128 v[198:201], v142 offset:54272
	ds_read_b128 v[202:205], v142 offset:55296
	ds_read_b128 v[206:209], v142 offset:56320
	global_load_lds_dwordx4 v[210:211], off
	s_add_i32 m0, s28, 0x2000
	s_add_u32 s26, s26, 0x400080
	v_lshl_add_u64 v[210:211], v[212:213], 0, s[2:3]
	s_addc_u32 s27, s27, 0
	s_add_i32 s28, s60, s33
	global_load_lds_dwordx4 v[210:211], off
	v_lshl_add_u64 v[210:211], s[26:27], 0, v[192:193]
	s_mov_b32 m0, s28
	s_nop 0
	global_load_lds_dwordx4 v[210:211], off
	v_lshl_add_u64 v[210:211], s[26:27], 0, v[132:133]
	s_add_i32 m0, s28, 0x2000
	s_nop 0
	global_load_lds_dwordx4 v[210:211], off
	v_lshl_add_u64 v[210:211], v[214:215], 0, s[2:3]
	s_mov_b32 m0, s43
	s_nop 0
	global_load_lds_dwordx4 v[210:211], off
	v_lshl_add_u64 v[210:211], v[216:217], 0, s[2:3]
	s_mov_b32 m0, s44
	s_nop 0
	global_load_lds_dwordx4 v[210:211], off
	s_waitcnt vmcnt(8)
	s_waitcnt lgkmcnt(0)
	s_barrier
	s_waitcnt lgkmcnt(0)
	v_mfma_f32_16x16x32_bf16 v[60:63], v[144:147], v[176:179], v[60:63]
	v_mfma_f32_16x16x32_bf16 v[56:59], v[152:155], v[176:179], v[56:59]
	v_mfma_f32_16x16x32_bf16 v[52:55], v[144:147], v[184:187], v[52:55]
	v_mfma_f32_16x16x32_bf16 v[48:51], v[152:155], v[184:187], v[48:51]
	v_mfma_f32_16x16x32_bf16 v[36:39], v[144:147], v[194:197], v[36:39]
	v_mfma_f32_16x16x32_bf16 v[32:35], v[152:155], v[194:197], v[32:35]
	v_mfma_f32_16x16x32_bf16 v[20:23], v[144:147], v[202:205], v[20:23]
	v_mfma_f32_16x16x32_bf16 v[16:19], v[152:155], v[202:205], v[16:19]
	v_mfma_f32_16x16x32_bf16 v[60:63], v[148:151], v[180:183], v[60:63]
	v_mfma_f32_16x16x32_bf16 v[56:59], v[156:159], v[180:183], v[56:59]
	v_mfma_f32_16x16x32_bf16 v[52:55], v[148:151], v[188:191], v[52:55]
	v_mfma_f32_16x16x32_bf16 v[48:51], v[156:159], v[188:191], v[48:51]
	v_mfma_f32_16x16x32_bf16 v[36:39], v[148:151], v[198:201], v[36:39]
	v_mfma_f32_16x16x32_bf16 v[32:35], v[156:159], v[198:201], v[32:35]
	v_mfma_f32_16x16x32_bf16 v[20:23], v[148:151], v[206:209], v[20:23]
	v_mfma_f32_16x16x32_bf16 v[16:19], v[156:159], v[206:209], v[16:19]
	v_mfma_f32_16x16x32_bf16 v[44:47], v[160:163], v[176:179], v[44:47]
	v_mfma_f32_16x16x32_bf16 v[40:43], v[168:171], v[176:179], v[40:43]
	v_mfma_f32_16x16x32_bf16 v[28:31], v[160:163], v[184:187], v[28:31]
	v_mfma_f32_16x16x32_bf16 v[24:27], v[168:171], v[184:187], v[24:27]
	v_mfma_f32_16x16x32_bf16 v[12:15], v[160:163], v[194:197], v[12:15]
	v_mfma_f32_16x16x32_bf16 v[8:11], v[168:171], v[194:197], v[8:11]
	v_mfma_f32_16x16x32_bf16 v[4:7], v[160:163], v[202:205], v[4:7]
	v_mfma_f32_16x16x32_bf16 v[0:3], v[168:171], v[202:205], v[0:3]
	v_mfma_f32_16x16x32_bf16 v[44:47], v[164:167], v[180:183], v[44:47]
	v_mfma_f32_16x16x32_bf16 v[40:43], v[172:175], v[180:183], v[40:43]
	v_mfma_f32_16x16x32_bf16 v[28:31], v[164:167], v[188:191], v[28:31]
	v_mfma_f32_16x16x32_bf16 v[24:27], v[172:175], v[188:191], v[24:27]
	v_mfma_f32_16x16x32_bf16 v[12:15], v[164:167], v[198:201], v[12:15]
	v_mfma_f32_16x16x32_bf16 v[8:11], v[172:175], v[198:201], v[8:11]
	v_mfma_f32_16x16x32_bf16 v[4:7], v[164:167], v[206:209], v[4:7]
	v_mfma_f32_16x16x32_bf16 v[0:3], v[172:175], v[206:209], v[0:3]
	s_barrier
	s_add_i32 s55, s55, 2
	s_add_u32 s51, s51, 0x100
	s_addc_u32 s54, s54, 0
	s_add_u32 s6, s6, 0x100
	s_addc_u32 s7, s7, 0
	s_cmp_gt_u32 s55, 13
	s_cbranch_scc0 .LBB0_189
	s_setprio 0
	s_and_b64 vcc, exec, s[18:19]
	s_cbranch_vccz .LBB0_192
	s_barrier

; #define PG8_STAGE(bufoff, gbase, voff) do { _Pragma("unroll") for (int _i = 0; _i < 2; ++_i) \
;         __builtin_amdgcn_global_load_lds((const unsigned*)((const char*)(gbase) + (voff)[_i]), (LAS unsigned*)(lds + (bufoff) + ldsw + _i * 8192), 16, 0, 0); } while (0)
; #define PG8_LDA(dst, b, h) do { _Pragma("unroll") for (int m = 0; m < 4; ++m) _Pragma("unroll") for (int k = 0; k < 2; ++k) dst[m][k] = *(const LAS bf16x8*)(lds + PG8_SA(b, h) + aoff + m * 2048 + k * 1024); } while (0)
; #define PG8_LDB(dst, b, h) do { _Pragma("unroll") for (int n = 0; n < 2; ++n) _Pragma("unroll") for (int k = 0; k < 2; ++k) dst[n][k] = *(const LAS bf16x8*)(lds + PG8_SB(b, h) + boff + n * 2048 + k * 1024); } while (0)
; #define PG8_SCHED __builtin_amdgcn_sched_barrier(0)
; template <class Epi>
; DI void gemm_phase(int wv, LAS unsigned char* lds, LAS unsigned char* scr, const Sched& S, const Epi& E) {
;     ...
;         const bool has_next = S.next(ui + 1, nxt);
;         const char* nA = has_next ? S.baseA(nxt) : cA; const char* nB = has_next ? S.baseB(nxt) : cB;
;         for (int t = 0; t < nt; t += 2) {
;             const bool last = (t == nt - 2);
;             const char* a1 = cA + (size_t)(t + 1) * kstep;
;             const char* a2 = last ? nA : cA + (size_t)(t + 2) * kstep; const char* b2 = last ? nB : cB + (size_t)(t + 2) * kstep;
;             const char* a3 = a2 + kstep; const char* b3 = b2 + kstep;
;             PG8_LDB(B0, 0, 0); PG8_LDB(B1, 0, 1); PG8_SCHED; PG8_LDA(At, 0, 0); PG8_STAGE(PG8_SA(1, 1), a1 + hstepA, voffA);
;     ...
; #pragma unroll
;         for (int a = 0; a < 2; ++a)
; #pragma unroll
;             for (int b = 0; b < 2; ++b)
; #pragma unroll
;                 for (int m = 0; m < 4; ++m)
; #pragma unroll
;                     for (int n = 0; n < 2; ++n) acc[a][b][m][n] = (f32x4){0.f, 0.f, 0.f, 0.f};
;         cur = nxt; cA = nA; cB = nB; ++ui;
.LBB0_255:
	v_mov_b32_e32 v0, 0
	s_mov_b32 s13, 0
	s_mov_b64 s[24:25], -1
	s_mov_b64 s[26:27], 0
	v_mov_b32_e32 v1, v0
	v_mov_b32_e32 v2, v0
	v_mov_b32_e32 v3, v0
	v_mov_b32_e32 v4, v0
	v_mov_b32_e32 v5, v0
	v_mov_b32_e32 v6, v0
	v_mov_b32_e32 v7, v0
	v_mov_b32_e32 v8, v0
	v_mov_b32_e32 v9, v0
	v_mov_b32_e32 v10, v0
	v_mov_b32_e32 v11, v0
	v_mov_b32_e32 v16, v0
	v_mov_b32_e32 v17, v0
	v_mov_b32_e32 v18, v0
	v_mov_b32_e32 v19, v0
	v_mov_b32_e32 v24, v0
	v_mov_b32_e32 v25, v0
	v_mov_b32_e32 v26, v0
	v_mov_b32_e32 v27, v0
	v_mov_b32_e32 v32, v0
	v_mov_b32_e32 v33, v0
	v_mov_b32_e32 v34, v0
	v_mov_b32_e32 v35, v0
	v_mov_b32_e32 v40, v0
	v_mov_b32_e32 v41, v0
	v_mov_b32_e32 v42, v0
	v_mov_b32_e32 v43, v0
	v_mov_b32_e32 v48, v0
	v_mov_b32_e32 v49, v0
	v_mov_b32_e32 v50, v0
	v_mov_b32_e32 v51, v0
	v_mov_b32_e32 v12, v0
	v_mov_b32_e32 v13, v0
	v_mov_b32_e32 v14, v0
	v_mov_b32_e32 v15, v0
	v_mov_b32_e32 v20, v0
	v_mov_b32_e32 v21, v0
	v_mov_b32_e32 v22, v0
	v_mov_b32_e32 v23, v0
	v_mov_b32_e32 v28, v0
	v_mov_b32_e32 v29, v0
	v_mov_b32_e32 v30, v0
	v_mov_b32_e32 v31, v0
	v_mov_b32_e32 v36, v0
	v_mov_b32_e32 v37, v0
	v_mov_b32_e32 v38, v0
	v_mov_b32_e32 v39, v0
	v_mov_b32_e32 v44, v0
	v_mov_b32_e32 v45, v0
	v_mov_b32_e32 v46, v0
	v_mov_b32_e32 v47, v0
	v_mov_b32_e32 v52, v0
	v_mov_b32_e32 v53, v0
	v_mov_b32_e32 v54, v0
	v_mov_b32_e32 v55, v0
	v_mov_b32_e32 v56, v0
	v_mov_b32_e32 v57, v0
	v_mov_b32_e32 v58, v0
	v_mov_b32_e32 v59, v0
	v_mov_b32_e32 v60, v0
	v_mov_b32_e32 v61, v0
	v_mov_b32_e32 v62, v0
	v_mov_b32_e32 v63, v0
	v_mov_b32_e32 v64, v0
	v_mov_b32_e32 v65, v0
	v_mov_b32_e32 v66, v0
	v_mov_b32_e32 v67, v0
	v_mov_b32_e32 v68, v0
	v_mov_b32_e32 v69, v0
	v_mov_b32_e32 v70, v0
	v_mov_b32_e32 v71, v0
	v_mov_b32_e32 v72, v0
	v_mov_b32_e32 v73, v0
	v_mov_b32_e32 v74, v0
	v_mov_b32_e32 v75, v0
	v_mov_b32_e32 v80, v0
	v_mov_b32_e32 v81, v0
	v_mov_b32_e32 v82, v0
	v_mov_b32_e32 v83, v0
	v_mov_b32_e32 v88, v0
	v_mov_b32_e32 v89, v0
	v_mov_b32_e32 v90, v0
	v_mov_b32_e32 v91, v0
	v_mov_b32_e32 v96, v0
	v_mov_b32_e32 v97, v0
	v_mov_b32_e32 v98, v0
	v_mov_b32_e32 v99, v0
	v_mov_b32_e32 v104, v0
	v_mov_b32_e32 v105, v0
	v_mov_b32_e32 v106, v0
	v_mov_b32_e32 v107, v0
	v_mov_b32_e32 v112, v0
	v_mov_b32_e32 v113, v0
	v_mov_b32_e32 v114, v0
	v_mov_b32_e32 v115, v0
	v_mov_b32_e32 v76, v0
	v_mov_b32_e32 v77, v0
	v_mov_b32_e32 v78, v0
	v_mov_b32_e32 v79, v0
	v_mov_b32_e32 v84, v0
	v_mov_b32_e32 v85, v0
	v_mov_b32_e32 v86, v0
	v_mov_b32_e32 v87, v0
	v_mov_b32_e32 v92, v0
	v_mov_b32_e32 v93, v0
	v_mov_b32_e32 v94, v0
	v_mov_b32_e32 v95, v0
	v_mov_b32_e32 v100, v0
	v_mov_b32_e32 v101, v0
	v_mov_b32_e32 v102, v0
	v_mov_b32_e32 v103, v0
	v_mov_b32_e32 v108, v0
	v_mov_b32_e32 v109, v0
	v_mov_b32_e32 v110, v0
	v_mov_b32_e32 v111, v0
	v_mov_b32_e32 v116, v0
	v_mov_b32_e32 v117, v0
	v_mov_b32_e32 v118, v0
	v_mov_b32_e32 v119, v0
	v_mov_b32_e32 v120, v0
	v_mov_b32_e32 v121, v0
	v_mov_b32_e32 v122, v0
	v_mov_b32_e32 v123, v0
	v_mov_b32_e32 v124, v0
	v_mov_b32_e32 v125, v0
	v_mov_b32_e32 v126, v0
	v_mov_b32_e32 v127, v0
	s_cmp_lg_u64 s[10:11], 0
	s_cbranch_scc1 .Lgp_8
	s_setprio 1
.Lgp_8:
.LBB0_256:
	s_add_u32 s21, s16, s13
	s_addc_u32 s23, s17, 0
	s_add_u32 s30, s21, 0x100
	s_addc_u32 s31, s23, 0
	s_and_b64 s[28:29], s[26:27], exec
	s_cselect_b32 s31, s9, s31
	s_cselect_b32 s30, s8, s30
	s_add_u32 s13, s18, s13
	s_addc_u32 s28, s19, 0
	s_add_u32 s13, s13, 0x100
	s_addc_u32 s28, s28, 0
	s_add_i32 s64, 0, 0x10000
	s_and_b64 s[26:27], s[26:27], exec
	s_cselect_b32 s35, s15, s28
	s_cselect_b32 s34, s14, s13
	s_add_i32 s27, 0, 0x14000
	s_add_u32 s38, s21, 0x40080
	s_addc_u32 s39, s23, 0
	s_add_i32 s63, s64, s45
	s_add_i32 m0, s46, 0xc000
	s_add_i32 s66, s46, 0xe000
	s_add_i32 s60, s63, 0x2000
	v_add_u32_e32 v138, s64, v140
	s_add_u32 s36, s34, 0x40000
	ds_read_b128 v[142:145], v138
	ds_read_b128 v[146:149], v138 offset:1024
	ds_read_b128 v[150:153], v138 offset:2048
	ds_read_b128 v[154:157], v138 offset:3072
	v_add_u32_e32 v138, s27, v140
	s_addc_u32 s37, s35, 0
	s_add_i32 s62, s27, s45
	ds_read_b128 v[158:161], v138
	ds_read_b128 v[162:165], v138 offset:1024
	ds_read_b128 v[166:169], v138 offset:2048
	ds_read_b128 v[170:173], v138 offset:3072
	s_add_i32 s61, s62, 0x2000
	s_add_i32 s59, 0, 0x18000
	s_add_i32 s23, 0, 0x1c000
	s_add_u32 s28, s30, 0x40000
	s_addc_u32 s29, s31, 0
	s_add_i32 s21, s59, s45
	s_add_i32 s13, s21, 0x2000
	s_add_u32 s26, s34, 0x40080
	s_addc_u32 s27, s35, 0
	s_add_i32 s65, s23, s45
	s_add_i32 s64, s65, 0x2000
	v_lshl_add_u64 v[138:139], s[38:39], 0, v[134:135]
	ds_read_b128 v[174:177], v141
	ds_read_b128 v[178:181], v141 offset:1024
	ds_read_b128 v[182:185], v141 offset:2048
	ds_read_b128 v[186:189], v141 offset:3072
	ds_read_b128 v[194:197], v141 offset:4096
	ds_read_b128 v[198:201], v141 offset:5120
	ds_read_b128 v[202:205], v141 offset:6144
	ds_read_b128 v[206:209], v141 offset:7168
	global_load_lds_dwordx4 v[138:139], off
	v_lshl_add_u64 v[138:139], s[38:39], 0, v[130:131]
	s_mov_b32 m0, s66
	s_nop 0
	global_load_lds_dwordx4 v[138:139], off
	s_waitcnt vmcnt(8)
	s_waitcnt lgkmcnt(0)
	s_barrier
; #define PG8_STAGE(bufoff, gbase, voff) do { _Pragma("unroll") for (int _i = 0; _i < 2; ++_i) \
;         __builtin_amdgcn_global_load_lds((const unsigned*)((const char*)(gbase) + (voff)[_i]), (LAS unsigned*)(lds + (bufoff) + ldsw + _i * 8192), 16, 0, 0); } while (0)
; #define PG8_LDA(dst, b, h) do { _Pragma("unroll") for (int m = 0; m < 4; ++m) _Pragma("unroll") for (int k = 0; k < 2; ++k) dst[m][k] = *(const LAS bf16x8*)(lds + PG8_SA(b, h) + aoff + m * 2048 + k * 1024); } while (0)
; #define PG8_MMA(ai, bj, At, Bt) do { __builtin_amdgcn_s_setprio(1); _Pragma("unroll") for (int m = 0; m < 4; ++m) _Pragma("unroll") for (int n = 0; n < 2; ++n) _Pragma("unroll") for (int k = 0; k < 2; ++k) \
;         acc[ai][bj][m][n] = __builtin_amdgcn_mfma_f32_16x16x32_bf16(Bt[n][k], At[m][k], acc[ai][bj][m][n], 0, 0, 0); __builtin_amdgcn_s_setprio(0); } while (0)
; #define PG8_WAIT_V(n) asm volatile("s_waitcnt vmcnt(" #n ")" ::: "memory")
; #define PG8_WAIT_L(n) asm volatile("s_waitcnt lgkmcnt(" #n ")" ::: "memory")
; #define PG8_BAR __builtin_amdgcn_s_barrier()
; #define PG8_SCHED __builtin_amdgcn_sched_barrier(0)
; template <class Epi>
; DI void gemm_phase(int wv, LAS unsigned char* lds, LAS unsigned char* scr, const Sched& S, const Epi& E) {
;     ...
;             PG8_WAIT_V(8); PG8_WAIT_L(0); PG8_BAR; PG8_MMA(0, 0, At, B0); PG8_MMA(0, 1, At, B1); PG8_BAR; PG8_SCHED;
;             PG8_LDA(At, 0, 1); PG8_STAGE(PG8_SB(0, 0), b2, voffB); PG8_STAGE(PG8_SB(0, 1), b2 + hstepB, voffB); PG8_STAGE(PG8_SA(0, 0), a2, voffA);
;             PG8_WAIT_V(8); PG8_WAIT_L(0); PG8_BAR; PG8_MMA(1, 0, At, B0); PG8_MMA(1, 1, At, B1); PG8_BAR; PG8_SCHED;
	s_waitcnt lgkmcnt(0)
	v_mfma_f32_16x16x32_bf16 v[124:127], v[142:145], v[174:177], v[124:127]
	v_mfma_f32_16x16x32_bf16 v[120:123], v[150:153], v[174:177], v[120:123]
	v_mfma_f32_16x16x32_bf16 v[116:119], v[142:145], v[182:185], v[116:119]
	v_mfma_f32_16x16x32_bf16 v[108:111], v[150:153], v[182:185], v[108:111]
	v_mfma_f32_16x16x32_bf16 v[100:103], v[142:145], v[194:197], v[100:103]
	v_mfma_f32_16x16x32_bf16 v[92:95], v[150:153], v[194:197], v[92:95]
	v_mfma_f32_16x16x32_bf16 v[84:87], v[142:145], v[202:205], v[84:87]
	v_mfma_f32_16x16x32_bf16 v[76:79], v[150:153], v[202:205], v[76:79]
	v_mfma_f32_16x16x32_bf16 v[124:127], v[146:149], v[178:181], v[124:127]
	v_mfma_f32_16x16x32_bf16 v[120:123], v[154:157], v[178:181], v[120:123]
	v_mfma_f32_16x16x32_bf16 v[116:119], v[146:149], v[186:189], v[116:119]
	v_mfma_f32_16x16x32_bf16 v[108:111], v[154:157], v[186:189], v[108:111]
	v_mfma_f32_16x16x32_bf16 v[100:103], v[146:149], v[198:201], v[100:103]
	v_mfma_f32_16x16x32_bf16 v[92:95], v[154:157], v[198:201], v[92:95]
	v_mfma_f32_16x16x32_bf16 v[84:87], v[146:149], v[206:209], v[84:87]
	v_mfma_f32_16x16x32_bf16 v[76:79], v[154:157], v[206:209], v[76:79]
	v_mfma_f32_16x16x32_bf16 v[112:115], v[158:161], v[174:177], v[112:115]
	v_mfma_f32_16x16x32_bf16 v[104:107], v[166:169], v[174:177], v[104:107]
	v_mfma_f32_16x16x32_bf16 v[96:99], v[158:161], v[182:185], v[96:99]
	v_mfma_f32_16x16x32_bf16 v[88:91], v[166:169], v[182:185], v[88:91]
	v_mfma_f32_16x16x32_bf16 v[80:83], v[158:161], v[194:197], v[80:83]
	v_mfma_f32_16x16x32_bf16 v[72:75], v[166:169], v[194:197], v[72:75]
	v_mfma_f32_16x16x32_bf16 v[68:71], v[158:161], v[202:205], v[68:71]
	v_mfma_f32_16x16x32_bf16 v[64:67], v[166:169], v[202:205], v[64:67]
	v_mfma_f32_16x16x32_bf16 v[112:115], v[162:165], v[178:181], v[112:115]
	v_mfma_f32_16x16x32_bf16 v[104:107], v[170:173], v[178:181], v[104:107]
	v_mfma_f32_16x16x32_bf16 v[96:99], v[162:165], v[186:189], v[96:99]
	v_mfma_f32_16x16x32_bf16 v[88:91], v[170:173], v[186:189], v[88:91]
	v_mfma_f32_16x16x32_bf16 v[80:83], v[162:165], v[198:201], v[80:83]
	v_mfma_f32_16x16x32_bf16 v[72:75], v[170:173], v[198:201], v[72:75]
	v_mfma_f32_16x16x32_bf16 v[68:71], v[162:165], v[206:209], v[68:71]
	v_mfma_f32_16x16x32_bf16 v[64:67], v[170:173], v[206:209], v[64:67]
	s_barrier
	s_mov_b32 m0, s63
	v_lshl_add_u64 v[138:139], s[34:35], 0, v[132:133]
	ds_read_b128 v[174:177], v141 offset:16384
	ds_read_b128 v[178:181], v141 offset:17408
	ds_read_b128 v[182:185], v141 offset:18432
	ds_read_b128 v[186:189], v141 offset:19456
	ds_read_b128 v[194:197], v141 offset:20480
	ds_read_b128 v[198:201], v141 offset:21504
	ds_read_b128 v[202:205], v141 offset:22528
	ds_read_b128 v[206:209], v141 offset:23552
	global_load_lds_dwordx4 v[138:139], off
	v_lshl_add_u64 v[190:191], s[34:35], 0, v[128:129]
	s_mov_b32 m0, s60
	v_lshl_add_u64 v[210:211], s[36:37], 0, v[132:133]
	global_load_lds_dwordx4 v[190:191], off
	s_mov_b32 m0, s62
	v_lshl_add_u64 v[212:213], s[30:31], 0, v[130:131]
	global_load_lds_dwordx4 v[210:211], off
	v_lshl_add_u64 v[210:211], s[36:37], 0, v[128:129]
	s_mov_b32 m0, s61
	s_nop 0
	global_load_lds_dwordx4 v[210:211], off
	v_lshl_add_u64 v[210:211], s[30:31], 0, v[134:135]
	s_mov_b32 m0, s46
	s_nop 0
	global_load_lds_dwordx4 v[210:211], off
	s_mov_b32 m0, s47
	s_nop 0
	global_load_lds_dwordx4 v[212:213], off
	s_waitcnt vmcnt(8)
	s_waitcnt lgkmcnt(0)
	s_barrier
	s_waitcnt lgkmcnt(0)
	v_mfma_f32_16x16x32_bf16 v[60:63], v[142:145], v[174:177], v[60:63]
	v_mfma_f32_16x16x32_bf16 v[56:59], v[150:153], v[174:177], v[56:59]
	v_mfma_f32_16x16x32_bf16 v[52:55], v[142:145], v[182:185], v[52:55]
	v_mfma_f32_16x16x32_bf16 v[44:47], v[150:153], v[182:185], v[44:47]
	v_mfma_f32_16x16x32_bf16 v[36:39], v[142:145], v[194:197], v[36:39]
	v_mfma_f32_16x16x32_bf16 v[28:31], v[150:153], v[194:197], v[28:31]
	v_mfma_f32_16x16x32_bf16 v[20:23], v[142:145], v[202:205], v[20:23]
	v_mfma_f32_16x16x32_bf16 v[12:15], v[150:153], v[202:205], v[12:15]
	v_mfma_f32_16x16x32_bf16 v[60:63], v[146:149], v[178:181], v[60:63]
	v_mfma_f32_16x16x32_bf16 v[56:59], v[154:157], v[178:181], v[56:59]
	v_mfma_f32_16x16x32_bf16 v[52:55], v[146:149], v[186:189], v[52:55]
	v_mfma_f32_16x16x32_bf16 v[44:47], v[154:157], v[186:189], v[44:47]
	v_mfma_f32_16x16x32_bf16 v[36:39], v[146:149], v[198:201], v[36:39]
	v_mfma_f32_16x16x32_bf16 v[28:31], v[154:157], v[198:201], v[28:31]
	v_mfma_f32_16x16x32_bf16 v[20:23], v[146:149], v[206:209], v[20:23]
	v_mfma_f32_16x16x32_bf16 v[12:15], v[154:157], v[206:209], v[12:15]
	v_mfma_f32_16x16x32_bf16 v[48:51], v[158:161], v[174:177], v[48:51]
	v_mfma_f32_16x16x32_bf16 v[40:43], v[166:169], v[174:177], v[40:43]
	v_mfma_f32_16x16x32_bf16 v[32:35], v[158:161], v[182:185], v[32:35]
	v_mfma_f32_16x16x32_bf16 v[24:27], v[166:169], v[182:185], v[24:27]
	v_mfma_f32_16x16x32_bf16 v[16:19], v[158:161], v[194:197], v[16:19]
	v_mfma_f32_16x16x32_bf16 v[8:11], v[166:169], v[194:197], v[8:11]
	v_mfma_f32_16x16x32_bf16 v[4:7], v[158:161], v[202:205], v[4:7]
	v_mfma_f32_16x16x32_bf16 v[0:3], v[166:169], v[202:205], v[0:3]
	v_mfma_f32_16x16x32_bf16 v[48:51], v[162:165], v[178:181], v[48:51]
	v_mfma_f32_16x16x32_bf16 v[40:43], v[170:173], v[178:181], v[40:43]
	v_mfma_f32_16x16x32_bf16 v[32:35], v[162:165], v[186:189], v[32:35]
	v_mfma_f32_16x16x32_bf16 v[24:27], v[170:173], v[186:189], v[24:27]
	v_mfma_f32_16x16x32_bf16 v[16:19], v[162:165], v[198:201], v[16:19]
	v_mfma_f32_16x16x32_bf16 v[8:11], v[170:173], v[198:201], v[8:11]
	v_mfma_f32_16x16x32_bf16 v[4:7], v[162:165], v[206:209], v[4:7]
	v_mfma_f32_16x16x32_bf16 v[0:3], v[170:173], v[206:209], v[0:3]
	s_barrier
; #define PG8_STAGE(bufoff, gbase, voff) do { _Pragma("unroll") for (int _i = 0; _i < 2; ++_i) \
;         __builtin_amdgcn_global_load_lds((const unsigned*)((const char*)(gbase) + (voff)[_i]), (LAS unsigned*)(lds + (bufoff) + ldsw + _i * 8192), 16, 0, 0); } while (0)
; #define PG8_LDA(dst, b, h) do { _Pragma("unroll") for (int m = 0; m < 4; ++m) _Pragma("unroll") for (int k = 0; k < 2; ++k) dst[m][k] = *(const LAS bf16x8*)(lds + PG8_SA(b, h) + aoff + m * 2048 + k * 1024); } while (0)
; #define PG8_LDB(dst, b, h) do { _Pragma("unroll") for (int n = 0; n < 2; ++n) _Pragma("unroll") for (int k = 0; k < 2; ++k) dst[n][k] = *(const LAS bf16x8*)(lds + PG8_SB(b, h) + boff + n * 2048 + k * 1024); } while (0)
; #define PG8_MMA(ai, bj, At, Bt) do { __builtin_amdgcn_s_setprio(1); _Pragma("unroll") for (int m = 0; m < 4; ++m) _Pragma("unroll") for (int n = 0; n < 2; ++n) _Pragma("unroll") for (int k = 0; k < 2; ++k) \
;         acc[ai][bj][m][n] = __builtin_amdgcn_mfma_f32_16x16x32_bf16(Bt[n][k], At[m][k], acc[ai][bj][m][n], 0, 0, 0); __builtin_amdgcn_s_setprio(0); } while (0)
; #define PG8_WAIT_V(n) asm volatile("s_waitcnt vmcnt(" #n ")" ::: "memory")
; #define PG8_WAIT_L(n) asm volatile("s_waitcnt lgkmcnt(" #n ")" ::: "memory")
; #define PG8_BAR __builtin_amdgcn_s_barrier()
; #define PG8_SCHED __builtin_amdgcn_sched_barrier(0)
; template <class Epi>
; DI void gemm_phase(int wv, LAS unsigned char* lds, LAS unsigned char* scr, const Sched& S, const Epi& E) {
;     ...
;             PG8_LDB(B0, 1, 0); PG8_LDB(B1, 1, 1); PG8_SCHED; PG8_LDA(At, 1, 0); PG8_STAGE(PG8_SA(0, 1), a2 + hstepA, voffA);
;             PG8_WAIT_V(8); PG8_WAIT_L(0); PG8_BAR; PG8_MMA(0, 0, At, B0); PG8_MMA(0, 1, At, B1); PG8_BAR; PG8_SCHED;
;             PG8_LDA(At, 1, 1); PG8_STAGE(PG8_SB(1, 0), b3, voffB); PG8_STAGE(PG8_SB(1, 1), b3 + hstepB, voffB); PG8_STAGE(PG8_SA(1, 0), a3, voffA);
;             PG8_WAIT_V(8); PG8_WAIT_L(0); PG8_BAR; PG8_MMA(1, 0, At, B0); PG8_MMA(1, 1, At, B1); PG8_BAR; PG8_SCHED;
;         }
	v_add_u32_e32 v154, s59, v140
	v_add_u32_e32 v170, s23, v140
	ds_read_b128 v[142:145], v154
	ds_read_b128 v[146:149], v154 offset:1024
	ds_read_b128 v[150:153], v154 offset:2048
	ds_read_b128 v[154:157], v154 offset:3072
	ds_read_b128 v[158:161], v170
	ds_read_b128 v[162:165], v170 offset:1024
	ds_read_b128 v[166:169], v170 offset:2048
	ds_read_b128 v[170:173], v170 offset:3072
	s_mov_b32 m0, s48
	v_lshl_add_u64 v[214:215], s[28:29], 0, v[134:135]
	ds_read_b128 v[174:177], v141 offset:32768
	ds_read_b128 v[178:181], v141 offset:33792
	ds_read_b128 v[182:185], v141 offset:34816
	ds_read_b128 v[186:189], v141 offset:35840
	ds_read_b128 v[194:197], v141 offset:36864
	ds_read_b128 v[198:201], v141 offset:37888
	ds_read_b128 v[202:205], v141 offset:38912
	ds_read_b128 v[206:209], v141 offset:39936
	global_load_lds_dwordx4 v[214:215], off
	v_lshl_add_u64 v[214:215], s[28:29], 0, v[130:131]
	s_mov_b32 m0, s49
	s_nop 0
	global_load_lds_dwordx4 v[214:215], off
	s_waitcnt vmcnt(8)
	s_waitcnt lgkmcnt(0)
	s_barrier
	s_waitcnt lgkmcnt(0)
	v_mfma_f32_16x16x32_bf16 v[124:127], v[142:145], v[174:177], v[124:127]
	v_mfma_f32_16x16x32_bf16 v[120:123], v[150:153], v[174:177], v[120:123]
	v_mfma_f32_16x16x32_bf16 v[116:119], v[142:145], v[182:185], v[116:119]
	v_mfma_f32_16x16x32_bf16 v[108:111], v[150:153], v[182:185], v[108:111]
	v_mfma_f32_16x16x32_bf16 v[100:103], v[142:145], v[194:197], v[100:103]
	v_mfma_f32_16x16x32_bf16 v[92:95], v[150:153], v[194:197], v[92:95]
	v_mfma_f32_16x16x32_bf16 v[84:87], v[142:145], v[202:205], v[84:87]
	v_mfma_f32_16x16x32_bf16 v[76:79], v[150:153], v[202:205], v[76:79]
	v_mfma_f32_16x16x32_bf16 v[124:127], v[146:149], v[178:181], v[124:127]
	v_mfma_f32_16x16x32_bf16 v[120:123], v[154:157], v[178:181], v[120:123]
	v_mfma_f32_16x16x32_bf16 v[116:119], v[146:149], v[186:189], v[116:119]
	v_mfma_f32_16x16x32_bf16 v[108:111], v[154:157], v[186:189], v[108:111]
	v_mfma_f32_16x16x32_bf16 v[100:103], v[146:149], v[198:201], v[100:103]
	v_mfma_f32_16x16x32_bf16 v[92:95], v[154:157], v[198:201], v[92:95]
	v_mfma_f32_16x16x32_bf16 v[84:87], v[146:149], v[206:209], v[84:87]
	v_mfma_f32_16x16x32_bf16 v[76:79], v[154:157], v[206:209], v[76:79]
	v_mfma_f32_16x16x32_bf16 v[112:115], v[158:161], v[174:177], v[112:115]
	v_mfma_f32_16x16x32_bf16 v[104:107], v[166:169], v[174:177], v[104:107]
	v_mfma_f32_16x16x32_bf16 v[96:99], v[158:161], v[182:185], v[96:99]
	v_mfma_f32_16x16x32_bf16 v[88:91], v[166:169], v[182:185], v[88:91]
	v_mfma_f32_16x16x32_bf16 v[80:83], v[158:161], v[194:197], v[80:83]
	v_mfma_f32_16x16x32_bf16 v[72:75], v[166:169], v[194:197], v[72:75]
	v_mfma_f32_16x16x32_bf16 v[68:71], v[158:161], v[202:205], v[68:71]
	v_mfma_f32_16x16x32_bf16 v[64:67], v[166:169], v[202:205], v[64:67]
	v_mfma_f32_16x16x32_bf16 v[112:115], v[162:165], v[178:181], v[112:115]
	v_mfma_f32_16x16x32_bf16 v[104:107], v[170:173], v[178:181], v[104:107]
	v_mfma_f32_16x16x32_bf16 v[96:99], v[162:165], v[186:189], v[96:99]
	v_mfma_f32_16x16x32_bf16 v[88:91], v[170:173], v[186:189], v[88:91]
	v_mfma_f32_16x16x32_bf16 v[80:83], v[162:165], v[198:201], v[80:83]
	v_mfma_f32_16x16x32_bf16 v[72:75], v[170:173], v[198:201], v[72:75]
	v_mfma_f32_16x16x32_bf16 v[68:71], v[162:165], v[206:209], v[68:71]
	v_mfma_f32_16x16x32_bf16 v[64:67], v[170:173], v[206:209], v[64:67]
	s_barrier
	s_mov_b32 m0, s21
	v_lshl_add_u64 v[138:139], v[138:139], 0, s[2:3]
	ds_read_b128 v[174:177], v141 offset:49152
	ds_read_b128 v[178:181], v141 offset:50176
	ds_read_b128 v[182:185], v141 offset:51200
	ds_read_b128 v[186:189], v141 offset:52224
	ds_read_b128 v[194:197], v141 offset:53248
	ds_read_b128 v[198:201], v141 offset:54272
	ds_read_b128 v[202:205], v141 offset:55296
	ds_read_b128 v[206:209], v141 offset:56320
	global_load_lds_dwordx4 v[138:139], off
	v_lshl_add_u64 v[138:139], v[190:191], 0, s[2:3]
	s_mov_b32 m0, s13
	s_nop 0
	global_load_lds_dwordx4 v[138:139], off
	v_lshl_add_u64 v[138:139], s[26:27], 0, v[132:133]
	s_mov_b32 m0, s65
	s_nop 0
	global_load_lds_dwordx4 v[138:139], off
	v_lshl_add_u64 v[138:139], s[26:27], 0, v[128:129]
	s_mov_b32 m0, s64
	s_nop 0
	global_load_lds_dwordx4 v[138:139], off
	v_lshl_add_u64 v[138:139], v[210:211], 0, s[2:3]
	s_mov_b32 m0, s52
	s_nop 0
	global_load_lds_dwordx4 v[138:139], off
	v_lshl_add_u64 v[138:139], v[212:213], 0, s[2:3]
	s_mov_b32 m0, s53
	s_nop 0
	global_load_lds_dwordx4 v[138:139], off
	s_waitcnt vmcnt(8)
	s_waitcnt lgkmcnt(0)
	s_barrier
	s_waitcnt lgkmcnt(0)
	v_mfma_f32_16x16x32_bf16 v[60:63], v[142:145], v[174:177], v[60:63]
	v_mfma_f32_16x16x32_bf16 v[56:59], v[150:153], v[174:177], v[56:59]
	v_mfma_f32_16x16x32_bf16 v[52:55], v[142:145], v[182:185], v[52:55]
	v_mfma_f32_16x16x32_bf16 v[44:47], v[150:153], v[182:185], v[44:47]
	v_mfma_f32_16x16x32_bf16 v[36:39], v[142:145], v[194:197], v[36:39]
	v_mfma_f32_16x16x32_bf16 v[28:31], v[150:153], v[194:197], v[28:31]
	v_mfma_f32_16x16x32_bf16 v[20:23], v[142:145], v[202:205], v[20:23]
	v_mfma_f32_16x16x32_bf16 v[12:15], v[150:153], v[202:205], v[12:15]
	v_mfma_f32_16x16x32_bf16 v[60:63], v[146:149], v[178:181], v[60:63]
	v_mfma_f32_16x16x32_bf16 v[56:59], v[154:157], v[178:181], v[56:59]
	v_mfma_f32_16x16x32_bf16 v[52:55], v[146:149], v[186:189], v[52:55]
	v_mfma_f32_16x16x32_bf16 v[44:47], v[154:157], v[186:189], v[44:47]
	v_mfma_f32_16x16x32_bf16 v[36:39], v[146:149], v[198:201], v[36:39]
	v_mfma_f32_16x16x32_bf16 v[28:31], v[154:157], v[198:201], v[28:31]
	v_mfma_f32_16x16x32_bf16 v[20:23], v[146:149], v[206:209], v[20:23]
	v_mfma_f32_16x16x32_bf16 v[12:15], v[154:157], v[206:209], v[12:15]
	v_mfma_f32_16x16x32_bf16 v[48:51], v[158:161], v[174:177], v[48:51]
	v_mfma_f32_16x16x32_bf16 v[40:43], v[166:169], v[174:177], v[40:43]
	v_mfma_f32_16x16x32_bf16 v[32:35], v[158:161], v[182:185], v[32:35]
	v_mfma_f32_16x16x32_bf16 v[24:27], v[166:169], v[182:185], v[24:27]
	v_mfma_f32_16x16x32_bf16 v[16:19], v[158:161], v[194:197], v[16:19]
	v_mfma_f32_16x16x32_bf16 v[8:11], v[166:169], v[194:197], v[8:11]
	v_mfma_f32_16x16x32_bf16 v[4:7], v[158:161], v[202:205], v[4:7]
	v_mfma_f32_16x16x32_bf16 v[0:3], v[166:169], v[202:205], v[0:3]
	v_mfma_f32_16x16x32_bf16 v[48:51], v[162:165], v[178:181], v[48:51]
	v_mfma_f32_16x16x32_bf16 v[40:43], v[170:173], v[178:181], v[40:43]
	v_mfma_f32_16x16x32_bf16 v[32:35], v[162:165], v[186:189], v[32:35]
	v_mfma_f32_16x16x32_bf16 v[24:27], v[170:173], v[186:189], v[24:27]
	v_mfma_f32_16x16x32_bf16 v[16:19], v[162:165], v[198:201], v[16:19]
	v_mfma_f32_16x16x32_bf16 v[8:11], v[170:173], v[198:201], v[8:11]
	v_mfma_f32_16x16x32_bf16 v[4:7], v[162:165], v[206:209], v[4:7]
	v_mfma_f32_16x16x32_bf16 v[0:3], v[170:173], v[206:209], v[0:3]
	s_barrier
	s_movk_i32 s13, 0x100
	s_andn2_b64 vcc, exec, s[24:25]
	s_mov_b64 s[26:27], -1
	s_mov_b64 s[24:25], 0
	s_cbranch_vccz .LBB0_256
	s_setprio 0
	s_and_b64 vcc, exec, s[10:11]
	s_cbranch_vccz .LBB0_259
	s_barrier

; #define PG8_STAGE(bufoff, gbase, voff) do { _Pragma("unroll") for (int _i = 0; _i < 2; ++_i) \
;         __builtin_amdgcn_global_load_lds((const unsigned*)((const char*)(gbase) + (voff)[_i]), (LAS unsigned*)(lds + (bufoff) + ldsw + _i * 8192), 16, 0, 0); } while (0)
; #define PG8_LDA(dst, b, h) do { _Pragma("unroll") for (int m = 0; m < 4; ++m) _Pragma("unroll") for (int k = 0; k < 2; ++k) dst[m][k] = *(const LAS bf16x8*)(lds + PG8_SA(b, h) + aoff + m * 2048 + k * 1024); } while (0)
; #define PG8_LDB(dst, b, h) do { _Pragma("unroll") for (int n = 0; n < 2; ++n) _Pragma("unroll") for (int k = 0; k < 2; ++k) dst[n][k] = *(const LAS bf16x8*)(lds + PG8_SB(b, h) + boff + n * 2048 + k * 1024); } while (0)
; #define PG8_SCHED __builtin_amdgcn_sched_barrier(0)
; template <class Epi>
; DI void gemm_phase(int wv, LAS unsigned char* lds, LAS unsigned char* scr, const Sched& S, const Epi& E) {
;     ...
;         const bool has_next = S.next(ui + 1, nxt);
;         const char* nA = has_next ? S.baseA(nxt) : cA; const char* nB = has_next ? S.baseB(nxt) : cB;
;         for (int t = 0; t < nt; t += 2) {
;             const bool last = (t == nt - 2);
;             const char* a1 = cA + (size_t)(t + 1) * kstep;
;             const char* a2 = last ? nA : cA + (size_t)(t + 2) * kstep; const char* b2 = last ? nB : cB + (size_t)(t + 2) * kstep;
;             const char* a3 = a2 + kstep; const char* b3 = b2 + kstep;
;             PG8_LDB(B0, 0, 0); PG8_LDB(B1, 0, 1); PG8_SCHED; PG8_LDA(At, 0, 0); PG8_STAGE(PG8_SA(1, 1), a1 + hstepA, voffA);
;     ...
; #pragma unroll
;         for (int a = 0; a < 2; ++a)
; #pragma unroll
;             for (int b = 0; b < 2; ++b)
; #pragma unroll
;                 for (int m = 0; m < 4; ++m)
; #pragma unroll
;                     for (int n = 0; n < 2; ++n) acc[a][b][m][n] = (f32x4){0.f, 0.f, 0.f, 0.f};
;         cur = nxt; cA = nA; cB = nB; ++ui;
.LBB0_276:
	v_mov_b32_e32 v0, 0
	s_mov_b32 s13, 0
	s_mov_b64 s[22:23], -1
	s_mov_b64 s[24:25], 0
	v_mov_b32_e32 v1, v0
	v_mov_b32_e32 v2, v0
	v_mov_b32_e32 v3, v0
	v_mov_b32_e32 v4, v0
	v_mov_b32_e32 v5, v0
	v_mov_b32_e32 v6, v0
	v_mov_b32_e32 v7, v0
	v_mov_b32_e32 v8, v0
	v_mov_b32_e32 v9, v0
	v_mov_b32_e32 v10, v0
	v_mov_b32_e32 v11, v0
	v_mov_b32_e32 v12, v0
	v_mov_b32_e32 v13, v0
	v_mov_b32_e32 v14, v0
	v_mov_b32_e32 v15, v0
	v_mov_b32_e32 v24, v0
	v_mov_b32_e32 v25, v0
	v_mov_b32_e32 v26, v0
	v_mov_b32_e32 v27, v0
	v_mov_b32_e32 v28, v0
	v_mov_b32_e32 v29, v0
	v_mov_b32_e32 v30, v0
	v_mov_b32_e32 v31, v0
	v_mov_b32_e32 v40, v0
	v_mov_b32_e32 v41, v0
	v_mov_b32_e32 v42, v0
	v_mov_b32_e32 v43, v0
	v_mov_b32_e32 v44, v0
	v_mov_b32_e32 v45, v0
	v_mov_b32_e32 v46, v0
	v_mov_b32_e32 v47, v0
	v_mov_b32_e32 v16, v0
	v_mov_b32_e32 v17, v0
	v_mov_b32_e32 v18, v0
	v_mov_b32_e32 v19, v0
	v_mov_b32_e32 v20, v0
	v_mov_b32_e32 v21, v0
	v_mov_b32_e32 v22, v0
	v_mov_b32_e32 v23, v0
	v_mov_b32_e32 v32, v0
	v_mov_b32_e32 v33, v0
	v_mov_b32_e32 v34, v0
	v_mov_b32_e32 v35, v0
	v_mov_b32_e32 v36, v0
	v_mov_b32_e32 v37, v0
	v_mov_b32_e32 v38, v0
	v_mov_b32_e32 v39, v0
	v_mov_b32_e32 v48, v0
	v_mov_b32_e32 v49, v0
	v_mov_b32_e32 v50, v0
	v_mov_b32_e32 v51, v0
	v_mov_b32_e32 v52, v0
	v_mov_b32_e32 v53, v0
	v_mov_b32_e32 v54, v0
	v_mov_b32_e32 v55, v0
	v_mov_b32_e32 v56, v0
	v_mov_b32_e32 v57, v0
	v_mov_b32_e32 v58, v0
	v_mov_b32_e32 v59, v0
	v_mov_b32_e32 v60, v0
	v_mov_b32_e32 v61, v0
	v_mov_b32_e32 v62, v0
	v_mov_b32_e32 v63, v0
	v_mov_b32_e32 v64, v0
	v_mov_b32_e32 v65, v0
	v_mov_b32_e32 v66, v0
	v_mov_b32_e32 v67, v0
	v_mov_b32_e32 v68, v0
	v_mov_b32_e32 v69, v0
	v_mov_b32_e32 v70, v0
	v_mov_b32_e32 v71, v0
	v_mov_b32_e32 v72, v0
	v_mov_b32_e32 v73, v0
	v_mov_b32_e32 v74, v0
	v_mov_b32_e32 v75, v0
	v_mov_b32_e32 v76, v0
	v_mov_b32_e32 v77, v0
	v_mov_b32_e32 v78, v0
	v_mov_b32_e32 v79, v0
	v_mov_b32_e32 v88, v0
	v_mov_b32_e32 v89, v0
	v_mov_b32_e32 v90, v0
	v_mov_b32_e32 v91, v0
	v_mov_b32_e32 v92, v0
	v_mov_b32_e32 v93, v0
	v_mov_b32_e32 v94, v0
	v_mov_b32_e32 v95, v0
	v_mov_b32_e32 v104, v0
	v_mov_b32_e32 v105, v0
	v_mov_b32_e32 v106, v0
	v_mov_b32_e32 v107, v0
	v_mov_b32_e32 v108, v0
	v_mov_b32_e32 v109, v0
	v_mov_b32_e32 v110, v0
	v_mov_b32_e32 v111, v0
	v_mov_b32_e32 v80, v0
	v_mov_b32_e32 v81, v0
	v_mov_b32_e32 v82, v0
	v_mov_b32_e32 v83, v0
	v_mov_b32_e32 v84, v0
	v_mov_b32_e32 v85, v0
	v_mov_b32_e32 v86, v0
	v_mov_b32_e32 v87, v0
	v_mov_b32_e32 v96, v0
	v_mov_b32_e32 v97, v0
	v_mov_b32_e32 v98, v0
	v_mov_b32_e32 v99, v0
	v_mov_b32_e32 v100, v0
	v_mov_b32_e32 v101, v0
	v_mov_b32_e32 v102, v0
	v_mov_b32_e32 v103, v0
	v_mov_b32_e32 v112, v0
	v_mov_b32_e32 v113, v0
	v_mov_b32_e32 v114, v0
	v_mov_b32_e32 v115, v0
	v_mov_b32_e32 v116, v0
	v_mov_b32_e32 v117, v0
	v_mov_b32_e32 v118, v0
	v_mov_b32_e32 v119, v0
	v_mov_b32_e32 v120, v0
	v_mov_b32_e32 v121, v0
	v_mov_b32_e32 v122, v0
	v_mov_b32_e32 v123, v0
	v_mov_b32_e32 v124, v0
	v_mov_b32_e32 v125, v0
	v_mov_b32_e32 v126, v0
	v_mov_b32_e32 v127, v0
	s_cmp_lg_u64 s[10:11], 0
	s_cbranch_scc1 .Lgp_9
	s_setprio 1
.Lgp_9:
.LBB0_277:
	s_add_u32 s21, s14, s13
	s_addc_u32 s34, s15, 0
	s_add_u32 s28, s21, 0x100
	s_addc_u32 s29, s34, 0
	s_and_b64 s[26:27], s[24:25], exec
	s_cselect_b32 s29, s9, s29
	s_cselect_b32 s28, s8, s28
	s_add_u32 s13, s16, s13
	s_addc_u32 s26, s17, 0
	s_add_u32 s13, s13, 0x100
	s_addc_u32 s26, s26, 0
	s_add_i32 s64, 0, 0x10000
	s_and_b64 s[24:25], s[24:25], exec
	s_cselect_b32 s31, s19, s26
	s_cselect_b32 s30, s18, s13
	s_add_i32 s25, 0, 0x14000
	s_add_u32 s36, s21, 0x40080
	s_addc_u32 s37, s34, 0
	s_add_i32 s63, s64, s43
	s_add_i32 m0, s44, 0xc000
	s_add_i32 s66, s44, 0xe000
	s_add_i32 s60, s63, 0x2000
	s_add_u32 s34, s30, 0x40000
	v_add_u32_e32 v152, s64, v138
	v_add_u32_e32 v168, s25, v138
	s_addc_u32 s35, s31, 0
	s_add_i32 s62, s25, s43
	ds_read_b128 v[140:143], v152
	ds_read_b128 v[144:147], v152 offset:1024
	ds_read_b128 v[148:151], v152 offset:2048
	ds_read_b128 v[152:155], v152 offset:3072
	ds_read_b128 v[156:159], v168
	ds_read_b128 v[160:163], v168 offset:1024
	ds_read_b128 v[164:167], v168 offset:2048
	ds_read_b128 v[168:171], v168 offset:3072
	s_add_i32 s61, s62, 0x2000
	s_add_i32 s59, 0, 0x18000
	s_add_i32 s55, 0, 0x1c000
	s_add_u32 s26, s28, 0x40000
	s_addc_u32 s27, s29, 0
	s_add_i32 s21, s59, s43
	s_add_i32 s13, s21, 0x2000
	s_add_u32 s24, s30, 0x40080
	s_addc_u32 s25, s31, 0
	s_add_i32 s65, s55, s43
	s_add_i32 s64, s65, 0x2000
	v_lshl_add_u64 v[206:207], s[36:37], 0, v[134:135]
	ds_read_b128 v[172:175], v139
	ds_read_b128 v[176:179], v139 offset:1024
	ds_read_b128 v[180:183], v139 offset:2048
	ds_read_b128 v[184:187], v139 offset:3072
	ds_read_b128 v[188:191], v139 offset:4096
	ds_read_b128 v[194:197], v139 offset:5120
	ds_read_b128 v[198:201], v139 offset:6144
	ds_read_b128 v[202:205], v139 offset:7168
	global_load_lds_dwordx4 v[206:207], off
	v_lshl_add_u64 v[206:207], s[36:37], 0, v[130:131]
	s_mov_b32 m0, s66
	s_nop 0
	global_load_lds_dwordx4 v[206:207], off
	s_waitcnt vmcnt(8)
	s_waitcnt lgkmcnt(0)
	s_barrier
; #define PG8_STAGE(bufoff, gbase, voff) do { _Pragma("unroll") for (int _i = 0; _i < 2; ++_i) \
;         __builtin_amdgcn_global_load_lds((const unsigned*)((const char*)(gbase) + (voff)[_i]), (LAS unsigned*)(lds + (bufoff) + ldsw + _i * 8192), 16, 0, 0); } while (0)
; #define PG8_LDA(dst, b, h) do { _Pragma("unroll") for (int m = 0; m < 4; ++m) _Pragma("unroll") for (int k = 0; k < 2; ++k) dst[m][k] = *(const LAS bf16x8*)(lds + PG8_SA(b, h) + aoff + m * 2048 + k * 1024); } while (0)
; #define PG8_MMA(ai, bj, At, Bt) do { __builtin_amdgcn_s_setprio(1); _Pragma("unroll") for (int m = 0; m < 4; ++m) _Pragma("unroll") for (int n = 0; n < 2; ++n) _Pragma("unroll") for (int k = 0; k < 2; ++k) \
;         acc[ai][bj][m][n] = __builtin_amdgcn_mfma_f32_16x16x32_bf16(Bt[n][k], At[m][k], acc[ai][bj][m][n], 0, 0, 0); __builtin_amdgcn_s_setprio(0); } while (0)
; #define PG8_WAIT_V(n) asm volatile("s_waitcnt vmcnt(" #n ")" ::: "memory")
; #define PG8_WAIT_L(n) asm volatile("s_waitcnt lgkmcnt(" #n ")" ::: "memory")
; #define PG8_BAR __builtin_amdgcn_s_barrier()
; #define PG8_SCHED __builtin_amdgcn_sched_barrier(0)
; template <class Epi>
; DI void gemm_phase(int wv, LAS unsigned char* lds, LAS unsigned char* scr, const Sched& S, const Epi& E) {
;     ...
;             PG8_WAIT_V(8); PG8_WAIT_L(0); PG8_BAR; PG8_MMA(0, 0, At, B0); PG8_MMA(0, 1, At, B1); PG8_BAR; PG8_SCHED;
;             PG8_LDA(At, 0, 1); PG8_STAGE(PG8_SB(0, 0), b2, voffB); PG8_STAGE(PG8_SB(0, 1), b2 + hstepB, voffB); PG8_STAGE(PG8_SA(0, 0), a2, voffA);
;             PG8_WAIT_V(8); PG8_WAIT_L(0); PG8_BAR; PG8_MMA(1, 0, At, B0); PG8_MMA(1, 1, At, B1); PG8_BAR; PG8_SCHED;
	s_waitcnt lgkmcnt(0)
	v_mfma_f32_16x16x32_bf16 v[124:127], v[140:143], v[172:175], v[124:127]
	v_mfma_f32_16x16x32_bf16 v[120:123], v[148:151], v[172:175], v[120:123]
	v_mfma_f32_16x16x32_bf16 v[116:119], v[140:143], v[180:183], v[116:119]
	v_mfma_f32_16x16x32_bf16 v[112:115], v[148:151], v[180:183], v[112:115]
	v_mfma_f32_16x16x32_bf16 v[100:103], v[140:143], v[188:191], v[100:103]
	v_mfma_f32_16x16x32_bf16 v[96:99], v[148:151], v[188:191], v[96:99]
	v_mfma_f32_16x16x32_bf16 v[84:87], v[140:143], v[198:201], v[84:87]
	v_mfma_f32_16x16x32_bf16 v[80:83], v[148:151], v[198:201], v[80:83]
	v_mfma_f32_16x16x32_bf16 v[124:127], v[144:147], v[176:179], v[124:127]
	v_mfma_f32_16x16x32_bf16 v[120:123], v[152:155], v[176:179], v[120:123]
	v_mfma_f32_16x16x32_bf16 v[116:119], v[144:147], v[184:187], v[116:119]
	v_mfma_f32_16x16x32_bf16 v[112:115], v[152:155], v[184:187], v[112:115]
	v_mfma_f32_16x16x32_bf16 v[100:103], v[144:147], v[194:197], v[100:103]
	v_mfma_f32_16x16x32_bf16 v[96:99], v[152:155], v[194:197], v[96:99]
	v_mfma_f32_16x16x32_bf16 v[84:87], v[144:147], v[202:205], v[84:87]
	v_mfma_f32_16x16x32_bf16 v[80:83], v[152:155], v[202:205], v[80:83]
	v_mfma_f32_16x16x32_bf16 v[108:111], v[156:159], v[172:175], v[108:111]
	v_mfma_f32_16x16x32_bf16 v[104:107], v[164:167], v[172:175], v[104:107]
	v_mfma_f32_16x16x32_bf16 v[92:95], v[156:159], v[180:183], v[92:95]
	v_mfma_f32_16x16x32_bf16 v[88:91], v[164:167], v[180:183], v[88:91]
	v_mfma_f32_16x16x32_bf16 v[76:79], v[156:159], v[188:191], v[76:79]
	v_mfma_f32_16x16x32_bf16 v[72:75], v[164:167], v[188:191], v[72:75]
	v_mfma_f32_16x16x32_bf16 v[68:71], v[156:159], v[198:201], v[68:71]
	v_mfma_f32_16x16x32_bf16 v[64:67], v[164:167], v[198:201], v[64:67]
	v_mfma_f32_16x16x32_bf16 v[108:111], v[160:163], v[176:179], v[108:111]
	v_mfma_f32_16x16x32_bf16 v[104:107], v[168:171], v[176:179], v[104:107]
	v_mfma_f32_16x16x32_bf16 v[92:95], v[160:163], v[184:187], v[92:95]
	v_mfma_f32_16x16x32_bf16 v[88:91], v[168:171], v[184:187], v[88:91]
	v_mfma_f32_16x16x32_bf16 v[76:79], v[160:163], v[194:197], v[76:79]
	v_mfma_f32_16x16x32_bf16 v[72:75], v[168:171], v[194:197], v[72:75]
	v_mfma_f32_16x16x32_bf16 v[68:71], v[160:163], v[202:205], v[68:71]
	v_mfma_f32_16x16x32_bf16 v[64:67], v[168:171], v[202:205], v[64:67]
	s_barrier
	s_mov_b32 m0, s63
	v_lshl_add_u64 v[206:207], s[30:31], 0, v[132:133]
	ds_read_b128 v[172:175], v139 offset:16384
	ds_read_b128 v[176:179], v139 offset:17408
	ds_read_b128 v[180:183], v139 offset:18432
	ds_read_b128 v[184:187], v139 offset:19456
	ds_read_b128 v[188:191], v139 offset:20480
	ds_read_b128 v[194:197], v139 offset:21504
	ds_read_b128 v[198:201], v139 offset:22528
	ds_read_b128 v[202:205], v139 offset:23552
	global_load_lds_dwordx4 v[206:207], off
	v_lshl_add_u64 v[208:209], s[30:31], 0, v[128:129]
	s_mov_b32 m0, s60
	v_lshl_add_u64 v[210:211], s[34:35], 0, v[132:133]
	global_load_lds_dwordx4 v[208:209], off
	s_mov_b32 m0, s62
	v_lshl_add_u64 v[212:213], s[28:29], 0, v[130:131]
	global_load_lds_dwordx4 v[210:211], off
	v_lshl_add_u64 v[210:211], s[34:35], 0, v[128:129]
	s_mov_b32 m0, s61
	s_nop 0
	global_load_lds_dwordx4 v[210:211], off
	v_lshl_add_u64 v[210:211], s[28:29], 0, v[134:135]
	s_mov_b32 m0, s44
	s_nop 0
	global_load_lds_dwordx4 v[210:211], off
	s_mov_b32 m0, s45
	s_nop 0
	global_load_lds_dwordx4 v[212:213], off
	s_waitcnt vmcnt(8)
	s_waitcnt lgkmcnt(0)
	s_barrier
	s_waitcnt lgkmcnt(0)
	v_mfma_f32_16x16x32_bf16 v[60:63], v[140:143], v[172:175], v[60:63]
	v_mfma_f32_16x16x32_bf16 v[56:59], v[148:151], v[172:175], v[56:59]
	v_mfma_f32_16x16x32_bf16 v[52:55], v[140:143], v[180:183], v[52:55]
	v_mfma_f32_16x16x32_bf16 v[48:51], v[148:151], v[180:183], v[48:51]
	v_mfma_f32_16x16x32_bf16 v[36:39], v[140:143], v[188:191], v[36:39]
	v_mfma_f32_16x16x32_bf16 v[32:35], v[148:151], v[188:191], v[32:35]
	v_mfma_f32_16x16x32_bf16 v[20:23], v[140:143], v[198:201], v[20:23]
	v_mfma_f32_16x16x32_bf16 v[16:19], v[148:151], v[198:201], v[16:19]
	v_mfma_f32_16x16x32_bf16 v[60:63], v[144:147], v[176:179], v[60:63]
	v_mfma_f32_16x16x32_bf16 v[56:59], v[152:155], v[176:179], v[56:59]
	v_mfma_f32_16x16x32_bf16 v[52:55], v[144:147], v[184:187], v[52:55]
	v_mfma_f32_16x16x32_bf16 v[48:51], v[152:155], v[184:187], v[48:51]
	v_mfma_f32_16x16x32_bf16 v[36:39], v[144:147], v[194:197], v[36:39]
	v_mfma_f32_16x16x32_bf16 v[32:35], v[152:155], v[194:197], v[32:35]
	v_mfma_f32_16x16x32_bf16 v[20:23], v[144:147], v[202:205], v[20:23]
	v_mfma_f32_16x16x32_bf16 v[16:19], v[152:155], v[202:205], v[16:19]
	v_mfma_f32_16x16x32_bf16 v[44:47], v[156:159], v[172:175], v[44:47]
	v_mfma_f32_16x16x32_bf16 v[40:43], v[164:167], v[172:175], v[40:43]
	v_mfma_f32_16x16x32_bf16 v[28:31], v[156:159], v[180:183], v[28:31]
	v_mfma_f32_16x16x32_bf16 v[24:27], v[164:167], v[180:183], v[24:27]
	v_mfma_f32_16x16x32_bf16 v[12:15], v[156:159], v[188:191], v[12:15]
	v_mfma_f32_16x16x32_bf16 v[8:11], v[164:167], v[188:191], v[8:11]
	v_mfma_f32_16x16x32_bf16 v[4:7], v[156:159], v[198:201], v[4:7]
	v_mfma_f32_16x16x32_bf16 v[0:3], v[164:167], v[198:201], v[0:3]
	v_mfma_f32_16x16x32_bf16 v[44:47], v[160:163], v[176:179], v[44:47]
	v_mfma_f32_16x16x32_bf16 v[40:43], v[168:171], v[176:179], v[40:43]
	v_mfma_f32_16x16x32_bf16 v[28:31], v[160:163], v[184:187], v[28:31]
	v_mfma_f32_16x16x32_bf16 v[24:27], v[168:171], v[184:187], v[24:27]
	v_mfma_f32_16x16x32_bf16 v[12:15], v[160:163], v[194:197], v[12:15]
	v_mfma_f32_16x16x32_bf16 v[8:11], v[168:171], v[194:197], v[8:11]
	v_mfma_f32_16x16x32_bf16 v[4:7], v[160:163], v[202:205], v[4:7]
	v_mfma_f32_16x16x32_bf16 v[0:3], v[168:171], v[202:205], v[0:3]
	s_barrier
; #define PG8_STAGE(bufoff, gbase, voff) do { _Pragma("unroll") for (int _i = 0; _i < 2; ++_i) \
;         __builtin_amdgcn_global_load_lds((const unsigned*)((const char*)(gbase) + (voff)[_i]), (LAS unsigned*)(lds + (bufoff) + ldsw + _i * 8192), 16, 0, 0); } while (0)
; #define PG8_LDA(dst, b, h) do { _Pragma("unroll") for (int m = 0; m < 4; ++m) _Pragma("unroll") for (int k = 0; k < 2; ++k) dst[m][k] = *(const LAS bf16x8*)(lds + PG8_SA(b, h) + aoff + m * 2048 + k * 1024); } while (0)
; #define PG8_LDB(dst, b, h) do { _Pragma("unroll") for (int n = 0; n < 2; ++n) _Pragma("unroll") for (int k = 0; k < 2; ++k) dst[n][k] = *(const LAS bf16x8*)(lds + PG8_SB(b, h) + boff + n * 2048 + k * 1024); } while (0)
; #define PG8_MMA(ai, bj, At, Bt) do { __builtin_amdgcn_s_setprio(1); _Pragma("unroll") for (int m = 0; m < 4; ++m) _Pragma("unroll") for (int n = 0; n < 2; ++n) _Pragma("unroll") for (int k = 0; k < 2; ++k) \
;         acc[ai][bj][m][n] = __builtin_amdgcn_mfma_f32_16x16x32_bf16(Bt[n][k], At[m][k], acc[ai][bj][m][n], 0, 0, 0); __builtin_amdgcn_s_setprio(0); } while (0)
; #define PG8_WAIT_V(n) asm volatile("s_waitcnt vmcnt(" #n ")" ::: "memory")
; #define PG8_WAIT_L(n) asm volatile("s_waitcnt lgkmcnt(" #n ")" ::: "memory")
; #define PG8_BAR __builtin_amdgcn_s_barrier()
; #define PG8_SCHED __builtin_amdgcn_sched_barrier(0)
; template <class Epi>
; DI void gemm_phase(int wv, LAS unsigned char* lds, LAS unsigned char* scr, const Sched& S, const Epi& E) {
;     ...
;             PG8_LDB(B0, 1, 0); PG8_LDB(B1, 1, 1); PG8_SCHED; PG8_LDA(At, 1, 0); PG8_STAGE(PG8_SA(0, 1), a2 + hstepA, voffA);
;             PG8_WAIT_V(8); PG8_WAIT_L(0); PG8_BAR; PG8_MMA(0, 0, At, B0); PG8_MMA(0, 1, At, B1); PG8_BAR; PG8_SCHED;
;             PG8_LDA(At, 1, 1); PG8_STAGE(PG8_SB(1, 0), b3, voffB); PG8_STAGE(PG8_SB(1, 1), b3 + hstepB, voffB); PG8_STAGE(PG8_SA(1, 0), a3, voffA);
;             PG8_WAIT_V(8); PG8_WAIT_L(0); PG8_BAR; PG8_MMA(1, 0, At, B0); PG8_MMA(1, 1, At, B1); PG8_BAR; PG8_SCHED;
;         }
	v_add_u32_e32 v152, s59, v138
	v_add_u32_e32 v168, s55, v138
	ds_read_b128 v[140:143], v152
	ds_read_b128 v[144:147], v152 offset:1024
	ds_read_b128 v[148:151], v152 offset:2048
	ds_read_b128 v[152:155], v152 offset:3072
	ds_read_b128 v[156:159], v168
	ds_read_b128 v[160:163], v168 offset:1024
	ds_read_b128 v[164:167], v168 offset:2048
	ds_read_b128 v[168:171], v168 offset:3072
	s_mov_b32 m0, s46
	v_lshl_add_u64 v[214:215], s[26:27], 0, v[134:135]
	ds_read_b128 v[172:175], v139 offset:32768
	ds_read_b128 v[176:179], v139 offset:33792
	ds_read_b128 v[180:183], v139 offset:34816
	ds_read_b128 v[184:187], v139 offset:35840
	ds_read_b128 v[188:191], v139 offset:36864
	ds_read_b128 v[194:197], v139 offset:37888
	ds_read_b128 v[198:201], v139 offset:38912
	ds_read_b128 v[202:205], v139 offset:39936
	global_load_lds_dwordx4 v[214:215], off
	v_lshl_add_u64 v[214:215], s[26:27], 0, v[130:131]
	s_mov_b32 m0, s47
	s_nop 0
	global_load_lds_dwordx4 v[214:215], off
	s_waitcnt vmcnt(8)
	s_waitcnt lgkmcnt(0)
	s_barrier
	s_waitcnt lgkmcnt(0)
	v_mfma_f32_16x16x32_bf16 v[124:127], v[140:143], v[172:175], v[124:127]
	v_mfma_f32_16x16x32_bf16 v[120:123], v[148:151], v[172:175], v[120:123]
	v_mfma_f32_16x16x32_bf16 v[116:119], v[140:143], v[180:183], v[116:119]
	v_mfma_f32_16x16x32_bf16 v[112:115], v[148:151], v[180:183], v[112:115]
	v_mfma_f32_16x16x32_bf16 v[100:103], v[140:143], v[188:191], v[100:103]
	v_mfma_f32_16x16x32_bf16 v[96:99], v[148:151], v[188:191], v[96:99]
	v_mfma_f32_16x16x32_bf16 v[84:87], v[140:143], v[198:201], v[84:87]
	v_mfma_f32_16x16x32_bf16 v[80:83], v[148:151], v[198:201], v[80:83]
	v_mfma_f32_16x16x32_bf16 v[124:127], v[144:147], v[176:179], v[124:127]
	v_mfma_f32_16x16x32_bf16 v[120:123], v[152:155], v[176:179], v[120:123]
	v_mfma_f32_16x16x32_bf16 v[116:119], v[144:147], v[184:187], v[116:119]
	v_mfma_f32_16x16x32_bf16 v[112:115], v[152:155], v[184:187], v[112:115]
	v_mfma_f32_16x16x32_bf16 v[100:103], v[144:147], v[194:197], v[100:103]
	v_mfma_f32_16x16x32_bf16 v[96:99], v[152:155], v[194:197], v[96:99]
	v_mfma_f32_16x16x32_bf16 v[84:87], v[144:147], v[202:205], v[84:87]
	v_mfma_f32_16x16x32_bf16 v[80:83], v[152:155], v[202:205], v[80:83]
	v_mfma_f32_16x16x32_bf16 v[108:111], v[156:159], v[172:175], v[108:111]
	v_mfma_f32_16x16x32_bf16 v[104:107], v[164:167], v[172:175], v[104:107]
	v_mfma_f32_16x16x32_bf16 v[92:95], v[156:159], v[180:183], v[92:95]
	v_mfma_f32_16x16x32_bf16 v[88:91], v[164:167], v[180:183], v[88:91]
	v_mfma_f32_16x16x32_bf16 v[76:79], v[156:159], v[188:191], v[76:79]
	v_mfma_f32_16x16x32_bf16 v[72:75], v[164:167], v[188:191], v[72:75]
	v_mfma_f32_16x16x32_bf16 v[68:71], v[156:159], v[198:201], v[68:71]
	v_mfma_f32_16x16x32_bf16 v[64:67], v[164:167], v[198:201], v[64:67]
	v_mfma_f32_16x16x32_bf16 v[108:111], v[160:163], v[176:179], v[108:111]
	v_mfma_f32_16x16x32_bf16 v[104:107], v[168:171], v[176:179], v[104:107]
	v_mfma_f32_16x16x32_bf16 v[92:95], v[160:163], v[184:187], v[92:95]
	v_mfma_f32_16x16x32_bf16 v[88:91], v[168:171], v[184:187], v[88:91]
	v_mfma_f32_16x16x32_bf16 v[76:79], v[160:163], v[194:197], v[76:79]
	v_mfma_f32_16x16x32_bf16 v[72:75], v[168:171], v[194:197], v[72:75]
	v_mfma_f32_16x16x32_bf16 v[68:71], v[160:163], v[202:205], v[68:71]
	v_mfma_f32_16x16x32_bf16 v[64:67], v[168:171], v[202:205], v[64:67]
	s_barrier
	s_mov_b32 m0, s21
	v_lshl_add_u64 v[206:207], v[206:207], 0, s[2:3]
	ds_read_b128 v[172:175], v139 offset:49152
	ds_read_b128 v[176:179], v139 offset:50176
	ds_read_b128 v[180:183], v139 offset:51200
	ds_read_b128 v[184:187], v139 offset:52224
	ds_read_b128 v[188:191], v139 offset:53248
	ds_read_b128 v[194:197], v139 offset:54272
	ds_read_b128 v[198:201], v139 offset:55296
	ds_read_b128 v[202:205], v139 offset:56320
	global_load_lds_dwordx4 v[206:207], off
	v_lshl_add_u64 v[206:207], v[208:209], 0, s[2:3]
	s_mov_b32 m0, s13
	s_nop 0
	global_load_lds_dwordx4 v[206:207], off
	v_lshl_add_u64 v[206:207], s[24:25], 0, v[132:133]
	s_mov_b32 m0, s65
	s_nop 0
	global_load_lds_dwordx4 v[206:207], off
	v_lshl_add_u64 v[206:207], s[24:25], 0, v[128:129]
	s_mov_b32 m0, s64
	s_nop 0
	global_load_lds_dwordx4 v[206:207], off
	v_lshl_add_u64 v[206:207], v[210:211], 0, s[2:3]
	s_mov_b32 m0, s50
	s_nop 0
	global_load_lds_dwordx4 v[206:207], off
	v_lshl_add_u64 v[206:207], v[212:213], 0, s[2:3]
	s_mov_b32 m0, s51
	s_nop 0
	global_load_lds_dwordx4 v[206:207], off
	s_waitcnt vmcnt(8)
	s_waitcnt lgkmcnt(0)
	s_barrier
	s_waitcnt lgkmcnt(0)
	v_mfma_f32_16x16x32_bf16 v[60:63], v[140:143], v[172:175], v[60:63]
	v_mfma_f32_16x16x32_bf16 v[56:59], v[148:151], v[172:175], v[56:59]
	v_mfma_f32_16x16x32_bf16 v[52:55], v[140:143], v[180:183], v[52:55]
	v_mfma_f32_16x16x32_bf16 v[48:51], v[148:151], v[180:183], v[48:51]
	v_mfma_f32_16x16x32_bf16 v[36:39], v[140:143], v[188:191], v[36:39]
	v_mfma_f32_16x16x32_bf16 v[32:35], v[148:151], v[188:191], v[32:35]
	v_mfma_f32_16x16x32_bf16 v[20:23], v[140:143], v[198:201], v[20:23]
	v_mfma_f32_16x16x32_bf16 v[16:19], v[148:151], v[198:201], v[16:19]
	v_mfma_f32_16x16x32_bf16 v[60:63], v[144:147], v[176:179], v[60:63]
	v_mfma_f32_16x16x32_bf16 v[56:59], v[152:155], v[176:179], v[56:59]
	v_mfma_f32_16x16x32_bf16 v[52:55], v[144:147], v[184:187], v[52:55]
	v_mfma_f32_16x16x32_bf16 v[48:51], v[152:155], v[184:187], v[48:51]
	v_mfma_f32_16x16x32_bf16 v[36:39], v[144:147], v[194:197], v[36:39]
	v_mfma_f32_16x16x32_bf16 v[32:35], v[152:155], v[194:197], v[32:35]
	v_mfma_f32_16x16x32_bf16 v[20:23], v[144:147], v[202:205], v[20:23]
	v_mfma_f32_16x16x32_bf16 v[16:19], v[152:155], v[202:205], v[16:19]
	v_mfma_f32_16x16x32_bf16 v[44:47], v[156:159], v[172:175], v[44:47]
	v_mfma_f32_16x16x32_bf16 v[40:43], v[164:167], v[172:175], v[40:43]
	v_mfma_f32_16x16x32_bf16 v[28:31], v[156:159], v[180:183], v[28:31]
	v_mfma_f32_16x16x32_bf16 v[24:27], v[164:167], v[180:183], v[24:27]
	v_mfma_f32_16x16x32_bf16 v[12:15], v[156:159], v[188:191], v[12:15]
	v_mfma_f32_16x16x32_bf16 v[8:11], v[164:167], v[188:191], v[8:11]
	v_mfma_f32_16x16x32_bf16 v[4:7], v[156:159], v[198:201], v[4:7]
	v_mfma_f32_16x16x32_bf16 v[0:3], v[164:167], v[198:201], v[0:3]
	v_mfma_f32_16x16x32_bf16 v[44:47], v[160:163], v[176:179], v[44:47]
	v_mfma_f32_16x16x32_bf16 v[40:43], v[168:171], v[176:179], v[40:43]
	v_mfma_f32_16x16x32_bf16 v[28:31], v[160:163], v[184:187], v[28:31]
	v_mfma_f32_16x16x32_bf16 v[24:27], v[168:171], v[184:187], v[24:27]
	v_mfma_f32_16x16x32_bf16 v[12:15], v[160:163], v[194:197], v[12:15]
	v_mfma_f32_16x16x32_bf16 v[8:11], v[168:171], v[194:197], v[8:11]
	v_mfma_f32_16x16x32_bf16 v[4:7], v[160:163], v[202:205], v[4:7]
	v_mfma_f32_16x16x32_bf16 v[0:3], v[168:171], v[202:205], v[0:3]
	s_barrier
	s_movk_i32 s13, 0x100
	s_andn2_b64 vcc, exec, s[22:23]
	s_mov_b64 s[24:25], -1
	s_mov_b64 s[22:23], 0
	s_cbranch_vccz .LBB0_277
	s_setprio 0
	s_and_b64 vcc, exec, s[10:11]
	s_cbranch_vccz .LBB0_280
	s_barrier

; #define PG8_STAGE(bufoff, gbase, voff) do { _Pragma("unroll") for (int _i = 0; _i < 2; ++_i) \
;         __builtin_amdgcn_global_load_lds((const unsigned*)((const char*)(gbase) + (voff)[_i]), (LAS unsigned*)(lds + (bufoff) + ldsw + _i * 8192), 16, 0, 0); } while (0)
; #define PG8_LDA(dst, b, h) do { _Pragma("unroll") for (int m = 0; m < 4; ++m) _Pragma("unroll") for (int k = 0; k < 2; ++k) dst[m][k] = *(const LAS bf16x8*)(lds + PG8_SA(b, h) + aoff + m * 2048 + k * 1024); } while (0)
; #define PG8_LDB(dst, b, h) do { _Pragma("unroll") for (int n = 0; n < 2; ++n) _Pragma("unroll") for (int k = 0; k < 2; ++k) dst[n][k] = *(const LAS bf16x8*)(lds + PG8_SB(b, h) + boff + n * 2048 + k * 1024); } while (0)
; #define PG8_SCHED __builtin_amdgcn_sched_barrier(0)
; template <class Epi>
; DI void gemm_phase(int wv, LAS unsigned char* lds, LAS unsigned char* scr, const Sched& S, const Epi& E) {
;     ...
;         const bool has_next = S.next(ui + 1, nxt);
;         const char* nA = has_next ? S.baseA(nxt) : cA; const char* nB = has_next ? S.baseB(nxt) : cB;
;         for (int t = 0; t < nt; t += 2) {
;             const bool last = (t == nt - 2);
;             const char* a1 = cA + (size_t)(t + 1) * kstep;
;             const char* a2 = last ? nA : cA + (size_t)(t + 2) * kstep; const char* b2 = last ? nB : cB + (size_t)(t + 2) * kstep;
;             const char* a3 = a2 + kstep; const char* b3 = b2 + kstep;
;             PG8_LDB(B0, 0, 0); PG8_LDB(B1, 0, 1); PG8_SCHED; PG8_LDA(At, 0, 0); PG8_STAGE(PG8_SA(1, 1), a1 + hstepA, voffA);
;     ...
; #pragma unroll
;         for (int a = 0; a < 2; ++a)
; #pragma unroll
;             for (int b = 0; b < 2; ++b)
; #pragma unroll
;                 for (int m = 0; m < 4; ++m)
; #pragma unroll
;                     for (int n = 0; n < 2; ++n) acc[a][b][m][n] = (f32x4){0.f, 0.f, 0.f, 0.f};
;         cur = nxt; cA = nA; cB = nB; ++ui;
.LBB0_462:
	s_ashr_i32 s15, s14, 31
	s_lshl_b64 s[16:17], s[14:15], 19
	s_add_u32 s16, s28, s16
	s_addc_u32 s17, s29, s17
	s_and_b64 s[18:19], s[6:7], exec
	s_cselect_b32 s11, s17, s23
	s_cselect_b32 s15, s16, s22
	s_ashr_i32 s13, s12, 31
	s_lshl_b64 s[18:19], s[12:13], 19
	s_add_u32 s18, s30, s18
	s_addc_u32 s19, s31, s19
	s_and_b64 s[26:27], s[6:7], exec
	s_cselect_b32 s13, s19, s25
	s_cselect_b32 s21, s18, s24
	s_add_u32 s45, s24, 0x100
	s_addc_u32 s46, s25, 0
	s_add_u32 s22, s22, 0x40080
	v_mov_b32_e32 v0, 0
	s_addc_u32 s23, s23, 0
	s_mov_b32 s47, -2
	v_mov_b32_e32 v1, v0
	v_mov_b32_e32 v2, v0
	v_mov_b32_e32 v3, v0
	v_mov_b32_e32 v4, v0
	v_mov_b32_e32 v5, v0
	v_mov_b32_e32 v6, v0
	v_mov_b32_e32 v7, v0
	v_mov_b32_e32 v8, v0
	v_mov_b32_e32 v9, v0
	v_mov_b32_e32 v10, v0
	v_mov_b32_e32 v11, v0
	v_mov_b32_e32 v12, v0
	v_mov_b32_e32 v13, v0
	v_mov_b32_e32 v14, v0
	v_mov_b32_e32 v15, v0
	v_mov_b32_e32 v24, v0
	v_mov_b32_e32 v25, v0
	v_mov_b32_e32 v26, v0
	v_mov_b32_e32 v27, v0
	v_mov_b32_e32 v28, v0
	v_mov_b32_e32 v29, v0
	v_mov_b32_e32 v30, v0
	v_mov_b32_e32 v31, v0
	v_mov_b32_e32 v40, v0
	v_mov_b32_e32 v41, v0
	v_mov_b32_e32 v42, v0
	v_mov_b32_e32 v43, v0
	v_mov_b32_e32 v44, v0
	v_mov_b32_e32 v45, v0
	v_mov_b32_e32 v46, v0
	v_mov_b32_e32 v47, v0
	v_mov_b32_e32 v16, v0
	v_mov_b32_e32 v17, v0
	v_mov_b32_e32 v18, v0
	v_mov_b32_e32 v19, v0
	v_mov_b32_e32 v20, v0
	v_mov_b32_e32 v21, v0
	v_mov_b32_e32 v22, v0
	v_mov_b32_e32 v23, v0
	v_mov_b32_e32 v32, v0
	v_mov_b32_e32 v33, v0
	v_mov_b32_e32 v34, v0
	v_mov_b32_e32 v35, v0
	v_mov_b32_e32 v36, v0
	v_mov_b32_e32 v37, v0
	v_mov_b32_e32 v38, v0
	v_mov_b32_e32 v39, v0
	v_mov_b32_e32 v48, v0
	v_mov_b32_e32 v49, v0
	v_mov_b32_e32 v50, v0
	v_mov_b32_e32 v51, v0
	v_mov_b32_e32 v52, v0
	v_mov_b32_e32 v53, v0
	v_mov_b32_e32 v54, v0
	v_mov_b32_e32 v55, v0
	v_mov_b32_e32 v56, v0
	v_mov_b32_e32 v57, v0
	v_mov_b32_e32 v58, v0
	v_mov_b32_e32 v59, v0
	v_mov_b32_e32 v60, v0
	v_mov_b32_e32 v61, v0
	v_mov_b32_e32 v62, v0
	v_mov_b32_e32 v63, v0
	v_mov_b32_e32 v64, v0
	v_mov_b32_e32 v65, v0
	v_mov_b32_e32 v66, v0
	v_mov_b32_e32 v67, v0
	v_mov_b32_e32 v68, v0
	v_mov_b32_e32 v69, v0
	v_mov_b32_e32 v70, v0
	v_mov_b32_e32 v71, v0
	v_mov_b32_e32 v72, v0
	v_mov_b32_e32 v73, v0
	v_mov_b32_e32 v74, v0
	v_mov_b32_e32 v75, v0
	v_mov_b32_e32 v76, v0
	v_mov_b32_e32 v77, v0
	v_mov_b32_e32 v78, v0
	v_mov_b32_e32 v79, v0
	v_mov_b32_e32 v88, v0
	v_mov_b32_e32 v89, v0
	v_mov_b32_e32 v90, v0
	v_mov_b32_e32 v91, v0
	v_mov_b32_e32 v92, v0
	v_mov_b32_e32 v93, v0
	v_mov_b32_e32 v94, v0
	v_mov_b32_e32 v95, v0
	v_mov_b32_e32 v104, v0
	v_mov_b32_e32 v105, v0
	v_mov_b32_e32 v106, v0
	v_mov_b32_e32 v107, v0
	v_mov_b32_e32 v108, v0
	v_mov_b32_e32 v109, v0
	v_mov_b32_e32 v110, v0
	v_mov_b32_e32 v111, v0
	v_mov_b32_e32 v80, v0
	v_mov_b32_e32 v81, v0
	v_mov_b32_e32 v82, v0
	v_mov_b32_e32 v83, v0
	v_mov_b32_e32 v84, v0
	v_mov_b32_e32 v85, v0
	v_mov_b32_e32 v86, v0
	v_mov_b32_e32 v87, v0
	v_mov_b32_e32 v96, v0
	v_mov_b32_e32 v97, v0
	v_mov_b32_e32 v98, v0
	v_mov_b32_e32 v99, v0
	v_mov_b32_e32 v100, v0
	v_mov_b32_e32 v101, v0
	v_mov_b32_e32 v102, v0
	v_mov_b32_e32 v103, v0
	v_mov_b32_e32 v112, v0
	v_mov_b32_e32 v113, v0
	v_mov_b32_e32 v114, v0
	v_mov_b32_e32 v115, v0
	v_mov_b32_e32 v116, v0
	v_mov_b32_e32 v117, v0
	v_mov_b32_e32 v118, v0
	v_mov_b32_e32 v119, v0
	v_mov_b32_e32 v120, v0
	v_mov_b32_e32 v121, v0
	v_mov_b32_e32 v122, v0
	v_mov_b32_e32 v123, v0
	v_mov_b32_e32 v124, v0
	v_mov_b32_e32 v125, v0
	v_mov_b32_e32 v126, v0
	v_mov_b32_e32 v127, v0
	s_cmp_lg_u64 s[8:9], 0
	s_cbranch_scc1 .Lgp_10
	s_setprio 1
.Lgp_10:
.LBB0_463:
	s_add_u32 s24, s22, 0xfffc0080
	s_addc_u32 s25, s23, -1
	s_add_i32 s48, 0, 0x10000
	s_cmp_eq_u32 s47, 12
	s_cselect_b32 s27, s11, s25
	s_cselect_b32 s26, s15, s24
	v_add_u32_e32 v143, s48, v144
	s_cselect_b32 s25, s13, s46
	s_cselect_b32 s24, s21, s45
	s_add_i32 s50, 0, 0x14000
	ds_read_b128 v[146:149], v143
	ds_read_b128 v[150:153], v143 offset:1024
	ds_read_b128 v[154:157], v143 offset:2048
	ds_read_b128 v[158:161], v143 offset:3072
	v_add_u32_e32 v143, s50, v144
	ds_read_b128 v[162:165], v143
	ds_read_b128 v[166:169], v143 offset:1024
	ds_read_b128 v[170:173], v143 offset:2048
	ds_read_b128 v[174:177], v143 offset:3072
	v_lshl_add_u64 v[190:191], s[22:23], 0, v[140:141]
	s_add_i32 m0, s34, 0xc000
	ds_read_b128 v[178:181], v145
	ds_read_b128 v[182:185], v145 offset:1024
	ds_read_b128 v[186:189], v145 offset:2048
	ds_read_b128 v[194:197], v145 offset:3072
	ds_read_b128 v[198:201], v145 offset:4096
	ds_read_b128 v[202:205], v145 offset:5120
	ds_read_b128 v[206:209], v145 offset:6144
	ds_read_b128 v[210:213], v145 offset:7168
	global_load_lds_dwordx4 v[190:191], off
	v_lshl_add_u64 v[190:191], s[22:23], 0, v[138:139]
	s_add_i32 m0, s34, 0xe000
	s_nop 0
	global_load_lds_dwordx4 v[190:191], off
	s_waitcnt vmcnt(8)
	s_waitcnt lgkmcnt(0)
	s_barrier
; #define PG8_STAGE(bufoff, gbase, voff) do { _Pragma("unroll") for (int _i = 0; _i < 2; ++_i) \
;         __builtin_amdgcn_global_load_lds((const unsigned*)((const char*)(gbase) + (voff)[_i]), (LAS unsigned*)(lds + (bufoff) + ldsw + _i * 8192), 16, 0, 0); } while (0)
; #define PG8_LDA(dst, b, h) do { _Pragma("unroll") for (int m = 0; m < 4; ++m) _Pragma("unroll") for (int k = 0; k < 2; ++k) dst[m][k] = *(const LAS bf16x8*)(lds + PG8_SA(b, h) + aoff + m * 2048 + k * 1024); } while (0)
; #define PG8_MMA(ai, bj, At, Bt) do { __builtin_amdgcn_s_setprio(1); _Pragma("unroll") for (int m = 0; m < 4; ++m) _Pragma("unroll") for (int n = 0; n < 2; ++n) _Pragma("unroll") for (int k = 0; k < 2; ++k) \
;         acc[ai][bj][m][n] = __builtin_amdgcn_mfma_f32_16x16x32_bf16(Bt[n][k], At[m][k], acc[ai][bj][m][n], 0, 0, 0); __builtin_amdgcn_s_setprio(0); } while (0)
; #define PG8_WAIT_V(n) asm volatile("s_waitcnt vmcnt(" #n ")" ::: "memory")
; #define PG8_WAIT_L(n) asm volatile("s_waitcnt lgkmcnt(" #n ")" ::: "memory")
; #define PG8_BAR __builtin_amdgcn_s_barrier()
; #define PG8_SCHED __builtin_amdgcn_sched_barrier(0)
; template <class Epi>
; DI void gemm_phase(int wv, LAS unsigned char* lds, LAS unsigned char* scr, const Sched& S, const Epi& E) {
;     ...
;             PG8_WAIT_V(8); PG8_WAIT_L(0); PG8_BAR; PG8_MMA(0, 0, At, B0); PG8_MMA(0, 1, At, B1); PG8_BAR; PG8_SCHED;
;             PG8_LDA(At, 0, 1); PG8_STAGE(PG8_SB(0, 0), b2, voffB); PG8_STAGE(PG8_SB(0, 1), b2 + hstepB, voffB); PG8_STAGE(PG8_SA(0, 0), a2, voffA);
;             PG8_WAIT_V(8); PG8_WAIT_L(0); PG8_BAR; PG8_MMA(1, 0, At, B0); PG8_MMA(1, 1, At, B1); PG8_BAR; PG8_SCHED;
	s_waitcnt lgkmcnt(0)
	v_mfma_f32_16x16x32_bf16 v[124:127], v[146:149], v[178:181], v[124:127]
	v_mfma_f32_16x16x32_bf16 v[120:123], v[154:157], v[178:181], v[120:123]
	v_mfma_f32_16x16x32_bf16 v[116:119], v[146:149], v[186:189], v[116:119]
	v_mfma_f32_16x16x32_bf16 v[112:115], v[154:157], v[186:189], v[112:115]
	v_mfma_f32_16x16x32_bf16 v[100:103], v[146:149], v[198:201], v[100:103]
	v_mfma_f32_16x16x32_bf16 v[96:99], v[154:157], v[198:201], v[96:99]
	v_mfma_f32_16x16x32_bf16 v[84:87], v[146:149], v[206:209], v[84:87]
	v_mfma_f32_16x16x32_bf16 v[80:83], v[154:157], v[206:209], v[80:83]
	v_mfma_f32_16x16x32_bf16 v[124:127], v[150:153], v[182:185], v[124:127]
	v_mfma_f32_16x16x32_bf16 v[120:123], v[158:161], v[182:185], v[120:123]
	v_mfma_f32_16x16x32_bf16 v[116:119], v[150:153], v[194:197], v[116:119]
	v_mfma_f32_16x16x32_bf16 v[112:115], v[158:161], v[194:197], v[112:115]
	v_mfma_f32_16x16x32_bf16 v[100:103], v[150:153], v[202:205], v[100:103]
	v_mfma_f32_16x16x32_bf16 v[96:99], v[158:161], v[202:205], v[96:99]
	v_mfma_f32_16x16x32_bf16 v[84:87], v[150:153], v[210:213], v[84:87]
	v_mfma_f32_16x16x32_bf16 v[80:83], v[158:161], v[210:213], v[80:83]
	v_mfma_f32_16x16x32_bf16 v[108:111], v[162:165], v[178:181], v[108:111]
	v_mfma_f32_16x16x32_bf16 v[104:107], v[170:173], v[178:181], v[104:107]
	v_mfma_f32_16x16x32_bf16 v[92:95], v[162:165], v[186:189], v[92:95]
	v_mfma_f32_16x16x32_bf16 v[88:91], v[170:173], v[186:189], v[88:91]
	v_mfma_f32_16x16x32_bf16 v[76:79], v[162:165], v[198:201], v[76:79]
	v_mfma_f32_16x16x32_bf16 v[72:75], v[170:173], v[198:201], v[72:75]
	v_mfma_f32_16x16x32_bf16 v[68:71], v[162:165], v[206:209], v[68:71]
	v_mfma_f32_16x16x32_bf16 v[64:67], v[170:173], v[206:209], v[64:67]
	v_mfma_f32_16x16x32_bf16 v[108:111], v[166:169], v[182:185], v[108:111]
	v_mfma_f32_16x16x32_bf16 v[104:107], v[174:177], v[182:185], v[104:107]
	v_mfma_f32_16x16x32_bf16 v[92:95], v[166:169], v[194:197], v[92:95]
	v_mfma_f32_16x16x32_bf16 v[88:91], v[174:177], v[194:197], v[88:91]
	v_mfma_f32_16x16x32_bf16 v[76:79], v[166:169], v[202:205], v[76:79]
	v_mfma_f32_16x16x32_bf16 v[72:75], v[174:177], v[202:205], v[72:75]
	v_mfma_f32_16x16x32_bf16 v[68:71], v[166:169], v[210:213], v[68:71]
	v_mfma_f32_16x16x32_bf16 v[64:67], v[174:177], v[210:213], v[64:67]
	s_barrier
	s_add_i32 s48, s48, s33
	v_lshl_add_u64 v[190:191], s[24:25], 0, v[132:133]
	s_mov_b32 m0, s48
	ds_read_b128 v[178:181], v145 offset:16384
	ds_read_b128 v[182:185], v145 offset:17408
	ds_read_b128 v[186:189], v145 offset:18432
	ds_read_b128 v[194:197], v145 offset:19456
	ds_read_b128 v[198:201], v145 offset:20480
	ds_read_b128 v[202:205], v145 offset:21504
	ds_read_b128 v[206:209], v145 offset:22528
	ds_read_b128 v[210:213], v145 offset:23552
	global_load_lds_dwordx4 v[190:191], off
	s_add_i32 m0, s48, 0x2000
	s_add_u32 s48, s24, 0x40000
	v_lshl_add_u64 v[214:215], s[24:25], 0, v[128:129]
	s_addc_u32 s49, s25, 0
	s_add_i32 s50, s50, s33
	global_load_lds_dwordx4 v[214:215], off
	v_lshl_add_u64 v[216:217], s[48:49], 0, v[132:133]
	s_mov_b32 m0, s50
	v_lshl_add_u64 v[218:219], s[26:27], 0, v[130:131]
	global_load_lds_dwordx4 v[216:217], off
	v_lshl_add_u64 v[216:217], s[48:49], 0, v[128:129]
	s_add_i32 m0, s50, 0x2000
	s_nop 0
	global_load_lds_dwordx4 v[216:217], off
	v_lshl_add_u64 v[216:217], s[26:27], 0, v[134:135]
	s_mov_b32 m0, s34
	s_nop 0
	global_load_lds_dwordx4 v[216:217], off
	s_mov_b32 m0, s35
	s_nop 0
	global_load_lds_dwordx4 v[218:219], off
	s_waitcnt vmcnt(8)
	s_waitcnt lgkmcnt(0)
	s_barrier
	s_waitcnt lgkmcnt(0)
	v_mfma_f32_16x16x32_bf16 v[60:63], v[146:149], v[178:181], v[60:63]
	v_mfma_f32_16x16x32_bf16 v[56:59], v[154:157], v[178:181], v[56:59]
	v_mfma_f32_16x16x32_bf16 v[52:55], v[146:149], v[186:189], v[52:55]
	v_mfma_f32_16x16x32_bf16 v[48:51], v[154:157], v[186:189], v[48:51]
	v_mfma_f32_16x16x32_bf16 v[36:39], v[146:149], v[198:201], v[36:39]
	v_mfma_f32_16x16x32_bf16 v[32:35], v[154:157], v[198:201], v[32:35]
	v_mfma_f32_16x16x32_bf16 v[20:23], v[146:149], v[206:209], v[20:23]
	v_mfma_f32_16x16x32_bf16 v[16:19], v[154:157], v[206:209], v[16:19]
	v_mfma_f32_16x16x32_bf16 v[60:63], v[150:153], v[182:185], v[60:63]
	v_mfma_f32_16x16x32_bf16 v[56:59], v[158:161], v[182:185], v[56:59]
	v_mfma_f32_16x16x32_bf16 v[52:55], v[150:153], v[194:197], v[52:55]
	v_mfma_f32_16x16x32_bf16 v[48:51], v[158:161], v[194:197], v[48:51]
	v_mfma_f32_16x16x32_bf16 v[36:39], v[150:153], v[202:205], v[36:39]
	v_mfma_f32_16x16x32_bf16 v[32:35], v[158:161], v[202:205], v[32:35]
	v_mfma_f32_16x16x32_bf16 v[20:23], v[150:153], v[210:213], v[20:23]
	v_mfma_f32_16x16x32_bf16 v[16:19], v[158:161], v[210:213], v[16:19]
	v_mfma_f32_16x16x32_bf16 v[44:47], v[162:165], v[178:181], v[44:47]
	v_mfma_f32_16x16x32_bf16 v[40:43], v[170:173], v[178:181], v[40:43]
	v_mfma_f32_16x16x32_bf16 v[28:31], v[162:165], v[186:189], v[28:31]
	v_mfma_f32_16x16x32_bf16 v[24:27], v[170:173], v[186:189], v[24:27]
	v_mfma_f32_16x16x32_bf16 v[12:15], v[162:165], v[198:201], v[12:15]
	v_mfma_f32_16x16x32_bf16 v[8:11], v[170:173], v[198:201], v[8:11]
	v_mfma_f32_16x16x32_bf16 v[4:7], v[162:165], v[206:209], v[4:7]
	v_mfma_f32_16x16x32_bf16 v[0:3], v[170:173], v[206:209], v[0:3]
	v_mfma_f32_16x16x32_bf16 v[44:47], v[166:169], v[182:185], v[44:47]
	v_mfma_f32_16x16x32_bf16 v[40:43], v[174:177], v[182:185], v[40:43]
	v_mfma_f32_16x16x32_bf16 v[28:31], v[166:169], v[194:197], v[28:31]
	v_mfma_f32_16x16x32_bf16 v[24:27], v[174:177], v[194:197], v[24:27]
	v_mfma_f32_16x16x32_bf16 v[12:15], v[166:169], v[202:205], v[12:15]
	v_mfma_f32_16x16x32_bf16 v[8:11], v[174:177], v[202:205], v[8:11]
	v_mfma_f32_16x16x32_bf16 v[4:7], v[166:169], v[210:213], v[4:7]
	v_mfma_f32_16x16x32_bf16 v[0:3], v[174:177], v[210:213], v[0:3]
	s_barrier
; #define PG8_STAGE(bufoff, gbase, voff) do { _Pragma("unroll") for (int _i = 0; _i < 2; ++_i) \
;         __builtin_amdgcn_global_load_lds((const unsigned*)((const char*)(gbase) + (voff)[_i]), (LAS unsigned*)(lds + (bufoff) + ldsw + _i * 8192), 16, 0, 0); } while (0)
; #define PG8_LDA(dst, b, h) do { _Pragma("unroll") for (int m = 0; m < 4; ++m) _Pragma("unroll") for (int k = 0; k < 2; ++k) dst[m][k] = *(const LAS bf16x8*)(lds + PG8_SA(b, h) + aoff + m * 2048 + k * 1024); } while (0)
; #define PG8_LDB(dst, b, h) do { _Pragma("unroll") for (int n = 0; n < 2; ++n) _Pragma("unroll") for (int k = 0; k < 2; ++k) dst[n][k] = *(const LAS bf16x8*)(lds + PG8_SB(b, h) + boff + n * 2048 + k * 1024); } while (0)
; #define PG8_MMA(ai, bj, At, Bt) do { __builtin_amdgcn_s_setprio(1); _Pragma("unroll") for (int m = 0; m < 4; ++m) _Pragma("unroll") for (int n = 0; n < 2; ++n) _Pragma("unroll") for (int k = 0; k < 2; ++k) \
;         acc[ai][bj][m][n] = __builtin_amdgcn_mfma_f32_16x16x32_bf16(Bt[n][k], At[m][k], acc[ai][bj][m][n], 0, 0, 0); __builtin_amdgcn_s_setprio(0); } while (0)
; #define PG8_WAIT_V(n) asm volatile("s_waitcnt vmcnt(" #n ")" ::: "memory")
; #define PG8_WAIT_L(n) asm volatile("s_waitcnt lgkmcnt(" #n ")" ::: "memory")
; #define PG8_BAR __builtin_amdgcn_s_barrier()
; #define PG8_SCHED __builtin_amdgcn_sched_barrier(0)
; template <class Epi>
; DI void gemm_phase(int wv, LAS unsigned char* lds, LAS unsigned char* scr, const Sched& S, const Epi& E) {
;     ...
;             PG8_LDB(B0, 1, 0); PG8_LDB(B1, 1, 1); PG8_SCHED; PG8_LDA(At, 1, 0); PG8_STAGE(PG8_SA(0, 1), a2 + hstepA, voffA);
;             PG8_WAIT_V(8); PG8_WAIT_L(0); PG8_BAR; PG8_MMA(0, 0, At, B0); PG8_MMA(0, 1, At, B1); PG8_BAR; PG8_SCHED;
	s_add_i32 s48, 0, 0x18000
	v_add_u32_e32 v143, s48, v144
	s_add_i32 s49, 0, 0x1c000
	ds_read_b128 v[146:149], v143
	ds_read_b128 v[150:153], v143 offset:1024
	ds_read_b128 v[154:157], v143 offset:2048
	ds_read_b128 v[158:161], v143 offset:3072
	v_add_u32_e32 v143, s49, v144
	ds_read_b128 v[162:165], v143
	ds_read_b128 v[166:169], v143 offset:1024
	ds_read_b128 v[170:173], v143 offset:2048
	ds_read_b128 v[174:177], v143 offset:3072
	s_add_u32 s26, s26, 0x40000
	s_addc_u32 s27, s27, 0
	s_mov_b32 m0, s36
	v_lshl_add_u64 v[220:221], s[26:27], 0, v[134:135]
	ds_read_b128 v[178:181], v145 offset:32768
	ds_read_b128 v[182:185], v145 offset:33792
	ds_read_b128 v[186:189], v145 offset:34816
	ds_read_b128 v[194:197], v145 offset:35840
	ds_read_b128 v[198:201], v145 offset:36864
	ds_read_b128 v[202:205], v145 offset:37888
	ds_read_b128 v[206:209], v145 offset:38912
	ds_read_b128 v[210:213], v145 offset:39936
	global_load_lds_dwordx4 v[220:221], off
	v_lshl_add_u64 v[220:221], s[26:27], 0, v[130:131]
	s_mov_b32 m0, s37
	s_nop 0
	global_load_lds_dwordx4 v[220:221], off
	s_waitcnt vmcnt(8)
	s_waitcnt lgkmcnt(0)
	s_barrier
	s_waitcnt lgkmcnt(0)
	v_mfma_f32_16x16x32_bf16 v[124:127], v[146:149], v[178:181], v[124:127]
	v_mfma_f32_16x16x32_bf16 v[120:123], v[154:157], v[178:181], v[120:123]
	v_mfma_f32_16x16x32_bf16 v[116:119], v[146:149], v[186:189], v[116:119]
	v_mfma_f32_16x16x32_bf16 v[112:115], v[154:157], v[186:189], v[112:115]
	v_mfma_f32_16x16x32_bf16 v[100:103], v[146:149], v[198:201], v[100:103]
	v_mfma_f32_16x16x32_bf16 v[96:99], v[154:157], v[198:201], v[96:99]
	v_mfma_f32_16x16x32_bf16 v[84:87], v[146:149], v[206:209], v[84:87]
	v_mfma_f32_16x16x32_bf16 v[80:83], v[154:157], v[206:209], v[80:83]
	v_mfma_f32_16x16x32_bf16 v[124:127], v[150:153], v[182:185], v[124:127]
	v_mfma_f32_16x16x32_bf16 v[120:123], v[158:161], v[182:185], v[120:123]
	v_mfma_f32_16x16x32_bf16 v[116:119], v[150:153], v[194:197], v[116:119]
	v_mfma_f32_16x16x32_bf16 v[112:115], v[158:161], v[194:197], v[112:115]
	v_mfma_f32_16x16x32_bf16 v[100:103], v[150:153], v[202:205], v[100:103]
	v_mfma_f32_16x16x32_bf16 v[96:99], v[158:161], v[202:205], v[96:99]
	v_mfma_f32_16x16x32_bf16 v[84:87], v[150:153], v[210:213], v[84:87]
	v_mfma_f32_16x16x32_bf16 v[80:83], v[158:161], v[210:213], v[80:83]
	v_mfma_f32_16x16x32_bf16 v[108:111], v[162:165], v[178:181], v[108:111]
	v_mfma_f32_16x16x32_bf16 v[104:107], v[170:173], v[178:181], v[104:107]
	v_mfma_f32_16x16x32_bf16 v[92:95], v[162:165], v[186:189], v[92:95]
	v_mfma_f32_16x16x32_bf16 v[88:91], v[170:173], v[186:189], v[88:91]
	v_mfma_f32_16x16x32_bf16 v[76:79], v[162:165], v[198:201], v[76:79]
	v_mfma_f32_16x16x32_bf16 v[72:75], v[170:173], v[198:201], v[72:75]
	v_mfma_f32_16x16x32_bf16 v[68:71], v[162:165], v[206:209], v[68:71]
	v_mfma_f32_16x16x32_bf16 v[64:67], v[170:173], v[206:209], v[64:67]
	v_mfma_f32_16x16x32_bf16 v[108:111], v[166:169], v[182:185], v[108:111]
	v_mfma_f32_16x16x32_bf16 v[104:107], v[174:177], v[182:185], v[104:107]
	v_mfma_f32_16x16x32_bf16 v[92:95], v[166:169], v[194:197], v[92:95]
	v_mfma_f32_16x16x32_bf16 v[88:91], v[174:177], v[194:197], v[88:91]
	v_mfma_f32_16x16x32_bf16 v[76:79], v[166:169], v[202:205], v[76:79]
	v_mfma_f32_16x16x32_bf16 v[72:75], v[174:177], v[202:205], v[72:75]
	v_mfma_f32_16x16x32_bf16 v[68:71], v[166:169], v[210:213], v[68:71]
	v_mfma_f32_16x16x32_bf16 v[64:67], v[174:177], v[210:213], v[64:67]
	s_barrier
; #define PG8_STAGE(bufoff, gbase, voff) do { _Pragma("unroll") for (int _i = 0; _i < 2; ++_i) \
;         __builtin_amdgcn_global_load_lds((const unsigned*)((const char*)(gbase) + (voff)[_i]), (LAS unsigned*)(lds + (bufoff) + ldsw + _i * 8192), 16, 0, 0); } while (0)
; #define PG8_LDA(dst, b, h) do { _Pragma("unroll") for (int m = 0; m < 4; ++m) _Pragma("unroll") for (int k = 0; k < 2; ++k) dst[m][k] = *(const LAS bf16x8*)(lds + PG8_SA(b, h) + aoff + m * 2048 + k * 1024); } while (0)
; #define PG8_MMA(ai, bj, At, Bt) do { __builtin_amdgcn_s_setprio(1); _Pragma("unroll") for (int m = 0; m < 4; ++m) _Pragma("unroll") for (int n = 0; n < 2; ++n) _Pragma("unroll") for (int k = 0; k < 2; ++k) \
;         acc[ai][bj][m][n] = __builtin_amdgcn_mfma_f32_16x16x32_bf16(Bt[n][k], At[m][k], acc[ai][bj][m][n], 0, 0, 0); __builtin_amdgcn_s_setprio(0); } while (0)
; #define PG8_WAIT_V(n) asm volatile("s_waitcnt vmcnt(" #n ")" ::: "memory")
; #define PG8_WAIT_L(n) asm volatile("s_waitcnt lgkmcnt(" #n ")" ::: "memory")
; #define PG8_BAR __builtin_amdgcn_s_barrier()
; #define PG8_SCHED __builtin_amdgcn_sched_barrier(0)
; template <class Epi>
; DI void gemm_phase(int wv, LAS unsigned char* lds, LAS unsigned char* scr, const Sched& S, const Epi& E) {
;     ...
;             PG8_LDA(At, 1, 1); PG8_STAGE(PG8_SB(1, 0), b3, voffB); PG8_STAGE(PG8_SB(1, 1), b3 + hstepB, voffB); PG8_STAGE(PG8_SA(1, 0), a3, voffA);
;             PG8_WAIT_V(8); PG8_WAIT_L(0); PG8_BAR; PG8_MMA(1, 0, At, B0); PG8_MMA(1, 1, At, B1); PG8_BAR; PG8_SCHED;
;         }
;         if (wr == 0) PG8_BAR;
	s_add_i32 s26, s48, s33
	v_lshl_add_u64 v[190:191], v[190:191], 0, s[2:3]
	s_mov_b32 m0, s26
	ds_read_b128 v[178:181], v145 offset:49152
	ds_read_b128 v[182:185], v145 offset:50176
	ds_read_b128 v[186:189], v145 offset:51200
	ds_read_b128 v[194:197], v145 offset:52224
	ds_read_b128 v[198:201], v145 offset:53248
	ds_read_b128 v[202:205], v145 offset:54272
	ds_read_b128 v[206:209], v145 offset:55296
	ds_read_b128 v[210:213], v145 offset:56320
	global_load_lds_dwordx4 v[190:191], off
	s_add_i32 m0, s26, 0x2000
	s_add_u32 s24, s24, 0x40080
	v_lshl_add_u64 v[190:191], v[214:215], 0, s[2:3]
	s_addc_u32 s25, s25, 0
	s_add_i32 s26, s49, s33
	global_load_lds_dwordx4 v[190:191], off
	v_lshl_add_u64 v[190:191], s[24:25], 0, v[132:133]
	s_mov_b32 m0, s26
	s_nop 0
	global_load_lds_dwordx4 v[190:191], off
	v_lshl_add_u64 v[190:191], s[24:25], 0, v[128:129]
	s_add_i32 m0, s26, 0x2000
	s_nop 0
	global_load_lds_dwordx4 v[190:191], off
	v_lshl_add_u64 v[190:191], v[216:217], 0, s[2:3]
	s_mov_b32 m0, s42
	s_nop 0
	global_load_lds_dwordx4 v[190:191], off
	v_lshl_add_u64 v[190:191], v[218:219], 0, s[2:3]
	s_mov_b32 m0, s43
	s_nop 0
	global_load_lds_dwordx4 v[190:191], off
	s_waitcnt vmcnt(8)
	s_waitcnt lgkmcnt(0)
	s_barrier
	s_waitcnt lgkmcnt(0)
	v_mfma_f32_16x16x32_bf16 v[60:63], v[146:149], v[178:181], v[60:63]
	v_mfma_f32_16x16x32_bf16 v[56:59], v[154:157], v[178:181], v[56:59]
	v_mfma_f32_16x16x32_bf16 v[52:55], v[146:149], v[186:189], v[52:55]
	v_mfma_f32_16x16x32_bf16 v[48:51], v[154:157], v[186:189], v[48:51]
	v_mfma_f32_16x16x32_bf16 v[36:39], v[146:149], v[198:201], v[36:39]
	v_mfma_f32_16x16x32_bf16 v[32:35], v[154:157], v[198:201], v[32:35]
	v_mfma_f32_16x16x32_bf16 v[20:23], v[146:149], v[206:209], v[20:23]
	v_mfma_f32_16x16x32_bf16 v[16:19], v[154:157], v[206:209], v[16:19]
	v_mfma_f32_16x16x32_bf16 v[60:63], v[150:153], v[182:185], v[60:63]
	v_mfma_f32_16x16x32_bf16 v[56:59], v[158:161], v[182:185], v[56:59]
	v_mfma_f32_16x16x32_bf16 v[52:55], v[150:153], v[194:197], v[52:55]
	v_mfma_f32_16x16x32_bf16 v[48:51], v[158:161], v[194:197], v[48:51]
	v_mfma_f32_16x16x32_bf16 v[36:39], v[150:153], v[202:205], v[36:39]
	v_mfma_f32_16x16x32_bf16 v[32:35], v[158:161], v[202:205], v[32:35]
	v_mfma_f32_16x16x32_bf16 v[20:23], v[150:153], v[210:213], v[20:23]
	v_mfma_f32_16x16x32_bf16 v[16:19], v[158:161], v[210:213], v[16:19]
	v_mfma_f32_16x16x32_bf16 v[44:47], v[162:165], v[178:181], v[44:47]
	v_mfma_f32_16x16x32_bf16 v[40:43], v[170:173], v[178:181], v[40:43]
	v_mfma_f32_16x16x32_bf16 v[28:31], v[162:165], v[186:189], v[28:31]
	v_mfma_f32_16x16x32_bf16 v[24:27], v[170:173], v[186:189], v[24:27]
	v_mfma_f32_16x16x32_bf16 v[12:15], v[162:165], v[198:201], v[12:15]
	v_mfma_f32_16x16x32_bf16 v[8:11], v[170:173], v[198:201], v[8:11]
	v_mfma_f32_16x16x32_bf16 v[4:7], v[162:165], v[206:209], v[4:7]
	v_mfma_f32_16x16x32_bf16 v[0:3], v[170:173], v[206:209], v[0:3]
	v_mfma_f32_16x16x32_bf16 v[44:47], v[166:169], v[182:185], v[44:47]
	v_mfma_f32_16x16x32_bf16 v[40:43], v[174:177], v[182:185], v[40:43]
	v_mfma_f32_16x16x32_bf16 v[28:31], v[166:169], v[194:197], v[28:31]
	v_mfma_f32_16x16x32_bf16 v[24:27], v[174:177], v[194:197], v[24:27]
	v_mfma_f32_16x16x32_bf16 v[12:15], v[166:169], v[202:205], v[12:15]
	v_mfma_f32_16x16x32_bf16 v[8:11], v[174:177], v[202:205], v[8:11]
	v_mfma_f32_16x16x32_bf16 v[4:7], v[166:169], v[210:213], v[4:7]
	v_mfma_f32_16x16x32_bf16 v[0:3], v[174:177], v[210:213], v[0:3]
	s_barrier
	s_add_i32 s47, s47, 2
	s_add_u32 s45, s45, 0x100
	s_addc_u32 s46, s46, 0
	s_add_u32 s22, s22, 0x100
	s_addc_u32 s23, s23, 0
	s_cmp_gt_u32 s47, 13
	s_cbranch_scc0 .LBB0_463
	s_setprio 0
	s_and_b64 vcc, exec, s[8:9]
	s_cbranch_vccz .LBB0_466
	s_barrier

; #define PG8_STAGE(bufoff, gbase, voff) do { _Pragma("unroll") for (int _i = 0; _i < 2; ++_i) \
;         __builtin_amdgcn_global_load_lds((const unsigned*)((const char*)(gbase) + (voff)[_i]), (LAS unsigned*)(lds + (bufoff) + ldsw + _i * 8192), 16, 0, 0); } while (0)
; #define PG8_LDA(dst, b, h) do { _Pragma("unroll") for (int m = 0; m < 4; ++m) _Pragma("unroll") for (int k = 0; k < 2; ++k) dst[m][k] = *(const LAS bf16x8*)(lds + PG8_SA(b, h) + aoff + m * 2048 + k * 1024); } while (0)
; #define PG8_LDB(dst, b, h) do { _Pragma("unroll") for (int n = 0; n < 2; ++n) _Pragma("unroll") for (int k = 0; k < 2; ++k) dst[n][k] = *(const LAS bf16x8*)(lds + PG8_SB(b, h) + boff + n * 2048 + k * 1024); } while (0)
; #define PG8_SCHED __builtin_amdgcn_sched_barrier(0)
; template <class Epi>
; DI void gemm_phase(int wv, LAS unsigned char* lds, LAS unsigned char* scr, const Sched& S, const Epi& E) {
;     ...
;         const bool has_next = S.next(ui + 1, nxt);
;         const char* nA = has_next ? S.baseA(nxt) : cA; const char* nB = has_next ? S.baseB(nxt) : cB;
;         for (int t = 0; t < nt; t += 2) {
;             const bool last = (t == nt - 2);
;             const char* a1 = cA + (size_t)(t + 1) * kstep;
;             const char* a2 = last ? nA : cA + (size_t)(t + 2) * kstep; const char* b2 = last ? nB : cB + (size_t)(t + 2) * kstep;
;             const char* a3 = a2 + kstep; const char* b3 = b2 + kstep;
;             PG8_LDB(B0, 0, 0); PG8_LDB(B1, 0, 1); PG8_SCHED; PG8_LDA(At, 0, 0); PG8_STAGE(PG8_SA(1, 1), a1 + hstepA, voffA);
;     ...
; #pragma unroll
;         for (int a = 0; a < 2; ++a)
; #pragma unroll
;             for (int b = 0; b < 2; ++b)
; #pragma unroll
;                 for (int m = 0; m < 4; ++m)
; #pragma unroll
;                     for (int n = 0; n < 2; ++n) acc[a][b][m][n] = (f32x4){0.f, 0.f, 0.f, 0.f};
;         cur = nxt; cA = nA; cB = nB; ++ui;
.LBB0_587:
	s_ashr_i32 s19, s18, 31
	s_lshl_b64 s[22:23], s[18:19], 19
	s_add_u32 s22, s34, s22
	s_addc_u32 s23, s35, s23
	s_and_b64 s[12:13], s[12:13], exec
	s_cselect_b32 s17, s23, s29
	s_cselect_b32 s19, s22, s28
	s_add_u32 s25, s30, 0x100
	s_addc_u32 s27, s31, 0
	s_add_u32 s12, s28, 0x40080
	v_mov_b32_e32 v0, 0
	s_addc_u32 s13, s29, 0
	s_mov_b32 s33, -2
	v_mov_b32_e32 v1, v0
	v_mov_b32_e32 v2, v0
	v_mov_b32_e32 v3, v0
	v_mov_b32_e32 v4, v0
	v_mov_b32_e32 v5, v0
	v_mov_b32_e32 v6, v0
	v_mov_b32_e32 v7, v0
	v_mov_b32_e32 v16, v0
	v_mov_b32_e32 v17, v0
	v_mov_b32_e32 v18, v0
	v_mov_b32_e32 v19, v0
	v_mov_b32_e32 v20, v0
	v_mov_b32_e32 v21, v0
	v_mov_b32_e32 v22, v0
	v_mov_b32_e32 v23, v0
	v_mov_b32_e32 v32, v0
	v_mov_b32_e32 v33, v0
	v_mov_b32_e32 v34, v0
	v_mov_b32_e32 v35, v0
	v_mov_b32_e32 v36, v0
	v_mov_b32_e32 v37, v0
	v_mov_b32_e32 v38, v0
	v_mov_b32_e32 v39, v0
	v_mov_b32_e32 v48, v0
	v_mov_b32_e32 v49, v0
	v_mov_b32_e32 v50, v0
	v_mov_b32_e32 v51, v0
	v_mov_b32_e32 v52, v0
	v_mov_b32_e32 v53, v0
	v_mov_b32_e32 v54, v0
	v_mov_b32_e32 v55, v0
	v_mov_b32_e32 v8, v0
	v_mov_b32_e32 v9, v0
	v_mov_b32_e32 v10, v0
	v_mov_b32_e32 v11, v0
	v_mov_b32_e32 v12, v0
	v_mov_b32_e32 v13, v0
	v_mov_b32_e32 v14, v0
	v_mov_b32_e32 v15, v0
	v_mov_b32_e32 v24, v0
	v_mov_b32_e32 v25, v0
	v_mov_b32_e32 v26, v0
	v_mov_b32_e32 v27, v0
	v_mov_b32_e32 v28, v0
	v_mov_b32_e32 v29, v0
	v_mov_b32_e32 v30, v0
	v_mov_b32_e32 v31, v0
	v_mov_b32_e32 v40, v0
	v_mov_b32_e32 v41, v0
	v_mov_b32_e32 v42, v0
	v_mov_b32_e32 v43, v0
	v_mov_b32_e32 v44, v0
	v_mov_b32_e32 v45, v0
	v_mov_b32_e32 v46, v0
	v_mov_b32_e32 v47, v0
	v_mov_b32_e32 v56, v0
	v_mov_b32_e32 v57, v0
	v_mov_b32_e32 v58, v0
	v_mov_b32_e32 v59, v0
	v_mov_b32_e32 v60, v0
	v_mov_b32_e32 v61, v0
	v_mov_b32_e32 v62, v0
	v_mov_b32_e32 v63, v0
	v_mov_b32_e32 v64, v0
	v_mov_b32_e32 v65, v0
	v_mov_b32_e32 v66, v0
	v_mov_b32_e32 v67, v0
	v_mov_b32_e32 v68, v0
	v_mov_b32_e32 v69, v0
	v_mov_b32_e32 v70, v0
	v_mov_b32_e32 v71, v0
	v_mov_b32_e32 v80, v0
	v_mov_b32_e32 v81, v0
	v_mov_b32_e32 v82, v0
	v_mov_b32_e32 v83, v0
	v_mov_b32_e32 v84, v0
	v_mov_b32_e32 v85, v0
	v_mov_b32_e32 v86, v0
	v_mov_b32_e32 v87, v0
	v_mov_b32_e32 v96, v0
	v_mov_b32_e32 v97, v0
	v_mov_b32_e32 v98, v0
	v_mov_b32_e32 v99, v0
	v_mov_b32_e32 v100, v0
	v_mov_b32_e32 v101, v0
	v_mov_b32_e32 v102, v0
	v_mov_b32_e32 v103, v0
	v_mov_b32_e32 v112, v0
	v_mov_b32_e32 v113, v0
	v_mov_b32_e32 v114, v0
	v_mov_b32_e32 v115, v0
	v_mov_b32_e32 v116, v0
	v_mov_b32_e32 v117, v0
	v_mov_b32_e32 v118, v0
	v_mov_b32_e32 v119, v0
	v_mov_b32_e32 v72, v0
	v_mov_b32_e32 v73, v0
	v_mov_b32_e32 v74, v0
	v_mov_b32_e32 v75, v0
	v_mov_b32_e32 v76, v0
	v_mov_b32_e32 v77, v0
	v_mov_b32_e32 v78, v0
	v_mov_b32_e32 v79, v0
	v_mov_b32_e32 v88, v0
	v_mov_b32_e32 v89, v0
	v_mov_b32_e32 v90, v0
	v_mov_b32_e32 v91, v0
	v_mov_b32_e32 v92, v0
	v_mov_b32_e32 v93, v0
	v_mov_b32_e32 v94, v0
	v_mov_b32_e32 v95, v0
	v_mov_b32_e32 v104, v0
	v_mov_b32_e32 v105, v0
	v_mov_b32_e32 v106, v0
	v_mov_b32_e32 v107, v0
	v_mov_b32_e32 v108, v0
	v_mov_b32_e32 v109, v0
	v_mov_b32_e32 v110, v0
	v_mov_b32_e32 v111, v0
	v_mov_b32_e32 v120, v0
	v_mov_b32_e32 v121, v0
	v_mov_b32_e32 v122, v0
	v_mov_b32_e32 v123, v0
	v_mov_b32_e32 v124, v0
	v_mov_b32_e32 v125, v0
	v_mov_b32_e32 v126, v0
	v_mov_b32_e32 v127, v0
	s_cmp_lg_u64 s[14:15], 0
	s_cbranch_scc1 .Lgp_11
	s_setprio 1
.Lgp_11:
.LBB0_588:
	s_add_u32 s28, s12, 0xfffc0080
	s_addc_u32 s29, s13, -1
	s_add_i32 s49, 0, 0x10000
	s_cmp_eq_u32 s33, 12
	s_cselect_b32 s31, s17, s29
	s_cselect_b32 s30, s19, s28
	v_add_u32_e32 v143, s49, v146
	s_cselect_b32 s29, s21, s27
	s_cselect_b32 s28, s20, s25
	s_add_i32 s52, 0, 0x14000
	ds_read_b128 v[168:171], v143
	ds_read_b128 v[172:175], v143 offset:1024
	ds_read_b128 v[176:179], v143 offset:2048
	ds_read_b128 v[180:183], v143 offset:3072
	v_add_u32_e32 v143, s52, v146
	ds_read_b128 v[184:187], v143
	ds_read_b128 v[188:191], v143 offset:1024
	ds_read_b128 v[194:197], v143 offset:2048
	ds_read_b128 v[198:201], v143 offset:3072
	v_lshl_add_u64 v[144:145], s[12:13], 0, v[140:141]
	s_add_i32 m0, s39, 0xc000
	ds_read_b128 v[202:205], v166
	ds_read_b128 v[206:209], v166 offset:1024
	ds_read_b128 v[210:213], v166 offset:2048
	ds_read_b128 v[214:217], v166 offset:3072
	ds_read_b128 v[218:221], v166 offset:4096
	ds_read_b128 v[222:225], v166 offset:5120
	ds_read_b128 v[226:229], v166 offset:6144
	ds_read_b128 v[230:233], v166 offset:7168
	global_load_lds_dwordx4 v[144:145], off
	v_lshl_add_u64 v[144:145], s[12:13], 0, v[138:139]
	s_add_i32 m0, s39, 0xe000
	s_nop 0
	global_load_lds_dwordx4 v[144:145], off
	s_waitcnt vmcnt(8)
	s_waitcnt lgkmcnt(0)
	s_barrier
; #define PG8_STAGE(bufoff, gbase, voff) do { _Pragma("unroll") for (int _i = 0; _i < 2; ++_i) \
;         __builtin_amdgcn_global_load_lds((const unsigned*)((const char*)(gbase) + (voff)[_i]), (LAS unsigned*)(lds + (bufoff) + ldsw + _i * 8192), 16, 0, 0); } while (0)
; #define PG8_LDA(dst, b, h) do { _Pragma("unroll") for (int m = 0; m < 4; ++m) _Pragma("unroll") for (int k = 0; k < 2; ++k) dst[m][k] = *(const LAS bf16x8*)(lds + PG8_SA(b, h) + aoff + m * 2048 + k * 1024); } while (0)
; #define PG8_MMA(ai, bj, At, Bt) do { __builtin_amdgcn_s_setprio(1); _Pragma("unroll") for (int m = 0; m < 4; ++m) _Pragma("unroll") for (int n = 0; n < 2; ++n) _Pragma("unroll") for (int k = 0; k < 2; ++k) \
;         acc[ai][bj][m][n] = __builtin_amdgcn_mfma_f32_16x16x32_bf16(Bt[n][k], At[m][k], acc[ai][bj][m][n], 0, 0, 0); __builtin_amdgcn_s_setprio(0); } while (0)
; #define PG8_WAIT_V(n) asm volatile("s_waitcnt vmcnt(" #n ")" ::: "memory")
; #define PG8_WAIT_L(n) asm volatile("s_waitcnt lgkmcnt(" #n ")" ::: "memory")
; #define PG8_BAR __builtin_amdgcn_s_barrier()
; #define PG8_SCHED __builtin_amdgcn_sched_barrier(0)
; template <class Epi>
; DI void gemm_phase(int wv, LAS unsigned char* lds, LAS unsigned char* scr, const Sched& S, const Epi& E) {
;     ...
;             PG8_WAIT_V(8); PG8_WAIT_L(0); PG8_BAR; PG8_MMA(0, 0, At, B0); PG8_MMA(0, 1, At, B1); PG8_BAR; PG8_SCHED;
;             PG8_LDA(At, 0, 1); PG8_STAGE(PG8_SB(0, 0), b2, voffB); PG8_STAGE(PG8_SB(0, 1), b2 + hstepB, voffB); PG8_STAGE(PG8_SA(0, 0), a2, voffA);
;             PG8_WAIT_V(8); PG8_WAIT_L(0); PG8_BAR; PG8_MMA(1, 0, At, B0); PG8_MMA(1, 1, At, B1); PG8_BAR; PG8_SCHED;
	s_waitcnt lgkmcnt(0)
	v_mfma_f32_16x16x32_bf16 v[124:127], v[168:171], v[202:205], v[124:127]
	v_mfma_f32_16x16x32_bf16 v[120:123], v[176:179], v[202:205], v[120:123]
	v_mfma_f32_16x16x32_bf16 v[108:111], v[168:171], v[210:213], v[108:111]
	v_mfma_f32_16x16x32_bf16 v[104:107], v[176:179], v[210:213], v[104:107]
	v_mfma_f32_16x16x32_bf16 v[92:95], v[168:171], v[218:221], v[92:95]
	v_mfma_f32_16x16x32_bf16 v[88:91], v[176:179], v[218:221], v[88:91]
	v_mfma_f32_16x16x32_bf16 v[76:79], v[168:171], v[226:229], v[76:79]
	v_mfma_f32_16x16x32_bf16 v[72:75], v[176:179], v[226:229], v[72:75]
	v_mfma_f32_16x16x32_bf16 v[124:127], v[172:175], v[206:209], v[124:127]
	v_mfma_f32_16x16x32_bf16 v[120:123], v[180:183], v[206:209], v[120:123]
	v_mfma_f32_16x16x32_bf16 v[108:111], v[172:175], v[214:217], v[108:111]
	v_mfma_f32_16x16x32_bf16 v[104:107], v[180:183], v[214:217], v[104:107]
	v_mfma_f32_16x16x32_bf16 v[92:95], v[172:175], v[222:225], v[92:95]
	v_mfma_f32_16x16x32_bf16 v[88:91], v[180:183], v[222:225], v[88:91]
	v_mfma_f32_16x16x32_bf16 v[76:79], v[172:175], v[230:233], v[76:79]
	v_mfma_f32_16x16x32_bf16 v[72:75], v[180:183], v[230:233], v[72:75]
	v_mfma_f32_16x16x32_bf16 v[116:119], v[184:187], v[202:205], v[116:119]
	v_mfma_f32_16x16x32_bf16 v[112:115], v[194:197], v[202:205], v[112:115]
	v_mfma_f32_16x16x32_bf16 v[100:103], v[184:187], v[210:213], v[100:103]
	v_mfma_f32_16x16x32_bf16 v[96:99], v[194:197], v[210:213], v[96:99]
	v_mfma_f32_16x16x32_bf16 v[84:87], v[184:187], v[218:221], v[84:87]
	v_mfma_f32_16x16x32_bf16 v[80:83], v[194:197], v[218:221], v[80:83]
	v_mfma_f32_16x16x32_bf16 v[68:71], v[184:187], v[226:229], v[68:71]
	v_mfma_f32_16x16x32_bf16 v[64:67], v[194:197], v[226:229], v[64:67]
	v_mfma_f32_16x16x32_bf16 v[116:119], v[188:191], v[206:209], v[116:119]
	v_mfma_f32_16x16x32_bf16 v[112:115], v[198:201], v[206:209], v[112:115]
	v_mfma_f32_16x16x32_bf16 v[100:103], v[188:191], v[214:217], v[100:103]
	v_mfma_f32_16x16x32_bf16 v[96:99], v[198:201], v[214:217], v[96:99]
	v_mfma_f32_16x16x32_bf16 v[84:87], v[188:191], v[222:225], v[84:87]
	v_mfma_f32_16x16x32_bf16 v[80:83], v[198:201], v[222:225], v[80:83]
	v_mfma_f32_16x16x32_bf16 v[68:71], v[188:191], v[230:233], v[68:71]
	v_mfma_f32_16x16x32_bf16 v[64:67], v[198:201], v[230:233], v[64:67]
	s_barrier
	s_add_i32 s49, s49, s38
	v_lshl_add_u64 v[144:145], s[28:29], 0, v[130:131]
	s_mov_b32 m0, s49
	ds_read_b128 v[202:205], v166 offset:16384
	ds_read_b128 v[206:209], v166 offset:17408
	ds_read_b128 v[210:213], v166 offset:18432
	ds_read_b128 v[214:217], v166 offset:19456
	ds_read_b128 v[218:221], v166 offset:20480
	ds_read_b128 v[222:225], v166 offset:21504
	ds_read_b128 v[226:229], v166 offset:22528
	ds_read_b128 v[230:233], v166 offset:23552
	global_load_lds_dwordx4 v[144:145], off
	s_add_i32 m0, s49, 0x2000
	s_add_u32 s50, s28, 0x40000
	v_lshl_add_u64 v[234:235], s[28:29], 0, v[134:135]
	s_addc_u32 s51, s29, 0
	s_add_i32 s49, s52, s38
	global_load_lds_dwordx4 v[234:235], off
	v_lshl_add_u64 v[236:237], s[50:51], 0, v[130:131]
	s_mov_b32 m0, s49
	v_lshl_add_u64 v[238:239], s[30:31], 0, v[132:133]
	global_load_lds_dwordx4 v[236:237], off
	v_lshl_add_u64 v[236:237], s[50:51], 0, v[134:135]
	s_add_i32 m0, s49, 0x2000
	s_nop 0
	global_load_lds_dwordx4 v[236:237], off
	v_lshl_add_u64 v[236:237], s[30:31], 0, v[128:129]
	s_mov_b32 m0, s39
	s_nop 0
	global_load_lds_dwordx4 v[236:237], off
	s_mov_b32 m0, s42
	s_nop 0
	global_load_lds_dwordx4 v[238:239], off
	s_waitcnt vmcnt(8)
	s_waitcnt lgkmcnt(0)
	s_barrier
	s_waitcnt lgkmcnt(0)
	v_mfma_f32_16x16x32_bf16 v[60:63], v[168:171], v[202:205], v[60:63]
	v_mfma_f32_16x16x32_bf16 v[56:59], v[176:179], v[202:205], v[56:59]
	v_mfma_f32_16x16x32_bf16 v[44:47], v[168:171], v[210:213], v[44:47]
	v_mfma_f32_16x16x32_bf16 v[40:43], v[176:179], v[210:213], v[40:43]
	v_mfma_f32_16x16x32_bf16 v[28:31], v[168:171], v[218:221], v[28:31]
	v_mfma_f32_16x16x32_bf16 v[24:27], v[176:179], v[218:221], v[24:27]
	v_mfma_f32_16x16x32_bf16 v[12:15], v[168:171], v[226:229], v[12:15]
	v_mfma_f32_16x16x32_bf16 v[8:11], v[176:179], v[226:229], v[8:11]
	v_mfma_f32_16x16x32_bf16 v[60:63], v[172:175], v[206:209], v[60:63]
	v_mfma_f32_16x16x32_bf16 v[56:59], v[180:183], v[206:209], v[56:59]
	v_mfma_f32_16x16x32_bf16 v[44:47], v[172:175], v[214:217], v[44:47]
	v_mfma_f32_16x16x32_bf16 v[40:43], v[180:183], v[214:217], v[40:43]
	v_mfma_f32_16x16x32_bf16 v[28:31], v[172:175], v[222:225], v[28:31]
	v_mfma_f32_16x16x32_bf16 v[24:27], v[180:183], v[222:225], v[24:27]
	v_mfma_f32_16x16x32_bf16 v[12:15], v[172:175], v[230:233], v[12:15]
	v_mfma_f32_16x16x32_bf16 v[8:11], v[180:183], v[230:233], v[8:11]
	v_mfma_f32_16x16x32_bf16 v[52:55], v[184:187], v[202:205], v[52:55]
	v_mfma_f32_16x16x32_bf16 v[48:51], v[194:197], v[202:205], v[48:51]
	v_mfma_f32_16x16x32_bf16 v[36:39], v[184:187], v[210:213], v[36:39]
	v_mfma_f32_16x16x32_bf16 v[32:35], v[194:197], v[210:213], v[32:35]
	v_mfma_f32_16x16x32_bf16 v[20:23], v[184:187], v[218:221], v[20:23]
	v_mfma_f32_16x16x32_bf16 v[16:19], v[194:197], v[218:221], v[16:19]
	v_mfma_f32_16x16x32_bf16 v[4:7], v[184:187], v[226:229], v[4:7]
	v_mfma_f32_16x16x32_bf16 v[0:3], v[194:197], v[226:229], v[0:3]
	v_mfma_f32_16x16x32_bf16 v[52:55], v[188:191], v[206:209], v[52:55]
	v_mfma_f32_16x16x32_bf16 v[48:51], v[198:201], v[206:209], v[48:51]
	v_mfma_f32_16x16x32_bf16 v[36:39], v[188:191], v[214:217], v[36:39]
	v_mfma_f32_16x16x32_bf16 v[32:35], v[198:201], v[214:217], v[32:35]
	v_mfma_f32_16x16x32_bf16 v[20:23], v[188:191], v[222:225], v[20:23]
	v_mfma_f32_16x16x32_bf16 v[16:19], v[198:201], v[222:225], v[16:19]
	v_mfma_f32_16x16x32_bf16 v[4:7], v[188:191], v[230:233], v[4:7]
	v_mfma_f32_16x16x32_bf16 v[0:3], v[198:201], v[230:233], v[0:3]
	s_barrier
; #define PG8_STAGE(bufoff, gbase, voff) do { _Pragma("unroll") for (int _i = 0; _i < 2; ++_i) \
;         __builtin_amdgcn_global_load_lds((const unsigned*)((const char*)(gbase) + (voff)[_i]), (LAS unsigned*)(lds + (bufoff) + ldsw + _i * 8192), 16, 0, 0); } while (0)
; #define PG8_LDA(dst, b, h) do { _Pragma("unroll") for (int m = 0; m < 4; ++m) _Pragma("unroll") for (int k = 0; k < 2; ++k) dst[m][k] = *(const LAS bf16x8*)(lds + PG8_SA(b, h) + aoff + m * 2048 + k * 1024); } while (0)
; #define PG8_LDB(dst, b, h) do { _Pragma("unroll") for (int n = 0; n < 2; ++n) _Pragma("unroll") for (int k = 0; k < 2; ++k) dst[n][k] = *(const LAS bf16x8*)(lds + PG8_SB(b, h) + boff + n * 2048 + k * 1024); } while (0)
; #define PG8_MMA(ai, bj, At, Bt) do { __builtin_amdgcn_s_setprio(1); _Pragma("unroll") for (int m = 0; m < 4; ++m) _Pragma("unroll") for (int n = 0; n < 2; ++n) _Pragma("unroll") for (int k = 0; k < 2; ++k) \
;         acc[ai][bj][m][n] = __builtin_amdgcn_mfma_f32_16x16x32_bf16(Bt[n][k], At[m][k], acc[ai][bj][m][n], 0, 0, 0); __builtin_amdgcn_s_setprio(0); } while (0)
; #define PG8_WAIT_V(n) asm volatile("s_waitcnt vmcnt(" #n ")" ::: "memory")
; #define PG8_WAIT_L(n) asm volatile("s_waitcnt lgkmcnt(" #n ")" ::: "memory")
; #define PG8_BAR __builtin_amdgcn_s_barrier()
; #define PG8_SCHED __builtin_amdgcn_sched_barrier(0)
; template <class Epi>
; DI void gemm_phase(int wv, LAS unsigned char* lds, LAS unsigned char* scr, const Sched& S, const Epi& E) {
;     ...
;             PG8_LDB(B0, 1, 0); PG8_LDB(B1, 1, 1); PG8_SCHED; PG8_LDA(At, 1, 0); PG8_STAGE(PG8_SA(0, 1), a2 + hstepA, voffA);
;             PG8_WAIT_V(8); PG8_WAIT_L(0); PG8_BAR; PG8_MMA(0, 0, At, B0); PG8_MMA(0, 1, At, B1); PG8_BAR; PG8_SCHED;
	s_add_i32 s49, 0, 0x18000
	v_add_u32_e32 v143, s49, v146
	s_add_i32 s50, 0, 0x1c000
	ds_read_b128 v[168:171], v143
	ds_read_b128 v[172:175], v143 offset:1024
	ds_read_b128 v[176:179], v143 offset:2048
	ds_read_b128 v[180:183], v143 offset:3072
	v_add_u32_e32 v143, s50, v146
	ds_read_b128 v[184:187], v143
	ds_read_b128 v[188:191], v143 offset:1024
	ds_read_b128 v[194:197], v143 offset:2048
	ds_read_b128 v[198:201], v143 offset:3072
	s_add_u32 s30, s30, 0x40000
	s_addc_u32 s31, s31, 0
	s_mov_b32 m0, s43
	v_lshl_add_u64 v[240:241], s[30:31], 0, v[128:129]
	ds_read_b128 v[202:205], v166 offset:32768
	ds_read_b128 v[206:209], v166 offset:33792
	ds_read_b128 v[210:213], v166 offset:34816
	ds_read_b128 v[214:217], v166 offset:35840
	ds_read_b128 v[218:221], v166 offset:36864
	ds_read_b128 v[222:225], v166 offset:37888
	ds_read_b128 v[226:229], v166 offset:38912
	ds_read_b128 v[230:233], v166 offset:39936
	global_load_lds_dwordx4 v[240:241], off
	v_lshl_add_u64 v[240:241], s[30:31], 0, v[132:133]
	s_mov_b32 m0, s44
	s_nop 0
	global_load_lds_dwordx4 v[240:241], off
	s_waitcnt vmcnt(8)
	s_waitcnt lgkmcnt(0)
	s_barrier
	s_waitcnt lgkmcnt(0)
	v_mfma_f32_16x16x32_bf16 v[124:127], v[168:171], v[202:205], v[124:127]
	v_mfma_f32_16x16x32_bf16 v[120:123], v[176:179], v[202:205], v[120:123]
	v_mfma_f32_16x16x32_bf16 v[108:111], v[168:171], v[210:213], v[108:111]
	v_mfma_f32_16x16x32_bf16 v[104:107], v[176:179], v[210:213], v[104:107]
	v_mfma_f32_16x16x32_bf16 v[92:95], v[168:171], v[218:221], v[92:95]
	v_mfma_f32_16x16x32_bf16 v[88:91], v[176:179], v[218:221], v[88:91]
	v_mfma_f32_16x16x32_bf16 v[76:79], v[168:171], v[226:229], v[76:79]
	v_mfma_f32_16x16x32_bf16 v[72:75], v[176:179], v[226:229], v[72:75]
	v_mfma_f32_16x16x32_bf16 v[124:127], v[172:175], v[206:209], v[124:127]
	v_mfma_f32_16x16x32_bf16 v[120:123], v[180:183], v[206:209], v[120:123]
	v_mfma_f32_16x16x32_bf16 v[108:111], v[172:175], v[214:217], v[108:111]
	v_mfma_f32_16x16x32_bf16 v[104:107], v[180:183], v[214:217], v[104:107]
	v_mfma_f32_16x16x32_bf16 v[92:95], v[172:175], v[222:225], v[92:95]
	v_mfma_f32_16x16x32_bf16 v[88:91], v[180:183], v[222:225], v[88:91]
	v_mfma_f32_16x16x32_bf16 v[76:79], v[172:175], v[230:233], v[76:79]
	v_mfma_f32_16x16x32_bf16 v[72:75], v[180:183], v[230:233], v[72:75]
	v_mfma_f32_16x16x32_bf16 v[116:119], v[184:187], v[202:205], v[116:119]
	v_mfma_f32_16x16x32_bf16 v[112:115], v[194:197], v[202:205], v[112:115]
	v_mfma_f32_16x16x32_bf16 v[100:103], v[184:187], v[210:213], v[100:103]
	v_mfma_f32_16x16x32_bf16 v[96:99], v[194:197], v[210:213], v[96:99]
	v_mfma_f32_16x16x32_bf16 v[84:87], v[184:187], v[218:221], v[84:87]
	v_mfma_f32_16x16x32_bf16 v[80:83], v[194:197], v[218:221], v[80:83]
	v_mfma_f32_16x16x32_bf16 v[68:71], v[184:187], v[226:229], v[68:71]
	v_mfma_f32_16x16x32_bf16 v[64:67], v[194:197], v[226:229], v[64:67]
	v_mfma_f32_16x16x32_bf16 v[116:119], v[188:191], v[206:209], v[116:119]
	v_mfma_f32_16x16x32_bf16 v[112:115], v[198:201], v[206:209], v[112:115]
	v_mfma_f32_16x16x32_bf16 v[100:103], v[188:191], v[214:217], v[100:103]
	v_mfma_f32_16x16x32_bf16 v[96:99], v[198:201], v[214:217], v[96:99]
	v_mfma_f32_16x16x32_bf16 v[84:87], v[188:191], v[222:225], v[84:87]
	v_mfma_f32_16x16x32_bf16 v[80:83], v[198:201], v[222:225], v[80:83]
	v_mfma_f32_16x16x32_bf16 v[68:71], v[188:191], v[230:233], v[68:71]
	v_mfma_f32_16x16x32_bf16 v[64:67], v[198:201], v[230:233], v[64:67]
	s_barrier
; #define PG8_STAGE(bufoff, gbase, voff) do { _Pragma("unroll") for (int _i = 0; _i < 2; ++_i) \
;         __builtin_amdgcn_global_load_lds((const unsigned*)((const char*)(gbase) + (voff)[_i]), (LAS unsigned*)(lds + (bufoff) + ldsw + _i * 8192), 16, 0, 0); } while (0)
; #define PG8_LDA(dst, b, h) do { _Pragma("unroll") for (int m = 0; m < 4; ++m) _Pragma("unroll") for (int k = 0; k < 2; ++k) dst[m][k] = *(const LAS bf16x8*)(lds + PG8_SA(b, h) + aoff + m * 2048 + k * 1024); } while (0)
; #define PG8_MMA(ai, bj, At, Bt) do { __builtin_amdgcn_s_setprio(1); _Pragma("unroll") for (int m = 0; m < 4; ++m) _Pragma("unroll") for (int n = 0; n < 2; ++n) _Pragma("unroll") for (int k = 0; k < 2; ++k) \
;         acc[ai][bj][m][n] = __builtin_amdgcn_mfma_f32_16x16x32_bf16(Bt[n][k], At[m][k], acc[ai][bj][m][n], 0, 0, 0); __builtin_amdgcn_s_setprio(0); } while (0)
; #define PG8_WAIT_V(n) asm volatile("s_waitcnt vmcnt(" #n ")" ::: "memory")
; #define PG8_WAIT_L(n) asm volatile("s_waitcnt lgkmcnt(" #n ")" ::: "memory")
; #define PG8_BAR __builtin_amdgcn_s_barrier()
; #define PG8_SCHED __builtin_amdgcn_sched_barrier(0)
; template <class Epi>
; DI void gemm_phase(int wv, LAS unsigned char* lds, LAS unsigned char* scr, const Sched& S, const Epi& E) {
;     ...
;             PG8_LDA(At, 1, 1); PG8_STAGE(PG8_SB(1, 0), b3, voffB); PG8_STAGE(PG8_SB(1, 1), b3 + hstepB, voffB); PG8_STAGE(PG8_SA(1, 0), a3, voffA);
;             PG8_WAIT_V(8); PG8_WAIT_L(0); PG8_BAR; PG8_MMA(1, 0, At, B0); PG8_MMA(1, 1, At, B1); PG8_BAR; PG8_SCHED;
;         }
;         if (wr == 0) PG8_BAR;
	s_add_i32 s30, s49, s38
	v_lshl_add_u64 v[144:145], v[144:145], 0, s[2:3]
	s_mov_b32 m0, s30
	ds_read_b128 v[202:205], v166 offset:49152
	ds_read_b128 v[206:209], v166 offset:50176
	ds_read_b128 v[210:213], v166 offset:51200
	ds_read_b128 v[214:217], v166 offset:52224
	ds_read_b128 v[218:221], v166 offset:53248
	ds_read_b128 v[222:225], v166 offset:54272
	ds_read_b128 v[226:229], v166 offset:55296
	ds_read_b128 v[230:233], v166 offset:56320
	global_load_lds_dwordx4 v[144:145], off
	s_add_i32 m0, s30, 0x2000
	s_add_u32 s28, s28, 0x40080
	v_lshl_add_u64 v[144:145], v[234:235], 0, s[2:3]
	s_addc_u32 s29, s29, 0
	s_add_i32 s30, s50, s38
	global_load_lds_dwordx4 v[144:145], off
	v_lshl_add_u64 v[144:145], s[28:29], 0, v[130:131]
	s_mov_b32 m0, s30
	s_nop 0
	global_load_lds_dwordx4 v[144:145], off
	v_lshl_add_u64 v[144:145], s[28:29], 0, v[134:135]
	s_add_i32 m0, s30, 0x2000
	s_nop 0
	global_load_lds_dwordx4 v[144:145], off
	v_lshl_add_u64 v[144:145], v[236:237], 0, s[2:3]
	s_mov_b32 m0, s45
	s_nop 0
	global_load_lds_dwordx4 v[144:145], off
	v_lshl_add_u64 v[144:145], v[238:239], 0, s[2:3]
	s_mov_b32 m0, s46
	s_nop 0
	global_load_lds_dwordx4 v[144:145], off
	s_waitcnt vmcnt(8)
	s_waitcnt lgkmcnt(0)
	s_barrier
	s_waitcnt lgkmcnt(0)
	v_mfma_f32_16x16x32_bf16 v[60:63], v[168:171], v[202:205], v[60:63]
	v_mfma_f32_16x16x32_bf16 v[56:59], v[176:179], v[202:205], v[56:59]
	v_mfma_f32_16x16x32_bf16 v[44:47], v[168:171], v[210:213], v[44:47]
	v_mfma_f32_16x16x32_bf16 v[40:43], v[176:179], v[210:213], v[40:43]
	v_mfma_f32_16x16x32_bf16 v[28:31], v[168:171], v[218:221], v[28:31]
	v_mfma_f32_16x16x32_bf16 v[24:27], v[176:179], v[218:221], v[24:27]
	v_mfma_f32_16x16x32_bf16 v[12:15], v[168:171], v[226:229], v[12:15]
	v_mfma_f32_16x16x32_bf16 v[8:11], v[176:179], v[226:229], v[8:11]
	v_mfma_f32_16x16x32_bf16 v[60:63], v[172:175], v[206:209], v[60:63]
	v_mfma_f32_16x16x32_bf16 v[56:59], v[180:183], v[206:209], v[56:59]
	v_mfma_f32_16x16x32_bf16 v[44:47], v[172:175], v[214:217], v[44:47]
	v_mfma_f32_16x16x32_bf16 v[40:43], v[180:183], v[214:217], v[40:43]
	v_mfma_f32_16x16x32_bf16 v[28:31], v[172:175], v[222:225], v[28:31]
	v_mfma_f32_16x16x32_bf16 v[24:27], v[180:183], v[222:225], v[24:27]
	v_mfma_f32_16x16x32_bf16 v[12:15], v[172:175], v[230:233], v[12:15]
	v_mfma_f32_16x16x32_bf16 v[8:11], v[180:183], v[230:233], v[8:11]
	v_mfma_f32_16x16x32_bf16 v[52:55], v[184:187], v[202:205], v[52:55]
	v_mfma_f32_16x16x32_bf16 v[48:51], v[194:197], v[202:205], v[48:51]
	v_mfma_f32_16x16x32_bf16 v[36:39], v[184:187], v[210:213], v[36:39]
	v_mfma_f32_16x16x32_bf16 v[32:35], v[194:197], v[210:213], v[32:35]
	v_mfma_f32_16x16x32_bf16 v[20:23], v[184:187], v[218:221], v[20:23]
	v_mfma_f32_16x16x32_bf16 v[16:19], v[194:197], v[218:221], v[16:19]
	v_mfma_f32_16x16x32_bf16 v[4:7], v[184:187], v[226:229], v[4:7]
	v_mfma_f32_16x16x32_bf16 v[0:3], v[194:197], v[226:229], v[0:3]
	v_mfma_f32_16x16x32_bf16 v[52:55], v[188:191], v[206:209], v[52:55]
	v_mfma_f32_16x16x32_bf16 v[48:51], v[198:201], v[206:209], v[48:51]
	v_mfma_f32_16x16x32_bf16 v[36:39], v[188:191], v[214:217], v[36:39]
	v_mfma_f32_16x16x32_bf16 v[32:35], v[198:201], v[214:217], v[32:35]
	v_mfma_f32_16x16x32_bf16 v[20:23], v[188:191], v[222:225], v[20:23]
	v_mfma_f32_16x16x32_bf16 v[16:19], v[198:201], v[222:225], v[16:19]
	v_mfma_f32_16x16x32_bf16 v[4:7], v[188:191], v[230:233], v[4:7]
	v_mfma_f32_16x16x32_bf16 v[0:3], v[198:201], v[230:233], v[0:3]
	s_barrier
	s_add_i32 s33, s33, 2
	s_add_u32 s25, s25, 0x100
	s_addc_u32 s27, s27, 0
	s_add_u32 s12, s12, 0x100
	s_addc_u32 s13, s13, 0
	s_cmp_gt_u32 s33, 13
	s_cbranch_scc0 .LBB0_588
	s_setprio 0
	s_and_b64 vcc, exec, s[14:15]
	s_cbranch_vccz .LBB0_591
	s_barrier

; #define PG8_STAGE(bufoff, gbase, voff) do { _Pragma("unroll") for (int _i = 0; _i < 2; ++_i) \
;         __builtin_amdgcn_global_load_lds((const unsigned*)((const char*)(gbase) + (voff)[_i]), (LAS unsigned*)(lds + (bufoff) + ldsw + _i * 8192), 16, 0, 0); } while (0)
; #define PG8_LDA(dst, b, h) do { _Pragma("unroll") for (int m = 0; m < 4; ++m) _Pragma("unroll") for (int k = 0; k < 2; ++k) dst[m][k] = *(const LAS bf16x8*)(lds + PG8_SA(b, h) + aoff + m * 2048 + k * 1024); } while (0)
; #define PG8_LDB(dst, b, h) do { _Pragma("unroll") for (int n = 0; n < 2; ++n) _Pragma("unroll") for (int k = 0; k < 2; ++k) dst[n][k] = *(const LAS bf16x8*)(lds + PG8_SB(b, h) + boff + n * 2048 + k * 1024); } while (0)
; #define PG8_SCHED __builtin_amdgcn_sched_barrier(0)
; template <class Epi>
; DI void gemm_phase(int wv, LAS unsigned char* lds, LAS unsigned char* scr, const Sched& S, const Epi& E) {
;     ...
;         const bool has_next = S.next(ui + 1, nxt);
;         const char* nA = has_next ? S.baseA(nxt) : cA; const char* nB = has_next ? S.baseB(nxt) : cB;
;         for (int t = 0; t < nt; t += 2) {
;             const bool last = (t == nt - 2);
;             const char* a1 = cA + (size_t)(t + 1) * kstep;
;             const char* a2 = last ? nA : cA + (size_t)(t + 2) * kstep; const char* b2 = last ? nB : cB + (size_t)(t + 2) * kstep;
;             const char* a3 = a2 + kstep; const char* b3 = b2 + kstep;
;             PG8_LDB(B0, 0, 0); PG8_LDB(B1, 0, 1); PG8_SCHED; PG8_LDA(At, 0, 0); PG8_STAGE(PG8_SA(1, 1), a1 + hstepA, voffA);
;     ...
; #pragma unroll
;         for (int a = 0; a < 2; ++a)
; #pragma unroll
;             for (int b = 0; b < 2; ++b)
; #pragma unroll
;                 for (int m = 0; m < 4; ++m)
; #pragma unroll
;                     for (int n = 0; n < 2; ++n) acc[a][b][m][n] = (f32x4){0.f, 0.f, 0.f, 0.f};
;         cur = nxt; cA = nA; cB = nB; ++ui;
.LBB0_683:
	s_ashr_i32 s19, s18, 31
	s_lshl_b64 s[22:23], s[18:19], 19
	s_add_u32 s22, s28, s22
	s_addc_u32 s23, s29, s23
	s_and_b64 s[8:9], s[8:9], exec
	s_cselect_b32 s11, s23, s25
	s_cselect_b32 s15, s22, s24
	s_add_u32 s17, s26, 0x100
	s_addc_u32 s19, s27, 0
	s_add_u32 s8, s24, 0x40080
	v_mov_b32_e32 v0, 0
	s_addc_u32 s9, s25, 0
	s_mov_b32 s45, -2
	v_mov_b32_e32 v1, v0
	v_mov_b32_e32 v2, v0
	v_mov_b32_e32 v3, v0
	v_mov_b32_e32 v4, v0
	v_mov_b32_e32 v5, v0
	v_mov_b32_e32 v6, v0
	v_mov_b32_e32 v7, v0
	v_mov_b32_e32 v8, v0
	v_mov_b32_e32 v9, v0
	v_mov_b32_e32 v10, v0
	v_mov_b32_e32 v11, v0
	v_mov_b32_e32 v12, v0
	v_mov_b32_e32 v13, v0
	v_mov_b32_e32 v14, v0
	v_mov_b32_e32 v15, v0
	v_mov_b32_e32 v24, v0
	v_mov_b32_e32 v25, v0
	v_mov_b32_e32 v26, v0
	v_mov_b32_e32 v27, v0
	v_mov_b32_e32 v28, v0
	v_mov_b32_e32 v29, v0
	v_mov_b32_e32 v30, v0
	v_mov_b32_e32 v31, v0
	v_mov_b32_e32 v40, v0
	v_mov_b32_e32 v41, v0
	v_mov_b32_e32 v42, v0
	v_mov_b32_e32 v43, v0
	v_mov_b32_e32 v44, v0
	v_mov_b32_e32 v45, v0
	v_mov_b32_e32 v46, v0
	v_mov_b32_e32 v47, v0
	v_mov_b32_e32 v16, v0
	v_mov_b32_e32 v17, v0
	v_mov_b32_e32 v18, v0
	v_mov_b32_e32 v19, v0
	v_mov_b32_e32 v20, v0
	v_mov_b32_e32 v21, v0
	v_mov_b32_e32 v22, v0
	v_mov_b32_e32 v23, v0
	v_mov_b32_e32 v32, v0
	v_mov_b32_e32 v33, v0
	v_mov_b32_e32 v34, v0
	v_mov_b32_e32 v35, v0
	v_mov_b32_e32 v36, v0
	v_mov_b32_e32 v37, v0
	v_mov_b32_e32 v38, v0
	v_mov_b32_e32 v39, v0
	v_mov_b32_e32 v48, v0
	v_mov_b32_e32 v49, v0
	v_mov_b32_e32 v50, v0
	v_mov_b32_e32 v51, v0
	v_mov_b32_e32 v52, v0
	v_mov_b32_e32 v53, v0
	v_mov_b32_e32 v54, v0
	v_mov_b32_e32 v55, v0
	v_mov_b32_e32 v56, v0
	v_mov_b32_e32 v57, v0
	v_mov_b32_e32 v58, v0
	v_mov_b32_e32 v59, v0
	v_mov_b32_e32 v60, v0
	v_mov_b32_e32 v61, v0
	v_mov_b32_e32 v62, v0
	v_mov_b32_e32 v63, v0
	v_mov_b32_e32 v64, v0
	v_mov_b32_e32 v65, v0
	v_mov_b32_e32 v66, v0
	v_mov_b32_e32 v67, v0
	v_mov_b32_e32 v68, v0
	v_mov_b32_e32 v69, v0
	v_mov_b32_e32 v70, v0
	v_mov_b32_e32 v71, v0
	v_mov_b32_e32 v72, v0
	v_mov_b32_e32 v73, v0
	v_mov_b32_e32 v74, v0
	v_mov_b32_e32 v75, v0
	v_mov_b32_e32 v76, v0
	v_mov_b32_e32 v77, v0
	v_mov_b32_e32 v78, v0
	v_mov_b32_e32 v79, v0
	v_mov_b32_e32 v88, v0
	v_mov_b32_e32 v89, v0
	v_mov_b32_e32 v90, v0
	v_mov_b32_e32 v91, v0
	v_mov_b32_e32 v92, v0
	v_mov_b32_e32 v93, v0
	v_mov_b32_e32 v94, v0
	v_mov_b32_e32 v95, v0
	v_mov_b32_e32 v104, v0
	v_mov_b32_e32 v105, v0
	v_mov_b32_e32 v106, v0
	v_mov_b32_e32 v107, v0
	v_mov_b32_e32 v108, v0
	v_mov_b32_e32 v109, v0
	v_mov_b32_e32 v110, v0
	v_mov_b32_e32 v111, v0
	v_mov_b32_e32 v80, v0
	v_mov_b32_e32 v81, v0
	v_mov_b32_e32 v82, v0
	v_mov_b32_e32 v83, v0
	v_mov_b32_e32 v84, v0
	v_mov_b32_e32 v85, v0
	v_mov_b32_e32 v86, v0
	v_mov_b32_e32 v87, v0
	v_mov_b32_e32 v96, v0
	v_mov_b32_e32 v97, v0
	v_mov_b32_e32 v98, v0
	v_mov_b32_e32 v99, v0
	v_mov_b32_e32 v100, v0
	v_mov_b32_e32 v101, v0
	v_mov_b32_e32 v102, v0
	v_mov_b32_e32 v103, v0
	v_mov_b32_e32 v112, v0
	v_mov_b32_e32 v113, v0
	v_mov_b32_e32 v114, v0
	v_mov_b32_e32 v115, v0
	v_mov_b32_e32 v116, v0
	v_mov_b32_e32 v117, v0
	v_mov_b32_e32 v118, v0
	v_mov_b32_e32 v119, v0
	v_mov_b32_e32 v120, v0
	v_mov_b32_e32 v121, v0
	v_mov_b32_e32 v122, v0
	v_mov_b32_e32 v123, v0
	v_mov_b32_e32 v124, v0
	v_mov_b32_e32 v125, v0
	v_mov_b32_e32 v126, v0
	v_mov_b32_e32 v127, v0
	s_cmp_lg_u64 s[12:13], 0
	s_cbranch_scc1 .Lgp_12
	s_setprio 1
.Lgp_12:
.LBB0_684:
	s_add_u32 s24, s8, 0xfffc0080
	s_addc_u32 s25, s9, -1
	s_add_i32 s46, 0, 0x10000
	s_cmp_eq_u32 s45, 12
	s_cselect_b32 s27, s11, s25
	s_cselect_b32 s26, s15, s24
	v_add_u32_e32 v143, s46, v144
	s_cselect_b32 s25, s21, s19
	s_cselect_b32 s24, s20, s17
	s_add_i32 s48, 0, 0x14000
	ds_read_b128 v[146:149], v143
	ds_read_b128 v[150:153], v143 offset:1024
	ds_read_b128 v[154:157], v143 offset:2048
	ds_read_b128 v[158:161], v143 offset:3072
	v_add_u32_e32 v143, s48, v144
	ds_read_b128 v[162:165], v143
	ds_read_b128 v[166:169], v143 offset:1024
	ds_read_b128 v[170:173], v143 offset:2048
	ds_read_b128 v[174:177], v143 offset:3072
	v_lshl_add_u64 v[190:191], s[8:9], 0, v[140:141]
	s_add_i32 m0, s34, 0xc000
	ds_read_b128 v[178:181], v145
	ds_read_b128 v[182:185], v145 offset:1024
	ds_read_b128 v[186:189], v145 offset:2048
	ds_read_b128 v[194:197], v145 offset:3072
	ds_read_b128 v[198:201], v145 offset:4096
	ds_read_b128 v[202:205], v145 offset:5120
	ds_read_b128 v[206:209], v145 offset:6144
	ds_read_b128 v[210:213], v145 offset:7168
	global_load_lds_dwordx4 v[190:191], off
	v_lshl_add_u64 v[190:191], s[8:9], 0, v[138:139]
	s_add_i32 m0, s34, 0xe000
	s_nop 0
	global_load_lds_dwordx4 v[190:191], off
	s_waitcnt vmcnt(8)
	s_waitcnt lgkmcnt(0)
	s_barrier
; #define PG8_STAGE(bufoff, gbase, voff) do { _Pragma("unroll") for (int _i = 0; _i < 2; ++_i) \
;         __builtin_amdgcn_global_load_lds((const unsigned*)((const char*)(gbase) + (voff)[_i]), (LAS unsigned*)(lds + (bufoff) + ldsw + _i * 8192), 16, 0, 0); } while (0)
; #define PG8_LDA(dst, b, h) do { _Pragma("unroll") for (int m = 0; m < 4; ++m) _Pragma("unroll") for (int k = 0; k < 2; ++k) dst[m][k] = *(const LAS bf16x8*)(lds + PG8_SA(b, h) + aoff + m * 2048 + k * 1024); } while (0)
; #define PG8_MMA(ai, bj, At, Bt) do { __builtin_amdgcn_s_setprio(1); _Pragma("unroll") for (int m = 0; m < 4; ++m) _Pragma("unroll") for (int n = 0; n < 2; ++n) _Pragma("unroll") for (int k = 0; k < 2; ++k) \
;         acc[ai][bj][m][n] = __builtin_amdgcn_mfma_f32_16x16x32_bf16(Bt[n][k], At[m][k], acc[ai][bj][m][n], 0, 0, 0); __builtin_amdgcn_s_setprio(0); } while (0)
; #define PG8_WAIT_V(n) asm volatile("s_waitcnt vmcnt(" #n ")" ::: "memory")
; #define PG8_WAIT_L(n) asm volatile("s_waitcnt lgkmcnt(" #n ")" ::: "memory")
; #define PG8_BAR __builtin_amdgcn_s_barrier()
; #define PG8_SCHED __builtin_amdgcn_sched_barrier(0)
; template <class Epi>
; DI void gemm_phase(int wv, LAS unsigned char* lds, LAS unsigned char* scr, const Sched& S, const Epi& E) {
;     ...
;             PG8_WAIT_V(8); PG8_WAIT_L(0); PG8_BAR; PG8_MMA(0, 0, At, B0); PG8_MMA(0, 1, At, B1); PG8_BAR; PG8_SCHED;
;             PG8_LDA(At, 0, 1); PG8_STAGE(PG8_SB(0, 0), b2, voffB); PG8_STAGE(PG8_SB(0, 1), b2 + hstepB, voffB); PG8_STAGE(PG8_SA(0, 0), a2, voffA);
;             PG8_WAIT_V(8); PG8_WAIT_L(0); PG8_BAR; PG8_MMA(1, 0, At, B0); PG8_MMA(1, 1, At, B1); PG8_BAR; PG8_SCHED;
	s_waitcnt lgkmcnt(0)
	v_mfma_f32_16x16x32_bf16 v[124:127], v[146:149], v[178:181], v[124:127]
	v_mfma_f32_16x16x32_bf16 v[120:123], v[154:157], v[178:181], v[120:123]
	v_mfma_f32_16x16x32_bf16 v[116:119], v[146:149], v[186:189], v[116:119]
	v_mfma_f32_16x16x32_bf16 v[112:115], v[154:157], v[186:189], v[112:115]
	v_mfma_f32_16x16x32_bf16 v[100:103], v[146:149], v[198:201], v[100:103]
	v_mfma_f32_16x16x32_bf16 v[96:99], v[154:157], v[198:201], v[96:99]
	v_mfma_f32_16x16x32_bf16 v[84:87], v[146:149], v[206:209], v[84:87]
	v_mfma_f32_16x16x32_bf16 v[80:83], v[154:157], v[206:209], v[80:83]
	v_mfma_f32_16x16x32_bf16 v[124:127], v[150:153], v[182:185], v[124:127]
	v_mfma_f32_16x16x32_bf16 v[120:123], v[158:161], v[182:185], v[120:123]
	v_mfma_f32_16x16x32_bf16 v[116:119], v[150:153], v[194:197], v[116:119]
	v_mfma_f32_16x16x32_bf16 v[112:115], v[158:161], v[194:197], v[112:115]
	v_mfma_f32_16x16x32_bf16 v[100:103], v[150:153], v[202:205], v[100:103]
	v_mfma_f32_16x16x32_bf16 v[96:99], v[158:161], v[202:205], v[96:99]
	v_mfma_f32_16x16x32_bf16 v[84:87], v[150:153], v[210:213], v[84:87]
	v_mfma_f32_16x16x32_bf16 v[80:83], v[158:161], v[210:213], v[80:83]
	v_mfma_f32_16x16x32_bf16 v[108:111], v[162:165], v[178:181], v[108:111]
	v_mfma_f32_16x16x32_bf16 v[104:107], v[170:173], v[178:181], v[104:107]
	v_mfma_f32_16x16x32_bf16 v[92:95], v[162:165], v[186:189], v[92:95]
	v_mfma_f32_16x16x32_bf16 v[88:91], v[170:173], v[186:189], v[88:91]
	v_mfma_f32_16x16x32_bf16 v[76:79], v[162:165], v[198:201], v[76:79]
	v_mfma_f32_16x16x32_bf16 v[72:75], v[170:173], v[198:201], v[72:75]
	v_mfma_f32_16x16x32_bf16 v[68:71], v[162:165], v[206:209], v[68:71]
	v_mfma_f32_16x16x32_bf16 v[64:67], v[170:173], v[206:209], v[64:67]
	v_mfma_f32_16x16x32_bf16 v[108:111], v[166:169], v[182:185], v[108:111]
	v_mfma_f32_16x16x32_bf16 v[104:107], v[174:177], v[182:185], v[104:107]
	v_mfma_f32_16x16x32_bf16 v[92:95], v[166:169], v[194:197], v[92:95]
	v_mfma_f32_16x16x32_bf16 v[88:91], v[174:177], v[194:197], v[88:91]
	v_mfma_f32_16x16x32_bf16 v[76:79], v[166:169], v[202:205], v[76:79]
	v_mfma_f32_16x16x32_bf16 v[72:75], v[174:177], v[202:205], v[72:75]
	v_mfma_f32_16x16x32_bf16 v[68:71], v[166:169], v[210:213], v[68:71]
	v_mfma_f32_16x16x32_bf16 v[64:67], v[174:177], v[210:213], v[64:67]
	s_barrier
	s_add_i32 s46, s46, s33
	v_lshl_add_u64 v[190:191], s[24:25], 0, v[132:133]
	s_mov_b32 m0, s46
	ds_read_b128 v[178:181], v145 offset:16384
	ds_read_b128 v[182:185], v145 offset:17408
	ds_read_b128 v[186:189], v145 offset:18432
	ds_read_b128 v[194:197], v145 offset:19456
	ds_read_b128 v[198:201], v145 offset:20480
	ds_read_b128 v[202:205], v145 offset:21504
	ds_read_b128 v[206:209], v145 offset:22528
	ds_read_b128 v[210:213], v145 offset:23552
	global_load_lds_dwordx4 v[190:191], off
	s_add_i32 m0, s46, 0x2000
	s_add_u32 s46, s24, 0x40000
	v_lshl_add_u64 v[214:215], s[24:25], 0, v[128:129]
	s_addc_u32 s47, s25, 0
	s_add_i32 s48, s48, s33
	global_load_lds_dwordx4 v[214:215], off
	v_lshl_add_u64 v[216:217], s[46:47], 0, v[132:133]
	s_mov_b32 m0, s48
	v_lshl_add_u64 v[218:219], s[26:27], 0, v[130:131]
	global_load_lds_dwordx4 v[216:217], off
	v_lshl_add_u64 v[216:217], s[46:47], 0, v[128:129]
	s_add_i32 m0, s48, 0x2000
	s_nop 0
	global_load_lds_dwordx4 v[216:217], off
	v_lshl_add_u64 v[216:217], s[26:27], 0, v[134:135]
	s_mov_b32 m0, s34
	s_nop 0
	global_load_lds_dwordx4 v[216:217], off
	s_mov_b32 m0, s35
	s_nop 0
	global_load_lds_dwordx4 v[218:219], off
	s_waitcnt vmcnt(8)
	s_waitcnt lgkmcnt(0)
	s_barrier
	s_waitcnt lgkmcnt(0)
	v_mfma_f32_16x16x32_bf16 v[60:63], v[146:149], v[178:181], v[60:63]
	v_mfma_f32_16x16x32_bf16 v[56:59], v[154:157], v[178:181], v[56:59]
	v_mfma_f32_16x16x32_bf16 v[52:55], v[146:149], v[186:189], v[52:55]
	v_mfma_f32_16x16x32_bf16 v[48:51], v[154:157], v[186:189], v[48:51]
	v_mfma_f32_16x16x32_bf16 v[36:39], v[146:149], v[198:201], v[36:39]
	v_mfma_f32_16x16x32_bf16 v[32:35], v[154:157], v[198:201], v[32:35]
	v_mfma_f32_16x16x32_bf16 v[20:23], v[146:149], v[206:209], v[20:23]
	v_mfma_f32_16x16x32_bf16 v[16:19], v[154:157], v[206:209], v[16:19]
	v_mfma_f32_16x16x32_bf16 v[60:63], v[150:153], v[182:185], v[60:63]
	v_mfma_f32_16x16x32_bf16 v[56:59], v[158:161], v[182:185], v[56:59]
	v_mfma_f32_16x16x32_bf16 v[52:55], v[150:153], v[194:197], v[52:55]
	v_mfma_f32_16x16x32_bf16 v[48:51], v[158:161], v[194:197], v[48:51]
	v_mfma_f32_16x16x32_bf16 v[36:39], v[150:153], v[202:205], v[36:39]
	v_mfma_f32_16x16x32_bf16 v[32:35], v[158:161], v[202:205], v[32:35]
	v_mfma_f32_16x16x32_bf16 v[20:23], v[150:153], v[210:213], v[20:23]
	v_mfma_f32_16x16x32_bf16 v[16:19], v[158:161], v[210:213], v[16:19]
	v_mfma_f32_16x16x32_bf16 v[44:47], v[162:165], v[178:181], v[44:47]
	v_mfma_f32_16x16x32_bf16 v[40:43], v[170:173], v[178:181], v[40:43]
	v_mfma_f32_16x16x32_bf16 v[28:31], v[162:165], v[186:189], v[28:31]
	v_mfma_f32_16x16x32_bf16 v[24:27], v[170:173], v[186:189], v[24:27]
	v_mfma_f32_16x16x32_bf16 v[12:15], v[162:165], v[198:201], v[12:15]
	v_mfma_f32_16x16x32_bf16 v[8:11], v[170:173], v[198:201], v[8:11]
	v_mfma_f32_16x16x32_bf16 v[4:7], v[162:165], v[206:209], v[4:7]
	v_mfma_f32_16x16x32_bf16 v[0:3], v[170:173], v[206:209], v[0:3]
	v_mfma_f32_16x16x32_bf16 v[44:47], v[166:169], v[182:185], v[44:47]
	v_mfma_f32_16x16x32_bf16 v[40:43], v[174:177], v[182:185], v[40:43]
	v_mfma_f32_16x16x32_bf16 v[28:31], v[166:169], v[194:197], v[28:31]
	v_mfma_f32_16x16x32_bf16 v[24:27], v[174:177], v[194:197], v[24:27]
	v_mfma_f32_16x16x32_bf16 v[12:15], v[166:169], v[202:205], v[12:15]
	v_mfma_f32_16x16x32_bf16 v[8:11], v[174:177], v[202:205], v[8:11]
	v_mfma_f32_16x16x32_bf16 v[4:7], v[166:169], v[210:213], v[4:7]
	v_mfma_f32_16x16x32_bf16 v[0:3], v[174:177], v[210:213], v[0:3]
	s_barrier
; #define PG8_STAGE(bufoff, gbase, voff) do { _Pragma("unroll") for (int _i = 0; _i < 2; ++_i) \
;         __builtin_amdgcn_global_load_lds((const unsigned*)((const char*)(gbase) + (voff)[_i]), (LAS unsigned*)(lds + (bufoff) + ldsw + _i * 8192), 16, 0, 0); } while (0)
; #define PG8_LDA(dst, b, h) do { _Pragma("unroll") for (int m = 0; m < 4; ++m) _Pragma("unroll") for (int k = 0; k < 2; ++k) dst[m][k] = *(const LAS bf16x8*)(lds + PG8_SA(b, h) + aoff + m * 2048 + k * 1024); } while (0)
; #define PG8_LDB(dst, b, h) do { _Pragma("unroll") for (int n = 0; n < 2; ++n) _Pragma("unroll") for (int k = 0; k < 2; ++k) dst[n][k] = *(const LAS bf16x8*)(lds + PG8_SB(b, h) + boff + n * 2048 + k * 1024); } while (0)
; #define PG8_MMA(ai, bj, At, Bt) do { __builtin_amdgcn_s_setprio(1); _Pragma("unroll") for (int m = 0; m < 4; ++m) _Pragma("unroll") for (int n = 0; n < 2; ++n) _Pragma("unroll") for (int k = 0; k < 2; ++k) \
;         acc[ai][bj][m][n] = __builtin_amdgcn_mfma_f32_16x16x32_bf16(Bt[n][k], At[m][k], acc[ai][bj][m][n], 0, 0, 0); __builtin_amdgcn_s_setprio(0); } while (0)
; #define PG8_WAIT_V(n) asm volatile("s_waitcnt vmcnt(" #n ")" ::: "memory")
; #define PG8_WAIT_L(n) asm volatile("s_waitcnt lgkmcnt(" #n ")" ::: "memory")
; #define PG8_BAR __builtin_amdgcn_s_barrier()
; #define PG8_SCHED __builtin_amdgcn_sched_barrier(0)
; template <class Epi>
; DI void gemm_phase(int wv, LAS unsigned char* lds, LAS unsigned char* scr, const Sched& S, const Epi& E) {
;     ...
;             PG8_LDB(B0, 1, 0); PG8_LDB(B1, 1, 1); PG8_SCHED; PG8_LDA(At, 1, 0); PG8_STAGE(PG8_SA(0, 1), a2 + hstepA, voffA);
;             PG8_WAIT_V(8); PG8_WAIT_L(0); PG8_BAR; PG8_MMA(0, 0, At, B0); PG8_MMA(0, 1, At, B1); PG8_BAR; PG8_SCHED;
	s_add_i32 s46, 0, 0x18000
	v_add_u32_e32 v143, s46, v144
	s_add_i32 s47, 0, 0x1c000
	ds_read_b128 v[146:149], v143
	ds_read_b128 v[150:153], v143 offset:1024
	ds_read_b128 v[154:157], v143 offset:2048
	ds_read_b128 v[158:161], v143 offset:3072
	v_add_u32_e32 v143, s47, v144
	ds_read_b128 v[162:165], v143
	ds_read_b128 v[166:169], v143 offset:1024
	ds_read_b128 v[170:173], v143 offset:2048
	ds_read_b128 v[174:177], v143 offset:3072
	s_add_u32 s26, s26, 0x40000
	s_addc_u32 s27, s27, 0
	s_mov_b32 m0, s36
	v_lshl_add_u64 v[220:221], s[26:27], 0, v[134:135]
	ds_read_b128 v[178:181], v145 offset:32768
	ds_read_b128 v[182:185], v145 offset:33792
	ds_read_b128 v[186:189], v145 offset:34816
	ds_read_b128 v[194:197], v145 offset:35840
	ds_read_b128 v[198:201], v145 offset:36864
	ds_read_b128 v[202:205], v145 offset:37888
	ds_read_b128 v[206:209], v145 offset:38912
	ds_read_b128 v[210:213], v145 offset:39936
	global_load_lds_dwordx4 v[220:221], off
	v_lshl_add_u64 v[220:221], s[26:27], 0, v[130:131]
	s_mov_b32 m0, s37
	s_nop 0
	global_load_lds_dwordx4 v[220:221], off
	s_waitcnt vmcnt(8)
	s_waitcnt lgkmcnt(0)
	s_barrier
	s_waitcnt lgkmcnt(0)
	v_mfma_f32_16x16x32_bf16 v[124:127], v[146:149], v[178:181], v[124:127]
	v_mfma_f32_16x16x32_bf16 v[120:123], v[154:157], v[178:181], v[120:123]
	v_mfma_f32_16x16x32_bf16 v[116:119], v[146:149], v[186:189], v[116:119]
	v_mfma_f32_16x16x32_bf16 v[112:115], v[154:157], v[186:189], v[112:115]
	v_mfma_f32_16x16x32_bf16 v[100:103], v[146:149], v[198:201], v[100:103]
	v_mfma_f32_16x16x32_bf16 v[96:99], v[154:157], v[198:201], v[96:99]
	v_mfma_f32_16x16x32_bf16 v[84:87], v[146:149], v[206:209], v[84:87]
	v_mfma_f32_16x16x32_bf16 v[80:83], v[154:157], v[206:209], v[80:83]
	v_mfma_f32_16x16x32_bf16 v[124:127], v[150:153], v[182:185], v[124:127]
	v_mfma_f32_16x16x32_bf16 v[120:123], v[158:161], v[182:185], v[120:123]
	v_mfma_f32_16x16x32_bf16 v[116:119], v[150:153], v[194:197], v[116:119]
	v_mfma_f32_16x16x32_bf16 v[112:115], v[158:161], v[194:197], v[112:115]
	v_mfma_f32_16x16x32_bf16 v[100:103], v[150:153], v[202:205], v[100:103]
	v_mfma_f32_16x16x32_bf16 v[96:99], v[158:161], v[202:205], v[96:99]
	v_mfma_f32_16x16x32_bf16 v[84:87], v[150:153], v[210:213], v[84:87]
	v_mfma_f32_16x16x32_bf16 v[80:83], v[158:161], v[210:213], v[80:83]
	v_mfma_f32_16x16x32_bf16 v[108:111], v[162:165], v[178:181], v[108:111]
	v_mfma_f32_16x16x32_bf16 v[104:107], v[170:173], v[178:181], v[104:107]
	v_mfma_f32_16x16x32_bf16 v[92:95], v[162:165], v[186:189], v[92:95]
	v_mfma_f32_16x16x32_bf16 v[88:91], v[170:173], v[186:189], v[88:91]
	v_mfma_f32_16x16x32_bf16 v[76:79], v[162:165], v[198:201], v[76:79]
	v_mfma_f32_16x16x32_bf16 v[72:75], v[170:173], v[198:201], v[72:75]
	v_mfma_f32_16x16x32_bf16 v[68:71], v[162:165], v[206:209], v[68:71]
	v_mfma_f32_16x16x32_bf16 v[64:67], v[170:173], v[206:209], v[64:67]
	v_mfma_f32_16x16x32_bf16 v[108:111], v[166:169], v[182:185], v[108:111]
	v_mfma_f32_16x16x32_bf16 v[104:107], v[174:177], v[182:185], v[104:107]
	v_mfma_f32_16x16x32_bf16 v[92:95], v[166:169], v[194:197], v[92:95]
	v_mfma_f32_16x16x32_bf16 v[88:91], v[174:177], v[194:197], v[88:91]
	v_mfma_f32_16x16x32_bf16 v[76:79], v[166:169], v[202:205], v[76:79]
	v_mfma_f32_16x16x32_bf16 v[72:75], v[174:177], v[202:205], v[72:75]
	v_mfma_f32_16x16x32_bf16 v[68:71], v[166:169], v[210:213], v[68:71]
	v_mfma_f32_16x16x32_bf16 v[64:67], v[174:177], v[210:213], v[64:67]
	s_barrier
; #define PG8_STAGE(bufoff, gbase, voff) do { _Pragma("unroll") for (int _i = 0; _i < 2; ++_i) \
;         __builtin_amdgcn_global_load_lds((const unsigned*)((const char*)(gbase) + (voff)[_i]), (LAS unsigned*)(lds + (bufoff) + ldsw + _i * 8192), 16, 0, 0); } while (0)
; #define PG8_LDA(dst, b, h) do { _Pragma("unroll") for (int m = 0; m < 4; ++m) _Pragma("unroll") for (int k = 0; k < 2; ++k) dst[m][k] = *(const LAS bf16x8*)(lds + PG8_SA(b, h) + aoff + m * 2048 + k * 1024); } while (0)
; #define PG8_MMA(ai, bj, At, Bt) do { __builtin_amdgcn_s_setprio(1); _Pragma("unroll") for (int m = 0; m < 4; ++m) _Pragma("unroll") for (int n = 0; n < 2; ++n) _Pragma("unroll") for (int k = 0; k < 2; ++k) \
;         acc[ai][bj][m][n] = __builtin_amdgcn_mfma_f32_16x16x32_bf16(Bt[n][k], At[m][k], acc[ai][bj][m][n], 0, 0, 0); __builtin_amdgcn_s_setprio(0); } while (0)
; #define PG8_WAIT_V(n) asm volatile("s_waitcnt vmcnt(" #n ")" ::: "memory")
; #define PG8_WAIT_L(n) asm volatile("s_waitcnt lgkmcnt(" #n ")" ::: "memory")
; #define PG8_BAR __builtin_amdgcn_s_barrier()
; #define PG8_SCHED __builtin_amdgcn_sched_barrier(0)
; template <class Epi>
; DI void gemm_phase(int wv, LAS unsigned char* lds, LAS unsigned char* scr, const Sched& S, const Epi& E) {
;     ...
;             PG8_LDA(At, 1, 1); PG8_STAGE(PG8_SB(1, 0), b3, voffB); PG8_STAGE(PG8_SB(1, 1), b3 + hstepB, voffB); PG8_STAGE(PG8_SA(1, 0), a3, voffA);
;             PG8_WAIT_V(8); PG8_WAIT_L(0); PG8_BAR; PG8_MMA(1, 0, At, B0); PG8_MMA(1, 1, At, B1); PG8_BAR; PG8_SCHED;
;         }
;         if (wr == 0) PG8_BAR;
	s_add_i32 s26, s46, s33
	v_lshl_add_u64 v[190:191], v[190:191], 0, s[2:3]
	s_mov_b32 m0, s26
	ds_read_b128 v[178:181], v145 offset:49152
	ds_read_b128 v[182:185], v145 offset:50176
	ds_read_b128 v[186:189], v145 offset:51200
	ds_read_b128 v[194:197], v145 offset:52224
	ds_read_b128 v[198:201], v145 offset:53248
	ds_read_b128 v[202:205], v145 offset:54272
	ds_read_b128 v[206:209], v145 offset:55296
	ds_read_b128 v[210:213], v145 offset:56320
	global_load_lds_dwordx4 v[190:191], off
	s_add_i32 m0, s26, 0x2000
	s_add_u32 s24, s24, 0x40080
	v_lshl_add_u64 v[190:191], v[214:215], 0, s[2:3]
	s_addc_u32 s25, s25, 0
	s_add_i32 s26, s47, s33
	global_load_lds_dwordx4 v[190:191], off
	v_lshl_add_u64 v[190:191], s[24:25], 0, v[132:133]
	s_mov_b32 m0, s26
	s_nop 0
	global_load_lds_dwordx4 v[190:191], off
	v_lshl_add_u64 v[190:191], s[24:25], 0, v[128:129]
	s_add_i32 m0, s26, 0x2000
	s_nop 0
	global_load_lds_dwordx4 v[190:191], off
	v_lshl_add_u64 v[190:191], v[216:217], 0, s[2:3]
	s_mov_b32 m0, s42
	s_nop 0
	global_load_lds_dwordx4 v[190:191], off
	v_lshl_add_u64 v[190:191], v[218:219], 0, s[2:3]
	s_mov_b32 m0, s43
	s_nop 0
	global_load_lds_dwordx4 v[190:191], off
	s_waitcnt vmcnt(8)
	s_waitcnt lgkmcnt(0)
	s_barrier
	s_waitcnt lgkmcnt(0)
	v_mfma_f32_16x16x32_bf16 v[60:63], v[146:149], v[178:181], v[60:63]
	v_mfma_f32_16x16x32_bf16 v[56:59], v[154:157], v[178:181], v[56:59]
	v_mfma_f32_16x16x32_bf16 v[52:55], v[146:149], v[186:189], v[52:55]
	v_mfma_f32_16x16x32_bf16 v[48:51], v[154:157], v[186:189], v[48:51]
	v_mfma_f32_16x16x32_bf16 v[36:39], v[146:149], v[198:201], v[36:39]
	v_mfma_f32_16x16x32_bf16 v[32:35], v[154:157], v[198:201], v[32:35]
	v_mfma_f32_16x16x32_bf16 v[20:23], v[146:149], v[206:209], v[20:23]
	v_mfma_f32_16x16x32_bf16 v[16:19], v[154:157], v[206:209], v[16:19]
	v_mfma_f32_16x16x32_bf16 v[60:63], v[150:153], v[182:185], v[60:63]
	v_mfma_f32_16x16x32_bf16 v[56:59], v[158:161], v[182:185], v[56:59]
	v_mfma_f32_16x16x32_bf16 v[52:55], v[150:153], v[194:197], v[52:55]
	v_mfma_f32_16x16x32_bf16 v[48:51], v[158:161], v[194:197], v[48:51]
	v_mfma_f32_16x16x32_bf16 v[36:39], v[150:153], v[202:205], v[36:39]
	v_mfma_f32_16x16x32_bf16 v[32:35], v[158:161], v[202:205], v[32:35]
	v_mfma_f32_16x16x32_bf16 v[20:23], v[150:153], v[210:213], v[20:23]
	v_mfma_f32_16x16x32_bf16 v[16:19], v[158:161], v[210:213], v[16:19]
	v_mfma_f32_16x16x32_bf16 v[44:47], v[162:165], v[178:181], v[44:47]
	v_mfma_f32_16x16x32_bf16 v[40:43], v[170:173], v[178:181], v[40:43]
	v_mfma_f32_16x16x32_bf16 v[28:31], v[162:165], v[186:189], v[28:31]
	v_mfma_f32_16x16x32_bf16 v[24:27], v[170:173], v[186:189], v[24:27]
	v_mfma_f32_16x16x32_bf16 v[12:15], v[162:165], v[198:201], v[12:15]
	v_mfma_f32_16x16x32_bf16 v[8:11], v[170:173], v[198:201], v[8:11]
	v_mfma_f32_16x16x32_bf16 v[4:7], v[162:165], v[206:209], v[4:7]
	v_mfma_f32_16x16x32_bf16 v[0:3], v[170:173], v[206:209], v[0:3]
	v_mfma_f32_16x16x32_bf16 v[44:47], v[166:169], v[182:185], v[44:47]
	v_mfma_f32_16x16x32_bf16 v[40:43], v[174:177], v[182:185], v[40:43]
	v_mfma_f32_16x16x32_bf16 v[28:31], v[166:169], v[194:197], v[28:31]
	v_mfma_f32_16x16x32_bf16 v[24:27], v[174:177], v[194:197], v[24:27]
	v_mfma_f32_16x16x32_bf16 v[12:15], v[166:169], v[202:205], v[12:15]
	v_mfma_f32_16x16x32_bf16 v[8:11], v[174:177], v[202:205], v[8:11]
	v_mfma_f32_16x16x32_bf16 v[4:7], v[166:169], v[210:213], v[4:7]
	v_mfma_f32_16x16x32_bf16 v[0:3], v[174:177], v[210:213], v[0:3]
	s_barrier
	s_add_i32 s45, s45, 2
	s_add_u32 s17, s17, 0x100
	s_addc_u32 s19, s19, 0
	s_add_u32 s8, s8, 0x100
	s_addc_u32 s9, s9, 0
	s_cmp_gt_u32 s45, 13
	s_cbranch_scc0 .LBB0_684
	s_setprio 0
	s_and_b64 vcc, exec, s[12:13]
	s_cbranch_vccz .LBB0_687
	s_barrier

; #define PG8_STAGE(bufoff, gbase, voff) do { _Pragma("unroll") for (int _i = 0; _i < 2; ++_i) \
;         __builtin_amdgcn_global_load_lds((const unsigned*)((const char*)(gbase) + (voff)[_i]), (LAS unsigned*)(lds + (bufoff) + ldsw + _i * 8192), 16, 0, 0); } while (0)
; #define PG8_LDA(dst, b, h) do { _Pragma("unroll") for (int m = 0; m < 4; ++m) _Pragma("unroll") for (int k = 0; k < 2; ++k) dst[m][k] = *(const LAS bf16x8*)(lds + PG8_SA(b, h) + aoff + m * 2048 + k * 1024); } while (0)
; #define PG8_LDB(dst, b, h) do { _Pragma("unroll") for (int n = 0; n < 2; ++n) _Pragma("unroll") for (int k = 0; k < 2; ++k) dst[n][k] = *(const LAS bf16x8*)(lds + PG8_SB(b, h) + boff + n * 2048 + k * 1024); } while (0)
; #define PG8_SCHED __builtin_amdgcn_sched_barrier(0)
; template <class Epi>
; DI void gemm_phase(int wv, LAS unsigned char* lds, LAS unsigned char* scr, const Sched& S, const Epi& E) {
;     ...
;         const bool has_next = S.next(ui + 1, nxt);
;         const char* nA = has_next ? S.baseA(nxt) : cA; const char* nB = has_next ? S.baseB(nxt) : cB;
;         for (int t = 0; t < nt; t += 2) {
;             const bool last = (t == nt - 2);
;             const char* a1 = cA + (size_t)(t + 1) * kstep;
;             const char* a2 = last ? nA : cA + (size_t)(t + 2) * kstep; const char* b2 = last ? nB : cB + (size_t)(t + 2) * kstep;
;             const char* a3 = a2 + kstep; const char* b3 = b2 + kstep;
;             PG8_LDB(B0, 0, 0); PG8_LDB(B1, 0, 1); PG8_SCHED; PG8_LDA(At, 0, 0); PG8_STAGE(PG8_SA(1, 1), a1 + hstepA, voffA);
;     ...
; #pragma unroll
;         for (int a = 0; a < 2; ++a)
; #pragma unroll
;             for (int b = 0; b < 2; ++b)
; #pragma unroll
;                 for (int m = 0; m < 4; ++m)
; #pragma unroll
;                     for (int n = 0; n < 2; ++n) acc[a][b][m][n] = (f32x4){0.f, 0.f, 0.f, 0.f};
;         cur = nxt; cA = nA; cB = nB; ++ui;
.LBB0_810:
	s_ashr_i32 s47, s46, 31
	s_lshl_b64 s[50:51], s[46:47], 19
	s_add_u32 s50, s63, s50
	s_addc_u32 s51, s64, s51
	s_and_b64 s[28:29], s[28:29], exec
	s_cselect_b32 s47, s51, s57
	s_cselect_b32 s53, s50, s56
	s_add_u32 s58, s56, 0x100
	s_addc_u32 s59, s57, 0
	s_add_u32 s28, s54, 0x40080
	v_mov_b32_e32 v92, 0
	s_addc_u32 s29, s55, 0
	s_mov_b32 s60, -2
	v_mov_b32_e32 v93, v92
	v_mov_b32_e32 v94, v92
	v_mov_b32_e32 v95, v92
	s_waitcnt vmcnt(0)
	v_mov_b32_e32 v68, v92
	v_mov_b32_e32 v69, v92
	v_mov_b32_e32 v70, v92
	v_mov_b32_e32 v71, v92
	v_mov_b32_e32 v88, v92
	v_mov_b32_e32 v89, v92
	v_mov_b32_e32 v90, v92
	v_mov_b32_e32 v91, v92
	v_mov_b32_e32 v64, v92
	v_mov_b32_e32 v65, v92
	v_mov_b32_e32 v66, v92
	v_mov_b32_e32 v67, v92
	v_mov_b32_e32 v28, v92
	v_mov_b32_e32 v29, v92
	v_mov_b32_e32 v30, v92
	v_mov_b32_e32 v31, v92
	v_mov_b32_e32 v4, v92
	v_mov_b32_e32 v5, v92
	v_mov_b32_e32 v6, v92
	v_mov_b32_e32 v7, v92
	v_mov_b32_e32 v24, v92
	v_mov_b32_e32 v25, v92
	v_mov_b32_e32 v26, v92
	v_mov_b32_e32 v27, v92
	v_mov_b32_e32 v0, v92
	v_mov_b32_e32 v1, v92
	v_mov_b32_e32 v2, v92
	v_mov_b32_e32 v3, v92
	v_mov_b32_e32 v32, v92
	v_mov_b32_e32 v33, v92
	v_mov_b32_e32 v34, v92
	v_mov_b32_e32 v35, v92
	v_mov_b32_e32 v8, v92
	v_mov_b32_e32 v9, v92
	v_mov_b32_e32 v10, v92
	v_mov_b32_e32 v11, v92
	s_waitcnt lgkmcnt(0)
	v_mov_b32_e32 v40, v92
	v_mov_b32_e32 v41, v92
	v_mov_b32_e32 v42, v92
	v_mov_b32_e32 v43, v92
	v_mov_b32_e32 v16, v92
	v_mov_b32_e32 v17, v92
	v_mov_b32_e32 v18, v92
	v_mov_b32_e32 v19, v92
	v_mov_b32_e32 v48, v92
	v_mov_b32_e32 v49, v92
	v_mov_b32_e32 v50, v92
	v_mov_b32_e32 v51, v92
	v_mov_b32_e32 v56, v92
	v_mov_b32_e32 v57, v92
	v_mov_b32_e32 v58, v92
	v_mov_b32_e32 v59, v92
	v_mov_b32_e32 v36, v92
	v_mov_b32_e32 v37, v92
	v_mov_b32_e32 v38, v92
	v_mov_b32_e32 v39, v92
	v_mov_b32_e32 v12, v92
	v_mov_b32_e32 v13, v92
	v_mov_b32_e32 v14, v92
	v_mov_b32_e32 v15, v92
	v_mov_b32_e32 v44, v92
	v_mov_b32_e32 v45, v92
	v_mov_b32_e32 v46, v92
	v_mov_b32_e32 v47, v92
	v_mov_b32_e32 v20, v92
	v_mov_b32_e32 v21, v92
	v_mov_b32_e32 v22, v92
	v_mov_b32_e32 v23, v92
	v_mov_b32_e32 v52, v92
	v_mov_b32_e32 v53, v92
	v_mov_b32_e32 v54, v92
	v_mov_b32_e32 v55, v92
	v_mov_b32_e32 v60, v92
	v_mov_b32_e32 v61, v92
	v_mov_b32_e32 v62, v92
	v_mov_b32_e32 v63, v92
	v_mov_b32_e32 v96, v92
	v_mov_b32_e32 v97, v92
	v_mov_b32_e32 v98, v92
	v_mov_b32_e32 v99, v92
	v_mov_b32_e32 v72, v92
	v_mov_b32_e32 v73, v92
	v_mov_b32_e32 v74, v92
	v_mov_b32_e32 v75, v92
	v_mov_b32_e32 v104, v92
	v_mov_b32_e32 v105, v92
	v_mov_b32_e32 v106, v92
	v_mov_b32_e32 v107, v92
	v_mov_b32_e32 v80, v92
	v_mov_b32_e32 v81, v92
	v_mov_b32_e32 v82, v92
	v_mov_b32_e32 v83, v92
	v_mov_b32_e32 v112, v92
	v_mov_b32_e32 v113, v92
	v_mov_b32_e32 v114, v92
	v_mov_b32_e32 v115, v92
	v_mov_b32_e32 v120, v92
	v_mov_b32_e32 v121, v92
	v_mov_b32_e32 v122, v92
	v_mov_b32_e32 v123, v92
	v_mov_b32_e32 v100, v92
	v_mov_b32_e32 v101, v92
	v_mov_b32_e32 v102, v92
	v_mov_b32_e32 v103, v92
	v_mov_b32_e32 v76, v92
	v_mov_b32_e32 v77, v92
	v_mov_b32_e32 v78, v92
	v_mov_b32_e32 v79, v92
	v_mov_b32_e32 v108, v92
	v_mov_b32_e32 v109, v92
	v_mov_b32_e32 v110, v92
	v_mov_b32_e32 v111, v92
	v_mov_b32_e32 v84, v92
	v_mov_b32_e32 v85, v92
	v_mov_b32_e32 v86, v92
	v_mov_b32_e32 v87, v92
	v_mov_b32_e32 v116, v92
	v_mov_b32_e32 v117, v92
	v_mov_b32_e32 v118, v92
	v_mov_b32_e32 v119, v92
	v_mov_b32_e32 v124, v92
	v_mov_b32_e32 v125, v92
	v_mov_b32_e32 v126, v92
	v_mov_b32_e32 v127, v92
	s_cmp_lg_u64 s[42:43], 0
	s_cbranch_scc1 .Lgp_13
	s_setprio 1
.Lgp_13:
.LBB0_811:
	s_add_u32 s54, s28, 0xfffc0080
	s_addc_u32 s55, s29, -1
	s_add_i32 s61, 0, 0x10000
	s_cmp_eq_u32 s60, 12
	s_cselect_b32 s57, s49, s55
	s_cselect_b32 s56, s48, s54
	s_cselect_b32 s55, s47, s59
	s_cselect_b32 s54, s53, s58
	s_add_i32 s76, 0, 0x14000
	v_add_u32_e32 v140, s61, v199
	v_add_u32_e32 v156, s76, v199
	ds_read_b128 v[128:131], v140
	ds_read_b128 v[132:135], v140 offset:1024
	ds_read_b128 v[136:139], v140 offset:2048
	ds_read_b128 v[140:143], v140 offset:3072
	ds_read_b128 v[144:147], v156
	ds_read_b128 v[148:151], v156 offset:1024
	ds_read_b128 v[152:155], v156 offset:2048
	ds_read_b128 v[156:159], v156 offset:3072
	v_lshl_add_u64 v[204:205], s[28:29], 0, v[178:179]
	s_add_i32 m0, s66, 0xc000
	ds_read_b128 v[160:163], v220
	ds_read_b128 v[164:167], v220 offset:1024
	ds_read_b128 v[180:183], v220 offset:2048
	ds_read_b128 v[184:187], v220 offset:3072
	ds_read_b128 v[188:191], v220 offset:4096
	ds_read_b128 v[194:197], v220 offset:5120
	ds_read_b128 v[200:203], v220 offset:6144
	ds_read_b128 v[222:225], v220 offset:7168
	global_load_lds_dwordx4 v[204:205], off
	v_lshl_add_u64 v[204:205], s[28:29], 0, v[176:177]
	s_add_i32 m0, s66, 0xe000
	s_nop 0
	global_load_lds_dwordx4 v[204:205], off
	s_waitcnt vmcnt(8)
	s_waitcnt lgkmcnt(0)
	s_barrier
; #define PG8_STAGE(bufoff, gbase, voff) do { _Pragma("unroll") for (int _i = 0; _i < 2; ++_i) \
;         __builtin_amdgcn_global_load_lds((const unsigned*)((const char*)(gbase) + (voff)[_i]), (LAS unsigned*)(lds + (bufoff) + ldsw + _i * 8192), 16, 0, 0); } while (0)
; #define PG8_LDA(dst, b, h) do { _Pragma("unroll") for (int m = 0; m < 4; ++m) _Pragma("unroll") for (int k = 0; k < 2; ++k) dst[m][k] = *(const LAS bf16x8*)(lds + PG8_SA(b, h) + aoff + m * 2048 + k * 1024); } while (0)
; #define PG8_MMA(ai, bj, At, Bt) do { __builtin_amdgcn_s_setprio(1); _Pragma("unroll") for (int m = 0; m < 4; ++m) _Pragma("unroll") for (int n = 0; n < 2; ++n) _Pragma("unroll") for (int k = 0; k < 2; ++k) \
;         acc[ai][bj][m][n] = __builtin_amdgcn_mfma_f32_16x16x32_bf16(Bt[n][k], At[m][k], acc[ai][bj][m][n], 0, 0, 0); __builtin_amdgcn_s_setprio(0); } while (0)
; #define PG8_WAIT_V(n) asm volatile("s_waitcnt vmcnt(" #n ")" ::: "memory")
; #define PG8_WAIT_L(n) asm volatile("s_waitcnt lgkmcnt(" #n ")" ::: "memory")
; #define PG8_BAR __builtin_amdgcn_s_barrier()
; #define PG8_SCHED __builtin_amdgcn_sched_barrier(0)
; template <class Epi>
; DI void gemm_phase(int wv, LAS unsigned char* lds, LAS unsigned char* scr, const Sched& S, const Epi& E) {
;     ...
;             PG8_WAIT_V(8); PG8_WAIT_L(0); PG8_BAR; PG8_MMA(0, 0, At, B0); PG8_MMA(0, 1, At, B1); PG8_BAR; PG8_SCHED;
;             PG8_LDA(At, 0, 1); PG8_STAGE(PG8_SB(0, 0), b2, voffB); PG8_STAGE(PG8_SB(0, 1), b2 + hstepB, voffB); PG8_STAGE(PG8_SA(0, 0), a2, voffA);
;             PG8_WAIT_V(8); PG8_WAIT_L(0); PG8_BAR; PG8_MMA(1, 0, At, B0); PG8_MMA(1, 1, At, B1); PG8_BAR; PG8_SCHED;
	s_waitcnt lgkmcnt(0)
	v_mfma_f32_16x16x32_bf16 v[124:127], v[128:131], v[160:163], v[124:127]
	v_mfma_f32_16x16x32_bf16 v[92:95], v[136:139], v[160:163], v[92:95]
	v_mfma_f32_16x16x32_bf16 v[116:119], v[128:131], v[180:183], v[116:119]
	v_mfma_f32_16x16x32_bf16 v[84:87], v[136:139], v[180:183], v[84:87]
	v_mfma_f32_16x16x32_bf16 v[108:111], v[128:131], v[188:191], v[108:111]
	v_mfma_f32_16x16x32_bf16 v[76:79], v[136:139], v[188:191], v[76:79]
	v_mfma_f32_16x16x32_bf16 v[100:103], v[128:131], v[200:203], v[100:103]
	v_mfma_f32_16x16x32_bf16 v[68:71], v[136:139], v[200:203], v[68:71]
	v_mfma_f32_16x16x32_bf16 v[124:127], v[132:135], v[164:167], v[124:127]
	v_mfma_f32_16x16x32_bf16 v[92:95], v[140:143], v[164:167], v[92:95]
	v_mfma_f32_16x16x32_bf16 v[116:119], v[132:135], v[184:187], v[116:119]
	v_mfma_f32_16x16x32_bf16 v[84:87], v[140:143], v[184:187], v[84:87]
	v_mfma_f32_16x16x32_bf16 v[108:111], v[132:135], v[194:197], v[108:111]
	v_mfma_f32_16x16x32_bf16 v[76:79], v[140:143], v[194:197], v[76:79]
	v_mfma_f32_16x16x32_bf16 v[100:103], v[132:135], v[222:225], v[100:103]
	v_mfma_f32_16x16x32_bf16 v[68:71], v[140:143], v[222:225], v[68:71]
	v_mfma_f32_16x16x32_bf16 v[120:123], v[144:147], v[160:163], v[120:123]
	v_mfma_f32_16x16x32_bf16 v[88:91], v[152:155], v[160:163], v[88:91]
	v_mfma_f32_16x16x32_bf16 v[112:115], v[144:147], v[180:183], v[112:115]
	v_mfma_f32_16x16x32_bf16 v[80:83], v[152:155], v[180:183], v[80:83]
	v_mfma_f32_16x16x32_bf16 v[104:107], v[144:147], v[188:191], v[104:107]
	v_mfma_f32_16x16x32_bf16 v[72:75], v[152:155], v[188:191], v[72:75]
	v_mfma_f32_16x16x32_bf16 v[96:99], v[144:147], v[200:203], v[96:99]
	v_mfma_f32_16x16x32_bf16 v[64:67], v[152:155], v[200:203], v[64:67]
	v_mfma_f32_16x16x32_bf16 v[120:123], v[148:151], v[164:167], v[120:123]
	v_mfma_f32_16x16x32_bf16 v[88:91], v[156:159], v[164:167], v[88:91]
	v_mfma_f32_16x16x32_bf16 v[112:115], v[148:151], v[184:187], v[112:115]
	v_mfma_f32_16x16x32_bf16 v[80:83], v[156:159], v[184:187], v[80:83]
	v_mfma_f32_16x16x32_bf16 v[104:107], v[148:151], v[194:197], v[104:107]
	v_mfma_f32_16x16x32_bf16 v[72:75], v[156:159], v[194:197], v[72:75]
	v_mfma_f32_16x16x32_bf16 v[96:99], v[148:151], v[222:225], v[96:99]
	v_mfma_f32_16x16x32_bf16 v[64:67], v[156:159], v[222:225], v[64:67]
	s_barrier
	s_add_i32 s61, s61, s65
	v_lshl_add_u64 v[204:205], s[54:55], 0, v[170:171]
	s_mov_b32 m0, s61
	ds_read_b128 v[160:163], v220 offset:16384
	ds_read_b128 v[164:167], v220 offset:17408
	ds_read_b128 v[180:183], v220 offset:18432
	ds_read_b128 v[184:187], v220 offset:19456
	ds_read_b128 v[188:191], v220 offset:20480
	ds_read_b128 v[194:197], v220 offset:21504
	ds_read_b128 v[200:203], v220 offset:22528
	ds_read_b128 v[222:225], v220 offset:23552
	global_load_lds_dwordx4 v[204:205], off
	s_add_i32 m0, s61, 0x2000
	s_add_u32 s74, s54, 0x40000
	v_lshl_add_u64 v[226:227], s[54:55], 0, v[174:175]
	s_addc_u32 s75, s55, 0
	s_add_i32 s61, s76, s65
	global_load_lds_dwordx4 v[226:227], off
	v_lshl_add_u64 v[228:229], s[74:75], 0, v[170:171]
	s_mov_b32 m0, s61
	v_lshl_add_u64 v[230:231], s[56:57], 0, v[172:173]
	global_load_lds_dwordx4 v[228:229], off
	v_lshl_add_u64 v[228:229], s[74:75], 0, v[174:175]
	s_add_i32 m0, s61, 0x2000
	s_nop 0
	global_load_lds_dwordx4 v[228:229], off
	v_lshl_add_u64 v[228:229], s[56:57], 0, v[168:169]
	s_mov_b32 m0, s66
	s_nop 0
	global_load_lds_dwordx4 v[228:229], off
	s_mov_b32 m0, s67
	s_nop 0
	global_load_lds_dwordx4 v[230:231], off
	s_waitcnt vmcnt(8)
	s_waitcnt lgkmcnt(0)
	s_barrier
	s_waitcnt lgkmcnt(0)
	v_mfma_f32_16x16x32_bf16 v[60:63], v[128:131], v[160:163], v[60:63]
	v_mfma_f32_16x16x32_bf16 v[28:31], v[136:139], v[160:163], v[28:31]
	v_mfma_f32_16x16x32_bf16 v[52:55], v[128:131], v[180:183], v[52:55]
	v_mfma_f32_16x16x32_bf16 v[20:23], v[136:139], v[180:183], v[20:23]
	v_mfma_f32_16x16x32_bf16 v[44:47], v[128:131], v[188:191], v[44:47]
	v_mfma_f32_16x16x32_bf16 v[12:15], v[136:139], v[188:191], v[12:15]
	v_mfma_f32_16x16x32_bf16 v[36:39], v[128:131], v[200:203], v[36:39]
	v_mfma_f32_16x16x32_bf16 v[4:7], v[136:139], v[200:203], v[4:7]
	v_mfma_f32_16x16x32_bf16 v[60:63], v[132:135], v[164:167], v[60:63]
	v_mfma_f32_16x16x32_bf16 v[28:31], v[140:143], v[164:167], v[28:31]
	v_mfma_f32_16x16x32_bf16 v[52:55], v[132:135], v[184:187], v[52:55]
	v_mfma_f32_16x16x32_bf16 v[20:23], v[140:143], v[184:187], v[20:23]
	v_mfma_f32_16x16x32_bf16 v[44:47], v[132:135], v[194:197], v[44:47]
	v_mfma_f32_16x16x32_bf16 v[12:15], v[140:143], v[194:197], v[12:15]
	v_mfma_f32_16x16x32_bf16 v[36:39], v[132:135], v[222:225], v[36:39]
	v_mfma_f32_16x16x32_bf16 v[4:7], v[140:143], v[222:225], v[4:7]
	v_mfma_f32_16x16x32_bf16 v[56:59], v[144:147], v[160:163], v[56:59]
	v_mfma_f32_16x16x32_bf16 v[24:27], v[152:155], v[160:163], v[24:27]
	v_mfma_f32_16x16x32_bf16 v[48:51], v[144:147], v[180:183], v[48:51]
	v_mfma_f32_16x16x32_bf16 v[16:19], v[152:155], v[180:183], v[16:19]
	v_mfma_f32_16x16x32_bf16 v[40:43], v[144:147], v[188:191], v[40:43]
	v_mfma_f32_16x16x32_bf16 v[8:11], v[152:155], v[188:191], v[8:11]
	v_mfma_f32_16x16x32_bf16 v[32:35], v[144:147], v[200:203], v[32:35]
	v_mfma_f32_16x16x32_bf16 v[0:3], v[152:155], v[200:203], v[0:3]
	v_mfma_f32_16x16x32_bf16 v[56:59], v[148:151], v[164:167], v[56:59]
	v_mfma_f32_16x16x32_bf16 v[24:27], v[156:159], v[164:167], v[24:27]
	v_mfma_f32_16x16x32_bf16 v[48:51], v[148:151], v[184:187], v[48:51]
	v_mfma_f32_16x16x32_bf16 v[16:19], v[156:159], v[184:187], v[16:19]
	v_mfma_f32_16x16x32_bf16 v[40:43], v[148:151], v[194:197], v[40:43]
	v_mfma_f32_16x16x32_bf16 v[8:11], v[156:159], v[194:197], v[8:11]
	v_mfma_f32_16x16x32_bf16 v[32:35], v[148:151], v[222:225], v[32:35]
	v_mfma_f32_16x16x32_bf16 v[0:3], v[156:159], v[222:225], v[0:3]
	s_barrier
; #define PG8_STAGE(bufoff, gbase, voff) do { _Pragma("unroll") for (int _i = 0; _i < 2; ++_i) \
;         __builtin_amdgcn_global_load_lds((const unsigned*)((const char*)(gbase) + (voff)[_i]), (LAS unsigned*)(lds + (bufoff) + ldsw + _i * 8192), 16, 0, 0); } while (0)
; #define PG8_LDA(dst, b, h) do { _Pragma("unroll") for (int m = 0; m < 4; ++m) _Pragma("unroll") for (int k = 0; k < 2; ++k) dst[m][k] = *(const LAS bf16x8*)(lds + PG8_SA(b, h) + aoff + m * 2048 + k * 1024); } while (0)
; #define PG8_LDB(dst, b, h) do { _Pragma("unroll") for (int n = 0; n < 2; ++n) _Pragma("unroll") for (int k = 0; k < 2; ++k) dst[n][k] = *(const LAS bf16x8*)(lds + PG8_SB(b, h) + boff + n * 2048 + k * 1024); } while (0)
; #define PG8_MMA(ai, bj, At, Bt) do { __builtin_amdgcn_s_setprio(1); _Pragma("unroll") for (int m = 0; m < 4; ++m) _Pragma("unroll") for (int n = 0; n < 2; ++n) _Pragma("unroll") for (int k = 0; k < 2; ++k) \
;         acc[ai][bj][m][n] = __builtin_amdgcn_mfma_f32_16x16x32_bf16(Bt[n][k], At[m][k], acc[ai][bj][m][n], 0, 0, 0); __builtin_amdgcn_s_setprio(0); } while (0)
; #define PG8_WAIT_V(n) asm volatile("s_waitcnt vmcnt(" #n ")" ::: "memory")
; #define PG8_WAIT_L(n) asm volatile("s_waitcnt lgkmcnt(" #n ")" ::: "memory")
; #define PG8_BAR __builtin_amdgcn_s_barrier()
; #define PG8_SCHED __builtin_amdgcn_sched_barrier(0)
; template <class Epi>
; DI void gemm_phase(int wv, LAS unsigned char* lds, LAS unsigned char* scr, const Sched& S, const Epi& E) {
;     ...
;             PG8_LDB(B0, 1, 0); PG8_LDB(B1, 1, 1); PG8_SCHED; PG8_LDA(At, 1, 0); PG8_STAGE(PG8_SA(0, 1), a2 + hstepA, voffA);
;             PG8_WAIT_V(8); PG8_WAIT_L(0); PG8_BAR; PG8_MMA(0, 0, At, B0); PG8_MMA(0, 1, At, B1); PG8_BAR; PG8_SCHED;
	s_add_i32 s61, 0, 0x18000
	s_add_i32 s74, 0, 0x1c000
	v_add_u32_e32 v140, s61, v199
	v_add_u32_e32 v156, s74, v199
	ds_read_b128 v[128:131], v140
	ds_read_b128 v[132:135], v140 offset:1024
	ds_read_b128 v[136:139], v140 offset:2048
	ds_read_b128 v[140:143], v140 offset:3072
	ds_read_b128 v[144:147], v156
	ds_read_b128 v[148:151], v156 offset:1024
	ds_read_b128 v[152:155], v156 offset:2048
	ds_read_b128 v[156:159], v156 offset:3072
	s_add_u32 s56, s56, 0x40000
	s_addc_u32 s57, s57, 0
	s_mov_b32 m0, s68
	v_lshl_add_u64 v[232:233], s[56:57], 0, v[168:169]
	ds_read_b128 v[160:163], v220 offset:32768
	ds_read_b128 v[164:167], v220 offset:33792
	ds_read_b128 v[180:183], v220 offset:34816
	ds_read_b128 v[184:187], v220 offset:35840
	ds_read_b128 v[188:191], v220 offset:36864
	ds_read_b128 v[194:197], v220 offset:37888
	ds_read_b128 v[200:203], v220 offset:38912
	ds_read_b128 v[222:225], v220 offset:39936
	global_load_lds_dwordx4 v[232:233], off
	v_lshl_add_u64 v[232:233], s[56:57], 0, v[172:173]
	s_mov_b32 m0, s69
	s_nop 0
	global_load_lds_dwordx4 v[232:233], off
	s_waitcnt vmcnt(8)
	s_waitcnt lgkmcnt(0)
	s_barrier
	s_waitcnt lgkmcnt(0)
	v_mfma_f32_16x16x32_bf16 v[124:127], v[128:131], v[160:163], v[124:127]
	v_mfma_f32_16x16x32_bf16 v[92:95], v[136:139], v[160:163], v[92:95]
	v_mfma_f32_16x16x32_bf16 v[116:119], v[128:131], v[180:183], v[116:119]
	v_mfma_f32_16x16x32_bf16 v[84:87], v[136:139], v[180:183], v[84:87]
	v_mfma_f32_16x16x32_bf16 v[108:111], v[128:131], v[188:191], v[108:111]
	v_mfma_f32_16x16x32_bf16 v[76:79], v[136:139], v[188:191], v[76:79]
	v_mfma_f32_16x16x32_bf16 v[100:103], v[128:131], v[200:203], v[100:103]
	v_mfma_f32_16x16x32_bf16 v[68:71], v[136:139], v[200:203], v[68:71]
	v_mfma_f32_16x16x32_bf16 v[124:127], v[132:135], v[164:167], v[124:127]
	v_mfma_f32_16x16x32_bf16 v[92:95], v[140:143], v[164:167], v[92:95]
	v_mfma_f32_16x16x32_bf16 v[116:119], v[132:135], v[184:187], v[116:119]
	v_mfma_f32_16x16x32_bf16 v[84:87], v[140:143], v[184:187], v[84:87]
	v_mfma_f32_16x16x32_bf16 v[108:111], v[132:135], v[194:197], v[108:111]
	v_mfma_f32_16x16x32_bf16 v[76:79], v[140:143], v[194:197], v[76:79]
	v_mfma_f32_16x16x32_bf16 v[100:103], v[132:135], v[222:225], v[100:103]
	v_mfma_f32_16x16x32_bf16 v[68:71], v[140:143], v[222:225], v[68:71]
	v_mfma_f32_16x16x32_bf16 v[120:123], v[144:147], v[160:163], v[120:123]
	v_mfma_f32_16x16x32_bf16 v[88:91], v[152:155], v[160:163], v[88:91]
	v_mfma_f32_16x16x32_bf16 v[112:115], v[144:147], v[180:183], v[112:115]
	v_mfma_f32_16x16x32_bf16 v[80:83], v[152:155], v[180:183], v[80:83]
	v_mfma_f32_16x16x32_bf16 v[104:107], v[144:147], v[188:191], v[104:107]
	v_mfma_f32_16x16x32_bf16 v[72:75], v[152:155], v[188:191], v[72:75]
	v_mfma_f32_16x16x32_bf16 v[96:99], v[144:147], v[200:203], v[96:99]
	v_mfma_f32_16x16x32_bf16 v[64:67], v[152:155], v[200:203], v[64:67]
	v_mfma_f32_16x16x32_bf16 v[120:123], v[148:151], v[164:167], v[120:123]
	v_mfma_f32_16x16x32_bf16 v[88:91], v[156:159], v[164:167], v[88:91]
	v_mfma_f32_16x16x32_bf16 v[112:115], v[148:151], v[184:187], v[112:115]
	v_mfma_f32_16x16x32_bf16 v[80:83], v[156:159], v[184:187], v[80:83]
	v_mfma_f32_16x16x32_bf16 v[104:107], v[148:151], v[194:197], v[104:107]
	v_mfma_f32_16x16x32_bf16 v[72:75], v[156:159], v[194:197], v[72:75]
	v_mfma_f32_16x16x32_bf16 v[96:99], v[148:151], v[222:225], v[96:99]
	v_mfma_f32_16x16x32_bf16 v[64:67], v[156:159], v[222:225], v[64:67]
	s_barrier
; #define PG8_STAGE(bufoff, gbase, voff) do { _Pragma("unroll") for (int _i = 0; _i < 2; ++_i) \
;         __builtin_amdgcn_global_load_lds((const unsigned*)((const char*)(gbase) + (voff)[_i]), (LAS unsigned*)(lds + (bufoff) + ldsw + _i * 8192), 16, 0, 0); } while (0)
; #define PG8_LDA(dst, b, h) do { _Pragma("unroll") for (int m = 0; m < 4; ++m) _Pragma("unroll") for (int k = 0; k < 2; ++k) dst[m][k] = *(const LAS bf16x8*)(lds + PG8_SA(b, h) + aoff + m * 2048 + k * 1024); } while (0)
; #define PG8_MMA(ai, bj, At, Bt) do { __builtin_amdgcn_s_setprio(1); _Pragma("unroll") for (int m = 0; m < 4; ++m) _Pragma("unroll") for (int n = 0; n < 2; ++n) _Pragma("unroll") for (int k = 0; k < 2; ++k) \
;         acc[ai][bj][m][n] = __builtin_amdgcn_mfma_f32_16x16x32_bf16(Bt[n][k], At[m][k], acc[ai][bj][m][n], 0, 0, 0); __builtin_amdgcn_s_setprio(0); } while (0)
; #define PG8_WAIT_V(n) asm volatile("s_waitcnt vmcnt(" #n ")" ::: "memory")
; #define PG8_WAIT_L(n) asm volatile("s_waitcnt lgkmcnt(" #n ")" ::: "memory")
; #define PG8_BAR __builtin_amdgcn_s_barrier()
; #define PG8_SCHED __builtin_amdgcn_sched_barrier(0)
; template <class Epi>
; DI void gemm_phase(int wv, LAS unsigned char* lds, LAS unsigned char* scr, const Sched& S, const Epi& E) {
;     ...
;             PG8_LDA(At, 1, 1); PG8_STAGE(PG8_SB(1, 0), b3, voffB); PG8_STAGE(PG8_SB(1, 1), b3 + hstepB, voffB); PG8_STAGE(PG8_SA(1, 0), a3, voffA);
;             PG8_WAIT_V(8); PG8_WAIT_L(0); PG8_BAR; PG8_MMA(1, 0, At, B0); PG8_MMA(1, 1, At, B1); PG8_BAR; PG8_SCHED;
;         }
;         if (wr == 0) PG8_BAR;
	s_add_i32 s56, s61, s65
	v_lshl_add_u64 v[204:205], v[204:205], 0, s[2:3]
	s_mov_b32 m0, s56
	ds_read_b128 v[160:163], v220 offset:49152
	ds_read_b128 v[164:167], v220 offset:50176
	ds_read_b128 v[180:183], v220 offset:51200
	ds_read_b128 v[184:187], v220 offset:52224
	ds_read_b128 v[188:191], v220 offset:53248
	ds_read_b128 v[194:197], v220 offset:54272
	ds_read_b128 v[200:203], v220 offset:55296
	ds_read_b128 v[222:225], v220 offset:56320
	global_load_lds_dwordx4 v[204:205], off
	s_add_i32 m0, s56, 0x2000
	s_add_u32 s54, s54, 0x40080
	v_lshl_add_u64 v[204:205], v[226:227], 0, s[2:3]
	s_addc_u32 s55, s55, 0
	s_add_i32 s56, s74, s65
	global_load_lds_dwordx4 v[204:205], off
	v_lshl_add_u64 v[204:205], s[54:55], 0, v[170:171]
	s_mov_b32 m0, s56
	s_nop 0
	global_load_lds_dwordx4 v[204:205], off
	v_lshl_add_u64 v[204:205], s[54:55], 0, v[174:175]
	s_add_i32 m0, s56, 0x2000
	s_nop 0
	global_load_lds_dwordx4 v[204:205], off
	v_lshl_add_u64 v[204:205], v[228:229], 0, s[2:3]
	s_mov_b32 m0, s70
	s_nop 0
	global_load_lds_dwordx4 v[204:205], off
	v_lshl_add_u64 v[204:205], v[230:231], 0, s[2:3]
	s_mov_b32 m0, s71
	s_nop 0
	global_load_lds_dwordx4 v[204:205], off
	s_waitcnt vmcnt(8)
	s_waitcnt lgkmcnt(0)
	s_barrier
	s_waitcnt lgkmcnt(0)
	v_mfma_f32_16x16x32_bf16 v[60:63], v[128:131], v[160:163], v[60:63]
	v_mfma_f32_16x16x32_bf16 v[28:31], v[136:139], v[160:163], v[28:31]
	v_mfma_f32_16x16x32_bf16 v[52:55], v[128:131], v[180:183], v[52:55]
	v_mfma_f32_16x16x32_bf16 v[20:23], v[136:139], v[180:183], v[20:23]
	v_mfma_f32_16x16x32_bf16 v[44:47], v[128:131], v[188:191], v[44:47]
	v_mfma_f32_16x16x32_bf16 v[12:15], v[136:139], v[188:191], v[12:15]
	v_mfma_f32_16x16x32_bf16 v[36:39], v[128:131], v[200:203], v[36:39]
	v_mfma_f32_16x16x32_bf16 v[4:7], v[136:139], v[200:203], v[4:7]
	v_mfma_f32_16x16x32_bf16 v[60:63], v[132:135], v[164:167], v[60:63]
	v_mfma_f32_16x16x32_bf16 v[28:31], v[140:143], v[164:167], v[28:31]
	v_mfma_f32_16x16x32_bf16 v[52:55], v[132:135], v[184:187], v[52:55]
	v_mfma_f32_16x16x32_bf16 v[20:23], v[140:143], v[184:187], v[20:23]
	v_mfma_f32_16x16x32_bf16 v[44:47], v[132:135], v[194:197], v[44:47]
	v_mfma_f32_16x16x32_bf16 v[12:15], v[140:143], v[194:197], v[12:15]
	v_mfma_f32_16x16x32_bf16 v[36:39], v[132:135], v[222:225], v[36:39]
	v_mfma_f32_16x16x32_bf16 v[4:7], v[140:143], v[222:225], v[4:7]
	v_mfma_f32_16x16x32_bf16 v[56:59], v[144:147], v[160:163], v[56:59]
	v_mfma_f32_16x16x32_bf16 v[24:27], v[152:155], v[160:163], v[24:27]
	v_mfma_f32_16x16x32_bf16 v[48:51], v[144:147], v[180:183], v[48:51]
	v_mfma_f32_16x16x32_bf16 v[16:19], v[152:155], v[180:183], v[16:19]
	v_mfma_f32_16x16x32_bf16 v[40:43], v[144:147], v[188:191], v[40:43]
	v_mfma_f32_16x16x32_bf16 v[8:11], v[152:155], v[188:191], v[8:11]
	v_mfma_f32_16x16x32_bf16 v[32:35], v[144:147], v[200:203], v[32:35]
	v_mfma_f32_16x16x32_bf16 v[0:3], v[152:155], v[200:203], v[0:3]
	v_mfma_f32_16x16x32_bf16 v[56:59], v[148:151], v[164:167], v[56:59]
	v_mfma_f32_16x16x32_bf16 v[24:27], v[156:159], v[164:167], v[24:27]
	v_mfma_f32_16x16x32_bf16 v[48:51], v[148:151], v[184:187], v[48:51]
	v_mfma_f32_16x16x32_bf16 v[16:19], v[156:159], v[184:187], v[16:19]
	v_mfma_f32_16x16x32_bf16 v[40:43], v[148:151], v[194:197], v[40:43]
	v_mfma_f32_16x16x32_bf16 v[8:11], v[156:159], v[194:197], v[8:11]
	v_mfma_f32_16x16x32_bf16 v[32:35], v[148:151], v[222:225], v[32:35]
	v_mfma_f32_16x16x32_bf16 v[0:3], v[156:159], v[222:225], v[0:3]
	s_barrier
	s_add_i32 s60, s60, 2
	s_add_u32 s58, s58, 0x100
	s_addc_u32 s59, s59, 0
	s_add_u32 s28, s28, 0x100
	s_addc_u32 s29, s29, 0
	s_cmp_gt_u32 s60, 13
	s_cbranch_scc0 .LBB0_811
	s_setprio 0
	s_and_b64 vcc, exec, s[42:43]
	s_cbranch_vccz .LBB0_814
	s_barrier

; #define PG8_STAGE(bufoff, gbase, voff) do { _Pragma("unroll") for (int _i = 0; _i < 2; ++_i) \
;         __builtin_amdgcn_global_load_lds((const unsigned*)((const char*)(gbase) + (voff)[_i]), (LAS unsigned*)(lds + (bufoff) + ldsw + _i * 8192), 16, 0, 0); } while (0)
; #define PG8_LDA(dst, b, h) do { _Pragma("unroll") for (int m = 0; m < 4; ++m) _Pragma("unroll") for (int k = 0; k < 2; ++k) dst[m][k] = *(const LAS bf16x8*)(lds + PG8_SA(b, h) + aoff + m * 2048 + k * 1024); } while (0)
; #define PG8_LDB(dst, b, h) do { _Pragma("unroll") for (int n = 0; n < 2; ++n) _Pragma("unroll") for (int k = 0; k < 2; ++k) dst[n][k] = *(const LAS bf16x8*)(lds + PG8_SB(b, h) + boff + n * 2048 + k * 1024); } while (0)
; #define PG8_MMA(ai, bj, At, Bt) do { __builtin_amdgcn_s_setprio(1); _Pragma("unroll") for (int m = 0; m < 4; ++m) _Pragma("unroll") for (int n = 0; n < 2; ++n) _Pragma("unroll") for (int k = 0; k < 2; ++k) \
;         acc[ai][bj][m][n] = __builtin_amdgcn_mfma_f32_16x16x32_bf16(Bt[n][k], At[m][k], acc[ai][bj][m][n], 0, 0, 0); __builtin_amdgcn_s_setprio(0); } while (0)
; #define PG8_WAIT_V(n) asm volatile("s_waitcnt vmcnt(" #n ")" ::: "memory")
; #define PG8_WAIT_L(n) asm volatile("s_waitcnt lgkmcnt(" #n ")" ::: "memory")
; #define PG8_BAR __builtin_amdgcn_s_barrier()
; template <class Epi>
; DI void gemm_phase(int wv, LAS unsigned char* lds, LAS unsigned char* scr, const Sched& S, const Epi& E) {
;     ...
;         for (int t = 0; t < nt; t += 2) {
;             const bool last = (t == nt - 2);
;             const char* a1 = cA + (size_t)(t + 1) * kstep;
;             const char* a2 = last ? nA : cA + (size_t)(t + 2) * kstep; const char* b2 = last ? nB : cB + (size_t)(t + 2) * kstep;
;             const char* a3 = a2 + kstep; const char* b3 = b2 + kstep;
;             PG8_LDB(B0, 0, 0); PG8_LDB(B1, 0, 1); PG8_SCHED; PG8_LDA(At, 0, 0); PG8_STAGE(PG8_SA(1, 1), a1 + hstepA, voffA);
;             PG8_WAIT_V(8); PG8_WAIT_L(0); PG8_BAR; PG8_MMA(0, 0, At, B0); PG8_MMA(0, 1, At, B1); PG8_BAR; PG8_SCHED;
;     ...
; #pragma unroll
;         for (int a = 0; a < 2; ++a)
; #pragma unroll
;             for (int b = 0; b < 2; ++b)
; #pragma unroll
;                 for (int m = 0; m < 4; ++m)
; #pragma unroll
;                     for (int n = 0; n < 2; ++n) acc[a][b][m][n] = (f32x4){0.f, 0.f, 0.f, 0.f};
;         cur = nxt; cA = nA; cB = nB; ++ui;
.LBB0_935:
	s_add_u32 s25, s30, 0x100
	v_mov_b32_e32 v0, 0
	s_addc_u32 s27, s31, 0
	s_mov_b32 s68, -2
	v_mov_b32_e32 v1, v0
	v_mov_b32_e32 v2, v0
	v_mov_b32_e32 v3, v0
	v_mov_b32_e32 v4, v0
	v_mov_b32_e32 v5, v0
	v_mov_b32_e32 v6, v0
	v_mov_b32_e32 v7, v0
	v_mov_b32_e32 v8, v0
	v_mov_b32_e32 v9, v0
	v_mov_b32_e32 v10, v0
	v_mov_b32_e32 v11, v0
	v_mov_b32_e32 v12, v0
	v_mov_b32_e32 v13, v0
	v_mov_b32_e32 v14, v0
	v_mov_b32_e32 v15, v0
	v_mov_b32_e32 v24, v0
	v_mov_b32_e32 v25, v0
	v_mov_b32_e32 v26, v0
	v_mov_b32_e32 v27, v0
	v_mov_b32_e32 v28, v0
	v_mov_b32_e32 v29, v0
	v_mov_b32_e32 v30, v0
	v_mov_b32_e32 v31, v0
	v_mov_b32_e32 v40, v0
	v_mov_b32_e32 v41, v0
	v_mov_b32_e32 v42, v0
	v_mov_b32_e32 v43, v0
	v_mov_b32_e32 v44, v0
	v_mov_b32_e32 v45, v0
	v_mov_b32_e32 v46, v0
	v_mov_b32_e32 v47, v0
	v_mov_b32_e32 v16, v0
	v_mov_b32_e32 v17, v0
	v_mov_b32_e32 v18, v0
	v_mov_b32_e32 v19, v0
	v_mov_b32_e32 v20, v0
	v_mov_b32_e32 v21, v0
	v_mov_b32_e32 v22, v0
	v_mov_b32_e32 v23, v0
	v_mov_b32_e32 v32, v0
	v_mov_b32_e32 v33, v0
	v_mov_b32_e32 v34, v0
	v_mov_b32_e32 v35, v0
	v_mov_b32_e32 v36, v0
	v_mov_b32_e32 v37, v0
	v_mov_b32_e32 v38, v0
	v_mov_b32_e32 v39, v0
	v_mov_b32_e32 v48, v0
	v_mov_b32_e32 v49, v0
	v_mov_b32_e32 v50, v0
	v_mov_b32_e32 v51, v0
	v_mov_b32_e32 v52, v0
	v_mov_b32_e32 v53, v0
	v_mov_b32_e32 v54, v0
	v_mov_b32_e32 v55, v0
	v_mov_b32_e32 v56, v0
	v_mov_b32_e32 v57, v0
	v_mov_b32_e32 v58, v0
	v_mov_b32_e32 v59, v0
	v_mov_b32_e32 v60, v0
	v_mov_b32_e32 v61, v0
	v_mov_b32_e32 v62, v0
	v_mov_b32_e32 v63, v0
	v_mov_b32_e32 v64, v0
	v_mov_b32_e32 v65, v0
	v_mov_b32_e32 v66, v0
	v_mov_b32_e32 v67, v0
	v_mov_b32_e32 v68, v0
	v_mov_b32_e32 v69, v0
	v_mov_b32_e32 v70, v0
	v_mov_b32_e32 v71, v0
	v_mov_b32_e32 v72, v0
	v_mov_b32_e32 v73, v0
	v_mov_b32_e32 v74, v0
	v_mov_b32_e32 v75, v0
	v_mov_b32_e32 v76, v0
	v_mov_b32_e32 v77, v0
	v_mov_b32_e32 v78, v0
	v_mov_b32_e32 v79, v0
	v_mov_b32_e32 v88, v0
	v_mov_b32_e32 v89, v0
	v_mov_b32_e32 v90, v0
	v_mov_b32_e32 v91, v0
	v_mov_b32_e32 v92, v0
	v_mov_b32_e32 v93, v0
	v_mov_b32_e32 v94, v0
	v_mov_b32_e32 v95, v0
	v_mov_b32_e32 v104, v0
	v_mov_b32_e32 v105, v0
	v_mov_b32_e32 v106, v0
	v_mov_b32_e32 v107, v0
	v_mov_b32_e32 v108, v0
	v_mov_b32_e32 v109, v0
	v_mov_b32_e32 v110, v0
	v_mov_b32_e32 v111, v0
	v_mov_b32_e32 v80, v0
	v_mov_b32_e32 v81, v0
	v_mov_b32_e32 v82, v0
	v_mov_b32_e32 v83, v0
	v_mov_b32_e32 v84, v0
	v_mov_b32_e32 v85, v0
	v_mov_b32_e32 v86, v0
	v_mov_b32_e32 v87, v0
	v_mov_b32_e32 v96, v0
	v_mov_b32_e32 v97, v0
	v_mov_b32_e32 v98, v0
	v_mov_b32_e32 v99, v0
	v_mov_b32_e32 v100, v0
	v_mov_b32_e32 v101, v0
	v_mov_b32_e32 v102, v0
	v_mov_b32_e32 v103, v0
	v_mov_b32_e32 v112, v0
	v_mov_b32_e32 v113, v0
	v_mov_b32_e32 v114, v0
	v_mov_b32_e32 v115, v0
	v_mov_b32_e32 v116, v0
	v_mov_b32_e32 v117, v0
	v_mov_b32_e32 v118, v0
	v_mov_b32_e32 v119, v0
	v_mov_b32_e32 v120, v0
	v_mov_b32_e32 v121, v0
	v_mov_b32_e32 v122, v0
	v_mov_b32_e32 v123, v0
	v_mov_b32_e32 v124, v0
	v_mov_b32_e32 v125, v0
	v_mov_b32_e32 v126, v0
	v_mov_b32_e32 v127, v0
	s_cmp_lg_u64 s[20:21], 0
	s_cbranch_scc1 .Lgp_14
	s_setprio 1
.Lgp_14:
.LBB0_936:
	s_add_u32 s30, s28, 0x100
	s_addc_u32 s31, s29, 0
	s_add_i32 s69, 0, 0x10000
	s_cmp_eq_u32 s68, 40
	s_cselect_b32 s37, s9, s31
	s_cselect_b32 s36, s8, s30
	s_cselect_b32 s35, s23, s27
	s_cselect_b32 s34, s22, s25
	s_add_i32 s70, 0, 0x14000
	v_add_u32_e32 v156, s69, v142
	v_add_u32_e32 v172, s70, v142
	ds_read_b128 v[144:147], v156
	ds_read_b128 v[148:151], v156 offset:1024
	ds_read_b128 v[152:155], v156 offset:2048
	ds_read_b128 v[156:159], v156 offset:3072
	ds_read_b128 v[160:163], v172
	ds_read_b128 v[164:167], v172 offset:1024
	ds_read_b128 v[168:171], v172 offset:2048
	ds_read_b128 v[172:175], v172 offset:3072
	v_lshl_add_u64 v[210:211], s[28:29], 0, v[140:141]
	s_add_i32 m0, s57, 0xc000
	ds_read_b128 v[176:179], v143
	ds_read_b128 v[180:183], v143 offset:1024
	ds_read_b128 v[184:187], v143 offset:2048
	ds_read_b128 v[188:191], v143 offset:3072
	ds_read_b128 v[194:197], v143 offset:4096
	ds_read_b128 v[198:201], v143 offset:5120
	ds_read_b128 v[202:205], v143 offset:6144
	ds_read_b128 v[206:209], v143 offset:7168
	global_load_lds_dwordx4 v[210:211], off
	v_lshl_add_u64 v[210:211], s[28:29], 0, v[138:139]
	s_add_i32 m0, s57, 0xe000
	s_nop 0
	global_load_lds_dwordx4 v[210:211], off
	s_waitcnt vmcnt(8)
	s_waitcnt lgkmcnt(0)
	s_barrier
	s_waitcnt lgkmcnt(0)
	v_mfma_f32_16x16x32_bf16 v[124:127], v[144:147], v[176:179], v[124:127]
	v_mfma_f32_16x16x32_bf16 v[120:123], v[152:155], v[176:179], v[120:123]
	v_mfma_f32_16x16x32_bf16 v[116:119], v[144:147], v[184:187], v[116:119]
	v_mfma_f32_16x16x32_bf16 v[112:115], v[152:155], v[184:187], v[112:115]
	v_mfma_f32_16x16x32_bf16 v[100:103], v[144:147], v[194:197], v[100:103]
	v_mfma_f32_16x16x32_bf16 v[96:99], v[152:155], v[194:197], v[96:99]
	v_mfma_f32_16x16x32_bf16 v[84:87], v[144:147], v[202:205], v[84:87]
	v_mfma_f32_16x16x32_bf16 v[80:83], v[152:155], v[202:205], v[80:83]
	v_mfma_f32_16x16x32_bf16 v[124:127], v[148:151], v[180:183], v[124:127]
	v_mfma_f32_16x16x32_bf16 v[120:123], v[156:159], v[180:183], v[120:123]
	v_mfma_f32_16x16x32_bf16 v[116:119], v[148:151], v[188:191], v[116:119]
	v_mfma_f32_16x16x32_bf16 v[112:115], v[156:159], v[188:191], v[112:115]
	v_mfma_f32_16x16x32_bf16 v[100:103], v[148:151], v[198:201], v[100:103]
	v_mfma_f32_16x16x32_bf16 v[96:99], v[156:159], v[198:201], v[96:99]
	v_mfma_f32_16x16x32_bf16 v[84:87], v[148:151], v[206:209], v[84:87]
	v_mfma_f32_16x16x32_bf16 v[80:83], v[156:159], v[206:209], v[80:83]
	v_mfma_f32_16x16x32_bf16 v[108:111], v[160:163], v[176:179], v[108:111]
	v_mfma_f32_16x16x32_bf16 v[104:107], v[168:171], v[176:179], v[104:107]
	v_mfma_f32_16x16x32_bf16 v[92:95], v[160:163], v[184:187], v[92:95]
	v_mfma_f32_16x16x32_bf16 v[88:91], v[168:171], v[184:187], v[88:91]
	v_mfma_f32_16x16x32_bf16 v[76:79], v[160:163], v[194:197], v[76:79]
	v_mfma_f32_16x16x32_bf16 v[72:75], v[168:171], v[194:197], v[72:75]
	v_mfma_f32_16x16x32_bf16 v[68:71], v[160:163], v[202:205], v[68:71]
	v_mfma_f32_16x16x32_bf16 v[64:67], v[168:171], v[202:205], v[64:67]
	v_mfma_f32_16x16x32_bf16 v[108:111], v[164:167], v[180:183], v[108:111]
	v_mfma_f32_16x16x32_bf16 v[104:107], v[172:175], v[180:183], v[104:107]
	v_mfma_f32_16x16x32_bf16 v[92:95], v[164:167], v[188:191], v[92:95]
	v_mfma_f32_16x16x32_bf16 v[88:91], v[172:175], v[188:191], v[88:91]
	v_mfma_f32_16x16x32_bf16 v[76:79], v[164:167], v[198:201], v[76:79]
	v_mfma_f32_16x16x32_bf16 v[72:75], v[172:175], v[198:201], v[72:75]
	v_mfma_f32_16x16x32_bf16 v[68:71], v[164:167], v[206:209], v[68:71]
	v_mfma_f32_16x16x32_bf16 v[64:67], v[172:175], v[206:209], v[64:67]
	s_barrier
; #define PG8_STAGE(bufoff, gbase, voff) do { _Pragma("unroll") for (int _i = 0; _i < 2; ++_i) \
;         __builtin_amdgcn_global_load_lds((const unsigned*)((const char*)(gbase) + (voff)[_i]), (LAS unsigned*)(lds + (bufoff) + ldsw + _i * 8192), 16, 0, 0); } while (0)
; #define PG8_LDA(dst, b, h) do { _Pragma("unroll") for (int m = 0; m < 4; ++m) _Pragma("unroll") for (int k = 0; k < 2; ++k) dst[m][k] = *(const LAS bf16x8*)(lds + PG8_SA(b, h) + aoff + m * 2048 + k * 1024); } while (0)
; #define PG8_LDB(dst, b, h) do { _Pragma("unroll") for (int n = 0; n < 2; ++n) _Pragma("unroll") for (int k = 0; k < 2; ++k) dst[n][k] = *(const LAS bf16x8*)(lds + PG8_SB(b, h) + boff + n * 2048 + k * 1024); } while (0)
; #define PG8_MMA(ai, bj, At, Bt) do { __builtin_amdgcn_s_setprio(1); _Pragma("unroll") for (int m = 0; m < 4; ++m) _Pragma("unroll") for (int n = 0; n < 2; ++n) _Pragma("unroll") for (int k = 0; k < 2; ++k) \
;         acc[ai][bj][m][n] = __builtin_amdgcn_mfma_f32_16x16x32_bf16(Bt[n][k], At[m][k], acc[ai][bj][m][n], 0, 0, 0); __builtin_amdgcn_s_setprio(0); } while (0)
; #define PG8_WAIT_V(n) asm volatile("s_waitcnt vmcnt(" #n ")" ::: "memory")
; #define PG8_WAIT_L(n) asm volatile("s_waitcnt lgkmcnt(" #n ")" ::: "memory")
; #define PG8_BAR __builtin_amdgcn_s_barrier()
; #define PG8_SCHED __builtin_amdgcn_sched_barrier(0)
; template <class Epi>
; DI void gemm_phase(int wv, LAS unsigned char* lds, LAS unsigned char* scr, const Sched& S, const Epi& E) {
;     ...
;             PG8_LDA(At, 0, 1); PG8_STAGE(PG8_SB(0, 0), b2, voffB); PG8_STAGE(PG8_SB(0, 1), b2 + hstepB, voffB); PG8_STAGE(PG8_SA(0, 0), a2, voffA);
;             PG8_WAIT_V(8); PG8_WAIT_L(0); PG8_BAR; PG8_MMA(1, 0, At, B0); PG8_MMA(1, 1, At, B1); PG8_BAR; PG8_SCHED;
;             PG8_LDB(B0, 1, 0); PG8_LDB(B1, 1, 1); PG8_SCHED; PG8_LDA(At, 1, 0); PG8_STAGE(PG8_SA(0, 1), a2 + hstepA, voffA);
	s_add_i32 s28, s69, s56
	v_lshl_add_u64 v[210:211], s[34:35], 0, v[132:133]
	s_mov_b32 m0, s28
	ds_read_b128 v[176:179], v143 offset:16384
	ds_read_b128 v[180:183], v143 offset:17408
	ds_read_b128 v[184:187], v143 offset:18432
	ds_read_b128 v[188:191], v143 offset:19456
	ds_read_b128 v[194:197], v143 offset:20480
	ds_read_b128 v[198:201], v143 offset:21504
	ds_read_b128 v[202:205], v143 offset:22528
	ds_read_b128 v[206:209], v143 offset:23552
	global_load_lds_dwordx4 v[210:211], off
	s_add_i32 m0, s28, 0x2000
	s_add_u32 s28, s34, 0xb0000
	v_lshl_add_u64 v[212:213], s[34:35], 0, v[128:129]
	s_addc_u32 s29, s35, 0
	s_add_i32 s69, s70, s56
	global_load_lds_dwordx4 v[212:213], off
	v_lshl_add_u64 v[214:215], s[28:29], 0, v[132:133]
	s_mov_b32 m0, s69
	v_lshl_add_u64 v[216:217], s[36:37], 0, v[130:131]
	global_load_lds_dwordx4 v[214:215], off
	v_lshl_add_u64 v[214:215], s[28:29], 0, v[128:129]
	s_add_i32 m0, s69, 0x2000
	s_nop 0
	global_load_lds_dwordx4 v[214:215], off
	v_lshl_add_u64 v[214:215], s[36:37], 0, v[134:135]
	s_mov_b32 m0, s57
	s_nop 0
	global_load_lds_dwordx4 v[214:215], off
	s_mov_b32 m0, s58
	s_nop 0
	global_load_lds_dwordx4 v[216:217], off
	s_waitcnt vmcnt(8)
	s_waitcnt lgkmcnt(0)
	s_barrier
	s_waitcnt lgkmcnt(0)
	v_mfma_f32_16x16x32_bf16 v[60:63], v[144:147], v[176:179], v[60:63]
	v_mfma_f32_16x16x32_bf16 v[56:59], v[152:155], v[176:179], v[56:59]
	v_mfma_f32_16x16x32_bf16 v[52:55], v[144:147], v[184:187], v[52:55]
	v_mfma_f32_16x16x32_bf16 v[48:51], v[152:155], v[184:187], v[48:51]
	v_mfma_f32_16x16x32_bf16 v[36:39], v[144:147], v[194:197], v[36:39]
	v_mfma_f32_16x16x32_bf16 v[32:35], v[152:155], v[194:197], v[32:35]
	v_mfma_f32_16x16x32_bf16 v[20:23], v[144:147], v[202:205], v[20:23]
	v_mfma_f32_16x16x32_bf16 v[16:19], v[152:155], v[202:205], v[16:19]
	v_mfma_f32_16x16x32_bf16 v[60:63], v[148:151], v[180:183], v[60:63]
	v_mfma_f32_16x16x32_bf16 v[56:59], v[156:159], v[180:183], v[56:59]
	v_mfma_f32_16x16x32_bf16 v[52:55], v[148:151], v[188:191], v[52:55]
	v_mfma_f32_16x16x32_bf16 v[48:51], v[156:159], v[188:191], v[48:51]
	v_mfma_f32_16x16x32_bf16 v[36:39], v[148:151], v[198:201], v[36:39]
	v_mfma_f32_16x16x32_bf16 v[32:35], v[156:159], v[198:201], v[32:35]
	v_mfma_f32_16x16x32_bf16 v[20:23], v[148:151], v[206:209], v[20:23]
	v_mfma_f32_16x16x32_bf16 v[16:19], v[156:159], v[206:209], v[16:19]
	v_mfma_f32_16x16x32_bf16 v[44:47], v[160:163], v[176:179], v[44:47]
	v_mfma_f32_16x16x32_bf16 v[40:43], v[168:171], v[176:179], v[40:43]
	v_mfma_f32_16x16x32_bf16 v[28:31], v[160:163], v[184:187], v[28:31]
	v_mfma_f32_16x16x32_bf16 v[24:27], v[168:171], v[184:187], v[24:27]
	v_mfma_f32_16x16x32_bf16 v[12:15], v[160:163], v[194:197], v[12:15]
	v_mfma_f32_16x16x32_bf16 v[8:11], v[168:171], v[194:197], v[8:11]
	v_mfma_f32_16x16x32_bf16 v[4:7], v[160:163], v[202:205], v[4:7]
	v_mfma_f32_16x16x32_bf16 v[0:3], v[168:171], v[202:205], v[0:3]
	v_mfma_f32_16x16x32_bf16 v[44:47], v[164:167], v[180:183], v[44:47]
	v_mfma_f32_16x16x32_bf16 v[40:43], v[172:175], v[180:183], v[40:43]
	v_mfma_f32_16x16x32_bf16 v[28:31], v[164:167], v[188:191], v[28:31]
	v_mfma_f32_16x16x32_bf16 v[24:27], v[172:175], v[188:191], v[24:27]
	v_mfma_f32_16x16x32_bf16 v[12:15], v[164:167], v[198:201], v[12:15]
	v_mfma_f32_16x16x32_bf16 v[8:11], v[172:175], v[198:201], v[8:11]
	v_mfma_f32_16x16x32_bf16 v[4:7], v[164:167], v[206:209], v[4:7]
	v_mfma_f32_16x16x32_bf16 v[0:3], v[172:175], v[206:209], v[0:3]
	s_barrier
	s_add_i32 s69, 0, 0x18000
	s_add_i32 s70, 0, 0x1c000
	v_add_u32_e32 v156, s69, v142
	v_add_u32_e32 v172, s70, v142
	ds_read_b128 v[144:147], v156
	ds_read_b128 v[148:151], v156 offset:1024
	ds_read_b128 v[152:155], v156 offset:2048
	ds_read_b128 v[156:159], v156 offset:3072
	ds_read_b128 v[160:163], v172
	ds_read_b128 v[164:167], v172 offset:1024
	ds_read_b128 v[168:171], v172 offset:2048
	ds_read_b128 v[172:175], v172 offset:3072
	s_add_u32 s28, s36, 0xb0000
	s_addc_u32 s29, s37, 0
	s_mov_b32 m0, s59
	v_lshl_add_u64 v[218:219], s[28:29], 0, v[134:135]
	ds_read_b128 v[176:179], v143 offset:32768
	ds_read_b128 v[180:183], v143 offset:33792
	ds_read_b128 v[184:187], v143 offset:34816
	ds_read_b128 v[188:191], v143 offset:35840
	ds_read_b128 v[194:197], v143 offset:36864
	ds_read_b128 v[198:201], v143 offset:37888
	ds_read_b128 v[202:205], v143 offset:38912
	ds_read_b128 v[206:209], v143 offset:39936
	global_load_lds_dwordx4 v[218:219], off
	v_lshl_add_u64 v[218:219], s[28:29], 0, v[130:131]
	s_mov_b32 m0, s60
	s_nop 0
	global_load_lds_dwordx4 v[218:219], off
	s_waitcnt vmcnt(8)
	s_waitcnt lgkmcnt(0)
	s_barrier
; #define PG8_STAGE(bufoff, gbase, voff) do { _Pragma("unroll") for (int _i = 0; _i < 2; ++_i) \
;         __builtin_amdgcn_global_load_lds((const unsigned*)((const char*)(gbase) + (voff)[_i]), (LAS unsigned*)(lds + (bufoff) + ldsw + _i * 8192), 16, 0, 0); } while (0)
; #define PG8_LDA(dst, b, h) do { _Pragma("unroll") for (int m = 0; m < 4; ++m) _Pragma("unroll") for (int k = 0; k < 2; ++k) dst[m][k] = *(const LAS bf16x8*)(lds + PG8_SA(b, h) + aoff + m * 2048 + k * 1024); } while (0)
; #define PG8_MMA(ai, bj, At, Bt) do { __builtin_amdgcn_s_setprio(1); _Pragma("unroll") for (int m = 0; m < 4; ++m) _Pragma("unroll") for (int n = 0; n < 2; ++n) _Pragma("unroll") for (int k = 0; k < 2; ++k) \
;         acc[ai][bj][m][n] = __builtin_amdgcn_mfma_f32_16x16x32_bf16(Bt[n][k], At[m][k], acc[ai][bj][m][n], 0, 0, 0); __builtin_amdgcn_s_setprio(0); } while (0)
; #define PG8_WAIT_V(n) asm volatile("s_waitcnt vmcnt(" #n ")" ::: "memory")
; #define PG8_WAIT_L(n) asm volatile("s_waitcnt lgkmcnt(" #n ")" ::: "memory")
; #define PG8_BAR __builtin_amdgcn_s_barrier()
; #define PG8_SCHED __builtin_amdgcn_sched_barrier(0)
; template <class Epi>
; DI void gemm_phase(int wv, LAS unsigned char* lds, LAS unsigned char* scr, const Sched& S, const Epi& E) {
;     ...
;             PG8_WAIT_V(8); PG8_WAIT_L(0); PG8_BAR; PG8_MMA(0, 0, At, B0); PG8_MMA(0, 1, At, B1); PG8_BAR; PG8_SCHED;
;             PG8_LDA(At, 1, 1); PG8_STAGE(PG8_SB(1, 0), b3, voffB); PG8_STAGE(PG8_SB(1, 1), b3 + hstepB, voffB); PG8_STAGE(PG8_SA(1, 0), a3, voffA);
;             PG8_WAIT_V(8); PG8_WAIT_L(0); PG8_BAR; PG8_MMA(1, 0, At, B0); PG8_MMA(1, 1, At, B1); PG8_BAR; PG8_SCHED;
;         }
;         if (wr == 0) PG8_BAR;
	s_waitcnt lgkmcnt(0)
	v_mfma_f32_16x16x32_bf16 v[124:127], v[144:147], v[176:179], v[124:127]
	v_mfma_f32_16x16x32_bf16 v[120:123], v[152:155], v[176:179], v[120:123]
	v_mfma_f32_16x16x32_bf16 v[116:119], v[144:147], v[184:187], v[116:119]
	v_mfma_f32_16x16x32_bf16 v[112:115], v[152:155], v[184:187], v[112:115]
	v_mfma_f32_16x16x32_bf16 v[100:103], v[144:147], v[194:197], v[100:103]
	v_mfma_f32_16x16x32_bf16 v[96:99], v[152:155], v[194:197], v[96:99]
	v_mfma_f32_16x16x32_bf16 v[84:87], v[144:147], v[202:205], v[84:87]
	v_mfma_f32_16x16x32_bf16 v[80:83], v[152:155], v[202:205], v[80:83]
	v_mfma_f32_16x16x32_bf16 v[124:127], v[148:151], v[180:183], v[124:127]
	v_mfma_f32_16x16x32_bf16 v[120:123], v[156:159], v[180:183], v[120:123]
	v_mfma_f32_16x16x32_bf16 v[116:119], v[148:151], v[188:191], v[116:119]
	v_mfma_f32_16x16x32_bf16 v[112:115], v[156:159], v[188:191], v[112:115]
	v_mfma_f32_16x16x32_bf16 v[100:103], v[148:151], v[198:201], v[100:103]
	v_mfma_f32_16x16x32_bf16 v[96:99], v[156:159], v[198:201], v[96:99]
	v_mfma_f32_16x16x32_bf16 v[84:87], v[148:151], v[206:209], v[84:87]
	v_mfma_f32_16x16x32_bf16 v[80:83], v[156:159], v[206:209], v[80:83]
	v_mfma_f32_16x16x32_bf16 v[108:111], v[160:163], v[176:179], v[108:111]
	v_mfma_f32_16x16x32_bf16 v[104:107], v[168:171], v[176:179], v[104:107]
	v_mfma_f32_16x16x32_bf16 v[92:95], v[160:163], v[184:187], v[92:95]
	v_mfma_f32_16x16x32_bf16 v[88:91], v[168:171], v[184:187], v[88:91]
	v_mfma_f32_16x16x32_bf16 v[76:79], v[160:163], v[194:197], v[76:79]
	v_mfma_f32_16x16x32_bf16 v[72:75], v[168:171], v[194:197], v[72:75]
	v_mfma_f32_16x16x32_bf16 v[68:71], v[160:163], v[202:205], v[68:71]
	v_mfma_f32_16x16x32_bf16 v[64:67], v[168:171], v[202:205], v[64:67]
	v_mfma_f32_16x16x32_bf16 v[108:111], v[164:167], v[180:183], v[108:111]
	v_mfma_f32_16x16x32_bf16 v[104:107], v[172:175], v[180:183], v[104:107]
	v_mfma_f32_16x16x32_bf16 v[92:95], v[164:167], v[188:191], v[92:95]
	v_mfma_f32_16x16x32_bf16 v[88:91], v[172:175], v[188:191], v[88:91]
	v_mfma_f32_16x16x32_bf16 v[76:79], v[164:167], v[198:201], v[76:79]
	v_mfma_f32_16x16x32_bf16 v[72:75], v[172:175], v[198:201], v[72:75]
	v_mfma_f32_16x16x32_bf16 v[68:71], v[164:167], v[206:209], v[68:71]
	v_mfma_f32_16x16x32_bf16 v[64:67], v[172:175], v[206:209], v[64:67]
	s_barrier
	s_add_i32 s28, s69, s56
	v_lshl_add_u64 v[210:211], v[210:211], 0, s[2:3]
	s_mov_b32 m0, s28
	ds_read_b128 v[176:179], v143 offset:49152
	ds_read_b128 v[180:183], v143 offset:50176
	ds_read_b128 v[184:187], v143 offset:51200
	ds_read_b128 v[188:191], v143 offset:52224
	ds_read_b128 v[194:197], v143 offset:53248
	ds_read_b128 v[198:201], v143 offset:54272
	ds_read_b128 v[202:205], v143 offset:55296
	ds_read_b128 v[206:209], v143 offset:56320
	global_load_lds_dwordx4 v[210:211], off
	s_add_i32 m0, s28, 0x2000
	s_add_u32 s28, s34, 0xb0080
	v_lshl_add_u64 v[210:211], v[212:213], 0, s[2:3]
	s_addc_u32 s29, s35, 0
	s_add_i32 s34, s70, s56
	global_load_lds_dwordx4 v[210:211], off
	v_lshl_add_u64 v[210:211], s[28:29], 0, v[132:133]
	s_mov_b32 m0, s34
	s_nop 0
	global_load_lds_dwordx4 v[210:211], off
	v_lshl_add_u64 v[210:211], s[28:29], 0, v[128:129]
	s_add_i32 m0, s34, 0x2000
	s_nop 0
	global_load_lds_dwordx4 v[210:211], off
	v_lshl_add_u64 v[210:211], v[214:215], 0, s[2:3]
	s_mov_b32 m0, s63
	s_nop 0
	global_load_lds_dwordx4 v[210:211], off
	v_lshl_add_u64 v[210:211], v[216:217], 0, s[2:3]
	s_mov_b32 m0, s64
	s_nop 0
	global_load_lds_dwordx4 v[210:211], off
	s_waitcnt vmcnt(8)
	s_waitcnt lgkmcnt(0)
	s_barrier
	s_waitcnt lgkmcnt(0)
	v_mfma_f32_16x16x32_bf16 v[60:63], v[144:147], v[176:179], v[60:63]
	v_mfma_f32_16x16x32_bf16 v[56:59], v[152:155], v[176:179], v[56:59]
	v_mfma_f32_16x16x32_bf16 v[52:55], v[144:147], v[184:187], v[52:55]
	v_mfma_f32_16x16x32_bf16 v[48:51], v[152:155], v[184:187], v[48:51]
	v_mfma_f32_16x16x32_bf16 v[36:39], v[144:147], v[194:197], v[36:39]
	v_mfma_f32_16x16x32_bf16 v[32:35], v[152:155], v[194:197], v[32:35]
	v_mfma_f32_16x16x32_bf16 v[20:23], v[144:147], v[202:205], v[20:23]
	v_mfma_f32_16x16x32_bf16 v[16:19], v[152:155], v[202:205], v[16:19]
	v_mfma_f32_16x16x32_bf16 v[60:63], v[148:151], v[180:183], v[60:63]
	v_mfma_f32_16x16x32_bf16 v[56:59], v[156:159], v[180:183], v[56:59]
	v_mfma_f32_16x16x32_bf16 v[52:55], v[148:151], v[188:191], v[52:55]
	v_mfma_f32_16x16x32_bf16 v[48:51], v[156:159], v[188:191], v[48:51]
	v_mfma_f32_16x16x32_bf16 v[36:39], v[148:151], v[198:201], v[36:39]
	v_mfma_f32_16x16x32_bf16 v[32:35], v[156:159], v[198:201], v[32:35]
	v_mfma_f32_16x16x32_bf16 v[20:23], v[148:151], v[206:209], v[20:23]
	v_mfma_f32_16x16x32_bf16 v[16:19], v[156:159], v[206:209], v[16:19]
	v_mfma_f32_16x16x32_bf16 v[44:47], v[160:163], v[176:179], v[44:47]
	v_mfma_f32_16x16x32_bf16 v[40:43], v[168:171], v[176:179], v[40:43]
	v_mfma_f32_16x16x32_bf16 v[28:31], v[160:163], v[184:187], v[28:31]
	v_mfma_f32_16x16x32_bf16 v[24:27], v[168:171], v[184:187], v[24:27]
	v_mfma_f32_16x16x32_bf16 v[12:15], v[160:163], v[194:197], v[12:15]
	v_mfma_f32_16x16x32_bf16 v[8:11], v[168:171], v[194:197], v[8:11]
	v_mfma_f32_16x16x32_bf16 v[4:7], v[160:163], v[202:205], v[4:7]
	v_mfma_f32_16x16x32_bf16 v[0:3], v[168:171], v[202:205], v[0:3]
	v_mfma_f32_16x16x32_bf16 v[44:47], v[164:167], v[180:183], v[44:47]
	v_mfma_f32_16x16x32_bf16 v[40:43], v[172:175], v[180:183], v[40:43]
	v_mfma_f32_16x16x32_bf16 v[28:31], v[164:167], v[188:191], v[28:31]
	v_mfma_f32_16x16x32_bf16 v[24:27], v[172:175], v[188:191], v[24:27]
	v_mfma_f32_16x16x32_bf16 v[12:15], v[164:167], v[198:201], v[12:15]
	v_mfma_f32_16x16x32_bf16 v[8:11], v[172:175], v[198:201], v[8:11]
	v_mfma_f32_16x16x32_bf16 v[4:7], v[164:167], v[206:209], v[4:7]
	v_mfma_f32_16x16x32_bf16 v[0:3], v[172:175], v[206:209], v[0:3]
	s_barrier
	s_add_i32 s68, s68, 2
	s_add_u32 s25, s25, 0x100
	s_addc_u32 s27, s27, 0
	s_cmp_gt_u32 s68, 41
	s_mov_b64 s[28:29], s[30:31]
	s_cbranch_scc0 .LBB0_936
	s_setprio 0
	s_and_b64 vcc, exec, s[20:21]
	s_cbranch_vccz .LBB0_939
	s_barrier
